# k-inner MFMA order plus Gray transitions: consecutive accumulator pairs share one operand fragment (k order alternates)
# speedup vs baseline: 1.0260x; 1.0084x over previous
.LBB0_114:
	s_lshl_b32 s26, s20, 20
	s_and_b64 s[50:51], s[22:23], exec
	s_cselect_b32 s50, s26, s55
	s_lshl_b32 s27, s48, 20
	s_and_b64 s[56:57], s[22:23], exec
	s_cselect_b32 s51, s27, s52
	s_addk_i32 s52, 0x100
	s_add_i32 s53, s55, 0x100
	s_mov_b32 s54, -2
	s_waitcnt vmcnt(0)
	v_add_u32_e32 v132, s55, v143
	v_add_u32_e32 v133, s55, v144
	ds_read_b128 v[150:153], v145
	ds_read_b128 v[154:157], v145 offset:1024
	ds_read_b128 v[158:161], v145 offset:2048
	ds_read_b128 v[162:165], v145 offset:3072
	ds_read_b128 v[166:169], v146
	ds_read_b128 v[170:173], v146 offset:1024
	ds_read_b128 v[174:177], v146 offset:2048
	ds_read_b128 v[178:181], v146 offset:3072
	s_cmp_eq_u32 s54, 28
	s_cselect_b32 s57, s50, s53
	s_cselect_b32 s56, s51, s52
	s_or_b32 s55, s57, 0x80
	s_add_i32 m0, s35, 0xc000
	ds_read_b128 v[182:185], v147
	ds_read_b128 v[186:189], v147 offset:1024
	ds_read_b128 v[190:193], v147 offset:2048
	ds_read_b128 v[194:197], v147 offset:3072
	ds_read_b128 v[198:201], v147 offset:4096
	ds_read_b128 v[212:215], v147 offset:5120
	ds_read_b128 v[218:221], v147 offset:6144
	ds_read_b128 v[222:225], v147 offset:7168
	global_load_lds_dwordx4 v133, s[4:5]
	s_add_i32 m0, s35, 0xe000
	s_nop 0
	global_load_lds_dwordx4 v132, s[4:5]
	s_waitcnt vmcnt(8)
	s_waitcnt lgkmcnt(0)
	s_setprio 1
	s_barrier
	v_mfma_f32_16x16x32_bf16 v[126:129], v[150:153], v[182:185], 0
	v_mfma_f32_16x16x32_bf16 v[126:129], v[154:157], v[186:189], v[126:129]
	v_mfma_f32_16x16x32_bf16 v[122:125], v[162:165], v[186:189], 0
	v_mfma_f32_16x16x32_bf16 v[122:125], v[158:161], v[182:185], v[122:125]
	v_mfma_f32_16x16x32_bf16 v[106:109], v[158:161], v[190:193], 0
	v_mfma_f32_16x16x32_bf16 v[106:109], v[162:165], v[194:197], v[106:109]
	v_mfma_f32_16x16x32_bf16 v[110:113], v[154:157], v[194:197], 0
	v_mfma_f32_16x16x32_bf16 v[110:113], v[150:153], v[190:193], v[110:113]
	v_mfma_f32_16x16x32_bf16 v[94:97], v[150:153], v[198:201], 0
	v_mfma_f32_16x16x32_bf16 v[94:97], v[154:157], v[212:215], v[94:97]
	v_mfma_f32_16x16x32_bf16 v[90:93], v[162:165], v[212:215], 0
	v_mfma_f32_16x16x32_bf16 v[90:93], v[158:161], v[198:201], v[90:93]
	v_mfma_f32_16x16x32_bf16 v[74:77], v[158:161], v[218:221], 0
	v_mfma_f32_16x16x32_bf16 v[74:77], v[162:165], v[222:225], v[74:77]
	v_mfma_f32_16x16x32_bf16 v[78:81], v[154:157], v[222:225], 0
	v_mfma_f32_16x16x32_bf16 v[78:81], v[150:153], v[218:221], v[78:81]
	s_setprio 0
	s_setprio 1
	v_mfma_f32_16x16x32_bf16 v[70:73], v[166:169], v[218:221], 0
	v_mfma_f32_16x16x32_bf16 v[70:73], v[170:173], v[222:225], v[70:73]
	v_mfma_f32_16x16x32_bf16 v[66:69], v[178:181], v[222:225], 0
	v_mfma_f32_16x16x32_bf16 v[66:69], v[174:177], v[218:221], v[66:69]
	v_mfma_f32_16x16x32_bf16 v[82:85], v[174:177], v[198:201], 0
	v_mfma_f32_16x16x32_bf16 v[82:85], v[178:181], v[212:215], v[82:85]
	v_mfma_f32_16x16x32_bf16 v[86:89], v[170:173], v[212:215], 0
	v_mfma_f32_16x16x32_bf16 v[86:89], v[166:169], v[198:201], v[86:89]
	v_mfma_f32_16x16x32_bf16 v[102:105], v[166:169], v[190:193], 0
	v_mfma_f32_16x16x32_bf16 v[102:105], v[170:173], v[194:197], v[102:105]
	v_mfma_f32_16x16x32_bf16 v[98:101], v[178:181], v[194:197], 0
	v_mfma_f32_16x16x32_bf16 v[98:101], v[174:177], v[190:193], v[98:101]
	v_mfma_f32_16x16x32_bf16 v[114:117], v[174:177], v[182:185], 0
	v_mfma_f32_16x16x32_bf16 v[114:117], v[178:181], v[186:189], v[114:117]
	v_mfma_f32_16x16x32_bf16 v[118:121], v[170:173], v[186:189], 0
	v_mfma_f32_16x16x32_bf16 v[118:121], v[166:169], v[182:185], v[118:121]
	s_setprio 0
	s_barrier
	s_mov_b32 m0, s25
	v_add_u32_e32 v134, s56, v137
	ds_read_b128 v[182:185], v147 offset:16384
	ds_read_b128 v[186:189], v147 offset:17408
	ds_read_b128 v[190:193], v147 offset:18432
	ds_read_b128 v[194:197], v147 offset:19456
	ds_read_b128 v[198:201], v147 offset:20480
	ds_read_b128 v[212:215], v147 offset:21504
	ds_read_b128 v[218:221], v147 offset:22528
	ds_read_b128 v[222:225], v147 offset:23552
	global_load_lds_dwordx4 v134, s[6:7]
	v_add_u32_e32 v134, s56, v139
	s_mov_b32 m0, s30
	s_add_i32 s58, s56, 0x80000
	global_load_lds_dwordx4 v134, s[6:7]
	v_add_u32_e32 v134, s58, v137
	s_mov_b32 m0, s31
	s_nop 0
	global_load_lds_dwordx4 v134, s[6:7]
	v_add_u32_e32 v134, s58, v139
	s_mov_b32 m0, s34
	s_nop 0
	global_load_lds_dwordx4 v134, s[6:7]
	v_add_u32_e32 v134, s57, v136
	s_mov_b32 m0, s35
	s_nop 0
	global_load_lds_dwordx4 v134, s[4:5]
	v_add_u32_e32 v134, s57, v138
	s_mov_b32 m0, s36
	s_nop 0
	global_load_lds_dwordx4 v134, s[4:5]
	s_waitcnt vmcnt(8)
	s_waitcnt lgkmcnt(0)
	s_setprio 1
	s_barrier
	v_mfma_f32_16x16x32_bf16 v[62:65], v[150:153], v[182:185], 0
	v_mfma_f32_16x16x32_bf16 v[62:65], v[154:157], v[186:189], v[62:65]
	v_mfma_f32_16x16x32_bf16 v[58:61], v[162:165], v[186:189], 0
	v_mfma_f32_16x16x32_bf16 v[58:61], v[158:161], v[182:185], v[58:61]
	v_mfma_f32_16x16x32_bf16 v[42:45], v[158:161], v[190:193], 0
	v_mfma_f32_16x16x32_bf16 v[42:45], v[162:165], v[194:197], v[42:45]
	v_mfma_f32_16x16x32_bf16 v[46:49], v[154:157], v[194:197], 0
	v_mfma_f32_16x16x32_bf16 v[46:49], v[150:153], v[190:193], v[46:49]
	v_mfma_f32_16x16x32_bf16 v[30:33], v[150:153], v[198:201], 0
	v_mfma_f32_16x16x32_bf16 v[30:33], v[154:157], v[212:215], v[30:33]
	v_mfma_f32_16x16x32_bf16 v[26:29], v[162:165], v[212:215], 0
	v_mfma_f32_16x16x32_bf16 v[26:29], v[158:161], v[198:201], v[26:29]
	v_mfma_f32_16x16x32_bf16 v[10:13], v[158:161], v[218:221], 0
	v_mfma_f32_16x16x32_bf16 v[10:13], v[162:165], v[222:225], v[10:13]
	v_mfma_f32_16x16x32_bf16 v[14:17], v[154:157], v[222:225], 0
	v_mfma_f32_16x16x32_bf16 v[14:17], v[150:153], v[218:221], v[14:17]
	s_setprio 0
	s_setprio 1
	v_mfma_f32_16x16x32_bf16 v[6:9], v[166:169], v[218:221], 0
	v_mfma_f32_16x16x32_bf16 v[6:9], v[170:173], v[222:225], v[6:9]
	v_mfma_f32_16x16x32_bf16 v[2:5], v[178:181], v[222:225], 0
	v_mfma_f32_16x16x32_bf16 v[2:5], v[174:177], v[218:221], v[2:5]
	v_mfma_f32_16x16x32_bf16 v[18:21], v[174:177], v[198:201], 0
	v_mfma_f32_16x16x32_bf16 v[18:21], v[178:181], v[212:215], v[18:21]
	v_mfma_f32_16x16x32_bf16 v[22:25], v[170:173], v[212:215], 0
	v_mfma_f32_16x16x32_bf16 v[22:25], v[166:169], v[198:201], v[22:25]
	v_mfma_f32_16x16x32_bf16 v[38:41], v[166:169], v[190:193], 0
	v_mfma_f32_16x16x32_bf16 v[38:41], v[170:173], v[194:197], v[38:41]
	v_mfma_f32_16x16x32_bf16 v[34:37], v[178:181], v[194:197], 0
	v_mfma_f32_16x16x32_bf16 v[34:37], v[174:177], v[190:193], v[34:37]
	v_mfma_f32_16x16x32_bf16 v[50:53], v[174:177], v[182:185], 0
	v_mfma_f32_16x16x32_bf16 v[50:53], v[178:181], v[186:189], v[50:53]
	v_mfma_f32_16x16x32_bf16 v[54:57], v[170:173], v[186:189], 0
	v_mfma_f32_16x16x32_bf16 v[54:57], v[166:169], v[182:185], v[54:57]
	s_setprio 0
	s_barrier
	ds_read_b128 v[150:153], v148
	ds_read_b128 v[154:157], v148 offset:1024
	ds_read_b128 v[158:161], v148 offset:2048
	ds_read_b128 v[162:165], v148 offset:3072
	ds_read_b128 v[166:169], v149
	ds_read_b128 v[170:173], v149 offset:1024
	ds_read_b128 v[174:177], v149 offset:2048
	ds_read_b128 v[178:181], v149 offset:3072
	s_add_i32 s57, s57, 0x80000
	s_mov_b32 m0, s37
	v_add_u32_e32 v134, s57, v136
	ds_read_b128 v[182:185], v147 offset:32768
	ds_read_b128 v[186:189], v147 offset:33792
	ds_read_b128 v[190:193], v147 offset:34816
	ds_read_b128 v[194:197], v147 offset:35840
	ds_read_b128 v[198:201], v147 offset:36864
	ds_read_b128 v[212:215], v147 offset:37888
	ds_read_b128 v[218:221], v147 offset:38912
	ds_read_b128 v[222:225], v147 offset:39936
	global_load_lds_dwordx4 v134, s[4:5]
	v_add_u32_e32 v134, s57, v138
	s_mov_b32 m0, s38
	s_nop 0
	global_load_lds_dwordx4 v134, s[4:5]
	s_waitcnt vmcnt(8)
	s_waitcnt lgkmcnt(0)
	s_setprio 1
	s_barrier
	v_mfma_f32_16x16x32_bf16 v[126:129], v[150:153], v[182:185], v[126:129]
	v_mfma_f32_16x16x32_bf16 v[126:129], v[154:157], v[186:189], v[126:129]
	v_mfma_f32_16x16x32_bf16 v[122:125], v[162:165], v[186:189], v[122:125]
	v_mfma_f32_16x16x32_bf16 v[122:125], v[158:161], v[182:185], v[122:125]
	v_mfma_f32_16x16x32_bf16 v[106:109], v[158:161], v[190:193], v[106:109]
	v_mfma_f32_16x16x32_bf16 v[106:109], v[162:165], v[194:197], v[106:109]
	v_mfma_f32_16x16x32_bf16 v[110:113], v[154:157], v[194:197], v[110:113]
	v_mfma_f32_16x16x32_bf16 v[110:113], v[150:153], v[190:193], v[110:113]
	v_mfma_f32_16x16x32_bf16 v[94:97], v[150:153], v[198:201], v[94:97]
	v_mfma_f32_16x16x32_bf16 v[94:97], v[154:157], v[212:215], v[94:97]
	v_mfma_f32_16x16x32_bf16 v[90:93], v[162:165], v[212:215], v[90:93]
	v_mfma_f32_16x16x32_bf16 v[90:93], v[158:161], v[198:201], v[90:93]
	v_mfma_f32_16x16x32_bf16 v[74:77], v[158:161], v[218:221], v[74:77]
	v_mfma_f32_16x16x32_bf16 v[74:77], v[162:165], v[222:225], v[74:77]
	v_mfma_f32_16x16x32_bf16 v[78:81], v[154:157], v[222:225], v[78:81]
	v_mfma_f32_16x16x32_bf16 v[78:81], v[150:153], v[218:221], v[78:81]
	s_setprio 0
	s_setprio 1
	v_mfma_f32_16x16x32_bf16 v[70:73], v[166:169], v[218:221], v[70:73]
	v_mfma_f32_16x16x32_bf16 v[70:73], v[170:173], v[222:225], v[70:73]
	v_mfma_f32_16x16x32_bf16 v[66:69], v[178:181], v[222:225], v[66:69]
	v_mfma_f32_16x16x32_bf16 v[66:69], v[174:177], v[218:221], v[66:69]
	v_mfma_f32_16x16x32_bf16 v[82:85], v[174:177], v[198:201], v[82:85]
	v_mfma_f32_16x16x32_bf16 v[82:85], v[178:181], v[212:215], v[82:85]
	v_mfma_f32_16x16x32_bf16 v[86:89], v[170:173], v[212:215], v[86:89]
	v_mfma_f32_16x16x32_bf16 v[86:89], v[166:169], v[198:201], v[86:89]
	v_mfma_f32_16x16x32_bf16 v[102:105], v[166:169], v[190:193], v[102:105]
	v_mfma_f32_16x16x32_bf16 v[102:105], v[170:173], v[194:197], v[102:105]
	v_mfma_f32_16x16x32_bf16 v[98:101], v[178:181], v[194:197], v[98:101]
	v_mfma_f32_16x16x32_bf16 v[98:101], v[174:177], v[190:193], v[98:101]
	v_mfma_f32_16x16x32_bf16 v[114:117], v[174:177], v[182:185], v[114:117]
	v_mfma_f32_16x16x32_bf16 v[114:117], v[178:181], v[186:189], v[114:117]
	v_mfma_f32_16x16x32_bf16 v[118:121], v[170:173], v[186:189], v[118:121]
	v_mfma_f32_16x16x32_bf16 v[118:121], v[166:169], v[182:185], v[118:121]
	s_setprio 0
	s_barrier
	s_or_b32 s57, s56, 0x80
	s_mov_b32 m0, s39
	v_add_u32_e32 v134, s57, v137
	ds_read_b128 v[182:185], v147 offset:49152
	ds_read_b128 v[186:189], v147 offset:50176
	ds_read_b128 v[190:193], v147 offset:51200
	ds_read_b128 v[194:197], v147 offset:52224
	ds_read_b128 v[198:201], v147 offset:53248
	ds_read_b128 v[212:215], v147 offset:54272
	ds_read_b128 v[218:221], v147 offset:55296
	ds_read_b128 v[222:225], v147 offset:56320
	global_load_lds_dwordx4 v134, s[6:7]
	v_add_u32_e32 v134, s57, v139
	s_mov_b32 m0, s40
	s_add_i32 s56, s56, 0x80080
	global_load_lds_dwordx4 v134, s[6:7]
	v_add_u32_e32 v134, s56, v137
	s_mov_b32 m0, s43
	s_nop 0
	global_load_lds_dwordx4 v134, s[6:7]
	v_add_u32_e32 v134, s56, v139
	s_mov_b32 m0, s44
	s_nop 0
	global_load_lds_dwordx4 v134, s[6:7]
	v_add_u32_e32 v134, s55, v136
	s_mov_b32 m0, s41
	s_nop 0
	global_load_lds_dwordx4 v134, s[4:5]
	v_add_u32_e32 v134, s55, v138
	s_mov_b32 m0, s42
	s_nop 0
	global_load_lds_dwordx4 v134, s[4:5]
	s_waitcnt vmcnt(8)
	s_waitcnt lgkmcnt(0)
	s_setprio 1
	s_barrier
	v_mfma_f32_16x16x32_bf16 v[62:65], v[150:153], v[182:185], v[62:65]
	v_mfma_f32_16x16x32_bf16 v[62:65], v[154:157], v[186:189], v[62:65]
	v_mfma_f32_16x16x32_bf16 v[58:61], v[162:165], v[186:189], v[58:61]
	v_mfma_f32_16x16x32_bf16 v[58:61], v[158:161], v[182:185], v[58:61]
	v_mfma_f32_16x16x32_bf16 v[42:45], v[158:161], v[190:193], v[42:45]
	v_mfma_f32_16x16x32_bf16 v[42:45], v[162:165], v[194:197], v[42:45]
	v_mfma_f32_16x16x32_bf16 v[46:49], v[154:157], v[194:197], v[46:49]
	v_mfma_f32_16x16x32_bf16 v[46:49], v[150:153], v[190:193], v[46:49]
	v_mfma_f32_16x16x32_bf16 v[30:33], v[150:153], v[198:201], v[30:33]
	v_mfma_f32_16x16x32_bf16 v[30:33], v[154:157], v[212:215], v[30:33]
	v_mfma_f32_16x16x32_bf16 v[26:29], v[162:165], v[212:215], v[26:29]
	v_mfma_f32_16x16x32_bf16 v[26:29], v[158:161], v[198:201], v[26:29]
	v_mfma_f32_16x16x32_bf16 v[10:13], v[158:161], v[218:221], v[10:13]
	v_mfma_f32_16x16x32_bf16 v[10:13], v[162:165], v[222:225], v[10:13]
	v_mfma_f32_16x16x32_bf16 v[14:17], v[154:157], v[222:225], v[14:17]
	v_mfma_f32_16x16x32_bf16 v[14:17], v[150:153], v[218:221], v[14:17]
	s_setprio 0
	s_setprio 1
	v_mfma_f32_16x16x32_bf16 v[6:9], v[166:169], v[218:221], v[6:9]
	v_mfma_f32_16x16x32_bf16 v[6:9], v[170:173], v[222:225], v[6:9]
	v_mfma_f32_16x16x32_bf16 v[2:5], v[178:181], v[222:225], v[2:5]
	v_mfma_f32_16x16x32_bf16 v[2:5], v[174:177], v[218:221], v[2:5]
	v_mfma_f32_16x16x32_bf16 v[18:21], v[174:177], v[198:201], v[18:21]
	v_mfma_f32_16x16x32_bf16 v[18:21], v[178:181], v[212:215], v[18:21]
	v_mfma_f32_16x16x32_bf16 v[22:25], v[170:173], v[212:215], v[22:25]
	v_mfma_f32_16x16x32_bf16 v[22:25], v[166:169], v[198:201], v[22:25]
	v_mfma_f32_16x16x32_bf16 v[38:41], v[166:169], v[190:193], v[38:41]
	v_mfma_f32_16x16x32_bf16 v[38:41], v[170:173], v[194:197], v[38:41]
	v_mfma_f32_16x16x32_bf16 v[34:37], v[178:181], v[194:197], v[34:37]
	v_mfma_f32_16x16x32_bf16 v[34:37], v[174:177], v[190:193], v[34:37]
	v_mfma_f32_16x16x32_bf16 v[50:53], v[174:177], v[182:185], v[50:53]
	v_mfma_f32_16x16x32_bf16 v[50:53], v[178:181], v[186:189], v[50:53]
	v_mfma_f32_16x16x32_bf16 v[54:57], v[170:173], v[186:189], v[54:57]
	v_mfma_f32_16x16x32_bf16 v[54:57], v[166:169], v[182:185], v[54:57]
	s_setprio 0
	s_barrier
	s_add_i32 s54, s54, 2
	s_addk_i32 s52, 0x100
	s_addk_i32 s53, 0x100
	v_add_u32_e32 v132, 0x100, v132
	s_cmp_gt_u32 s54, 29
	v_add_u32_e32 v133, 0x100, v133
.LBB0_115:
	ds_read_b128 v[150:153], v145
	ds_read_b128 v[154:157], v145 offset:1024
	ds_read_b128 v[158:161], v145 offset:2048
	ds_read_b128 v[162:165], v145 offset:3072
	ds_read_b128 v[166:169], v146
	ds_read_b128 v[170:173], v146 offset:1024
	ds_read_b128 v[174:177], v146 offset:2048
	ds_read_b128 v[178:181], v146 offset:3072
	s_cmp_eq_u32 s54, 28
	s_cselect_b32 s57, s50, s53
	s_cselect_b32 s56, s51, s52
	s_or_b32 s55, s57, 0x80
	s_add_i32 m0, s35, 0xc000
	ds_read_b128 v[182:185], v147
	ds_read_b128 v[186:189], v147 offset:1024
	ds_read_b128 v[190:193], v147 offset:2048
	ds_read_b128 v[194:197], v147 offset:3072
	ds_read_b128 v[198:201], v147 offset:4096
	ds_read_b128 v[212:215], v147 offset:5120
	ds_read_b128 v[218:221], v147 offset:6144
	ds_read_b128 v[222:225], v147 offset:7168
	global_load_lds_dwordx4 v133, s[4:5]
	s_add_i32 m0, s35, 0xe000
	s_nop 0
	global_load_lds_dwordx4 v132, s[4:5]
	s_waitcnt vmcnt(8)
	s_waitcnt lgkmcnt(0)
	s_setprio 1
	s_barrier
	v_mfma_f32_16x16x32_bf16 v[126:129], v[150:153], v[182:185], v[126:129]
	v_mfma_f32_16x16x32_bf16 v[126:129], v[154:157], v[186:189], v[126:129]
	v_mfma_f32_16x16x32_bf16 v[122:125], v[162:165], v[186:189], v[122:125]
	v_mfma_f32_16x16x32_bf16 v[122:125], v[158:161], v[182:185], v[122:125]
	v_mfma_f32_16x16x32_bf16 v[106:109], v[158:161], v[190:193], v[106:109]
	v_mfma_f32_16x16x32_bf16 v[106:109], v[162:165], v[194:197], v[106:109]
	v_mfma_f32_16x16x32_bf16 v[110:113], v[154:157], v[194:197], v[110:113]
	v_mfma_f32_16x16x32_bf16 v[110:113], v[150:153], v[190:193], v[110:113]
	v_mfma_f32_16x16x32_bf16 v[94:97], v[150:153], v[198:201], v[94:97]
	v_mfma_f32_16x16x32_bf16 v[94:97], v[154:157], v[212:215], v[94:97]
	v_mfma_f32_16x16x32_bf16 v[90:93], v[162:165], v[212:215], v[90:93]
	v_mfma_f32_16x16x32_bf16 v[90:93], v[158:161], v[198:201], v[90:93]
	v_mfma_f32_16x16x32_bf16 v[74:77], v[158:161], v[218:221], v[74:77]
	v_mfma_f32_16x16x32_bf16 v[74:77], v[162:165], v[222:225], v[74:77]
	v_mfma_f32_16x16x32_bf16 v[78:81], v[154:157], v[222:225], v[78:81]
	v_mfma_f32_16x16x32_bf16 v[78:81], v[150:153], v[218:221], v[78:81]
	s_setprio 0
	s_setprio 1
	v_mfma_f32_16x16x32_bf16 v[70:73], v[166:169], v[218:221], v[70:73]
	v_mfma_f32_16x16x32_bf16 v[70:73], v[170:173], v[222:225], v[70:73]
	v_mfma_f32_16x16x32_bf16 v[66:69], v[178:181], v[222:225], v[66:69]
	v_mfma_f32_16x16x32_bf16 v[66:69], v[174:177], v[218:221], v[66:69]
	v_mfma_f32_16x16x32_bf16 v[82:85], v[174:177], v[198:201], v[82:85]
	v_mfma_f32_16x16x32_bf16 v[82:85], v[178:181], v[212:215], v[82:85]
	v_mfma_f32_16x16x32_bf16 v[86:89], v[170:173], v[212:215], v[86:89]
	v_mfma_f32_16x16x32_bf16 v[86:89], v[166:169], v[198:201], v[86:89]
	v_mfma_f32_16x16x32_bf16 v[102:105], v[166:169], v[190:193], v[102:105]
	v_mfma_f32_16x16x32_bf16 v[102:105], v[170:173], v[194:197], v[102:105]
	v_mfma_f32_16x16x32_bf16 v[98:101], v[178:181], v[194:197], v[98:101]
	v_mfma_f32_16x16x32_bf16 v[98:101], v[174:177], v[190:193], v[98:101]
	v_mfma_f32_16x16x32_bf16 v[114:117], v[174:177], v[182:185], v[114:117]
	v_mfma_f32_16x16x32_bf16 v[114:117], v[178:181], v[186:189], v[114:117]
	v_mfma_f32_16x16x32_bf16 v[118:121], v[170:173], v[186:189], v[118:121]
	v_mfma_f32_16x16x32_bf16 v[118:121], v[166:169], v[182:185], v[118:121]
	s_setprio 0
	s_barrier
	s_mov_b32 m0, s25
	v_add_u32_e32 v134, s56, v137
	ds_read_b128 v[182:185], v147 offset:16384
	ds_read_b128 v[186:189], v147 offset:17408
	ds_read_b128 v[190:193], v147 offset:18432
	ds_read_b128 v[194:197], v147 offset:19456
	ds_read_b128 v[198:201], v147 offset:20480
	ds_read_b128 v[212:215], v147 offset:21504
	ds_read_b128 v[218:221], v147 offset:22528
	ds_read_b128 v[222:225], v147 offset:23552
	global_load_lds_dwordx4 v134, s[6:7]
	v_add_u32_e32 v134, s56, v139
	s_mov_b32 m0, s30
	s_add_i32 s58, s56, 0x80000
	global_load_lds_dwordx4 v134, s[6:7]
	v_add_u32_e32 v134, s58, v137
	s_mov_b32 m0, s31
	s_nop 0
	global_load_lds_dwordx4 v134, s[6:7]
	v_add_u32_e32 v134, s58, v139
	s_mov_b32 m0, s34
	s_nop 0
	global_load_lds_dwordx4 v134, s[6:7]
	v_add_u32_e32 v134, s57, v136
	s_mov_b32 m0, s35
	s_nop 0
	global_load_lds_dwordx4 v134, s[4:5]
	v_add_u32_e32 v134, s57, v138
	s_mov_b32 m0, s36
	s_nop 0
	global_load_lds_dwordx4 v134, s[4:5]
	s_waitcnt vmcnt(8)
	s_waitcnt lgkmcnt(0)
	s_setprio 1
	s_barrier
	v_mfma_f32_16x16x32_bf16 v[62:65], v[150:153], v[182:185], v[62:65]
	v_mfma_f32_16x16x32_bf16 v[62:65], v[154:157], v[186:189], v[62:65]
	v_mfma_f32_16x16x32_bf16 v[58:61], v[162:165], v[186:189], v[58:61]
	v_mfma_f32_16x16x32_bf16 v[58:61], v[158:161], v[182:185], v[58:61]
	v_mfma_f32_16x16x32_bf16 v[42:45], v[158:161], v[190:193], v[42:45]
	v_mfma_f32_16x16x32_bf16 v[42:45], v[162:165], v[194:197], v[42:45]
	v_mfma_f32_16x16x32_bf16 v[46:49], v[154:157], v[194:197], v[46:49]
	v_mfma_f32_16x16x32_bf16 v[46:49], v[150:153], v[190:193], v[46:49]
	v_mfma_f32_16x16x32_bf16 v[30:33], v[150:153], v[198:201], v[30:33]
	v_mfma_f32_16x16x32_bf16 v[30:33], v[154:157], v[212:215], v[30:33]
	v_mfma_f32_16x16x32_bf16 v[26:29], v[162:165], v[212:215], v[26:29]
	v_mfma_f32_16x16x32_bf16 v[26:29], v[158:161], v[198:201], v[26:29]
	v_mfma_f32_16x16x32_bf16 v[10:13], v[158:161], v[218:221], v[10:13]
	v_mfma_f32_16x16x32_bf16 v[10:13], v[162:165], v[222:225], v[10:13]
	v_mfma_f32_16x16x32_bf16 v[14:17], v[154:157], v[222:225], v[14:17]
	v_mfma_f32_16x16x32_bf16 v[14:17], v[150:153], v[218:221], v[14:17]
	s_setprio 0
	s_setprio 1
	v_mfma_f32_16x16x32_bf16 v[6:9], v[166:169], v[218:221], v[6:9]
	v_mfma_f32_16x16x32_bf16 v[6:9], v[170:173], v[222:225], v[6:9]
	v_mfma_f32_16x16x32_bf16 v[2:5], v[178:181], v[222:225], v[2:5]
	v_mfma_f32_16x16x32_bf16 v[2:5], v[174:177], v[218:221], v[2:5]
	v_mfma_f32_16x16x32_bf16 v[18:21], v[174:177], v[198:201], v[18:21]
	v_mfma_f32_16x16x32_bf16 v[18:21], v[178:181], v[212:215], v[18:21]
	v_mfma_f32_16x16x32_bf16 v[22:25], v[170:173], v[212:215], v[22:25]
	v_mfma_f32_16x16x32_bf16 v[22:25], v[166:169], v[198:201], v[22:25]
	v_mfma_f32_16x16x32_bf16 v[38:41], v[166:169], v[190:193], v[38:41]
	v_mfma_f32_16x16x32_bf16 v[38:41], v[170:173], v[194:197], v[38:41]
	v_mfma_f32_16x16x32_bf16 v[34:37], v[178:181], v[194:197], v[34:37]
	v_mfma_f32_16x16x32_bf16 v[34:37], v[174:177], v[190:193], v[34:37]
	v_mfma_f32_16x16x32_bf16 v[50:53], v[174:177], v[182:185], v[50:53]
	v_mfma_f32_16x16x32_bf16 v[50:53], v[178:181], v[186:189], v[50:53]
	v_mfma_f32_16x16x32_bf16 v[54:57], v[170:173], v[186:189], v[54:57]
	v_mfma_f32_16x16x32_bf16 v[54:57], v[166:169], v[182:185], v[54:57]
	s_setprio 0
	s_barrier
	ds_read_b128 v[150:153], v148
	ds_read_b128 v[154:157], v148 offset:1024
	ds_read_b128 v[158:161], v148 offset:2048
	ds_read_b128 v[162:165], v148 offset:3072
	ds_read_b128 v[166:169], v149
	ds_read_b128 v[170:173], v149 offset:1024
	ds_read_b128 v[174:177], v149 offset:2048
	ds_read_b128 v[178:181], v149 offset:3072
	s_add_i32 s57, s57, 0x80000
	s_mov_b32 m0, s37
	v_add_u32_e32 v134, s57, v136
	ds_read_b128 v[182:185], v147 offset:32768
	ds_read_b128 v[186:189], v147 offset:33792
	ds_read_b128 v[190:193], v147 offset:34816
	ds_read_b128 v[194:197], v147 offset:35840
	ds_read_b128 v[198:201], v147 offset:36864
	ds_read_b128 v[212:215], v147 offset:37888
	ds_read_b128 v[218:221], v147 offset:38912
	ds_read_b128 v[222:225], v147 offset:39936
	global_load_lds_dwordx4 v134, s[4:5]
	v_add_u32_e32 v134, s57, v138
	s_mov_b32 m0, s38
	s_nop 0
	global_load_lds_dwordx4 v134, s[4:5]
	s_waitcnt vmcnt(8)
	s_waitcnt lgkmcnt(0)
	s_setprio 1
	s_barrier
	v_mfma_f32_16x16x32_bf16 v[126:129], v[150:153], v[182:185], v[126:129]
	v_mfma_f32_16x16x32_bf16 v[126:129], v[154:157], v[186:189], v[126:129]
	v_mfma_f32_16x16x32_bf16 v[122:125], v[162:165], v[186:189], v[122:125]
	v_mfma_f32_16x16x32_bf16 v[122:125], v[158:161], v[182:185], v[122:125]
	v_mfma_f32_16x16x32_bf16 v[106:109], v[158:161], v[190:193], v[106:109]
	v_mfma_f32_16x16x32_bf16 v[106:109], v[162:165], v[194:197], v[106:109]
	v_mfma_f32_16x16x32_bf16 v[110:113], v[154:157], v[194:197], v[110:113]
	v_mfma_f32_16x16x32_bf16 v[110:113], v[150:153], v[190:193], v[110:113]
	v_mfma_f32_16x16x32_bf16 v[94:97], v[150:153], v[198:201], v[94:97]
	v_mfma_f32_16x16x32_bf16 v[94:97], v[154:157], v[212:215], v[94:97]
	v_mfma_f32_16x16x32_bf16 v[90:93], v[162:165], v[212:215], v[90:93]
	v_mfma_f32_16x16x32_bf16 v[90:93], v[158:161], v[198:201], v[90:93]
	v_mfma_f32_16x16x32_bf16 v[74:77], v[158:161], v[218:221], v[74:77]
	v_mfma_f32_16x16x32_bf16 v[74:77], v[162:165], v[222:225], v[74:77]
	v_mfma_f32_16x16x32_bf16 v[78:81], v[154:157], v[222:225], v[78:81]
	v_mfma_f32_16x16x32_bf16 v[78:81], v[150:153], v[218:221], v[78:81]
	s_setprio 0
	s_setprio 1
	v_mfma_f32_16x16x32_bf16 v[70:73], v[166:169], v[218:221], v[70:73]
	v_mfma_f32_16x16x32_bf16 v[70:73], v[170:173], v[222:225], v[70:73]
	v_mfma_f32_16x16x32_bf16 v[66:69], v[178:181], v[222:225], v[66:69]
	v_mfma_f32_16x16x32_bf16 v[66:69], v[174:177], v[218:221], v[66:69]
	v_mfma_f32_16x16x32_bf16 v[82:85], v[174:177], v[198:201], v[82:85]
	v_mfma_f32_16x16x32_bf16 v[82:85], v[178:181], v[212:215], v[82:85]
	v_mfma_f32_16x16x32_bf16 v[86:89], v[170:173], v[212:215], v[86:89]
	v_mfma_f32_16x16x32_bf16 v[86:89], v[166:169], v[198:201], v[86:89]
	v_mfma_f32_16x16x32_bf16 v[102:105], v[166:169], v[190:193], v[102:105]
	v_mfma_f32_16x16x32_bf16 v[102:105], v[170:173], v[194:197], v[102:105]
	v_mfma_f32_16x16x32_bf16 v[98:101], v[178:181], v[194:197], v[98:101]
	v_mfma_f32_16x16x32_bf16 v[98:101], v[174:177], v[190:193], v[98:101]
	v_mfma_f32_16x16x32_bf16 v[114:117], v[174:177], v[182:185], v[114:117]
	v_mfma_f32_16x16x32_bf16 v[114:117], v[178:181], v[186:189], v[114:117]
	v_mfma_f32_16x16x32_bf16 v[118:121], v[170:173], v[186:189], v[118:121]
	v_mfma_f32_16x16x32_bf16 v[118:121], v[166:169], v[182:185], v[118:121]
	s_setprio 0
	s_barrier
	s_or_b32 s57, s56, 0x80
	s_mov_b32 m0, s39
	v_add_u32_e32 v134, s57, v137
	ds_read_b128 v[182:185], v147 offset:49152
	ds_read_b128 v[186:189], v147 offset:50176
	ds_read_b128 v[190:193], v147 offset:51200
	ds_read_b128 v[194:197], v147 offset:52224
	ds_read_b128 v[198:201], v147 offset:53248
	ds_read_b128 v[212:215], v147 offset:54272
	ds_read_b128 v[218:221], v147 offset:55296
	ds_read_b128 v[222:225], v147 offset:56320
	global_load_lds_dwordx4 v134, s[6:7]
	v_add_u32_e32 v134, s57, v139
	s_mov_b32 m0, s40
	s_add_i32 s56, s56, 0x80080
	global_load_lds_dwordx4 v134, s[6:7]
	v_add_u32_e32 v134, s56, v137
	s_mov_b32 m0, s43
	s_nop 0
	global_load_lds_dwordx4 v134, s[6:7]
	v_add_u32_e32 v134, s56, v139
	s_mov_b32 m0, s44
	s_nop 0
	global_load_lds_dwordx4 v134, s[6:7]
	v_add_u32_e32 v134, s55, v136
	s_mov_b32 m0, s41
	s_nop 0
	global_load_lds_dwordx4 v134, s[4:5]
	v_add_u32_e32 v134, s55, v138
	s_mov_b32 m0, s42
	s_nop 0
	global_load_lds_dwordx4 v134, s[4:5]
	s_add_i32 s54, s54, 2
	s_addk_i32 s52, 0x100
	s_addk_i32 s53, 0x100
	v_add_u32_e32 v132, 0x100, v132
	s_cmp_gt_u32 s54, 29
	v_add_u32_e32 v133, 0x100, v133
	s_waitcnt vmcnt(8)
	s_waitcnt lgkmcnt(0)
	s_setprio 1
	s_barrier
	v_mfma_f32_16x16x32_bf16 v[62:65], v[150:153], v[182:185], v[62:65]
	v_mfma_f32_16x16x32_bf16 v[62:65], v[154:157], v[186:189], v[62:65]
	v_mfma_f32_16x16x32_bf16 v[58:61], v[162:165], v[186:189], v[58:61]
	v_mfma_f32_16x16x32_bf16 v[58:61], v[158:161], v[182:185], v[58:61]
	v_mfma_f32_16x16x32_bf16 v[42:45], v[158:161], v[190:193], v[42:45]
	v_mfma_f32_16x16x32_bf16 v[42:45], v[162:165], v[194:197], v[42:45]
	v_mfma_f32_16x16x32_bf16 v[46:49], v[154:157], v[194:197], v[46:49]
	v_mfma_f32_16x16x32_bf16 v[46:49], v[150:153], v[190:193], v[46:49]
	v_mfma_f32_16x16x32_bf16 v[30:33], v[150:153], v[198:201], v[30:33]
	v_mfma_f32_16x16x32_bf16 v[30:33], v[154:157], v[212:215], v[30:33]
	v_mfma_f32_16x16x32_bf16 v[26:29], v[162:165], v[212:215], v[26:29]
	v_mfma_f32_16x16x32_bf16 v[26:29], v[158:161], v[198:201], v[26:29]
	v_mfma_f32_16x16x32_bf16 v[10:13], v[158:161], v[218:221], v[10:13]
	v_mfma_f32_16x16x32_bf16 v[10:13], v[162:165], v[222:225], v[10:13]
	v_mfma_f32_16x16x32_bf16 v[14:17], v[154:157], v[222:225], v[14:17]
	v_mfma_f32_16x16x32_bf16 v[14:17], v[150:153], v[218:221], v[14:17]
	s_setprio 0
	s_setprio 1
	v_mfma_f32_16x16x32_bf16 v[6:9], v[166:169], v[218:221], v[6:9]
	v_mfma_f32_16x16x32_bf16 v[6:9], v[170:173], v[222:225], v[6:9]
	v_mfma_f32_16x16x32_bf16 v[2:5], v[178:181], v[222:225], v[2:5]
	v_mfma_f32_16x16x32_bf16 v[2:5], v[174:177], v[218:221], v[2:5]
	v_mfma_f32_16x16x32_bf16 v[18:21], v[174:177], v[198:201], v[18:21]
	v_mfma_f32_16x16x32_bf16 v[18:21], v[178:181], v[212:215], v[18:21]
	v_mfma_f32_16x16x32_bf16 v[22:25], v[170:173], v[212:215], v[22:25]
	v_mfma_f32_16x16x32_bf16 v[22:25], v[166:169], v[198:201], v[22:25]
	v_mfma_f32_16x16x32_bf16 v[38:41], v[166:169], v[190:193], v[38:41]
	v_mfma_f32_16x16x32_bf16 v[38:41], v[170:173], v[194:197], v[38:41]
	v_mfma_f32_16x16x32_bf16 v[34:37], v[178:181], v[194:197], v[34:37]
	v_mfma_f32_16x16x32_bf16 v[34:37], v[174:177], v[190:193], v[34:37]
	v_mfma_f32_16x16x32_bf16 v[50:53], v[174:177], v[182:185], v[50:53]
	v_mfma_f32_16x16x32_bf16 v[50:53], v[178:181], v[186:189], v[50:53]
	v_mfma_f32_16x16x32_bf16 v[54:57], v[170:173], v[186:189], v[54:57]
	v_mfma_f32_16x16x32_bf16 v[54:57], v[166:169], v[182:185], v[54:57]
	s_setprio 0
	s_barrier
	s_cbranch_scc0 .LBB0_115
	s_and_b64 vcc, exec, s[16:17]
	s_cbranch_vccz .LBB0_118
	s_barrier

.LBB0_135:
	v_lshrrev_b32_e32 v9, 1, v5
	v_and_b32_e32 v135, 24, v9
	v_and_b32_e32 v136, 15, v5
	v_lshlrev_b32_e32 v9, 1, v135
	v_lshlrev_b32_e32 v5, 2, v5
	s_lshl_b32 s27, s27, 5
	s_lshl_b32 s26, s29, 6
	v_lshl_or_b32 v9, v136, 6, v9
	s_lshl_b32 s29, s29, 13
	v_and_b32_e32 v5, 32, v5
	s_and_b32 s27, s27, 0x60
	v_bitop3_b32 v10, v9, s29, v5 bitop3:0xde
	s_lshl_b32 s29, s27, 7
	v_bitop3_b32 v137, v9, s29, v5 bitop3:0xde
	s_add_i32 s29, s28, 0x18000
	s_or_b32 s31, s12, 0x80
	s_add_i32 s30, s29, s37
	v_add_u32_e32 v5, s31, v131
	s_mov_b32 m0, s30
	s_waitcnt vmcnt(2)
	s_barrier
	global_load_lds_dwordx4 v5, s[6:7]
	v_add_u32_e32 v5, s31, v133
	s_add_i32 s31, s30, 0x2000
	s_mov_b32 m0, s31
	s_or_b32 s35, s21, 0x80
	s_add_i32 s34, s22, 0x8000
	global_load_lds_dwordx4 v5, s[6:7]
	v_add_u32_e32 v5, s35, v130
	s_mov_b32 m0, s34
	s_add_i32 s36, s28, 0x1c000
	global_load_lds_dwordx4 v5, s[4:5]
	v_add_u32_e32 v5, s35, v132
	s_add_i32 s35, s22, 0xa000
	s_mov_b32 m0, s35
	s_or_b32 s38, s12, 0x80080
	s_add_i32 s37, s36, s37
	global_load_lds_dwordx4 v5, s[4:5]
	v_add_u32_e32 v5, s38, v131
	s_mov_b32 m0, s37
	s_add_i32 s39, s21, 0x80080
	global_load_lds_dwordx4 v5, s[6:7]
	v_add_u32_e32 v5, s38, v133
	s_add_i32 s38, s37, 0x2000
	s_mov_b32 m0, s38
	v_lshlrev_b32_e32 v7, 12, v7
	global_load_lds_dwordx4 v5, s[6:7]
	v_lshlrev_b32_e32 v5, 15, v6
	v_and_b32_e32 v5, 0xffff0000, v5
	v_and_b32_e32 v6, 1, v6
	v_add3_u32 v5, s39, v5, v7
	v_lshlrev_b32_e32 v6, 6, v6
	v_lshlrev_b32_e32 v7, 1, v8
	v_add3_u32 v138, v5, v6, v7
	v_lshlrev_b32_e32 v5, 15, v2
	v_and_b32_e32 v5, 0xffff0000, v5
	v_lshlrev_b32_e32 v3, 12, v3
	v_and_b32_e32 v2, 1, v2
	s_waitcnt vmcnt(6)
	v_add3_u32 v3, s39, v5, v3
	v_lshlrev_b32_e32 v2, 6, v2
	v_lshlrev_b32_e32 v4, 1, v4
	v_add3_u32 v139, v3, v2, v4
	v_or_b32_e32 v134, s26, v136
	s_mov_b32 s39, -2
	s_mov_b32 s40, 0
	v_add_u32_e32 v140, s28, v10
	s_barrier
	v_add_u32_e32 v141, s13, v137
	ds_read_b128 v[142:145], v141
	ds_read_b128 v[146:149], v141 offset:1024
	ds_read_b128 v[150:153], v141 offset:2048
	ds_read_b128 v[154:157], v141 offset:3072
	v_add_u32_e32 v141, s16, v137
	ds_read_b128 v[158:161], v141
	ds_read_b128 v[162:165], v141 offset:1024
	ds_read_b128 v[166:169], v141 offset:2048
	ds_read_b128 v[170:173], v141 offset:3072
	s_add_i32 s41, s40, 0x100
	s_cmp_lg_u32 s39, 28
	s_cselect_b32 s43, s41, 0
	s_add_i32 s44, s43, s21
	s_or_b32 s42, s44, 0x80
	s_add_i32 s43, s43, s12
	v_add_u32_e32 v141, s40, v139
	s_add_i32 m0, s22, 0xc000
	ds_read_b128 v[174:177], v140
	ds_read_b128 v[178:181], v140 offset:1024
	ds_read_b128 v[182:185], v140 offset:2048
	ds_read_b128 v[186:189], v140 offset:3072
	ds_read_b128 v[190:193], v140 offset:4096
	ds_read_b128 v[194:197], v140 offset:5120
	ds_read_b128 v[198:201], v140 offset:6144
	ds_read_b128 v[212:215], v140 offset:7168
	global_load_lds_dwordx4 v141, s[4:5]
	v_add_u32_e32 v141, s40, v138
	s_add_i32 m0, s22, 0xe000
	s_nop 0
	global_load_lds_dwordx4 v141, s[4:5]
	s_waitcnt vmcnt(8)
	s_waitcnt lgkmcnt(0)
	s_setprio 1
	s_barrier
	v_mfma_f32_16x16x32_bf16 v[126:129], v[142:145], v[174:177], 0
	v_mfma_f32_16x16x32_bf16 v[126:129], v[146:149], v[178:181], v[126:129]
	v_mfma_f32_16x16x32_bf16 v[122:125], v[154:157], v[178:181], 0
	v_mfma_f32_16x16x32_bf16 v[122:125], v[150:153], v[174:177], v[122:125]
	v_mfma_f32_16x16x32_bf16 v[106:109], v[150:153], v[182:185], 0
	v_mfma_f32_16x16x32_bf16 v[106:109], v[154:157], v[186:189], v[106:109]
	v_mfma_f32_16x16x32_bf16 v[110:113], v[146:149], v[186:189], 0
	v_mfma_f32_16x16x32_bf16 v[110:113], v[142:145], v[182:185], v[110:113]
	v_mfma_f32_16x16x32_bf16 v[94:97], v[142:145], v[190:193], 0
	v_mfma_f32_16x16x32_bf16 v[94:97], v[146:149], v[194:197], v[94:97]
	v_mfma_f32_16x16x32_bf16 v[90:93], v[154:157], v[194:197], 0
	v_mfma_f32_16x16x32_bf16 v[90:93], v[150:153], v[190:193], v[90:93]
	v_mfma_f32_16x16x32_bf16 v[74:77], v[150:153], v[198:201], 0
	v_mfma_f32_16x16x32_bf16 v[74:77], v[154:157], v[212:215], v[74:77]
	v_mfma_f32_16x16x32_bf16 v[78:81], v[146:149], v[212:215], 0
	v_mfma_f32_16x16x32_bf16 v[78:81], v[142:145], v[198:201], v[78:81]
	s_setprio 0
	s_setprio 1
	v_mfma_f32_16x16x32_bf16 v[70:73], v[158:161], v[198:201], 0
	v_mfma_f32_16x16x32_bf16 v[70:73], v[162:165], v[212:215], v[70:73]
	v_mfma_f32_16x16x32_bf16 v[66:69], v[170:173], v[212:215], 0
	v_mfma_f32_16x16x32_bf16 v[66:69], v[166:169], v[198:201], v[66:69]
	v_mfma_f32_16x16x32_bf16 v[82:85], v[166:169], v[190:193], 0
	v_mfma_f32_16x16x32_bf16 v[82:85], v[170:173], v[194:197], v[82:85]
	v_mfma_f32_16x16x32_bf16 v[86:89], v[162:165], v[194:197], 0
	v_mfma_f32_16x16x32_bf16 v[86:89], v[158:161], v[190:193], v[86:89]
	v_mfma_f32_16x16x32_bf16 v[102:105], v[158:161], v[182:185], 0
	v_mfma_f32_16x16x32_bf16 v[102:105], v[162:165], v[186:189], v[102:105]
	v_mfma_f32_16x16x32_bf16 v[98:101], v[170:173], v[186:189], 0
	v_mfma_f32_16x16x32_bf16 v[98:101], v[166:169], v[182:185], v[98:101]
	v_mfma_f32_16x16x32_bf16 v[114:117], v[166:169], v[174:177], 0
	v_mfma_f32_16x16x32_bf16 v[114:117], v[170:173], v[178:181], v[114:117]
	v_mfma_f32_16x16x32_bf16 v[118:121], v[162:165], v[178:181], 0
	v_mfma_f32_16x16x32_bf16 v[118:121], v[158:161], v[174:177], v[118:121]
	s_setprio 0
	s_barrier
	s_mov_b32 m0, s14
	v_add_u32_e32 v141, s43, v131
	ds_read_b128 v[174:177], v140 offset:16384
	ds_read_b128 v[178:181], v140 offset:17408
	ds_read_b128 v[182:185], v140 offset:18432
	ds_read_b128 v[186:189], v140 offset:19456
	ds_read_b128 v[190:193], v140 offset:20480
	ds_read_b128 v[194:197], v140 offset:21504
	ds_read_b128 v[198:201], v140 offset:22528
	ds_read_b128 v[212:215], v140 offset:23552
	global_load_lds_dwordx4 v141, s[6:7]
	v_add_u32_e32 v141, s43, v133
	s_mov_b32 m0, s15
	s_add_i32 s40, s43, 0x80000
	global_load_lds_dwordx4 v141, s[6:7]
	v_add_u32_e32 v141, s40, v131
	s_mov_b32 m0, s17
	s_nop 0
	global_load_lds_dwordx4 v141, s[6:7]
	v_add_u32_e32 v141, s40, v133
	s_mov_b32 m0, s20
	s_nop 0
	global_load_lds_dwordx4 v141, s[6:7]
	v_add_u32_e32 v141, s44, v130
	s_mov_b32 m0, s22
	s_nop 0
	global_load_lds_dwordx4 v141, s[4:5]
	v_add_u32_e32 v141, s44, v132
	s_mov_b32 m0, s23
	s_nop 0
	global_load_lds_dwordx4 v141, s[4:5]
	s_waitcnt vmcnt(8)
	s_waitcnt lgkmcnt(0)
	s_setprio 1
	s_barrier
	v_mfma_f32_16x16x32_bf16 v[62:65], v[142:145], v[174:177], 0
	v_mfma_f32_16x16x32_bf16 v[62:65], v[146:149], v[178:181], v[62:65]
	v_mfma_f32_16x16x32_bf16 v[58:61], v[154:157], v[178:181], 0
	v_mfma_f32_16x16x32_bf16 v[58:61], v[150:153], v[174:177], v[58:61]
	v_mfma_f32_16x16x32_bf16 v[42:45], v[150:153], v[182:185], 0
	v_mfma_f32_16x16x32_bf16 v[42:45], v[154:157], v[186:189], v[42:45]
	v_mfma_f32_16x16x32_bf16 v[46:49], v[146:149], v[186:189], 0
	v_mfma_f32_16x16x32_bf16 v[46:49], v[142:145], v[182:185], v[46:49]
	v_mfma_f32_16x16x32_bf16 v[30:33], v[142:145], v[190:193], 0
	v_mfma_f32_16x16x32_bf16 v[30:33], v[146:149], v[194:197], v[30:33]
	v_mfma_f32_16x16x32_bf16 v[26:29], v[154:157], v[194:197], 0
	v_mfma_f32_16x16x32_bf16 v[26:29], v[150:153], v[190:193], v[26:29]
	v_mfma_f32_16x16x32_bf16 v[10:13], v[150:153], v[198:201], 0
	v_mfma_f32_16x16x32_bf16 v[10:13], v[154:157], v[212:215], v[10:13]
	v_mfma_f32_16x16x32_bf16 v[14:17], v[146:149], v[212:215], 0
	v_mfma_f32_16x16x32_bf16 v[14:17], v[142:145], v[198:201], v[14:17]
	s_setprio 0
	s_setprio 1
	v_mfma_f32_16x16x32_bf16 v[6:9], v[158:161], v[198:201], 0
	v_mfma_f32_16x16x32_bf16 v[6:9], v[162:165], v[212:215], v[6:9]
	v_mfma_f32_16x16x32_bf16 v[2:5], v[170:173], v[212:215], 0
	v_mfma_f32_16x16x32_bf16 v[2:5], v[166:169], v[198:201], v[2:5]
	v_mfma_f32_16x16x32_bf16 v[18:21], v[166:169], v[190:193], 0
	v_mfma_f32_16x16x32_bf16 v[18:21], v[170:173], v[194:197], v[18:21]
	v_mfma_f32_16x16x32_bf16 v[22:25], v[162:165], v[194:197], 0
	v_mfma_f32_16x16x32_bf16 v[22:25], v[158:161], v[190:193], v[22:25]
	v_mfma_f32_16x16x32_bf16 v[38:41], v[158:161], v[182:185], 0
	v_mfma_f32_16x16x32_bf16 v[38:41], v[162:165], v[186:189], v[38:41]
	v_mfma_f32_16x16x32_bf16 v[34:37], v[170:173], v[186:189], 0
	v_mfma_f32_16x16x32_bf16 v[34:37], v[166:169], v[182:185], v[34:37]
	v_mfma_f32_16x16x32_bf16 v[50:53], v[166:169], v[174:177], 0
	v_mfma_f32_16x16x32_bf16 v[50:53], v[170:173], v[178:181], v[50:53]
	v_mfma_f32_16x16x32_bf16 v[54:57], v[162:165], v[178:181], 0
	v_mfma_f32_16x16x32_bf16 v[54:57], v[158:161], v[174:177], v[54:57]
	s_setprio 0
	s_barrier
	v_add_u32_e32 v141, s29, v137
	ds_read_b128 v[142:145], v141
	ds_read_b128 v[146:149], v141 offset:1024
	ds_read_b128 v[150:153], v141 offset:2048
	ds_read_b128 v[154:157], v141 offset:3072
	v_add_u32_e32 v141, s36, v137
	ds_read_b128 v[158:161], v141
	ds_read_b128 v[162:165], v141 offset:1024
	ds_read_b128 v[166:169], v141 offset:2048
	ds_read_b128 v[170:173], v141 offset:3072
	s_add_i32 s44, s44, 0x80000
	s_mov_b32 m0, s24
	v_add_u32_e32 v141, s44, v130
	ds_read_b128 v[174:177], v140 offset:32768
	ds_read_b128 v[178:181], v140 offset:33792
	ds_read_b128 v[182:185], v140 offset:34816
	ds_read_b128 v[186:189], v140 offset:35840
	ds_read_b128 v[190:193], v140 offset:36864
	ds_read_b128 v[194:197], v140 offset:37888
	ds_read_b128 v[198:201], v140 offset:38912
	ds_read_b128 v[212:215], v140 offset:39936
	global_load_lds_dwordx4 v141, s[4:5]
	v_add_u32_e32 v141, s44, v132
	s_mov_b32 m0, s25
	s_nop 0
	global_load_lds_dwordx4 v141, s[4:5]
	s_waitcnt vmcnt(8)
	s_waitcnt lgkmcnt(0)
	s_setprio 1
	s_barrier
	v_mfma_f32_16x16x32_bf16 v[126:129], v[142:145], v[174:177], v[126:129]
	v_mfma_f32_16x16x32_bf16 v[126:129], v[146:149], v[178:181], v[126:129]
	v_mfma_f32_16x16x32_bf16 v[122:125], v[154:157], v[178:181], v[122:125]
	v_mfma_f32_16x16x32_bf16 v[122:125], v[150:153], v[174:177], v[122:125]
	v_mfma_f32_16x16x32_bf16 v[106:109], v[150:153], v[182:185], v[106:109]
	v_mfma_f32_16x16x32_bf16 v[106:109], v[154:157], v[186:189], v[106:109]
	v_mfma_f32_16x16x32_bf16 v[110:113], v[146:149], v[186:189], v[110:113]
	v_mfma_f32_16x16x32_bf16 v[110:113], v[142:145], v[182:185], v[110:113]
	v_mfma_f32_16x16x32_bf16 v[94:97], v[142:145], v[190:193], v[94:97]
	v_mfma_f32_16x16x32_bf16 v[94:97], v[146:149], v[194:197], v[94:97]
	v_mfma_f32_16x16x32_bf16 v[90:93], v[154:157], v[194:197], v[90:93]
	v_mfma_f32_16x16x32_bf16 v[90:93], v[150:153], v[190:193], v[90:93]
	v_mfma_f32_16x16x32_bf16 v[74:77], v[150:153], v[198:201], v[74:77]
	v_mfma_f32_16x16x32_bf16 v[74:77], v[154:157], v[212:215], v[74:77]
	v_mfma_f32_16x16x32_bf16 v[78:81], v[146:149], v[212:215], v[78:81]
	v_mfma_f32_16x16x32_bf16 v[78:81], v[142:145], v[198:201], v[78:81]
	s_setprio 0
	s_setprio 1
	v_mfma_f32_16x16x32_bf16 v[70:73], v[158:161], v[198:201], v[70:73]
	v_mfma_f32_16x16x32_bf16 v[70:73], v[162:165], v[212:215], v[70:73]
	v_mfma_f32_16x16x32_bf16 v[66:69], v[170:173], v[212:215], v[66:69]
	v_mfma_f32_16x16x32_bf16 v[66:69], v[166:169], v[198:201], v[66:69]
	v_mfma_f32_16x16x32_bf16 v[82:85], v[166:169], v[190:193], v[82:85]
	v_mfma_f32_16x16x32_bf16 v[82:85], v[170:173], v[194:197], v[82:85]
	v_mfma_f32_16x16x32_bf16 v[86:89], v[162:165], v[194:197], v[86:89]
	v_mfma_f32_16x16x32_bf16 v[86:89], v[158:161], v[190:193], v[86:89]
	v_mfma_f32_16x16x32_bf16 v[102:105], v[158:161], v[182:185], v[102:105]
	v_mfma_f32_16x16x32_bf16 v[102:105], v[162:165], v[186:189], v[102:105]
	v_mfma_f32_16x16x32_bf16 v[98:101], v[170:173], v[186:189], v[98:101]
	v_mfma_f32_16x16x32_bf16 v[98:101], v[166:169], v[182:185], v[98:101]
	v_mfma_f32_16x16x32_bf16 v[114:117], v[166:169], v[174:177], v[114:117]
	v_mfma_f32_16x16x32_bf16 v[114:117], v[170:173], v[178:181], v[114:117]
	v_mfma_f32_16x16x32_bf16 v[118:121], v[162:165], v[178:181], v[118:121]
	v_mfma_f32_16x16x32_bf16 v[118:121], v[158:161], v[174:177], v[118:121]
	s_setprio 0
	s_barrier
	s_or_b32 s40, s43, 0x80
	s_mov_b32 m0, s30
	v_add_u32_e32 v141, s40, v131
	ds_read_b128 v[174:177], v140 offset:49152
	ds_read_b128 v[178:181], v140 offset:50176
	ds_read_b128 v[182:185], v140 offset:51200
	ds_read_b128 v[186:189], v140 offset:52224
	ds_read_b128 v[190:193], v140 offset:53248
	ds_read_b128 v[194:197], v140 offset:54272
	ds_read_b128 v[198:201], v140 offset:55296
	ds_read_b128 v[212:215], v140 offset:56320
	global_load_lds_dwordx4 v141, s[6:7]
	v_add_u32_e32 v141, s40, v133
	s_mov_b32 m0, s31
	s_add_i32 s43, s43, 0x80080
	global_load_lds_dwordx4 v141, s[6:7]
	v_add_u32_e32 v141, s43, v131
	s_mov_b32 m0, s37
	s_nop 0
	global_load_lds_dwordx4 v141, s[6:7]
	v_add_u32_e32 v141, s43, v133
	s_mov_b32 m0, s38
	s_nop 0
	global_load_lds_dwordx4 v141, s[6:7]
	v_add_u32_e32 v141, s42, v130
	s_mov_b32 m0, s34
	s_nop 0
	global_load_lds_dwordx4 v141, s[4:5]
	v_add_u32_e32 v141, s42, v132
	s_mov_b32 m0, s35
	s_nop 0
	global_load_lds_dwordx4 v141, s[4:5]
	s_waitcnt vmcnt(8)
	s_waitcnt lgkmcnt(0)
	s_setprio 1
	s_barrier
	v_mfma_f32_16x16x32_bf16 v[62:65], v[142:145], v[174:177], v[62:65]
	v_mfma_f32_16x16x32_bf16 v[62:65], v[146:149], v[178:181], v[62:65]
	v_mfma_f32_16x16x32_bf16 v[58:61], v[154:157], v[178:181], v[58:61]
	v_mfma_f32_16x16x32_bf16 v[58:61], v[150:153], v[174:177], v[58:61]
	v_mfma_f32_16x16x32_bf16 v[42:45], v[150:153], v[182:185], v[42:45]
	v_mfma_f32_16x16x32_bf16 v[42:45], v[154:157], v[186:189], v[42:45]
	v_mfma_f32_16x16x32_bf16 v[46:49], v[146:149], v[186:189], v[46:49]
	v_mfma_f32_16x16x32_bf16 v[46:49], v[142:145], v[182:185], v[46:49]
	v_mfma_f32_16x16x32_bf16 v[30:33], v[142:145], v[190:193], v[30:33]
	v_mfma_f32_16x16x32_bf16 v[30:33], v[146:149], v[194:197], v[30:33]
	v_mfma_f32_16x16x32_bf16 v[26:29], v[154:157], v[194:197], v[26:29]
	v_mfma_f32_16x16x32_bf16 v[26:29], v[150:153], v[190:193], v[26:29]
	v_mfma_f32_16x16x32_bf16 v[10:13], v[150:153], v[198:201], v[10:13]
	v_mfma_f32_16x16x32_bf16 v[10:13], v[154:157], v[212:215], v[10:13]
	v_mfma_f32_16x16x32_bf16 v[14:17], v[146:149], v[212:215], v[14:17]
	v_mfma_f32_16x16x32_bf16 v[14:17], v[142:145], v[198:201], v[14:17]
	s_setprio 0
	s_setprio 1
	v_mfma_f32_16x16x32_bf16 v[6:9], v[158:161], v[198:201], v[6:9]
	v_mfma_f32_16x16x32_bf16 v[6:9], v[162:165], v[212:215], v[6:9]
	v_mfma_f32_16x16x32_bf16 v[2:5], v[170:173], v[212:215], v[2:5]
	v_mfma_f32_16x16x32_bf16 v[2:5], v[166:169], v[198:201], v[2:5]
	v_mfma_f32_16x16x32_bf16 v[18:21], v[166:169], v[190:193], v[18:21]
	v_mfma_f32_16x16x32_bf16 v[18:21], v[170:173], v[194:197], v[18:21]
	v_mfma_f32_16x16x32_bf16 v[22:25], v[162:165], v[194:197], v[22:25]
	v_mfma_f32_16x16x32_bf16 v[22:25], v[158:161], v[190:193], v[22:25]
	v_mfma_f32_16x16x32_bf16 v[38:41], v[158:161], v[182:185], v[38:41]
	v_mfma_f32_16x16x32_bf16 v[38:41], v[162:165], v[186:189], v[38:41]
	v_mfma_f32_16x16x32_bf16 v[34:37], v[170:173], v[186:189], v[34:37]
	v_mfma_f32_16x16x32_bf16 v[34:37], v[166:169], v[182:185], v[34:37]
	v_mfma_f32_16x16x32_bf16 v[50:53], v[166:169], v[174:177], v[50:53]
	v_mfma_f32_16x16x32_bf16 v[50:53], v[170:173], v[178:181], v[50:53]
	v_mfma_f32_16x16x32_bf16 v[54:57], v[162:165], v[178:181], v[54:57]
	v_mfma_f32_16x16x32_bf16 v[54:57], v[158:161], v[174:177], v[54:57]
	s_setprio 0
	s_barrier
	s_add_i32 s39, s39, 2
	s_cmp_gt_u32 s39, 29
	s_mov_b32 s40, s41
.LBB0_136:
	v_add_u32_e32 v141, s13, v137
	ds_read_b128 v[142:145], v141
	ds_read_b128 v[146:149], v141 offset:1024
	ds_read_b128 v[150:153], v141 offset:2048
	ds_read_b128 v[154:157], v141 offset:3072
	v_add_u32_e32 v141, s16, v137
	ds_read_b128 v[158:161], v141
	ds_read_b128 v[162:165], v141 offset:1024
	ds_read_b128 v[166:169], v141 offset:2048
	ds_read_b128 v[170:173], v141 offset:3072
	s_add_i32 s41, s40, 0x100
	s_cmp_lg_u32 s39, 28
	s_cselect_b32 s43, s41, 0
	s_add_i32 s44, s43, s21
	s_or_b32 s42, s44, 0x80
	s_add_i32 s43, s43, s12
	v_add_u32_e32 v141, s40, v139
	s_add_i32 m0, s22, 0xc000
	ds_read_b128 v[174:177], v140
	ds_read_b128 v[178:181], v140 offset:1024
	ds_read_b128 v[182:185], v140 offset:2048
	ds_read_b128 v[186:189], v140 offset:3072
	ds_read_b128 v[190:193], v140 offset:4096
	ds_read_b128 v[194:197], v140 offset:5120
	ds_read_b128 v[198:201], v140 offset:6144
	ds_read_b128 v[212:215], v140 offset:7168
	global_load_lds_dwordx4 v141, s[4:5]
	v_add_u32_e32 v141, s40, v138
	s_add_i32 m0, s22, 0xe000
	s_nop 0
	global_load_lds_dwordx4 v141, s[4:5]
	s_waitcnt vmcnt(8)
	s_waitcnt lgkmcnt(0)
	s_setprio 1
	s_barrier
	v_mfma_f32_16x16x32_bf16 v[126:129], v[142:145], v[174:177], v[126:129]
	v_mfma_f32_16x16x32_bf16 v[126:129], v[146:149], v[178:181], v[126:129]
	v_mfma_f32_16x16x32_bf16 v[122:125], v[154:157], v[178:181], v[122:125]
	v_mfma_f32_16x16x32_bf16 v[122:125], v[150:153], v[174:177], v[122:125]
	v_mfma_f32_16x16x32_bf16 v[106:109], v[150:153], v[182:185], v[106:109]
	v_mfma_f32_16x16x32_bf16 v[106:109], v[154:157], v[186:189], v[106:109]
	v_mfma_f32_16x16x32_bf16 v[110:113], v[146:149], v[186:189], v[110:113]
	v_mfma_f32_16x16x32_bf16 v[110:113], v[142:145], v[182:185], v[110:113]
	v_mfma_f32_16x16x32_bf16 v[94:97], v[142:145], v[190:193], v[94:97]
	v_mfma_f32_16x16x32_bf16 v[94:97], v[146:149], v[194:197], v[94:97]
	v_mfma_f32_16x16x32_bf16 v[90:93], v[154:157], v[194:197], v[90:93]
	v_mfma_f32_16x16x32_bf16 v[90:93], v[150:153], v[190:193], v[90:93]
	v_mfma_f32_16x16x32_bf16 v[74:77], v[150:153], v[198:201], v[74:77]
	v_mfma_f32_16x16x32_bf16 v[74:77], v[154:157], v[212:215], v[74:77]
	v_mfma_f32_16x16x32_bf16 v[78:81], v[146:149], v[212:215], v[78:81]
	v_mfma_f32_16x16x32_bf16 v[78:81], v[142:145], v[198:201], v[78:81]
	s_setprio 0
	s_setprio 1
	v_mfma_f32_16x16x32_bf16 v[70:73], v[158:161], v[198:201], v[70:73]
	v_mfma_f32_16x16x32_bf16 v[70:73], v[162:165], v[212:215], v[70:73]
	v_mfma_f32_16x16x32_bf16 v[66:69], v[170:173], v[212:215], v[66:69]
	v_mfma_f32_16x16x32_bf16 v[66:69], v[166:169], v[198:201], v[66:69]
	v_mfma_f32_16x16x32_bf16 v[82:85], v[166:169], v[190:193], v[82:85]
	v_mfma_f32_16x16x32_bf16 v[82:85], v[170:173], v[194:197], v[82:85]
	v_mfma_f32_16x16x32_bf16 v[86:89], v[162:165], v[194:197], v[86:89]
	v_mfma_f32_16x16x32_bf16 v[86:89], v[158:161], v[190:193], v[86:89]
	v_mfma_f32_16x16x32_bf16 v[102:105], v[158:161], v[182:185], v[102:105]
	v_mfma_f32_16x16x32_bf16 v[102:105], v[162:165], v[186:189], v[102:105]
	v_mfma_f32_16x16x32_bf16 v[98:101], v[170:173], v[186:189], v[98:101]
	v_mfma_f32_16x16x32_bf16 v[98:101], v[166:169], v[182:185], v[98:101]
	v_mfma_f32_16x16x32_bf16 v[114:117], v[166:169], v[174:177], v[114:117]
	v_mfma_f32_16x16x32_bf16 v[114:117], v[170:173], v[178:181], v[114:117]
	v_mfma_f32_16x16x32_bf16 v[118:121], v[162:165], v[178:181], v[118:121]
	v_mfma_f32_16x16x32_bf16 v[118:121], v[158:161], v[174:177], v[118:121]
	s_setprio 0
	s_barrier
	s_mov_b32 m0, s14
	v_add_u32_e32 v141, s43, v131
	ds_read_b128 v[174:177], v140 offset:16384
	ds_read_b128 v[178:181], v140 offset:17408
	ds_read_b128 v[182:185], v140 offset:18432
	ds_read_b128 v[186:189], v140 offset:19456
	ds_read_b128 v[190:193], v140 offset:20480
	ds_read_b128 v[194:197], v140 offset:21504
	ds_read_b128 v[198:201], v140 offset:22528
	ds_read_b128 v[212:215], v140 offset:23552
	global_load_lds_dwordx4 v141, s[6:7]
	v_add_u32_e32 v141, s43, v133
	s_mov_b32 m0, s15
	s_add_i32 s40, s43, 0x80000
	global_load_lds_dwordx4 v141, s[6:7]
	v_add_u32_e32 v141, s40, v131
	s_mov_b32 m0, s17
	s_nop 0
	global_load_lds_dwordx4 v141, s[6:7]
	v_add_u32_e32 v141, s40, v133
	s_mov_b32 m0, s20
	s_nop 0
	global_load_lds_dwordx4 v141, s[6:7]
	v_add_u32_e32 v141, s44, v130
	s_mov_b32 m0, s22
	s_nop 0
	global_load_lds_dwordx4 v141, s[4:5]
	v_add_u32_e32 v141, s44, v132
	s_mov_b32 m0, s23
	s_nop 0
	global_load_lds_dwordx4 v141, s[4:5]
	s_waitcnt vmcnt(8)
	s_waitcnt lgkmcnt(0)
	s_setprio 1
	s_barrier
	v_mfma_f32_16x16x32_bf16 v[62:65], v[142:145], v[174:177], v[62:65]
	v_mfma_f32_16x16x32_bf16 v[62:65], v[146:149], v[178:181], v[62:65]
	v_mfma_f32_16x16x32_bf16 v[58:61], v[154:157], v[178:181], v[58:61]
	v_mfma_f32_16x16x32_bf16 v[58:61], v[150:153], v[174:177], v[58:61]
	v_mfma_f32_16x16x32_bf16 v[42:45], v[150:153], v[182:185], v[42:45]
	v_mfma_f32_16x16x32_bf16 v[42:45], v[154:157], v[186:189], v[42:45]
	v_mfma_f32_16x16x32_bf16 v[46:49], v[146:149], v[186:189], v[46:49]
	v_mfma_f32_16x16x32_bf16 v[46:49], v[142:145], v[182:185], v[46:49]
	v_mfma_f32_16x16x32_bf16 v[30:33], v[142:145], v[190:193], v[30:33]
	v_mfma_f32_16x16x32_bf16 v[30:33], v[146:149], v[194:197], v[30:33]
	v_mfma_f32_16x16x32_bf16 v[26:29], v[154:157], v[194:197], v[26:29]
	v_mfma_f32_16x16x32_bf16 v[26:29], v[150:153], v[190:193], v[26:29]
	v_mfma_f32_16x16x32_bf16 v[10:13], v[150:153], v[198:201], v[10:13]
	v_mfma_f32_16x16x32_bf16 v[10:13], v[154:157], v[212:215], v[10:13]
	v_mfma_f32_16x16x32_bf16 v[14:17], v[146:149], v[212:215], v[14:17]
	v_mfma_f32_16x16x32_bf16 v[14:17], v[142:145], v[198:201], v[14:17]
	s_setprio 0
	s_setprio 1
	v_mfma_f32_16x16x32_bf16 v[6:9], v[158:161], v[198:201], v[6:9]
	v_mfma_f32_16x16x32_bf16 v[6:9], v[162:165], v[212:215], v[6:9]
	v_mfma_f32_16x16x32_bf16 v[2:5], v[170:173], v[212:215], v[2:5]
	v_mfma_f32_16x16x32_bf16 v[2:5], v[166:169], v[198:201], v[2:5]
	v_mfma_f32_16x16x32_bf16 v[18:21], v[166:169], v[190:193], v[18:21]
	v_mfma_f32_16x16x32_bf16 v[18:21], v[170:173], v[194:197], v[18:21]
	v_mfma_f32_16x16x32_bf16 v[22:25], v[162:165], v[194:197], v[22:25]
	v_mfma_f32_16x16x32_bf16 v[22:25], v[158:161], v[190:193], v[22:25]
	v_mfma_f32_16x16x32_bf16 v[38:41], v[158:161], v[182:185], v[38:41]
	v_mfma_f32_16x16x32_bf16 v[38:41], v[162:165], v[186:189], v[38:41]
	v_mfma_f32_16x16x32_bf16 v[34:37], v[170:173], v[186:189], v[34:37]
	v_mfma_f32_16x16x32_bf16 v[34:37], v[166:169], v[182:185], v[34:37]
	v_mfma_f32_16x16x32_bf16 v[50:53], v[166:169], v[174:177], v[50:53]
	v_mfma_f32_16x16x32_bf16 v[50:53], v[170:173], v[178:181], v[50:53]
	v_mfma_f32_16x16x32_bf16 v[54:57], v[162:165], v[178:181], v[54:57]
	v_mfma_f32_16x16x32_bf16 v[54:57], v[158:161], v[174:177], v[54:57]
	s_setprio 0
	s_barrier
	v_add_u32_e32 v141, s29, v137
	ds_read_b128 v[142:145], v141
	ds_read_b128 v[146:149], v141 offset:1024
	ds_read_b128 v[150:153], v141 offset:2048
	ds_read_b128 v[154:157], v141 offset:3072
	v_add_u32_e32 v141, s36, v137
	ds_read_b128 v[158:161], v141
	ds_read_b128 v[162:165], v141 offset:1024
	ds_read_b128 v[166:169], v141 offset:2048
	ds_read_b128 v[170:173], v141 offset:3072
	s_add_i32 s44, s44, 0x80000
	s_mov_b32 m0, s24
	v_add_u32_e32 v141, s44, v130
	ds_read_b128 v[174:177], v140 offset:32768
	ds_read_b128 v[178:181], v140 offset:33792
	ds_read_b128 v[182:185], v140 offset:34816
	ds_read_b128 v[186:189], v140 offset:35840
	ds_read_b128 v[190:193], v140 offset:36864
	ds_read_b128 v[194:197], v140 offset:37888
	ds_read_b128 v[198:201], v140 offset:38912
	ds_read_b128 v[212:215], v140 offset:39936
	global_load_lds_dwordx4 v141, s[4:5]
	v_add_u32_e32 v141, s44, v132
	s_mov_b32 m0, s25
	s_nop 0
	global_load_lds_dwordx4 v141, s[4:5]
	s_waitcnt vmcnt(8)
	s_waitcnt lgkmcnt(0)
	s_setprio 1
	s_barrier
	v_mfma_f32_16x16x32_bf16 v[126:129], v[142:145], v[174:177], v[126:129]
	v_mfma_f32_16x16x32_bf16 v[126:129], v[146:149], v[178:181], v[126:129]
	v_mfma_f32_16x16x32_bf16 v[122:125], v[154:157], v[178:181], v[122:125]
	v_mfma_f32_16x16x32_bf16 v[122:125], v[150:153], v[174:177], v[122:125]
	v_mfma_f32_16x16x32_bf16 v[106:109], v[150:153], v[182:185], v[106:109]
	v_mfma_f32_16x16x32_bf16 v[106:109], v[154:157], v[186:189], v[106:109]
	v_mfma_f32_16x16x32_bf16 v[110:113], v[146:149], v[186:189], v[110:113]
	v_mfma_f32_16x16x32_bf16 v[110:113], v[142:145], v[182:185], v[110:113]
	v_mfma_f32_16x16x32_bf16 v[94:97], v[142:145], v[190:193], v[94:97]
	v_mfma_f32_16x16x32_bf16 v[94:97], v[146:149], v[194:197], v[94:97]
	v_mfma_f32_16x16x32_bf16 v[90:93], v[154:157], v[194:197], v[90:93]
	v_mfma_f32_16x16x32_bf16 v[90:93], v[150:153], v[190:193], v[90:93]
	v_mfma_f32_16x16x32_bf16 v[74:77], v[150:153], v[198:201], v[74:77]
	v_mfma_f32_16x16x32_bf16 v[74:77], v[154:157], v[212:215], v[74:77]
	v_mfma_f32_16x16x32_bf16 v[78:81], v[146:149], v[212:215], v[78:81]
	v_mfma_f32_16x16x32_bf16 v[78:81], v[142:145], v[198:201], v[78:81]
	s_setprio 0
	s_setprio 1
	v_mfma_f32_16x16x32_bf16 v[70:73], v[158:161], v[198:201], v[70:73]
	v_mfma_f32_16x16x32_bf16 v[70:73], v[162:165], v[212:215], v[70:73]
	v_mfma_f32_16x16x32_bf16 v[66:69], v[170:173], v[212:215], v[66:69]
	v_mfma_f32_16x16x32_bf16 v[66:69], v[166:169], v[198:201], v[66:69]
	v_mfma_f32_16x16x32_bf16 v[82:85], v[166:169], v[190:193], v[82:85]
	v_mfma_f32_16x16x32_bf16 v[82:85], v[170:173], v[194:197], v[82:85]
	v_mfma_f32_16x16x32_bf16 v[86:89], v[162:165], v[194:197], v[86:89]
	v_mfma_f32_16x16x32_bf16 v[86:89], v[158:161], v[190:193], v[86:89]
	v_mfma_f32_16x16x32_bf16 v[102:105], v[158:161], v[182:185], v[102:105]
	v_mfma_f32_16x16x32_bf16 v[102:105], v[162:165], v[186:189], v[102:105]
	v_mfma_f32_16x16x32_bf16 v[98:101], v[170:173], v[186:189], v[98:101]
	v_mfma_f32_16x16x32_bf16 v[98:101], v[166:169], v[182:185], v[98:101]
	v_mfma_f32_16x16x32_bf16 v[114:117], v[166:169], v[174:177], v[114:117]
	v_mfma_f32_16x16x32_bf16 v[114:117], v[170:173], v[178:181], v[114:117]
	v_mfma_f32_16x16x32_bf16 v[118:121], v[162:165], v[178:181], v[118:121]
	v_mfma_f32_16x16x32_bf16 v[118:121], v[158:161], v[174:177], v[118:121]
	s_setprio 0
	s_barrier
	s_or_b32 s40, s43, 0x80
	s_mov_b32 m0, s30
	v_add_u32_e32 v141, s40, v131
	ds_read_b128 v[174:177], v140 offset:49152
	ds_read_b128 v[178:181], v140 offset:50176
	ds_read_b128 v[182:185], v140 offset:51200
	ds_read_b128 v[186:189], v140 offset:52224
	ds_read_b128 v[190:193], v140 offset:53248
	ds_read_b128 v[194:197], v140 offset:54272
	ds_read_b128 v[198:201], v140 offset:55296
	ds_read_b128 v[212:215], v140 offset:56320
	global_load_lds_dwordx4 v141, s[6:7]
	v_add_u32_e32 v141, s40, v133
	s_mov_b32 m0, s31
	s_add_i32 s43, s43, 0x80080
	global_load_lds_dwordx4 v141, s[6:7]
	v_add_u32_e32 v141, s43, v131
	s_mov_b32 m0, s37
	s_nop 0
	global_load_lds_dwordx4 v141, s[6:7]
	v_add_u32_e32 v141, s43, v133
	s_mov_b32 m0, s38
	s_nop 0
	global_load_lds_dwordx4 v141, s[6:7]
	v_add_u32_e32 v141, s42, v130
	s_mov_b32 m0, s34
	s_nop 0
	global_load_lds_dwordx4 v141, s[4:5]
	v_add_u32_e32 v141, s42, v132
	s_mov_b32 m0, s35
	s_nop 0
	global_load_lds_dwordx4 v141, s[4:5]
	s_waitcnt vmcnt(8)
	s_waitcnt lgkmcnt(0)
	s_setprio 1
	s_barrier
	v_mfma_f32_16x16x32_bf16 v[62:65], v[142:145], v[174:177], v[62:65]
	v_mfma_f32_16x16x32_bf16 v[62:65], v[146:149], v[178:181], v[62:65]
	v_mfma_f32_16x16x32_bf16 v[58:61], v[154:157], v[178:181], v[58:61]
	v_mfma_f32_16x16x32_bf16 v[58:61], v[150:153], v[174:177], v[58:61]
	v_mfma_f32_16x16x32_bf16 v[42:45], v[150:153], v[182:185], v[42:45]
	v_mfma_f32_16x16x32_bf16 v[42:45], v[154:157], v[186:189], v[42:45]
	v_mfma_f32_16x16x32_bf16 v[46:49], v[146:149], v[186:189], v[46:49]
	v_mfma_f32_16x16x32_bf16 v[46:49], v[142:145], v[182:185], v[46:49]
	v_mfma_f32_16x16x32_bf16 v[30:33], v[142:145], v[190:193], v[30:33]
	v_mfma_f32_16x16x32_bf16 v[30:33], v[146:149], v[194:197], v[30:33]
	v_mfma_f32_16x16x32_bf16 v[26:29], v[154:157], v[194:197], v[26:29]
	v_mfma_f32_16x16x32_bf16 v[26:29], v[150:153], v[190:193], v[26:29]
	v_mfma_f32_16x16x32_bf16 v[10:13], v[150:153], v[198:201], v[10:13]
	v_mfma_f32_16x16x32_bf16 v[10:13], v[154:157], v[212:215], v[10:13]
	v_mfma_f32_16x16x32_bf16 v[14:17], v[146:149], v[212:215], v[14:17]
	v_mfma_f32_16x16x32_bf16 v[14:17], v[142:145], v[198:201], v[14:17]
	s_setprio 0
	s_setprio 1
	v_mfma_f32_16x16x32_bf16 v[6:9], v[158:161], v[198:201], v[6:9]
	v_mfma_f32_16x16x32_bf16 v[6:9], v[162:165], v[212:215], v[6:9]
	v_mfma_f32_16x16x32_bf16 v[2:5], v[170:173], v[212:215], v[2:5]
	v_mfma_f32_16x16x32_bf16 v[2:5], v[166:169], v[198:201], v[2:5]
	v_mfma_f32_16x16x32_bf16 v[18:21], v[166:169], v[190:193], v[18:21]
	v_mfma_f32_16x16x32_bf16 v[18:21], v[170:173], v[194:197], v[18:21]
	v_mfma_f32_16x16x32_bf16 v[22:25], v[162:165], v[194:197], v[22:25]
	v_mfma_f32_16x16x32_bf16 v[22:25], v[158:161], v[190:193], v[22:25]
	v_mfma_f32_16x16x32_bf16 v[38:41], v[158:161], v[182:185], v[38:41]
	v_mfma_f32_16x16x32_bf16 v[38:41], v[162:165], v[186:189], v[38:41]
	v_mfma_f32_16x16x32_bf16 v[34:37], v[170:173], v[186:189], v[34:37]
	v_mfma_f32_16x16x32_bf16 v[34:37], v[166:169], v[182:185], v[34:37]
	v_mfma_f32_16x16x32_bf16 v[50:53], v[166:169], v[174:177], v[50:53]
	v_mfma_f32_16x16x32_bf16 v[50:53], v[170:173], v[178:181], v[50:53]
	v_mfma_f32_16x16x32_bf16 v[54:57], v[162:165], v[178:181], v[54:57]
	v_mfma_f32_16x16x32_bf16 v[54:57], v[158:161], v[174:177], v[54:57]
	s_setprio 0
	s_barrier
	s_add_i32 s39, s39, 2
	s_cmp_gt_u32 s39, 29
	s_mov_b32 s40, s41
	s_cbranch_scc0 .LBB0_136
	s_cmpk_lt_u32 s9, 0x100
	s_cbranch_scc0 .LBB0_139
	s_barrier

.LBB0_151:
	v_lshrrev_b32_e32 v9, 1, v5
	v_and_b32_e32 v135, 24, v9
	v_and_b32_e32 v136, 15, v5
	v_lshlrev_b32_e32 v9, 1, v135
	v_lshlrev_b32_e32 v5, 2, v5
	s_lshl_b32 s20, s20, 5
	s_lshl_b32 s19, s21, 6
	v_lshl_or_b32 v9, v136, 6, v9
	s_lshl_b32 s21, s21, 13
	v_and_b32_e32 v5, 32, v5
	s_and_b32 s20, s20, 0x60
	v_bitop3_b32 v10, v9, s21, v5 bitop3:0xde
	s_lshl_b32 s21, s20, 7
	v_bitop3_b32 v137, v9, s21, v5 bitop3:0xde
	s_add_i32 s21, s28, 0x18000
	s_or_b32 s23, s2, 0x80
	s_add_i32 s22, s21, s27
	v_add_u32_e32 v5, s23, v131
	s_mov_b32 m0, s22
	s_waitcnt vmcnt(2)
	s_barrier
	global_load_lds_dwordx4 v5, s[6:7]
	v_add_u32_e32 v5, s23, v133
	s_add_i32 s23, s22, 0x2000
	s_mov_b32 m0, s23
	s_or_b32 s25, s14, 0x80
	s_add_i32 s24, s15, 0x8000
	global_load_lds_dwordx4 v5, s[6:7]
	v_add_u32_e32 v5, s25, v130
	s_mov_b32 m0, s24
	s_add_i32 s26, s28, 0x1c000
	global_load_lds_dwordx4 v5, s[4:5]
	v_add_u32_e32 v5, s25, v132
	s_add_i32 s25, s15, 0xa000
	s_mov_b32 m0, s25
	s_or_b32 s29, s2, 0x80080
	s_add_i32 s27, s26, s27
	global_load_lds_dwordx4 v5, s[4:5]
	v_add_u32_e32 v5, s29, v131
	s_mov_b32 m0, s27
	s_add_i32 s30, s14, 0x80080
	global_load_lds_dwordx4 v5, s[6:7]
	v_add_u32_e32 v5, s29, v133
	s_add_i32 s29, s27, 0x2000
	s_mov_b32 m0, s29
	v_lshlrev_b32_e32 v7, 12, v7
	global_load_lds_dwordx4 v5, s[6:7]
	v_lshlrev_b32_e32 v5, 15, v6
	v_and_b32_e32 v5, 0xffff0000, v5
	v_and_b32_e32 v6, 1, v6
	v_add3_u32 v5, s30, v5, v7
	v_lshlrev_b32_e32 v6, 6, v6
	v_lshlrev_b32_e32 v7, 1, v8
	v_add3_u32 v138, v5, v6, v7
	v_lshlrev_b32_e32 v5, 15, v2
	v_and_b32_e32 v5, 0xffff0000, v5
	v_lshlrev_b32_e32 v3, 12, v3
	v_and_b32_e32 v2, 1, v2
	s_waitcnt vmcnt(6)
	v_add3_u32 v3, s30, v5, v3
	v_lshlrev_b32_e32 v2, 6, v2
	v_lshlrev_b32_e32 v4, 1, v4
	v_add3_u32 v139, v3, v2, v4
	v_or_b32_e32 v134, s19, v136
	s_mov_b32 s30, -2
	s_mov_b32 s31, 0
	v_add_u32_e32 v140, s28, v10
	s_barrier
	v_add_u32_e32 v141, s3, v137
	ds_read_b128 v[142:145], v141
	ds_read_b128 v[146:149], v141 offset:1024
	ds_read_b128 v[150:153], v141 offset:2048
	ds_read_b128 v[154:157], v141 offset:3072
	v_add_u32_e32 v141, s11, v137
	ds_read_b128 v[158:161], v141
	ds_read_b128 v[162:165], v141 offset:1024
	ds_read_b128 v[166:169], v141 offset:2048
	ds_read_b128 v[170:173], v141 offset:3072
	s_add_i32 s34, s31, 0x100
	s_cmp_lg_u32 s30, 28
	s_cselect_b32 s36, s34, 0
	s_add_i32 s37, s36, s14
	s_or_b32 s35, s37, 0x80
	s_add_i32 s36, s36, s2
	v_add_u32_e32 v141, s31, v139
	s_add_i32 m0, s15, 0xc000
	ds_read_b128 v[174:177], v140
	ds_read_b128 v[178:181], v140 offset:1024
	ds_read_b128 v[182:185], v140 offset:2048
	ds_read_b128 v[186:189], v140 offset:3072
	ds_read_b128 v[190:193], v140 offset:4096
	ds_read_b128 v[194:197], v140 offset:5120
	ds_read_b128 v[198:201], v140 offset:6144
	ds_read_b128 v[212:215], v140 offset:7168
	global_load_lds_dwordx4 v141, s[4:5]
	v_add_u32_e32 v141, s31, v138
	s_add_i32 m0, s15, 0xe000
	s_nop 0
	global_load_lds_dwordx4 v141, s[4:5]
	s_waitcnt vmcnt(8)
	s_waitcnt lgkmcnt(0)
	s_setprio 1
	s_barrier
	v_mfma_f32_16x16x32_bf16 v[126:129], v[142:145], v[174:177], 0
	v_mfma_f32_16x16x32_bf16 v[126:129], v[146:149], v[178:181], v[126:129]
	v_mfma_f32_16x16x32_bf16 v[122:125], v[154:157], v[178:181], 0
	v_mfma_f32_16x16x32_bf16 v[122:125], v[150:153], v[174:177], v[122:125]
	v_mfma_f32_16x16x32_bf16 v[106:109], v[150:153], v[182:185], 0
	v_mfma_f32_16x16x32_bf16 v[106:109], v[154:157], v[186:189], v[106:109]
	v_mfma_f32_16x16x32_bf16 v[110:113], v[146:149], v[186:189], 0
	v_mfma_f32_16x16x32_bf16 v[110:113], v[142:145], v[182:185], v[110:113]
	v_mfma_f32_16x16x32_bf16 v[94:97], v[142:145], v[190:193], 0
	v_mfma_f32_16x16x32_bf16 v[94:97], v[146:149], v[194:197], v[94:97]
	v_mfma_f32_16x16x32_bf16 v[90:93], v[154:157], v[194:197], 0
	v_mfma_f32_16x16x32_bf16 v[90:93], v[150:153], v[190:193], v[90:93]
	v_mfma_f32_16x16x32_bf16 v[74:77], v[150:153], v[198:201], 0
	v_mfma_f32_16x16x32_bf16 v[74:77], v[154:157], v[212:215], v[74:77]
	v_mfma_f32_16x16x32_bf16 v[78:81], v[146:149], v[212:215], 0
	v_mfma_f32_16x16x32_bf16 v[78:81], v[142:145], v[198:201], v[78:81]
	s_setprio 0
	s_setprio 1
	v_mfma_f32_16x16x32_bf16 v[70:73], v[158:161], v[198:201], 0
	v_mfma_f32_16x16x32_bf16 v[70:73], v[162:165], v[212:215], v[70:73]
	v_mfma_f32_16x16x32_bf16 v[66:69], v[170:173], v[212:215], 0
	v_mfma_f32_16x16x32_bf16 v[66:69], v[166:169], v[198:201], v[66:69]
	v_mfma_f32_16x16x32_bf16 v[82:85], v[166:169], v[190:193], 0
	v_mfma_f32_16x16x32_bf16 v[82:85], v[170:173], v[194:197], v[82:85]
	v_mfma_f32_16x16x32_bf16 v[86:89], v[162:165], v[194:197], 0
	v_mfma_f32_16x16x32_bf16 v[86:89], v[158:161], v[190:193], v[86:89]
	v_mfma_f32_16x16x32_bf16 v[102:105], v[158:161], v[182:185], 0
	v_mfma_f32_16x16x32_bf16 v[102:105], v[162:165], v[186:189], v[102:105]
	v_mfma_f32_16x16x32_bf16 v[98:101], v[170:173], v[186:189], 0
	v_mfma_f32_16x16x32_bf16 v[98:101], v[166:169], v[182:185], v[98:101]
	v_mfma_f32_16x16x32_bf16 v[114:117], v[166:169], v[174:177], 0
	v_mfma_f32_16x16x32_bf16 v[114:117], v[170:173], v[178:181], v[114:117]
	v_mfma_f32_16x16x32_bf16 v[118:121], v[162:165], v[178:181], 0
	v_mfma_f32_16x16x32_bf16 v[118:121], v[158:161], v[174:177], v[118:121]
	s_setprio 0
	s_barrier
	s_mov_b32 m0, s9
	v_add_u32_e32 v141, s36, v131
	ds_read_b128 v[174:177], v140 offset:16384
	ds_read_b128 v[178:181], v140 offset:17408
	ds_read_b128 v[182:185], v140 offset:18432
	ds_read_b128 v[186:189], v140 offset:19456
	ds_read_b128 v[190:193], v140 offset:20480
	ds_read_b128 v[194:197], v140 offset:21504
	ds_read_b128 v[198:201], v140 offset:22528
	ds_read_b128 v[212:215], v140 offset:23552
	global_load_lds_dwordx4 v141, s[6:7]
	v_add_u32_e32 v141, s36, v133
	s_mov_b32 m0, s10
	s_add_i32 s31, s36, 0x80000
	global_load_lds_dwordx4 v141, s[6:7]
	v_add_u32_e32 v141, s31, v131
	s_mov_b32 m0, s12
	s_nop 0
	global_load_lds_dwordx4 v141, s[6:7]
	v_add_u32_e32 v141, s31, v133
	s_mov_b32 m0, s13
	s_nop 0
	global_load_lds_dwordx4 v141, s[6:7]
	v_add_u32_e32 v141, s37, v130
	s_mov_b32 m0, s15
	s_nop 0
	global_load_lds_dwordx4 v141, s[4:5]
	v_add_u32_e32 v141, s37, v132
	s_mov_b32 m0, s16
	s_nop 0
	global_load_lds_dwordx4 v141, s[4:5]
	s_waitcnt vmcnt(8)
	s_waitcnt lgkmcnt(0)
	s_setprio 1
	s_barrier
	v_mfma_f32_16x16x32_bf16 v[62:65], v[142:145], v[174:177], 0
	v_mfma_f32_16x16x32_bf16 v[62:65], v[146:149], v[178:181], v[62:65]
	v_mfma_f32_16x16x32_bf16 v[58:61], v[154:157], v[178:181], 0
	v_mfma_f32_16x16x32_bf16 v[58:61], v[150:153], v[174:177], v[58:61]
	v_mfma_f32_16x16x32_bf16 v[42:45], v[150:153], v[182:185], 0
	v_mfma_f32_16x16x32_bf16 v[42:45], v[154:157], v[186:189], v[42:45]
	v_mfma_f32_16x16x32_bf16 v[46:49], v[146:149], v[186:189], 0
	v_mfma_f32_16x16x32_bf16 v[46:49], v[142:145], v[182:185], v[46:49]
	v_mfma_f32_16x16x32_bf16 v[30:33], v[142:145], v[190:193], 0
	v_mfma_f32_16x16x32_bf16 v[30:33], v[146:149], v[194:197], v[30:33]
	v_mfma_f32_16x16x32_bf16 v[26:29], v[154:157], v[194:197], 0
	v_mfma_f32_16x16x32_bf16 v[26:29], v[150:153], v[190:193], v[26:29]
	v_mfma_f32_16x16x32_bf16 v[10:13], v[150:153], v[198:201], 0
	v_mfma_f32_16x16x32_bf16 v[10:13], v[154:157], v[212:215], v[10:13]
	v_mfma_f32_16x16x32_bf16 v[14:17], v[146:149], v[212:215], 0
	v_mfma_f32_16x16x32_bf16 v[14:17], v[142:145], v[198:201], v[14:17]
	s_setprio 0
	s_setprio 1
	v_mfma_f32_16x16x32_bf16 v[6:9], v[158:161], v[198:201], 0
	v_mfma_f32_16x16x32_bf16 v[6:9], v[162:165], v[212:215], v[6:9]
	v_mfma_f32_16x16x32_bf16 v[2:5], v[170:173], v[212:215], 0
	v_mfma_f32_16x16x32_bf16 v[2:5], v[166:169], v[198:201], v[2:5]
	v_mfma_f32_16x16x32_bf16 v[18:21], v[166:169], v[190:193], 0
	v_mfma_f32_16x16x32_bf16 v[18:21], v[170:173], v[194:197], v[18:21]
	v_mfma_f32_16x16x32_bf16 v[22:25], v[162:165], v[194:197], 0
	v_mfma_f32_16x16x32_bf16 v[22:25], v[158:161], v[190:193], v[22:25]
	v_mfma_f32_16x16x32_bf16 v[38:41], v[158:161], v[182:185], 0
	v_mfma_f32_16x16x32_bf16 v[38:41], v[162:165], v[186:189], v[38:41]
	v_mfma_f32_16x16x32_bf16 v[34:37], v[170:173], v[186:189], 0
	v_mfma_f32_16x16x32_bf16 v[34:37], v[166:169], v[182:185], v[34:37]
	v_mfma_f32_16x16x32_bf16 v[50:53], v[166:169], v[174:177], 0
	v_mfma_f32_16x16x32_bf16 v[50:53], v[170:173], v[178:181], v[50:53]
	v_mfma_f32_16x16x32_bf16 v[54:57], v[162:165], v[178:181], 0
	v_mfma_f32_16x16x32_bf16 v[54:57], v[158:161], v[174:177], v[54:57]
	s_setprio 0
	s_barrier
	v_add_u32_e32 v141, s21, v137
	ds_read_b128 v[142:145], v141
	ds_read_b128 v[146:149], v141 offset:1024
	ds_read_b128 v[150:153], v141 offset:2048
	ds_read_b128 v[154:157], v141 offset:3072
	v_add_u32_e32 v141, s26, v137
	ds_read_b128 v[158:161], v141
	ds_read_b128 v[162:165], v141 offset:1024
	ds_read_b128 v[166:169], v141 offset:2048
	ds_read_b128 v[170:173], v141 offset:3072
	s_add_i32 s37, s37, 0x80000
	s_mov_b32 m0, s17
	v_add_u32_e32 v141, s37, v130
	ds_read_b128 v[174:177], v140 offset:32768
	ds_read_b128 v[178:181], v140 offset:33792
	ds_read_b128 v[182:185], v140 offset:34816
	ds_read_b128 v[186:189], v140 offset:35840
	ds_read_b128 v[190:193], v140 offset:36864
	ds_read_b128 v[194:197], v140 offset:37888
	ds_read_b128 v[198:201], v140 offset:38912
	ds_read_b128 v[212:215], v140 offset:39936
	global_load_lds_dwordx4 v141, s[4:5]
	v_add_u32_e32 v141, s37, v132
	s_mov_b32 m0, s18
	s_nop 0
	global_load_lds_dwordx4 v141, s[4:5]
	s_waitcnt vmcnt(8)
	s_waitcnt lgkmcnt(0)
	s_setprio 1
	s_barrier
	v_mfma_f32_16x16x32_bf16 v[126:129], v[142:145], v[174:177], v[126:129]
	v_mfma_f32_16x16x32_bf16 v[126:129], v[146:149], v[178:181], v[126:129]
	v_mfma_f32_16x16x32_bf16 v[122:125], v[154:157], v[178:181], v[122:125]
	v_mfma_f32_16x16x32_bf16 v[122:125], v[150:153], v[174:177], v[122:125]
	v_mfma_f32_16x16x32_bf16 v[106:109], v[150:153], v[182:185], v[106:109]
	v_mfma_f32_16x16x32_bf16 v[106:109], v[154:157], v[186:189], v[106:109]
	v_mfma_f32_16x16x32_bf16 v[110:113], v[146:149], v[186:189], v[110:113]
	v_mfma_f32_16x16x32_bf16 v[110:113], v[142:145], v[182:185], v[110:113]
	v_mfma_f32_16x16x32_bf16 v[94:97], v[142:145], v[190:193], v[94:97]
	v_mfma_f32_16x16x32_bf16 v[94:97], v[146:149], v[194:197], v[94:97]
	v_mfma_f32_16x16x32_bf16 v[90:93], v[154:157], v[194:197], v[90:93]
	v_mfma_f32_16x16x32_bf16 v[90:93], v[150:153], v[190:193], v[90:93]
	v_mfma_f32_16x16x32_bf16 v[74:77], v[150:153], v[198:201], v[74:77]
	v_mfma_f32_16x16x32_bf16 v[74:77], v[154:157], v[212:215], v[74:77]
	v_mfma_f32_16x16x32_bf16 v[78:81], v[146:149], v[212:215], v[78:81]
	v_mfma_f32_16x16x32_bf16 v[78:81], v[142:145], v[198:201], v[78:81]
	s_setprio 0
	s_setprio 1
	v_mfma_f32_16x16x32_bf16 v[70:73], v[158:161], v[198:201], v[70:73]
	v_mfma_f32_16x16x32_bf16 v[70:73], v[162:165], v[212:215], v[70:73]
	v_mfma_f32_16x16x32_bf16 v[66:69], v[170:173], v[212:215], v[66:69]
	v_mfma_f32_16x16x32_bf16 v[66:69], v[166:169], v[198:201], v[66:69]
	v_mfma_f32_16x16x32_bf16 v[82:85], v[166:169], v[190:193], v[82:85]
	v_mfma_f32_16x16x32_bf16 v[82:85], v[170:173], v[194:197], v[82:85]
	v_mfma_f32_16x16x32_bf16 v[86:89], v[162:165], v[194:197], v[86:89]
	v_mfma_f32_16x16x32_bf16 v[86:89], v[158:161], v[190:193], v[86:89]
	v_mfma_f32_16x16x32_bf16 v[102:105], v[158:161], v[182:185], v[102:105]
	v_mfma_f32_16x16x32_bf16 v[102:105], v[162:165], v[186:189], v[102:105]
	v_mfma_f32_16x16x32_bf16 v[98:101], v[170:173], v[186:189], v[98:101]
	v_mfma_f32_16x16x32_bf16 v[98:101], v[166:169], v[182:185], v[98:101]
	v_mfma_f32_16x16x32_bf16 v[114:117], v[166:169], v[174:177], v[114:117]
	v_mfma_f32_16x16x32_bf16 v[114:117], v[170:173], v[178:181], v[114:117]
	v_mfma_f32_16x16x32_bf16 v[118:121], v[162:165], v[178:181], v[118:121]
	v_mfma_f32_16x16x32_bf16 v[118:121], v[158:161], v[174:177], v[118:121]
	s_setprio 0
	s_barrier
	s_or_b32 s31, s36, 0x80
	s_mov_b32 m0, s22
	v_add_u32_e32 v141, s31, v131
	ds_read_b128 v[174:177], v140 offset:49152
	ds_read_b128 v[178:181], v140 offset:50176
	ds_read_b128 v[182:185], v140 offset:51200
	ds_read_b128 v[186:189], v140 offset:52224
	ds_read_b128 v[190:193], v140 offset:53248
	ds_read_b128 v[194:197], v140 offset:54272
	ds_read_b128 v[198:201], v140 offset:55296
	ds_read_b128 v[212:215], v140 offset:56320
	global_load_lds_dwordx4 v141, s[6:7]
	v_add_u32_e32 v141, s31, v133
	s_mov_b32 m0, s23
	s_add_i32 s36, s36, 0x80080
	global_load_lds_dwordx4 v141, s[6:7]
	v_add_u32_e32 v141, s36, v131
	s_mov_b32 m0, s27
	s_nop 0
	global_load_lds_dwordx4 v141, s[6:7]
	v_add_u32_e32 v141, s36, v133
	s_mov_b32 m0, s29
	s_nop 0
	global_load_lds_dwordx4 v141, s[6:7]
	v_add_u32_e32 v141, s35, v130
	s_mov_b32 m0, s24
	s_nop 0
	global_load_lds_dwordx4 v141, s[4:5]
	v_add_u32_e32 v141, s35, v132
	s_mov_b32 m0, s25
	s_nop 0
	global_load_lds_dwordx4 v141, s[4:5]
	s_waitcnt vmcnt(8)
	s_waitcnt lgkmcnt(0)
	s_setprio 1
	s_barrier
	v_mfma_f32_16x16x32_bf16 v[62:65], v[142:145], v[174:177], v[62:65]
	v_mfma_f32_16x16x32_bf16 v[62:65], v[146:149], v[178:181], v[62:65]
	v_mfma_f32_16x16x32_bf16 v[58:61], v[154:157], v[178:181], v[58:61]
	v_mfma_f32_16x16x32_bf16 v[58:61], v[150:153], v[174:177], v[58:61]
	v_mfma_f32_16x16x32_bf16 v[42:45], v[150:153], v[182:185], v[42:45]
	v_mfma_f32_16x16x32_bf16 v[42:45], v[154:157], v[186:189], v[42:45]
	v_mfma_f32_16x16x32_bf16 v[46:49], v[146:149], v[186:189], v[46:49]
	v_mfma_f32_16x16x32_bf16 v[46:49], v[142:145], v[182:185], v[46:49]
	v_mfma_f32_16x16x32_bf16 v[30:33], v[142:145], v[190:193], v[30:33]
	v_mfma_f32_16x16x32_bf16 v[30:33], v[146:149], v[194:197], v[30:33]
	v_mfma_f32_16x16x32_bf16 v[26:29], v[154:157], v[194:197], v[26:29]
	v_mfma_f32_16x16x32_bf16 v[26:29], v[150:153], v[190:193], v[26:29]
	v_mfma_f32_16x16x32_bf16 v[10:13], v[150:153], v[198:201], v[10:13]
	v_mfma_f32_16x16x32_bf16 v[10:13], v[154:157], v[212:215], v[10:13]
	v_mfma_f32_16x16x32_bf16 v[14:17], v[146:149], v[212:215], v[14:17]
	v_mfma_f32_16x16x32_bf16 v[14:17], v[142:145], v[198:201], v[14:17]
	s_setprio 0
	s_setprio 1
	v_mfma_f32_16x16x32_bf16 v[6:9], v[158:161], v[198:201], v[6:9]
	v_mfma_f32_16x16x32_bf16 v[6:9], v[162:165], v[212:215], v[6:9]
	v_mfma_f32_16x16x32_bf16 v[2:5], v[170:173], v[212:215], v[2:5]
	v_mfma_f32_16x16x32_bf16 v[2:5], v[166:169], v[198:201], v[2:5]
	v_mfma_f32_16x16x32_bf16 v[18:21], v[166:169], v[190:193], v[18:21]
	v_mfma_f32_16x16x32_bf16 v[18:21], v[170:173], v[194:197], v[18:21]
	v_mfma_f32_16x16x32_bf16 v[22:25], v[162:165], v[194:197], v[22:25]
	v_mfma_f32_16x16x32_bf16 v[22:25], v[158:161], v[190:193], v[22:25]
	v_mfma_f32_16x16x32_bf16 v[38:41], v[158:161], v[182:185], v[38:41]
	v_mfma_f32_16x16x32_bf16 v[38:41], v[162:165], v[186:189], v[38:41]
	v_mfma_f32_16x16x32_bf16 v[34:37], v[170:173], v[186:189], v[34:37]
	v_mfma_f32_16x16x32_bf16 v[34:37], v[166:169], v[182:185], v[34:37]
	v_mfma_f32_16x16x32_bf16 v[50:53], v[166:169], v[174:177], v[50:53]
	v_mfma_f32_16x16x32_bf16 v[50:53], v[170:173], v[178:181], v[50:53]
	v_mfma_f32_16x16x32_bf16 v[54:57], v[162:165], v[178:181], v[54:57]
	v_mfma_f32_16x16x32_bf16 v[54:57], v[158:161], v[174:177], v[54:57]
	s_setprio 0
	s_barrier
	s_add_i32 s30, s30, 2
	s_cmp_gt_u32 s30, 29
	s_mov_b32 s31, s34
.LBB0_152:
	v_add_u32_e32 v141, s3, v137
	ds_read_b128 v[142:145], v141
	ds_read_b128 v[146:149], v141 offset:1024
	ds_read_b128 v[150:153], v141 offset:2048
	ds_read_b128 v[154:157], v141 offset:3072
	v_add_u32_e32 v141, s11, v137
	ds_read_b128 v[158:161], v141
	ds_read_b128 v[162:165], v141 offset:1024
	ds_read_b128 v[166:169], v141 offset:2048
	ds_read_b128 v[170:173], v141 offset:3072
	s_add_i32 s34, s31, 0x100
	s_cmp_lg_u32 s30, 28
	s_cselect_b32 s36, s34, 0
	s_add_i32 s37, s36, s14
	s_or_b32 s35, s37, 0x80
	s_add_i32 s36, s36, s2
	v_add_u32_e32 v141, s31, v139
	s_add_i32 m0, s15, 0xc000
	ds_read_b128 v[174:177], v140
	ds_read_b128 v[178:181], v140 offset:1024
	ds_read_b128 v[182:185], v140 offset:2048
	ds_read_b128 v[186:189], v140 offset:3072
	ds_read_b128 v[190:193], v140 offset:4096
	ds_read_b128 v[194:197], v140 offset:5120
	ds_read_b128 v[198:201], v140 offset:6144
	ds_read_b128 v[212:215], v140 offset:7168
	global_load_lds_dwordx4 v141, s[4:5]
	v_add_u32_e32 v141, s31, v138
	s_add_i32 m0, s15, 0xe000
	s_nop 0
	global_load_lds_dwordx4 v141, s[4:5]
	s_waitcnt vmcnt(8)
	s_waitcnt lgkmcnt(0)
	s_setprio 1
	s_barrier
	v_mfma_f32_16x16x32_bf16 v[126:129], v[142:145], v[174:177], v[126:129]
	v_mfma_f32_16x16x32_bf16 v[126:129], v[146:149], v[178:181], v[126:129]
	v_mfma_f32_16x16x32_bf16 v[122:125], v[154:157], v[178:181], v[122:125]
	v_mfma_f32_16x16x32_bf16 v[122:125], v[150:153], v[174:177], v[122:125]
	v_mfma_f32_16x16x32_bf16 v[106:109], v[150:153], v[182:185], v[106:109]
	v_mfma_f32_16x16x32_bf16 v[106:109], v[154:157], v[186:189], v[106:109]
	v_mfma_f32_16x16x32_bf16 v[110:113], v[146:149], v[186:189], v[110:113]
	v_mfma_f32_16x16x32_bf16 v[110:113], v[142:145], v[182:185], v[110:113]
	v_mfma_f32_16x16x32_bf16 v[94:97], v[142:145], v[190:193], v[94:97]
	v_mfma_f32_16x16x32_bf16 v[94:97], v[146:149], v[194:197], v[94:97]
	v_mfma_f32_16x16x32_bf16 v[90:93], v[154:157], v[194:197], v[90:93]
	v_mfma_f32_16x16x32_bf16 v[90:93], v[150:153], v[190:193], v[90:93]
	v_mfma_f32_16x16x32_bf16 v[74:77], v[150:153], v[198:201], v[74:77]
	v_mfma_f32_16x16x32_bf16 v[74:77], v[154:157], v[212:215], v[74:77]
	v_mfma_f32_16x16x32_bf16 v[78:81], v[146:149], v[212:215], v[78:81]
	v_mfma_f32_16x16x32_bf16 v[78:81], v[142:145], v[198:201], v[78:81]
	s_setprio 0
	s_setprio 1
	v_mfma_f32_16x16x32_bf16 v[70:73], v[158:161], v[198:201], v[70:73]
	v_mfma_f32_16x16x32_bf16 v[70:73], v[162:165], v[212:215], v[70:73]
	v_mfma_f32_16x16x32_bf16 v[66:69], v[170:173], v[212:215], v[66:69]
	v_mfma_f32_16x16x32_bf16 v[66:69], v[166:169], v[198:201], v[66:69]
	v_mfma_f32_16x16x32_bf16 v[82:85], v[166:169], v[190:193], v[82:85]
	v_mfma_f32_16x16x32_bf16 v[82:85], v[170:173], v[194:197], v[82:85]
	v_mfma_f32_16x16x32_bf16 v[86:89], v[162:165], v[194:197], v[86:89]
	v_mfma_f32_16x16x32_bf16 v[86:89], v[158:161], v[190:193], v[86:89]
	v_mfma_f32_16x16x32_bf16 v[102:105], v[158:161], v[182:185], v[102:105]
	v_mfma_f32_16x16x32_bf16 v[102:105], v[162:165], v[186:189], v[102:105]
	v_mfma_f32_16x16x32_bf16 v[98:101], v[170:173], v[186:189], v[98:101]
	v_mfma_f32_16x16x32_bf16 v[98:101], v[166:169], v[182:185], v[98:101]
	v_mfma_f32_16x16x32_bf16 v[114:117], v[166:169], v[174:177], v[114:117]
	v_mfma_f32_16x16x32_bf16 v[114:117], v[170:173], v[178:181], v[114:117]
	v_mfma_f32_16x16x32_bf16 v[118:121], v[162:165], v[178:181], v[118:121]
	v_mfma_f32_16x16x32_bf16 v[118:121], v[158:161], v[174:177], v[118:121]
	s_setprio 0
	s_barrier
	s_mov_b32 m0, s9
	v_add_u32_e32 v141, s36, v131
	ds_read_b128 v[174:177], v140 offset:16384
	ds_read_b128 v[178:181], v140 offset:17408
	ds_read_b128 v[182:185], v140 offset:18432
	ds_read_b128 v[186:189], v140 offset:19456
	ds_read_b128 v[190:193], v140 offset:20480
	ds_read_b128 v[194:197], v140 offset:21504
	ds_read_b128 v[198:201], v140 offset:22528
	ds_read_b128 v[212:215], v140 offset:23552
	global_load_lds_dwordx4 v141, s[6:7]
	v_add_u32_e32 v141, s36, v133
	s_mov_b32 m0, s10
	s_add_i32 s31, s36, 0x80000
	global_load_lds_dwordx4 v141, s[6:7]
	v_add_u32_e32 v141, s31, v131
	s_mov_b32 m0, s12
	s_nop 0
	global_load_lds_dwordx4 v141, s[6:7]
	v_add_u32_e32 v141, s31, v133
	s_mov_b32 m0, s13
	s_nop 0
	global_load_lds_dwordx4 v141, s[6:7]
	v_add_u32_e32 v141, s37, v130
	s_mov_b32 m0, s15
	s_nop 0
	global_load_lds_dwordx4 v141, s[4:5]
	v_add_u32_e32 v141, s37, v132
	s_mov_b32 m0, s16
	s_nop 0
	global_load_lds_dwordx4 v141, s[4:5]
	s_waitcnt vmcnt(8)
	s_waitcnt lgkmcnt(0)
	s_setprio 1
	s_barrier
	v_mfma_f32_16x16x32_bf16 v[62:65], v[142:145], v[174:177], v[62:65]
	v_mfma_f32_16x16x32_bf16 v[62:65], v[146:149], v[178:181], v[62:65]
	v_mfma_f32_16x16x32_bf16 v[58:61], v[154:157], v[178:181], v[58:61]
	v_mfma_f32_16x16x32_bf16 v[58:61], v[150:153], v[174:177], v[58:61]
	v_mfma_f32_16x16x32_bf16 v[42:45], v[150:153], v[182:185], v[42:45]
	v_mfma_f32_16x16x32_bf16 v[42:45], v[154:157], v[186:189], v[42:45]
	v_mfma_f32_16x16x32_bf16 v[46:49], v[146:149], v[186:189], v[46:49]
	v_mfma_f32_16x16x32_bf16 v[46:49], v[142:145], v[182:185], v[46:49]
	v_mfma_f32_16x16x32_bf16 v[30:33], v[142:145], v[190:193], v[30:33]
	v_mfma_f32_16x16x32_bf16 v[30:33], v[146:149], v[194:197], v[30:33]
	v_mfma_f32_16x16x32_bf16 v[26:29], v[154:157], v[194:197], v[26:29]
	v_mfma_f32_16x16x32_bf16 v[26:29], v[150:153], v[190:193], v[26:29]
	v_mfma_f32_16x16x32_bf16 v[10:13], v[150:153], v[198:201], v[10:13]
	v_mfma_f32_16x16x32_bf16 v[10:13], v[154:157], v[212:215], v[10:13]
	v_mfma_f32_16x16x32_bf16 v[14:17], v[146:149], v[212:215], v[14:17]
	v_mfma_f32_16x16x32_bf16 v[14:17], v[142:145], v[198:201], v[14:17]
	s_setprio 0
	s_setprio 1
	v_mfma_f32_16x16x32_bf16 v[6:9], v[158:161], v[198:201], v[6:9]
	v_mfma_f32_16x16x32_bf16 v[6:9], v[162:165], v[212:215], v[6:9]
	v_mfma_f32_16x16x32_bf16 v[2:5], v[170:173], v[212:215], v[2:5]
	v_mfma_f32_16x16x32_bf16 v[2:5], v[166:169], v[198:201], v[2:5]
	v_mfma_f32_16x16x32_bf16 v[18:21], v[166:169], v[190:193], v[18:21]
	v_mfma_f32_16x16x32_bf16 v[18:21], v[170:173], v[194:197], v[18:21]
	v_mfma_f32_16x16x32_bf16 v[22:25], v[162:165], v[194:197], v[22:25]
	v_mfma_f32_16x16x32_bf16 v[22:25], v[158:161], v[190:193], v[22:25]
	v_mfma_f32_16x16x32_bf16 v[38:41], v[158:161], v[182:185], v[38:41]
	v_mfma_f32_16x16x32_bf16 v[38:41], v[162:165], v[186:189], v[38:41]
	v_mfma_f32_16x16x32_bf16 v[34:37], v[170:173], v[186:189], v[34:37]
	v_mfma_f32_16x16x32_bf16 v[34:37], v[166:169], v[182:185], v[34:37]
	v_mfma_f32_16x16x32_bf16 v[50:53], v[166:169], v[174:177], v[50:53]
	v_mfma_f32_16x16x32_bf16 v[50:53], v[170:173], v[178:181], v[50:53]
	v_mfma_f32_16x16x32_bf16 v[54:57], v[162:165], v[178:181], v[54:57]
	v_mfma_f32_16x16x32_bf16 v[54:57], v[158:161], v[174:177], v[54:57]
	s_setprio 0
	s_barrier
	v_add_u32_e32 v141, s21, v137
	ds_read_b128 v[142:145], v141
	ds_read_b128 v[146:149], v141 offset:1024
	ds_read_b128 v[150:153], v141 offset:2048
	ds_read_b128 v[154:157], v141 offset:3072
	v_add_u32_e32 v141, s26, v137
	ds_read_b128 v[158:161], v141
	ds_read_b128 v[162:165], v141 offset:1024
	ds_read_b128 v[166:169], v141 offset:2048
	ds_read_b128 v[170:173], v141 offset:3072
	s_add_i32 s37, s37, 0x80000
	s_mov_b32 m0, s17
	v_add_u32_e32 v141, s37, v130
	ds_read_b128 v[174:177], v140 offset:32768
	ds_read_b128 v[178:181], v140 offset:33792
	ds_read_b128 v[182:185], v140 offset:34816
	ds_read_b128 v[186:189], v140 offset:35840
	ds_read_b128 v[190:193], v140 offset:36864
	ds_read_b128 v[194:197], v140 offset:37888
	ds_read_b128 v[198:201], v140 offset:38912
	ds_read_b128 v[212:215], v140 offset:39936
	global_load_lds_dwordx4 v141, s[4:5]
	v_add_u32_e32 v141, s37, v132
	s_mov_b32 m0, s18
	s_nop 0
	global_load_lds_dwordx4 v141, s[4:5]
	s_waitcnt vmcnt(8)
	s_waitcnt lgkmcnt(0)
	s_setprio 1
	s_barrier
	v_mfma_f32_16x16x32_bf16 v[126:129], v[142:145], v[174:177], v[126:129]
	v_mfma_f32_16x16x32_bf16 v[126:129], v[146:149], v[178:181], v[126:129]
	v_mfma_f32_16x16x32_bf16 v[122:125], v[154:157], v[178:181], v[122:125]
	v_mfma_f32_16x16x32_bf16 v[122:125], v[150:153], v[174:177], v[122:125]
	v_mfma_f32_16x16x32_bf16 v[106:109], v[150:153], v[182:185], v[106:109]
	v_mfma_f32_16x16x32_bf16 v[106:109], v[154:157], v[186:189], v[106:109]
	v_mfma_f32_16x16x32_bf16 v[110:113], v[146:149], v[186:189], v[110:113]
	v_mfma_f32_16x16x32_bf16 v[110:113], v[142:145], v[182:185], v[110:113]
	v_mfma_f32_16x16x32_bf16 v[94:97], v[142:145], v[190:193], v[94:97]
	v_mfma_f32_16x16x32_bf16 v[94:97], v[146:149], v[194:197], v[94:97]
	v_mfma_f32_16x16x32_bf16 v[90:93], v[154:157], v[194:197], v[90:93]
	v_mfma_f32_16x16x32_bf16 v[90:93], v[150:153], v[190:193], v[90:93]
	v_mfma_f32_16x16x32_bf16 v[74:77], v[150:153], v[198:201], v[74:77]
	v_mfma_f32_16x16x32_bf16 v[74:77], v[154:157], v[212:215], v[74:77]
	v_mfma_f32_16x16x32_bf16 v[78:81], v[146:149], v[212:215], v[78:81]
	v_mfma_f32_16x16x32_bf16 v[78:81], v[142:145], v[198:201], v[78:81]
	s_setprio 0
	s_setprio 1
	v_mfma_f32_16x16x32_bf16 v[70:73], v[158:161], v[198:201], v[70:73]
	v_mfma_f32_16x16x32_bf16 v[70:73], v[162:165], v[212:215], v[70:73]
	v_mfma_f32_16x16x32_bf16 v[66:69], v[170:173], v[212:215], v[66:69]
	v_mfma_f32_16x16x32_bf16 v[66:69], v[166:169], v[198:201], v[66:69]
	v_mfma_f32_16x16x32_bf16 v[82:85], v[166:169], v[190:193], v[82:85]
	v_mfma_f32_16x16x32_bf16 v[82:85], v[170:173], v[194:197], v[82:85]
	v_mfma_f32_16x16x32_bf16 v[86:89], v[162:165], v[194:197], v[86:89]
	v_mfma_f32_16x16x32_bf16 v[86:89], v[158:161], v[190:193], v[86:89]
	v_mfma_f32_16x16x32_bf16 v[102:105], v[158:161], v[182:185], v[102:105]
	v_mfma_f32_16x16x32_bf16 v[102:105], v[162:165], v[186:189], v[102:105]
	v_mfma_f32_16x16x32_bf16 v[98:101], v[170:173], v[186:189], v[98:101]
	v_mfma_f32_16x16x32_bf16 v[98:101], v[166:169], v[182:185], v[98:101]
	v_mfma_f32_16x16x32_bf16 v[114:117], v[166:169], v[174:177], v[114:117]
	v_mfma_f32_16x16x32_bf16 v[114:117], v[170:173], v[178:181], v[114:117]
	v_mfma_f32_16x16x32_bf16 v[118:121], v[162:165], v[178:181], v[118:121]
	v_mfma_f32_16x16x32_bf16 v[118:121], v[158:161], v[174:177], v[118:121]
	s_setprio 0
	s_barrier
	s_or_b32 s31, s36, 0x80
	s_mov_b32 m0, s22
	v_add_u32_e32 v141, s31, v131
	ds_read_b128 v[174:177], v140 offset:49152
	ds_read_b128 v[178:181], v140 offset:50176
	ds_read_b128 v[182:185], v140 offset:51200
	ds_read_b128 v[186:189], v140 offset:52224
	ds_read_b128 v[190:193], v140 offset:53248
	ds_read_b128 v[194:197], v140 offset:54272
	ds_read_b128 v[198:201], v140 offset:55296
	ds_read_b128 v[212:215], v140 offset:56320
	global_load_lds_dwordx4 v141, s[6:7]
	v_add_u32_e32 v141, s31, v133
	s_mov_b32 m0, s23
	s_add_i32 s36, s36, 0x80080
	global_load_lds_dwordx4 v141, s[6:7]
	v_add_u32_e32 v141, s36, v131
	s_mov_b32 m0, s27
	s_nop 0
	global_load_lds_dwordx4 v141, s[6:7]
	v_add_u32_e32 v141, s36, v133
	s_mov_b32 m0, s29
	s_nop 0
	global_load_lds_dwordx4 v141, s[6:7]
	v_add_u32_e32 v141, s35, v130
	s_mov_b32 m0, s24
	s_nop 0
	global_load_lds_dwordx4 v141, s[4:5]
	v_add_u32_e32 v141, s35, v132
	s_mov_b32 m0, s25
	s_nop 0
	global_load_lds_dwordx4 v141, s[4:5]
	s_waitcnt vmcnt(8)
	s_waitcnt lgkmcnt(0)
	s_setprio 1
	s_barrier
	v_mfma_f32_16x16x32_bf16 v[62:65], v[142:145], v[174:177], v[62:65]
	v_mfma_f32_16x16x32_bf16 v[62:65], v[146:149], v[178:181], v[62:65]
	v_mfma_f32_16x16x32_bf16 v[58:61], v[154:157], v[178:181], v[58:61]
	v_mfma_f32_16x16x32_bf16 v[58:61], v[150:153], v[174:177], v[58:61]
	v_mfma_f32_16x16x32_bf16 v[42:45], v[150:153], v[182:185], v[42:45]
	v_mfma_f32_16x16x32_bf16 v[42:45], v[154:157], v[186:189], v[42:45]
	v_mfma_f32_16x16x32_bf16 v[46:49], v[146:149], v[186:189], v[46:49]
	v_mfma_f32_16x16x32_bf16 v[46:49], v[142:145], v[182:185], v[46:49]
	v_mfma_f32_16x16x32_bf16 v[30:33], v[142:145], v[190:193], v[30:33]
	v_mfma_f32_16x16x32_bf16 v[30:33], v[146:149], v[194:197], v[30:33]
	v_mfma_f32_16x16x32_bf16 v[26:29], v[154:157], v[194:197], v[26:29]
	v_mfma_f32_16x16x32_bf16 v[26:29], v[150:153], v[190:193], v[26:29]
	v_mfma_f32_16x16x32_bf16 v[10:13], v[150:153], v[198:201], v[10:13]
	v_mfma_f32_16x16x32_bf16 v[10:13], v[154:157], v[212:215], v[10:13]
	v_mfma_f32_16x16x32_bf16 v[14:17], v[146:149], v[212:215], v[14:17]
	v_mfma_f32_16x16x32_bf16 v[14:17], v[142:145], v[198:201], v[14:17]
	s_setprio 0
	s_setprio 1
	v_mfma_f32_16x16x32_bf16 v[6:9], v[158:161], v[198:201], v[6:9]
	v_mfma_f32_16x16x32_bf16 v[6:9], v[162:165], v[212:215], v[6:9]
	v_mfma_f32_16x16x32_bf16 v[2:5], v[170:173], v[212:215], v[2:5]
	v_mfma_f32_16x16x32_bf16 v[2:5], v[166:169], v[198:201], v[2:5]
	v_mfma_f32_16x16x32_bf16 v[18:21], v[166:169], v[190:193], v[18:21]
	v_mfma_f32_16x16x32_bf16 v[18:21], v[170:173], v[194:197], v[18:21]
	v_mfma_f32_16x16x32_bf16 v[22:25], v[162:165], v[194:197], v[22:25]
	v_mfma_f32_16x16x32_bf16 v[22:25], v[158:161], v[190:193], v[22:25]
	v_mfma_f32_16x16x32_bf16 v[38:41], v[158:161], v[182:185], v[38:41]
	v_mfma_f32_16x16x32_bf16 v[38:41], v[162:165], v[186:189], v[38:41]
	v_mfma_f32_16x16x32_bf16 v[34:37], v[170:173], v[186:189], v[34:37]
	v_mfma_f32_16x16x32_bf16 v[34:37], v[166:169], v[182:185], v[34:37]
	v_mfma_f32_16x16x32_bf16 v[50:53], v[166:169], v[174:177], v[50:53]
	v_mfma_f32_16x16x32_bf16 v[50:53], v[170:173], v[178:181], v[50:53]
	v_mfma_f32_16x16x32_bf16 v[54:57], v[162:165], v[178:181], v[54:57]
	v_mfma_f32_16x16x32_bf16 v[54:57], v[158:161], v[174:177], v[54:57]
	s_setprio 0
	s_barrier
	s_add_i32 s30, s30, 2
	s_cmp_gt_u32 s30, 29
	s_mov_b32 s31, s34
	s_cbranch_scc0 .LBB0_152
	s_cmpk_lt_u32 s8, 0x100
	s_cbranch_scc0 .LBB0_155
	s_barrier

.LBB0_194:
	s_mul_i32 s12, s40, 0x2c0000
	s_and_b64 s[48:49], s[4:5], exec
	s_mul_i32 s13, s39, 0x2c0000
	s_cselect_b32 s43, s12, s45
	s_cselect_b32 s44, s13, s46
	s_add_i32 s45, s45, 0x160080
	s_addk_i32 s46, 0x100
	s_mov_b32 s47, -2
	v_add_u32_e32 v130, s17, v137
	ds_read_b128 v[142:145], v130
	ds_read_b128 v[146:149], v130 offset:1024
	ds_read_b128 v[150:153], v130 offset:2048
	ds_read_b128 v[154:157], v130 offset:3072
	v_add_u32_e32 v130, s20, v137
	ds_read_b128 v[158:161], v130
	ds_read_b128 v[162:165], v130 offset:1024
	ds_read_b128 v[166:169], v130 offset:2048
	ds_read_b128 v[170:173], v130 offset:3072
	s_add_i32 s48, s45, 0xffea0080
	s_cmpk_eq_i32 s47, 0x54
	s_cselect_b32 s50, s43, s48
	s_cselect_b32 s49, s44, s46
	s_or_b32 s48, s50, 0x80
	v_add_u32_e32 v130, s45, v140
	s_add_i32 m0, s23, 0xc000
	ds_read_b128 v[174:177], v141
	ds_read_b128 v[178:181], v141 offset:1024
	ds_read_b128 v[182:185], v141 offset:2048
	ds_read_b128 v[186:189], v141 offset:3072
	ds_read_b128 v[190:193], v141 offset:4096
	ds_read_b128 v[194:197], v141 offset:5120
	ds_read_b128 v[198:201], v141 offset:6144
	ds_read_b128 v[212:215], v141 offset:7168
	global_load_lds_dwordx4 v130, s[0:1]
	v_add_u32_e32 v130, s45, v139
	s_add_i32 m0, s23, 0xe000
	s_nop 0
	global_load_lds_dwordx4 v130, s[0:1]
	s_waitcnt vmcnt(8)
	s_waitcnt lgkmcnt(0)
	s_setprio 1
	s_barrier
	v_mfma_f32_16x16x32_bf16 v[126:129], v[142:145], v[174:177], 0
	v_mfma_f32_16x16x32_bf16 v[126:129], v[146:149], v[178:181], v[126:129]
	v_mfma_f32_16x16x32_bf16 v[122:125], v[154:157], v[178:181], 0
	v_mfma_f32_16x16x32_bf16 v[122:125], v[150:153], v[174:177], v[122:125]
	v_mfma_f32_16x16x32_bf16 v[110:113], v[150:153], v[182:185], 0
	v_mfma_f32_16x16x32_bf16 v[110:113], v[154:157], v[186:189], v[110:113]
	v_mfma_f32_16x16x32_bf16 v[118:121], v[146:149], v[186:189], 0
	v_mfma_f32_16x16x32_bf16 v[118:121], v[142:145], v[182:185], v[118:121]
	v_mfma_f32_16x16x32_bf16 v[102:105], v[142:145], v[190:193], 0
	v_mfma_f32_16x16x32_bf16 v[102:105], v[146:149], v[194:197], v[102:105]
	v_mfma_f32_16x16x32_bf16 v[94:97], v[154:157], v[194:197], 0
	v_mfma_f32_16x16x32_bf16 v[94:97], v[150:153], v[190:193], v[94:97]
	v_mfma_f32_16x16x32_bf16 v[78:81], v[150:153], v[198:201], 0
	v_mfma_f32_16x16x32_bf16 v[78:81], v[154:157], v[212:215], v[78:81]
	v_mfma_f32_16x16x32_bf16 v[86:89], v[146:149], v[212:215], 0
	v_mfma_f32_16x16x32_bf16 v[86:89], v[142:145], v[198:201], v[86:89]
	s_setprio 0
	s_setprio 1
	v_mfma_f32_16x16x32_bf16 v[70:73], v[158:161], v[198:201], 0
	v_mfma_f32_16x16x32_bf16 v[70:73], v[162:165], v[212:215], v[70:73]
	v_mfma_f32_16x16x32_bf16 v[66:69], v[170:173], v[212:215], 0
	v_mfma_f32_16x16x32_bf16 v[66:69], v[166:169], v[198:201], v[66:69]
	v_mfma_f32_16x16x32_bf16 v[74:77], v[166:169], v[190:193], 0
	v_mfma_f32_16x16x32_bf16 v[74:77], v[170:173], v[194:197], v[74:77]
	v_mfma_f32_16x16x32_bf16 v[82:85], v[162:165], v[194:197], 0
	v_mfma_f32_16x16x32_bf16 v[82:85], v[158:161], v[190:193], v[82:85]
	v_mfma_f32_16x16x32_bf16 v[98:101], v[158:161], v[182:185], 0
	v_mfma_f32_16x16x32_bf16 v[98:101], v[162:165], v[186:189], v[98:101]
	v_mfma_f32_16x16x32_bf16 v[90:93], v[170:173], v[186:189], 0
	v_mfma_f32_16x16x32_bf16 v[90:93], v[166:169], v[182:185], v[90:93]
	v_mfma_f32_16x16x32_bf16 v[106:109], v[166:169], v[174:177], 0
	v_mfma_f32_16x16x32_bf16 v[106:109], v[170:173], v[178:181], v[106:109]
	v_mfma_f32_16x16x32_bf16 v[114:117], v[162:165], v[178:181], 0
	v_mfma_f32_16x16x32_bf16 v[114:117], v[158:161], v[174:177], v[114:117]
	s_setprio 0
	s_barrier
	s_mov_b32 m0, s18
	v_add_u32_e32 v130, s49, v133
	ds_read_b128 v[174:177], v141 offset:16384
	ds_read_b128 v[178:181], v141 offset:17408
	ds_read_b128 v[182:185], v141 offset:18432
	ds_read_b128 v[186:189], v141 offset:19456
	ds_read_b128 v[190:193], v141 offset:20480
	ds_read_b128 v[194:197], v141 offset:21504
	ds_read_b128 v[198:201], v141 offset:22528
	ds_read_b128 v[212:215], v141 offset:23552
	global_load_lds_dwordx4 v130, s[2:3]
	v_add_u32_e32 v130, s49, v135
	s_mov_b32 m0, s19
	s_add_i32 s51, s49, 0x160000
	global_load_lds_dwordx4 v130, s[2:3]
	v_add_u32_e32 v130, s51, v133
	s_mov_b32 m0, s21
	s_nop 0
	global_load_lds_dwordx4 v130, s[2:3]
	v_add_u32_e32 v130, s51, v135
	s_mov_b32 m0, s22
	s_nop 0
	global_load_lds_dwordx4 v130, s[2:3]
	v_add_u32_e32 v130, s50, v132
	s_mov_b32 m0, s23
	s_nop 0
	global_load_lds_dwordx4 v130, s[0:1]
	v_add_u32_e32 v130, s50, v134
	s_mov_b32 m0, s24
	s_nop 0
	global_load_lds_dwordx4 v130, s[0:1]
	s_waitcnt vmcnt(8)
	s_waitcnt lgkmcnt(0)
	s_setprio 1
	s_barrier
	v_mfma_f32_16x16x32_bf16 v[62:65], v[142:145], v[174:177], 0
	v_mfma_f32_16x16x32_bf16 v[62:65], v[146:149], v[178:181], v[62:65]
	v_mfma_f32_16x16x32_bf16 v[58:61], v[154:157], v[178:181], 0
	v_mfma_f32_16x16x32_bf16 v[58:61], v[150:153], v[174:177], v[58:61]
	v_mfma_f32_16x16x32_bf16 v[46:49], v[150:153], v[182:185], 0
	v_mfma_f32_16x16x32_bf16 v[46:49], v[154:157], v[186:189], v[46:49]
	v_mfma_f32_16x16x32_bf16 v[54:57], v[146:149], v[186:189], 0
	v_mfma_f32_16x16x32_bf16 v[54:57], v[142:145], v[182:185], v[54:57]
	v_mfma_f32_16x16x32_bf16 v[38:41], v[142:145], v[190:193], 0
	v_mfma_f32_16x16x32_bf16 v[38:41], v[146:149], v[194:197], v[38:41]
	v_mfma_f32_16x16x32_bf16 v[30:33], v[154:157], v[194:197], 0
	v_mfma_f32_16x16x32_bf16 v[30:33], v[150:153], v[190:193], v[30:33]
	v_mfma_f32_16x16x32_bf16 v[14:17], v[150:153], v[198:201], 0
	v_mfma_f32_16x16x32_bf16 v[14:17], v[154:157], v[212:215], v[14:17]
	v_mfma_f32_16x16x32_bf16 v[22:25], v[146:149], v[212:215], 0
	v_mfma_f32_16x16x32_bf16 v[22:25], v[142:145], v[198:201], v[22:25]
	s_setprio 0
	s_setprio 1
	v_mfma_f32_16x16x32_bf16 v[6:9], v[158:161], v[198:201], 0
	v_mfma_f32_16x16x32_bf16 v[6:9], v[162:165], v[212:215], v[6:9]
	v_mfma_f32_16x16x32_bf16 v[2:5], v[170:173], v[212:215], 0
	v_mfma_f32_16x16x32_bf16 v[2:5], v[166:169], v[198:201], v[2:5]
	v_mfma_f32_16x16x32_bf16 v[10:13], v[166:169], v[190:193], 0
	v_mfma_f32_16x16x32_bf16 v[10:13], v[170:173], v[194:197], v[10:13]
	v_mfma_f32_16x16x32_bf16 v[18:21], v[162:165], v[194:197], 0
	v_mfma_f32_16x16x32_bf16 v[18:21], v[158:161], v[190:193], v[18:21]
	v_mfma_f32_16x16x32_bf16 v[34:37], v[158:161], v[182:185], 0
	v_mfma_f32_16x16x32_bf16 v[34:37], v[162:165], v[186:189], v[34:37]
	v_mfma_f32_16x16x32_bf16 v[26:29], v[170:173], v[186:189], 0
	v_mfma_f32_16x16x32_bf16 v[26:29], v[166:169], v[182:185], v[26:29]
	v_mfma_f32_16x16x32_bf16 v[42:45], v[166:169], v[174:177], 0
	v_mfma_f32_16x16x32_bf16 v[42:45], v[170:173], v[178:181], v[42:45]
	v_mfma_f32_16x16x32_bf16 v[50:53], v[162:165], v[178:181], 0
	v_mfma_f32_16x16x32_bf16 v[50:53], v[158:161], v[174:177], v[50:53]
	s_setprio 0
	s_barrier
	v_add_u32_e32 v130, s27, v137
	ds_read_b128 v[142:145], v130
	ds_read_b128 v[146:149], v130 offset:1024
	ds_read_b128 v[150:153], v130 offset:2048
	ds_read_b128 v[154:157], v130 offset:3072
	v_add_u32_e32 v130, s34, v137
	ds_read_b128 v[158:161], v130
	ds_read_b128 v[162:165], v130 offset:1024
	ds_read_b128 v[166:169], v130 offset:2048
	ds_read_b128 v[170:173], v130 offset:3072
	s_add_i32 s50, s50, 0x160000
	s_mov_b32 m0, s25
	v_add_u32_e32 v130, s50, v132
	ds_read_b128 v[174:177], v141 offset:32768
	ds_read_b128 v[178:181], v141 offset:33792
	ds_read_b128 v[182:185], v141 offset:34816
	ds_read_b128 v[186:189], v141 offset:35840
	ds_read_b128 v[190:193], v141 offset:36864
	ds_read_b128 v[194:197], v141 offset:37888
	ds_read_b128 v[198:201], v141 offset:38912
	ds_read_b128 v[212:215], v141 offset:39936
	global_load_lds_dwordx4 v130, s[0:1]
	v_add_u32_e32 v130, s50, v134
	s_mov_b32 m0, s26
	s_nop 0
	global_load_lds_dwordx4 v130, s[0:1]
	s_waitcnt vmcnt(8)
	s_waitcnt lgkmcnt(0)
	s_setprio 1
	s_barrier
	v_mfma_f32_16x16x32_bf16 v[126:129], v[142:145], v[174:177], v[126:129]
	v_mfma_f32_16x16x32_bf16 v[126:129], v[146:149], v[178:181], v[126:129]
	v_mfma_f32_16x16x32_bf16 v[122:125], v[154:157], v[178:181], v[122:125]
	v_mfma_f32_16x16x32_bf16 v[122:125], v[150:153], v[174:177], v[122:125]
	v_mfma_f32_16x16x32_bf16 v[110:113], v[150:153], v[182:185], v[110:113]
	v_mfma_f32_16x16x32_bf16 v[110:113], v[154:157], v[186:189], v[110:113]
	v_mfma_f32_16x16x32_bf16 v[118:121], v[146:149], v[186:189], v[118:121]
	v_mfma_f32_16x16x32_bf16 v[118:121], v[142:145], v[182:185], v[118:121]
	v_mfma_f32_16x16x32_bf16 v[102:105], v[142:145], v[190:193], v[102:105]
	v_mfma_f32_16x16x32_bf16 v[102:105], v[146:149], v[194:197], v[102:105]
	v_mfma_f32_16x16x32_bf16 v[94:97], v[154:157], v[194:197], v[94:97]
	v_mfma_f32_16x16x32_bf16 v[94:97], v[150:153], v[190:193], v[94:97]
	v_mfma_f32_16x16x32_bf16 v[78:81], v[150:153], v[198:201], v[78:81]
	v_mfma_f32_16x16x32_bf16 v[78:81], v[154:157], v[212:215], v[78:81]
	v_mfma_f32_16x16x32_bf16 v[86:89], v[146:149], v[212:215], v[86:89]
	v_mfma_f32_16x16x32_bf16 v[86:89], v[142:145], v[198:201], v[86:89]
	s_setprio 0
	s_setprio 1
	v_mfma_f32_16x16x32_bf16 v[70:73], v[158:161], v[198:201], v[70:73]
	v_mfma_f32_16x16x32_bf16 v[70:73], v[162:165], v[212:215], v[70:73]
	v_mfma_f32_16x16x32_bf16 v[66:69], v[170:173], v[212:215], v[66:69]
	v_mfma_f32_16x16x32_bf16 v[66:69], v[166:169], v[198:201], v[66:69]
	v_mfma_f32_16x16x32_bf16 v[74:77], v[166:169], v[190:193], v[74:77]
	v_mfma_f32_16x16x32_bf16 v[74:77], v[170:173], v[194:197], v[74:77]
	v_mfma_f32_16x16x32_bf16 v[82:85], v[162:165], v[194:197], v[82:85]
	v_mfma_f32_16x16x32_bf16 v[82:85], v[158:161], v[190:193], v[82:85]
	v_mfma_f32_16x16x32_bf16 v[98:101], v[158:161], v[182:185], v[98:101]
	v_mfma_f32_16x16x32_bf16 v[98:101], v[162:165], v[186:189], v[98:101]
	v_mfma_f32_16x16x32_bf16 v[90:93], v[170:173], v[186:189], v[90:93]
	v_mfma_f32_16x16x32_bf16 v[90:93], v[166:169], v[182:185], v[90:93]
	v_mfma_f32_16x16x32_bf16 v[106:109], v[166:169], v[174:177], v[106:109]
	v_mfma_f32_16x16x32_bf16 v[106:109], v[170:173], v[178:181], v[106:109]
	v_mfma_f32_16x16x32_bf16 v[114:117], v[162:165], v[178:181], v[114:117]
	v_mfma_f32_16x16x32_bf16 v[114:117], v[158:161], v[174:177], v[114:117]
	s_setprio 0
	s_barrier
	s_or_b32 s50, s49, 0x80
	s_mov_b32 m0, s28
	v_add_u32_e32 v130, s50, v133
	ds_read_b128 v[174:177], v141 offset:49152
	ds_read_b128 v[178:181], v141 offset:50176
	ds_read_b128 v[182:185], v141 offset:51200
	ds_read_b128 v[186:189], v141 offset:52224
	ds_read_b128 v[190:193], v141 offset:53248
	ds_read_b128 v[194:197], v141 offset:54272
	ds_read_b128 v[198:201], v141 offset:55296
	ds_read_b128 v[212:215], v141 offset:56320
	global_load_lds_dwordx4 v130, s[2:3]
	v_add_u32_e32 v130, s50, v135
	s_mov_b32 m0, s29
	s_add_i32 s49, s49, 0x160080
	global_load_lds_dwordx4 v130, s[2:3]
	v_add_u32_e32 v130, s49, v133
	s_mov_b32 m0, s35
	s_nop 0
	global_load_lds_dwordx4 v130, s[2:3]
	v_add_u32_e32 v130, s49, v135
	s_mov_b32 m0, s36
	s_nop 0
	global_load_lds_dwordx4 v130, s[2:3]
	v_add_u32_e32 v130, s48, v132
	s_mov_b32 m0, s30
	s_nop 0
	global_load_lds_dwordx4 v130, s[0:1]
	v_add_u32_e32 v130, s48, v134
	s_mov_b32 m0, s31
	s_nop 0
	global_load_lds_dwordx4 v130, s[0:1]
	s_waitcnt vmcnt(8)
	s_waitcnt lgkmcnt(0)
	s_setprio 1
	s_barrier
	v_mfma_f32_16x16x32_bf16 v[62:65], v[142:145], v[174:177], v[62:65]
	v_mfma_f32_16x16x32_bf16 v[62:65], v[146:149], v[178:181], v[62:65]
	v_mfma_f32_16x16x32_bf16 v[58:61], v[154:157], v[178:181], v[58:61]
	v_mfma_f32_16x16x32_bf16 v[58:61], v[150:153], v[174:177], v[58:61]
	v_mfma_f32_16x16x32_bf16 v[46:49], v[150:153], v[182:185], v[46:49]
	v_mfma_f32_16x16x32_bf16 v[46:49], v[154:157], v[186:189], v[46:49]
	v_mfma_f32_16x16x32_bf16 v[54:57], v[146:149], v[186:189], v[54:57]
	v_mfma_f32_16x16x32_bf16 v[54:57], v[142:145], v[182:185], v[54:57]
	v_mfma_f32_16x16x32_bf16 v[38:41], v[142:145], v[190:193], v[38:41]
	v_mfma_f32_16x16x32_bf16 v[38:41], v[146:149], v[194:197], v[38:41]
	v_mfma_f32_16x16x32_bf16 v[30:33], v[154:157], v[194:197], v[30:33]
	v_mfma_f32_16x16x32_bf16 v[30:33], v[150:153], v[190:193], v[30:33]
	v_mfma_f32_16x16x32_bf16 v[14:17], v[150:153], v[198:201], v[14:17]
	v_mfma_f32_16x16x32_bf16 v[14:17], v[154:157], v[212:215], v[14:17]
	v_mfma_f32_16x16x32_bf16 v[22:25], v[146:149], v[212:215], v[22:25]
	v_mfma_f32_16x16x32_bf16 v[22:25], v[142:145], v[198:201], v[22:25]
	s_setprio 0
	s_setprio 1
	v_mfma_f32_16x16x32_bf16 v[6:9], v[158:161], v[198:201], v[6:9]
	v_mfma_f32_16x16x32_bf16 v[6:9], v[162:165], v[212:215], v[6:9]
	v_mfma_f32_16x16x32_bf16 v[2:5], v[170:173], v[212:215], v[2:5]
	v_mfma_f32_16x16x32_bf16 v[2:5], v[166:169], v[198:201], v[2:5]
	v_mfma_f32_16x16x32_bf16 v[10:13], v[166:169], v[190:193], v[10:13]
	v_mfma_f32_16x16x32_bf16 v[10:13], v[170:173], v[194:197], v[10:13]
	v_mfma_f32_16x16x32_bf16 v[18:21], v[162:165], v[194:197], v[18:21]
	v_mfma_f32_16x16x32_bf16 v[18:21], v[158:161], v[190:193], v[18:21]
	v_mfma_f32_16x16x32_bf16 v[34:37], v[158:161], v[182:185], v[34:37]
	v_mfma_f32_16x16x32_bf16 v[34:37], v[162:165], v[186:189], v[34:37]
	v_mfma_f32_16x16x32_bf16 v[26:29], v[170:173], v[186:189], v[26:29]
	v_mfma_f32_16x16x32_bf16 v[26:29], v[166:169], v[182:185], v[26:29]
	v_mfma_f32_16x16x32_bf16 v[42:45], v[166:169], v[174:177], v[42:45]
	v_mfma_f32_16x16x32_bf16 v[42:45], v[170:173], v[178:181], v[42:45]
	v_mfma_f32_16x16x32_bf16 v[50:53], v[162:165], v[178:181], v[50:53]
	v_mfma_f32_16x16x32_bf16 v[50:53], v[158:161], v[174:177], v[50:53]
	s_setprio 0
	s_barrier
	s_add_i32 s47, s47, 2
	s_addk_i32 s45, 0x100
	s_addk_i32 s46, 0x100
	s_cmpk_gt_u32 s47, 0x55
.LBB0_195:
	v_add_u32_e32 v130, s17, v137
	ds_read_b128 v[142:145], v130
	ds_read_b128 v[146:149], v130 offset:1024
	ds_read_b128 v[150:153], v130 offset:2048
	ds_read_b128 v[154:157], v130 offset:3072
	v_add_u32_e32 v130, s20, v137
	ds_read_b128 v[158:161], v130
	ds_read_b128 v[162:165], v130 offset:1024
	ds_read_b128 v[166:169], v130 offset:2048
	ds_read_b128 v[170:173], v130 offset:3072
	s_add_i32 s48, s45, 0xffea0080
	s_cmpk_eq_i32 s47, 0x54
	s_cselect_b32 s50, s43, s48
	s_cselect_b32 s49, s44, s46
	s_or_b32 s48, s50, 0x80
	v_add_u32_e32 v130, s45, v140
	s_add_i32 m0, s23, 0xc000
	ds_read_b128 v[174:177], v141
	ds_read_b128 v[178:181], v141 offset:1024
	ds_read_b128 v[182:185], v141 offset:2048
	ds_read_b128 v[186:189], v141 offset:3072
	ds_read_b128 v[190:193], v141 offset:4096
	ds_read_b128 v[194:197], v141 offset:5120
	ds_read_b128 v[198:201], v141 offset:6144
	ds_read_b128 v[212:215], v141 offset:7168
	global_load_lds_dwordx4 v130, s[0:1]
	v_add_u32_e32 v130, s45, v139
	s_add_i32 m0, s23, 0xe000
	s_nop 0
	global_load_lds_dwordx4 v130, s[0:1]
	s_waitcnt vmcnt(8)
	s_waitcnt lgkmcnt(0)
	s_setprio 1
	s_barrier
	v_mfma_f32_16x16x32_bf16 v[126:129], v[142:145], v[174:177], v[126:129]
	v_mfma_f32_16x16x32_bf16 v[126:129], v[146:149], v[178:181], v[126:129]
	v_mfma_f32_16x16x32_bf16 v[122:125], v[154:157], v[178:181], v[122:125]
	v_mfma_f32_16x16x32_bf16 v[122:125], v[150:153], v[174:177], v[122:125]
	v_mfma_f32_16x16x32_bf16 v[110:113], v[150:153], v[182:185], v[110:113]
	v_mfma_f32_16x16x32_bf16 v[110:113], v[154:157], v[186:189], v[110:113]
	v_mfma_f32_16x16x32_bf16 v[118:121], v[146:149], v[186:189], v[118:121]
	v_mfma_f32_16x16x32_bf16 v[118:121], v[142:145], v[182:185], v[118:121]
	v_mfma_f32_16x16x32_bf16 v[102:105], v[142:145], v[190:193], v[102:105]
	v_mfma_f32_16x16x32_bf16 v[102:105], v[146:149], v[194:197], v[102:105]
	v_mfma_f32_16x16x32_bf16 v[94:97], v[154:157], v[194:197], v[94:97]
	v_mfma_f32_16x16x32_bf16 v[94:97], v[150:153], v[190:193], v[94:97]
	v_mfma_f32_16x16x32_bf16 v[78:81], v[150:153], v[198:201], v[78:81]
	v_mfma_f32_16x16x32_bf16 v[78:81], v[154:157], v[212:215], v[78:81]
	v_mfma_f32_16x16x32_bf16 v[86:89], v[146:149], v[212:215], v[86:89]
	v_mfma_f32_16x16x32_bf16 v[86:89], v[142:145], v[198:201], v[86:89]
	s_setprio 0
	s_setprio 1
	v_mfma_f32_16x16x32_bf16 v[70:73], v[158:161], v[198:201], v[70:73]
	v_mfma_f32_16x16x32_bf16 v[70:73], v[162:165], v[212:215], v[70:73]
	v_mfma_f32_16x16x32_bf16 v[66:69], v[170:173], v[212:215], v[66:69]
	v_mfma_f32_16x16x32_bf16 v[66:69], v[166:169], v[198:201], v[66:69]
	v_mfma_f32_16x16x32_bf16 v[74:77], v[166:169], v[190:193], v[74:77]
	v_mfma_f32_16x16x32_bf16 v[74:77], v[170:173], v[194:197], v[74:77]
	v_mfma_f32_16x16x32_bf16 v[82:85], v[162:165], v[194:197], v[82:85]
	v_mfma_f32_16x16x32_bf16 v[82:85], v[158:161], v[190:193], v[82:85]
	v_mfma_f32_16x16x32_bf16 v[98:101], v[158:161], v[182:185], v[98:101]
	v_mfma_f32_16x16x32_bf16 v[98:101], v[162:165], v[186:189], v[98:101]
	v_mfma_f32_16x16x32_bf16 v[90:93], v[170:173], v[186:189], v[90:93]
	v_mfma_f32_16x16x32_bf16 v[90:93], v[166:169], v[182:185], v[90:93]
	v_mfma_f32_16x16x32_bf16 v[106:109], v[166:169], v[174:177], v[106:109]
	v_mfma_f32_16x16x32_bf16 v[106:109], v[170:173], v[178:181], v[106:109]
	v_mfma_f32_16x16x32_bf16 v[114:117], v[162:165], v[178:181], v[114:117]
	v_mfma_f32_16x16x32_bf16 v[114:117], v[158:161], v[174:177], v[114:117]
	s_setprio 0
	s_barrier
	s_mov_b32 m0, s18
	v_add_u32_e32 v130, s49, v133
	ds_read_b128 v[174:177], v141 offset:16384
	ds_read_b128 v[178:181], v141 offset:17408
	ds_read_b128 v[182:185], v141 offset:18432
	ds_read_b128 v[186:189], v141 offset:19456
	ds_read_b128 v[190:193], v141 offset:20480
	ds_read_b128 v[194:197], v141 offset:21504
	ds_read_b128 v[198:201], v141 offset:22528
	ds_read_b128 v[212:215], v141 offset:23552
	global_load_lds_dwordx4 v130, s[2:3]
	v_add_u32_e32 v130, s49, v135
	s_mov_b32 m0, s19
	s_add_i32 s51, s49, 0x160000
	global_load_lds_dwordx4 v130, s[2:3]
	v_add_u32_e32 v130, s51, v133
	s_mov_b32 m0, s21
	s_nop 0
	global_load_lds_dwordx4 v130, s[2:3]
	v_add_u32_e32 v130, s51, v135
	s_mov_b32 m0, s22
	s_nop 0
	global_load_lds_dwordx4 v130, s[2:3]
	v_add_u32_e32 v130, s50, v132
	s_mov_b32 m0, s23
	s_nop 0
	global_load_lds_dwordx4 v130, s[0:1]
	v_add_u32_e32 v130, s50, v134
	s_mov_b32 m0, s24
	s_nop 0
	global_load_lds_dwordx4 v130, s[0:1]
	s_waitcnt vmcnt(8)
	s_waitcnt lgkmcnt(0)
	s_setprio 1
	s_barrier
	v_mfma_f32_16x16x32_bf16 v[62:65], v[142:145], v[174:177], v[62:65]
	v_mfma_f32_16x16x32_bf16 v[62:65], v[146:149], v[178:181], v[62:65]
	v_mfma_f32_16x16x32_bf16 v[58:61], v[154:157], v[178:181], v[58:61]
	v_mfma_f32_16x16x32_bf16 v[58:61], v[150:153], v[174:177], v[58:61]
	v_mfma_f32_16x16x32_bf16 v[46:49], v[150:153], v[182:185], v[46:49]
	v_mfma_f32_16x16x32_bf16 v[46:49], v[154:157], v[186:189], v[46:49]
	v_mfma_f32_16x16x32_bf16 v[54:57], v[146:149], v[186:189], v[54:57]
	v_mfma_f32_16x16x32_bf16 v[54:57], v[142:145], v[182:185], v[54:57]
	v_mfma_f32_16x16x32_bf16 v[38:41], v[142:145], v[190:193], v[38:41]
	v_mfma_f32_16x16x32_bf16 v[38:41], v[146:149], v[194:197], v[38:41]
	v_mfma_f32_16x16x32_bf16 v[30:33], v[154:157], v[194:197], v[30:33]
	v_mfma_f32_16x16x32_bf16 v[30:33], v[150:153], v[190:193], v[30:33]
	v_mfma_f32_16x16x32_bf16 v[14:17], v[150:153], v[198:201], v[14:17]
	v_mfma_f32_16x16x32_bf16 v[14:17], v[154:157], v[212:215], v[14:17]
	v_mfma_f32_16x16x32_bf16 v[22:25], v[146:149], v[212:215], v[22:25]
	v_mfma_f32_16x16x32_bf16 v[22:25], v[142:145], v[198:201], v[22:25]
	s_setprio 0
	s_setprio 1
	v_mfma_f32_16x16x32_bf16 v[6:9], v[158:161], v[198:201], v[6:9]
	v_mfma_f32_16x16x32_bf16 v[6:9], v[162:165], v[212:215], v[6:9]
	v_mfma_f32_16x16x32_bf16 v[2:5], v[170:173], v[212:215], v[2:5]
	v_mfma_f32_16x16x32_bf16 v[2:5], v[166:169], v[198:201], v[2:5]
	v_mfma_f32_16x16x32_bf16 v[10:13], v[166:169], v[190:193], v[10:13]
	v_mfma_f32_16x16x32_bf16 v[10:13], v[170:173], v[194:197], v[10:13]
	v_mfma_f32_16x16x32_bf16 v[18:21], v[162:165], v[194:197], v[18:21]
	v_mfma_f32_16x16x32_bf16 v[18:21], v[158:161], v[190:193], v[18:21]
	v_mfma_f32_16x16x32_bf16 v[34:37], v[158:161], v[182:185], v[34:37]
	v_mfma_f32_16x16x32_bf16 v[34:37], v[162:165], v[186:189], v[34:37]
	v_mfma_f32_16x16x32_bf16 v[26:29], v[170:173], v[186:189], v[26:29]
	v_mfma_f32_16x16x32_bf16 v[26:29], v[166:169], v[182:185], v[26:29]
	v_mfma_f32_16x16x32_bf16 v[42:45], v[166:169], v[174:177], v[42:45]
	v_mfma_f32_16x16x32_bf16 v[42:45], v[170:173], v[178:181], v[42:45]
	v_mfma_f32_16x16x32_bf16 v[50:53], v[162:165], v[178:181], v[50:53]
	v_mfma_f32_16x16x32_bf16 v[50:53], v[158:161], v[174:177], v[50:53]
	s_setprio 0
	s_barrier
	v_add_u32_e32 v130, s27, v137
	ds_read_b128 v[142:145], v130
	ds_read_b128 v[146:149], v130 offset:1024
	ds_read_b128 v[150:153], v130 offset:2048
	ds_read_b128 v[154:157], v130 offset:3072
	v_add_u32_e32 v130, s34, v137
	ds_read_b128 v[158:161], v130
	ds_read_b128 v[162:165], v130 offset:1024
	ds_read_b128 v[166:169], v130 offset:2048
	ds_read_b128 v[170:173], v130 offset:3072
	s_add_i32 s50, s50, 0x160000
	s_mov_b32 m0, s25
	v_add_u32_e32 v130, s50, v132
	ds_read_b128 v[174:177], v141 offset:32768
	ds_read_b128 v[178:181], v141 offset:33792
	ds_read_b128 v[182:185], v141 offset:34816
	ds_read_b128 v[186:189], v141 offset:35840
	ds_read_b128 v[190:193], v141 offset:36864
	ds_read_b128 v[194:197], v141 offset:37888
	ds_read_b128 v[198:201], v141 offset:38912
	ds_read_b128 v[212:215], v141 offset:39936
	global_load_lds_dwordx4 v130, s[0:1]
	v_add_u32_e32 v130, s50, v134
	s_mov_b32 m0, s26
	s_nop 0
	global_load_lds_dwordx4 v130, s[0:1]
	s_waitcnt vmcnt(8)
	s_waitcnt lgkmcnt(0)
	s_setprio 1
	s_barrier
	v_mfma_f32_16x16x32_bf16 v[126:129], v[142:145], v[174:177], v[126:129]
	v_mfma_f32_16x16x32_bf16 v[126:129], v[146:149], v[178:181], v[126:129]
	v_mfma_f32_16x16x32_bf16 v[122:125], v[154:157], v[178:181], v[122:125]
	v_mfma_f32_16x16x32_bf16 v[122:125], v[150:153], v[174:177], v[122:125]
	v_mfma_f32_16x16x32_bf16 v[110:113], v[150:153], v[182:185], v[110:113]
	v_mfma_f32_16x16x32_bf16 v[110:113], v[154:157], v[186:189], v[110:113]
	v_mfma_f32_16x16x32_bf16 v[118:121], v[146:149], v[186:189], v[118:121]
	v_mfma_f32_16x16x32_bf16 v[118:121], v[142:145], v[182:185], v[118:121]
	v_mfma_f32_16x16x32_bf16 v[102:105], v[142:145], v[190:193], v[102:105]
	v_mfma_f32_16x16x32_bf16 v[102:105], v[146:149], v[194:197], v[102:105]
	v_mfma_f32_16x16x32_bf16 v[94:97], v[154:157], v[194:197], v[94:97]
	v_mfma_f32_16x16x32_bf16 v[94:97], v[150:153], v[190:193], v[94:97]
	v_mfma_f32_16x16x32_bf16 v[78:81], v[150:153], v[198:201], v[78:81]
	v_mfma_f32_16x16x32_bf16 v[78:81], v[154:157], v[212:215], v[78:81]
	v_mfma_f32_16x16x32_bf16 v[86:89], v[146:149], v[212:215], v[86:89]
	v_mfma_f32_16x16x32_bf16 v[86:89], v[142:145], v[198:201], v[86:89]
	s_setprio 0
	s_setprio 1
	v_mfma_f32_16x16x32_bf16 v[70:73], v[158:161], v[198:201], v[70:73]
	v_mfma_f32_16x16x32_bf16 v[70:73], v[162:165], v[212:215], v[70:73]
	v_mfma_f32_16x16x32_bf16 v[66:69], v[170:173], v[212:215], v[66:69]
	v_mfma_f32_16x16x32_bf16 v[66:69], v[166:169], v[198:201], v[66:69]
	v_mfma_f32_16x16x32_bf16 v[74:77], v[166:169], v[190:193], v[74:77]
	v_mfma_f32_16x16x32_bf16 v[74:77], v[170:173], v[194:197], v[74:77]
	v_mfma_f32_16x16x32_bf16 v[82:85], v[162:165], v[194:197], v[82:85]
	v_mfma_f32_16x16x32_bf16 v[82:85], v[158:161], v[190:193], v[82:85]
	v_mfma_f32_16x16x32_bf16 v[98:101], v[158:161], v[182:185], v[98:101]
	v_mfma_f32_16x16x32_bf16 v[98:101], v[162:165], v[186:189], v[98:101]
	v_mfma_f32_16x16x32_bf16 v[90:93], v[170:173], v[186:189], v[90:93]
	v_mfma_f32_16x16x32_bf16 v[90:93], v[166:169], v[182:185], v[90:93]
	v_mfma_f32_16x16x32_bf16 v[106:109], v[166:169], v[174:177], v[106:109]
	v_mfma_f32_16x16x32_bf16 v[106:109], v[170:173], v[178:181], v[106:109]
	v_mfma_f32_16x16x32_bf16 v[114:117], v[162:165], v[178:181], v[114:117]
	v_mfma_f32_16x16x32_bf16 v[114:117], v[158:161], v[174:177], v[114:117]
	s_setprio 0
	s_barrier
	s_or_b32 s50, s49, 0x80
	s_mov_b32 m0, s28
	v_add_u32_e32 v130, s50, v133
	ds_read_b128 v[174:177], v141 offset:49152
	ds_read_b128 v[178:181], v141 offset:50176
	ds_read_b128 v[182:185], v141 offset:51200
	ds_read_b128 v[186:189], v141 offset:52224
	ds_read_b128 v[190:193], v141 offset:53248
	ds_read_b128 v[194:197], v141 offset:54272
	ds_read_b128 v[198:201], v141 offset:55296
	ds_read_b128 v[212:215], v141 offset:56320
	global_load_lds_dwordx4 v130, s[2:3]
	v_add_u32_e32 v130, s50, v135
	s_mov_b32 m0, s29
	s_add_i32 s49, s49, 0x160080
	global_load_lds_dwordx4 v130, s[2:3]
	v_add_u32_e32 v130, s49, v133
	s_mov_b32 m0, s35
	s_nop 0
	global_load_lds_dwordx4 v130, s[2:3]
	v_add_u32_e32 v130, s49, v135
	s_mov_b32 m0, s36
	s_nop 0
	global_load_lds_dwordx4 v130, s[2:3]
	v_add_u32_e32 v130, s48, v132
	s_mov_b32 m0, s30
	s_nop 0
	global_load_lds_dwordx4 v130, s[0:1]
	v_add_u32_e32 v130, s48, v134
	s_mov_b32 m0, s31
	s_nop 0
	global_load_lds_dwordx4 v130, s[0:1]
	s_add_i32 s47, s47, 2
	s_addk_i32 s45, 0x100
	s_addk_i32 s46, 0x100
	s_cmpk_gt_u32 s47, 0x55
	s_waitcnt vmcnt(8)
	s_waitcnt lgkmcnt(0)
	s_setprio 1
	s_barrier
	v_mfma_f32_16x16x32_bf16 v[62:65], v[142:145], v[174:177], v[62:65]
	v_mfma_f32_16x16x32_bf16 v[62:65], v[146:149], v[178:181], v[62:65]
	v_mfma_f32_16x16x32_bf16 v[58:61], v[154:157], v[178:181], v[58:61]
	v_mfma_f32_16x16x32_bf16 v[58:61], v[150:153], v[174:177], v[58:61]
	v_mfma_f32_16x16x32_bf16 v[46:49], v[150:153], v[182:185], v[46:49]
	v_mfma_f32_16x16x32_bf16 v[46:49], v[154:157], v[186:189], v[46:49]
	v_mfma_f32_16x16x32_bf16 v[54:57], v[146:149], v[186:189], v[54:57]
	v_mfma_f32_16x16x32_bf16 v[54:57], v[142:145], v[182:185], v[54:57]
	v_mfma_f32_16x16x32_bf16 v[38:41], v[142:145], v[190:193], v[38:41]
	v_mfma_f32_16x16x32_bf16 v[38:41], v[146:149], v[194:197], v[38:41]
	v_mfma_f32_16x16x32_bf16 v[30:33], v[154:157], v[194:197], v[30:33]
	v_mfma_f32_16x16x32_bf16 v[30:33], v[150:153], v[190:193], v[30:33]
	v_mfma_f32_16x16x32_bf16 v[14:17], v[150:153], v[198:201], v[14:17]
	v_mfma_f32_16x16x32_bf16 v[14:17], v[154:157], v[212:215], v[14:17]
	v_mfma_f32_16x16x32_bf16 v[22:25], v[146:149], v[212:215], v[22:25]
	v_mfma_f32_16x16x32_bf16 v[22:25], v[142:145], v[198:201], v[22:25]
	s_setprio 0
	s_setprio 1
	v_mfma_f32_16x16x32_bf16 v[6:9], v[158:161], v[198:201], v[6:9]
	v_mfma_f32_16x16x32_bf16 v[6:9], v[162:165], v[212:215], v[6:9]
	v_mfma_f32_16x16x32_bf16 v[2:5], v[170:173], v[212:215], v[2:5]
	v_mfma_f32_16x16x32_bf16 v[2:5], v[166:169], v[198:201], v[2:5]
	v_mfma_f32_16x16x32_bf16 v[10:13], v[166:169], v[190:193], v[10:13]
	v_mfma_f32_16x16x32_bf16 v[10:13], v[170:173], v[194:197], v[10:13]
	v_mfma_f32_16x16x32_bf16 v[18:21], v[162:165], v[194:197], v[18:21]
	v_mfma_f32_16x16x32_bf16 v[18:21], v[158:161], v[190:193], v[18:21]
	v_mfma_f32_16x16x32_bf16 v[34:37], v[158:161], v[182:185], v[34:37]
	v_mfma_f32_16x16x32_bf16 v[34:37], v[162:165], v[186:189], v[34:37]
	v_mfma_f32_16x16x32_bf16 v[26:29], v[170:173], v[186:189], v[26:29]
	v_mfma_f32_16x16x32_bf16 v[26:29], v[166:169], v[182:185], v[26:29]
	v_mfma_f32_16x16x32_bf16 v[42:45], v[166:169], v[174:177], v[42:45]
	v_mfma_f32_16x16x32_bf16 v[42:45], v[170:173], v[178:181], v[42:45]
	v_mfma_f32_16x16x32_bf16 v[50:53], v[162:165], v[178:181], v[50:53]
	v_mfma_f32_16x16x32_bf16 v[50:53], v[158:161], v[174:177], v[50:53]
	s_setprio 0
	s_barrier
	s_cbranch_scc0 .LBB0_195
	s_and_b64 vcc, exec, s[10:11]
	s_cbranch_vccz .LBB0_198
	s_barrier

.LBB0_282:
	s_lshl_b32 s65, s28, 20
	s_and_b64 s[36:37], s[30:31], exec
	s_cselect_b32 s36, s65, s68
	s_lshl_b32 s66, s64, 20
	s_and_b64 s[70:71], s[30:31], exec
	s_cselect_b32 s37, s66, s67
	v_add_u32_e32 v135, s68, v150
	v_add_u32_e32 v136, s68, v151
	s_addk_i32 s67, 0x100
	s_addk_i32 s68, 0x100
	s_mov_b32 s69, -2
	s_waitcnt vmcnt(0)
	v_add_u32_e32 v137, s42, v148
	ds_read_b128 v[138:141], v137
	ds_read_b128 v[154:157], v137 offset:1024
	ds_read_b128 v[158:161], v137 offset:2048
	ds_read_b128 v[162:165], v137 offset:3072
	v_add_u32_e32 v137, s45, v148
	ds_read_b128 v[166:169], v137
	ds_read_b128 v[170:173], v137 offset:1024
	ds_read_b128 v[174:177], v137 offset:2048
	ds_read_b128 v[178:181], v137 offset:3072
	s_cmp_eq_u32 s69, 28
	s_cselect_b32 s72, s36, s68
	s_cselect_b32 s71, s37, s67
	s_or_b32 s70, s72, 0x80
	s_add_i32 m0, s48, 0xc000
	ds_read_b128 v[182:185], v152
	ds_read_b128 v[186:189], v152 offset:1024
	ds_read_b128 v[190:193], v152 offset:2048
	ds_read_b128 v[194:197], v152 offset:3072
	ds_read_b128 v[198:201], v152 offset:4096
	ds_read_b128 v[212:215], v152 offset:5120
	ds_read_b128 v[218:221], v152 offset:6144
	ds_read_b128 v[222:225], v152 offset:7168
	global_load_lds_dwordx4 v136, s[8:9]
	s_add_i32 m0, s48, 0xe000
	s_nop 0
	global_load_lds_dwordx4 v135, s[8:9]
	s_waitcnt vmcnt(8)
	s_waitcnt lgkmcnt(0)
	s_setprio 1
	s_barrier
	v_mfma_f32_16x16x32_bf16 v[126:129], v[138:141], v[182:185], 0
	v_mfma_f32_16x16x32_bf16 v[126:129], v[154:157], v[186:189], v[126:129]
	v_mfma_f32_16x16x32_bf16 v[122:125], v[162:165], v[186:189], 0
	v_mfma_f32_16x16x32_bf16 v[122:125], v[158:161], v[182:185], v[122:125]
	v_mfma_f32_16x16x32_bf16 v[106:109], v[158:161], v[190:193], 0
	v_mfma_f32_16x16x32_bf16 v[106:109], v[162:165], v[194:197], v[106:109]
	v_mfma_f32_16x16x32_bf16 v[110:113], v[154:157], v[194:197], 0
	v_mfma_f32_16x16x32_bf16 v[110:113], v[138:141], v[190:193], v[110:113]
	v_mfma_f32_16x16x32_bf16 v[94:97], v[138:141], v[198:201], 0
	v_mfma_f32_16x16x32_bf16 v[94:97], v[154:157], v[212:215], v[94:97]
	v_mfma_f32_16x16x32_bf16 v[90:93], v[162:165], v[212:215], 0
	v_mfma_f32_16x16x32_bf16 v[90:93], v[158:161], v[198:201], v[90:93]
	v_mfma_f32_16x16x32_bf16 v[74:77], v[158:161], v[218:221], 0
	v_mfma_f32_16x16x32_bf16 v[74:77], v[162:165], v[222:225], v[74:77]
	v_mfma_f32_16x16x32_bf16 v[78:81], v[154:157], v[222:225], 0
	v_mfma_f32_16x16x32_bf16 v[78:81], v[138:141], v[218:221], v[78:81]
	s_setprio 0
	s_setprio 1
	v_mfma_f32_16x16x32_bf16 v[70:73], v[166:169], v[218:221], 0
	v_mfma_f32_16x16x32_bf16 v[70:73], v[170:173], v[222:225], v[70:73]
	v_mfma_f32_16x16x32_bf16 v[66:69], v[178:181], v[222:225], 0
	v_mfma_f32_16x16x32_bf16 v[66:69], v[174:177], v[218:221], v[66:69]
	v_mfma_f32_16x16x32_bf16 v[82:85], v[174:177], v[198:201], 0
	v_mfma_f32_16x16x32_bf16 v[82:85], v[178:181], v[212:215], v[82:85]
	v_mfma_f32_16x16x32_bf16 v[86:89], v[170:173], v[212:215], 0
	v_mfma_f32_16x16x32_bf16 v[86:89], v[166:169], v[198:201], v[86:89]
	v_mfma_f32_16x16x32_bf16 v[102:105], v[166:169], v[190:193], 0
	v_mfma_f32_16x16x32_bf16 v[102:105], v[170:173], v[194:197], v[102:105]
	v_mfma_f32_16x16x32_bf16 v[98:101], v[178:181], v[194:197], 0
	v_mfma_f32_16x16x32_bf16 v[98:101], v[174:177], v[190:193], v[98:101]
	v_mfma_f32_16x16x32_bf16 v[114:117], v[174:177], v[182:185], 0
	v_mfma_f32_16x16x32_bf16 v[114:117], v[178:181], v[186:189], v[114:117]
	v_mfma_f32_16x16x32_bf16 v[118:121], v[170:173], v[186:189], 0
	v_mfma_f32_16x16x32_bf16 v[118:121], v[166:169], v[182:185], v[118:121]
	s_setprio 0
	s_barrier
	s_mov_b32 m0, s43
	v_add_u32_e32 v137, s71, v143
	ds_read_b128 v[182:185], v152 offset:16384
	ds_read_b128 v[186:189], v152 offset:17408
	ds_read_b128 v[190:193], v152 offset:18432
	ds_read_b128 v[194:197], v152 offset:19456
	ds_read_b128 v[198:201], v152 offset:20480
	ds_read_b128 v[212:215], v152 offset:21504
	ds_read_b128 v[218:221], v152 offset:22528
	ds_read_b128 v[222:225], v152 offset:23552
	global_load_lds_dwordx4 v137, s[10:11]
	v_add_u32_e32 v137, s71, v145
	s_mov_b32 m0, s44
	s_add_i32 s73, s71, 0x80000
	global_load_lds_dwordx4 v137, s[10:11]
	v_add_u32_e32 v137, s73, v143
	s_mov_b32 m0, s46
	s_nop 0
	global_load_lds_dwordx4 v137, s[10:11]
	v_add_u32_e32 v137, s73, v145
	s_mov_b32 m0, s47
	s_nop 0
	global_load_lds_dwordx4 v137, s[10:11]
	v_add_u32_e32 v137, s72, v142
	s_mov_b32 m0, s48
	s_nop 0
	global_load_lds_dwordx4 v137, s[8:9]
	v_add_u32_e32 v137, s72, v144
	s_mov_b32 m0, s49
	s_nop 0
	global_load_lds_dwordx4 v137, s[8:9]
	s_waitcnt vmcnt(8)
	s_waitcnt lgkmcnt(0)
	s_setprio 1
	s_barrier
	v_mfma_f32_16x16x32_bf16 v[62:65], v[138:141], v[182:185], 0
	v_mfma_f32_16x16x32_bf16 v[62:65], v[154:157], v[186:189], v[62:65]
	v_mfma_f32_16x16x32_bf16 v[58:61], v[162:165], v[186:189], 0
	v_mfma_f32_16x16x32_bf16 v[58:61], v[158:161], v[182:185], v[58:61]
	v_mfma_f32_16x16x32_bf16 v[42:45], v[158:161], v[190:193], 0
	v_mfma_f32_16x16x32_bf16 v[42:45], v[162:165], v[194:197], v[42:45]
	v_mfma_f32_16x16x32_bf16 v[46:49], v[154:157], v[194:197], 0
	v_mfma_f32_16x16x32_bf16 v[46:49], v[138:141], v[190:193], v[46:49]
	v_mfma_f32_16x16x32_bf16 v[30:33], v[138:141], v[198:201], 0
	v_mfma_f32_16x16x32_bf16 v[30:33], v[154:157], v[212:215], v[30:33]
	v_mfma_f32_16x16x32_bf16 v[26:29], v[162:165], v[212:215], 0
	v_mfma_f32_16x16x32_bf16 v[26:29], v[158:161], v[198:201], v[26:29]
	v_mfma_f32_16x16x32_bf16 v[10:13], v[158:161], v[218:221], 0
	v_mfma_f32_16x16x32_bf16 v[10:13], v[162:165], v[222:225], v[10:13]
	v_mfma_f32_16x16x32_bf16 v[14:17], v[154:157], v[222:225], 0
	v_mfma_f32_16x16x32_bf16 v[14:17], v[138:141], v[218:221], v[14:17]
	s_setprio 0
	s_setprio 1
	v_mfma_f32_16x16x32_bf16 v[6:9], v[166:169], v[218:221], 0
	v_mfma_f32_16x16x32_bf16 v[6:9], v[170:173], v[222:225], v[6:9]
	v_mfma_f32_16x16x32_bf16 v[2:5], v[178:181], v[222:225], 0
	v_mfma_f32_16x16x32_bf16 v[2:5], v[174:177], v[218:221], v[2:5]
	v_mfma_f32_16x16x32_bf16 v[18:21], v[174:177], v[198:201], 0
	v_mfma_f32_16x16x32_bf16 v[18:21], v[178:181], v[212:215], v[18:21]
	v_mfma_f32_16x16x32_bf16 v[22:25], v[170:173], v[212:215], 0
	v_mfma_f32_16x16x32_bf16 v[22:25], v[166:169], v[198:201], v[22:25]
	v_mfma_f32_16x16x32_bf16 v[38:41], v[166:169], v[190:193], 0
	v_mfma_f32_16x16x32_bf16 v[38:41], v[170:173], v[194:197], v[38:41]
	v_mfma_f32_16x16x32_bf16 v[34:37], v[178:181], v[194:197], 0
	v_mfma_f32_16x16x32_bf16 v[34:37], v[174:177], v[190:193], v[34:37]
	v_mfma_f32_16x16x32_bf16 v[50:53], v[174:177], v[182:185], 0
	v_mfma_f32_16x16x32_bf16 v[50:53], v[178:181], v[186:189], v[50:53]
	v_mfma_f32_16x16x32_bf16 v[54:57], v[170:173], v[186:189], 0
	v_mfma_f32_16x16x32_bf16 v[54:57], v[166:169], v[182:185], v[54:57]
	s_setprio 0
	s_barrier
	v_add_u32_e32 v137, s52, v148
	ds_read_b128 v[138:141], v137
	ds_read_b128 v[154:157], v137 offset:1024
	ds_read_b128 v[158:161], v137 offset:2048
	ds_read_b128 v[162:165], v137 offset:3072
	v_add_u32_e32 v137, s57, v148
	ds_read_b128 v[166:169], v137
	ds_read_b128 v[170:173], v137 offset:1024
	ds_read_b128 v[174:177], v137 offset:2048
	ds_read_b128 v[178:181], v137 offset:3072
	s_add_i32 s72, s72, 0x80000
	s_mov_b32 m0, s50
	v_add_u32_e32 v137, s72, v142
	ds_read_b128 v[182:185], v152 offset:32768
	ds_read_b128 v[186:189], v152 offset:33792
	ds_read_b128 v[190:193], v152 offset:34816
	ds_read_b128 v[194:197], v152 offset:35840
	ds_read_b128 v[198:201], v152 offset:36864
	ds_read_b128 v[212:215], v152 offset:37888
	ds_read_b128 v[218:221], v152 offset:38912
	ds_read_b128 v[222:225], v152 offset:39936
	global_load_lds_dwordx4 v137, s[8:9]
	v_add_u32_e32 v137, s72, v144
	s_mov_b32 m0, s51
	s_nop 0
	global_load_lds_dwordx4 v137, s[8:9]
	s_waitcnt vmcnt(8)
	s_waitcnt lgkmcnt(0)
	s_setprio 1
	s_barrier
	v_mfma_f32_16x16x32_bf16 v[126:129], v[138:141], v[182:185], v[126:129]
	v_mfma_f32_16x16x32_bf16 v[126:129], v[154:157], v[186:189], v[126:129]
	v_mfma_f32_16x16x32_bf16 v[122:125], v[162:165], v[186:189], v[122:125]
	v_mfma_f32_16x16x32_bf16 v[122:125], v[158:161], v[182:185], v[122:125]
	v_mfma_f32_16x16x32_bf16 v[106:109], v[158:161], v[190:193], v[106:109]
	v_mfma_f32_16x16x32_bf16 v[106:109], v[162:165], v[194:197], v[106:109]
	v_mfma_f32_16x16x32_bf16 v[110:113], v[154:157], v[194:197], v[110:113]
	v_mfma_f32_16x16x32_bf16 v[110:113], v[138:141], v[190:193], v[110:113]
	v_mfma_f32_16x16x32_bf16 v[94:97], v[138:141], v[198:201], v[94:97]
	v_mfma_f32_16x16x32_bf16 v[94:97], v[154:157], v[212:215], v[94:97]
	v_mfma_f32_16x16x32_bf16 v[90:93], v[162:165], v[212:215], v[90:93]
	v_mfma_f32_16x16x32_bf16 v[90:93], v[158:161], v[198:201], v[90:93]
	v_mfma_f32_16x16x32_bf16 v[74:77], v[158:161], v[218:221], v[74:77]
	v_mfma_f32_16x16x32_bf16 v[74:77], v[162:165], v[222:225], v[74:77]
	v_mfma_f32_16x16x32_bf16 v[78:81], v[154:157], v[222:225], v[78:81]
	v_mfma_f32_16x16x32_bf16 v[78:81], v[138:141], v[218:221], v[78:81]
	s_setprio 0
	s_setprio 1
	v_mfma_f32_16x16x32_bf16 v[70:73], v[166:169], v[218:221], v[70:73]
	v_mfma_f32_16x16x32_bf16 v[70:73], v[170:173], v[222:225], v[70:73]
	v_mfma_f32_16x16x32_bf16 v[66:69], v[178:181], v[222:225], v[66:69]
	v_mfma_f32_16x16x32_bf16 v[66:69], v[174:177], v[218:221], v[66:69]
	v_mfma_f32_16x16x32_bf16 v[82:85], v[174:177], v[198:201], v[82:85]
	v_mfma_f32_16x16x32_bf16 v[82:85], v[178:181], v[212:215], v[82:85]
	v_mfma_f32_16x16x32_bf16 v[86:89], v[170:173], v[212:215], v[86:89]
	v_mfma_f32_16x16x32_bf16 v[86:89], v[166:169], v[198:201], v[86:89]
	v_mfma_f32_16x16x32_bf16 v[102:105], v[166:169], v[190:193], v[102:105]
	v_mfma_f32_16x16x32_bf16 v[102:105], v[170:173], v[194:197], v[102:105]
	v_mfma_f32_16x16x32_bf16 v[98:101], v[178:181], v[194:197], v[98:101]
	v_mfma_f32_16x16x32_bf16 v[98:101], v[174:177], v[190:193], v[98:101]
	v_mfma_f32_16x16x32_bf16 v[114:117], v[174:177], v[182:185], v[114:117]
	v_mfma_f32_16x16x32_bf16 v[114:117], v[178:181], v[186:189], v[114:117]
	v_mfma_f32_16x16x32_bf16 v[118:121], v[170:173], v[186:189], v[118:121]
	v_mfma_f32_16x16x32_bf16 v[118:121], v[166:169], v[182:185], v[118:121]
	s_setprio 0
	s_barrier
	s_or_b32 s72, s71, 0x80
	s_mov_b32 m0, s53
	v_add_u32_e32 v137, s72, v143
	ds_read_b128 v[182:185], v152 offset:49152
	ds_read_b128 v[186:189], v152 offset:50176
	ds_read_b128 v[190:193], v152 offset:51200
	ds_read_b128 v[194:197], v152 offset:52224
	ds_read_b128 v[198:201], v152 offset:53248
	ds_read_b128 v[212:215], v152 offset:54272
	ds_read_b128 v[218:221], v152 offset:55296
	ds_read_b128 v[222:225], v152 offset:56320
	global_load_lds_dwordx4 v137, s[10:11]
	v_add_u32_e32 v137, s72, v145
	s_mov_b32 m0, s54
	s_add_i32 s71, s71, 0x80080
	global_load_lds_dwordx4 v137, s[10:11]
	v_add_u32_e32 v137, s71, v143
	s_mov_b32 m0, s58
	s_nop 0
	global_load_lds_dwordx4 v137, s[10:11]
	v_add_u32_e32 v137, s71, v145
	s_mov_b32 m0, s59
	s_nop 0
	global_load_lds_dwordx4 v137, s[10:11]
	v_add_u32_e32 v137, s70, v142
	s_mov_b32 m0, s55
	s_nop 0
	global_load_lds_dwordx4 v137, s[8:9]
	v_add_u32_e32 v137, s70, v144
	s_mov_b32 m0, s56
	s_nop 0
	global_load_lds_dwordx4 v137, s[8:9]
	s_waitcnt vmcnt(8)
	s_waitcnt lgkmcnt(0)
	s_setprio 1
	s_barrier
	v_mfma_f32_16x16x32_bf16 v[62:65], v[138:141], v[182:185], v[62:65]
	v_mfma_f32_16x16x32_bf16 v[62:65], v[154:157], v[186:189], v[62:65]
	v_mfma_f32_16x16x32_bf16 v[58:61], v[162:165], v[186:189], v[58:61]
	v_mfma_f32_16x16x32_bf16 v[58:61], v[158:161], v[182:185], v[58:61]
	v_mfma_f32_16x16x32_bf16 v[42:45], v[158:161], v[190:193], v[42:45]
	v_mfma_f32_16x16x32_bf16 v[42:45], v[162:165], v[194:197], v[42:45]
	v_mfma_f32_16x16x32_bf16 v[46:49], v[154:157], v[194:197], v[46:49]
	v_mfma_f32_16x16x32_bf16 v[46:49], v[138:141], v[190:193], v[46:49]
	v_mfma_f32_16x16x32_bf16 v[30:33], v[138:141], v[198:201], v[30:33]
	v_mfma_f32_16x16x32_bf16 v[30:33], v[154:157], v[212:215], v[30:33]
	v_mfma_f32_16x16x32_bf16 v[26:29], v[162:165], v[212:215], v[26:29]
	v_mfma_f32_16x16x32_bf16 v[26:29], v[158:161], v[198:201], v[26:29]
	v_mfma_f32_16x16x32_bf16 v[10:13], v[158:161], v[218:221], v[10:13]
	v_mfma_f32_16x16x32_bf16 v[10:13], v[162:165], v[222:225], v[10:13]
	v_mfma_f32_16x16x32_bf16 v[14:17], v[154:157], v[222:225], v[14:17]
	v_mfma_f32_16x16x32_bf16 v[14:17], v[138:141], v[218:221], v[14:17]
	s_setprio 0
	s_setprio 1
	v_mfma_f32_16x16x32_bf16 v[6:9], v[166:169], v[218:221], v[6:9]
	v_mfma_f32_16x16x32_bf16 v[6:9], v[170:173], v[222:225], v[6:9]
	v_mfma_f32_16x16x32_bf16 v[2:5], v[178:181], v[222:225], v[2:5]
	v_mfma_f32_16x16x32_bf16 v[2:5], v[174:177], v[218:221], v[2:5]
	v_mfma_f32_16x16x32_bf16 v[18:21], v[174:177], v[198:201], v[18:21]
	v_mfma_f32_16x16x32_bf16 v[18:21], v[178:181], v[212:215], v[18:21]
	v_mfma_f32_16x16x32_bf16 v[22:25], v[170:173], v[212:215], v[22:25]
	v_mfma_f32_16x16x32_bf16 v[22:25], v[166:169], v[198:201], v[22:25]
	v_mfma_f32_16x16x32_bf16 v[38:41], v[166:169], v[190:193], v[38:41]
	v_mfma_f32_16x16x32_bf16 v[38:41], v[170:173], v[194:197], v[38:41]
	v_mfma_f32_16x16x32_bf16 v[34:37], v[178:181], v[194:197], v[34:37]
	v_mfma_f32_16x16x32_bf16 v[34:37], v[174:177], v[190:193], v[34:37]
	v_mfma_f32_16x16x32_bf16 v[50:53], v[174:177], v[182:185], v[50:53]
	v_mfma_f32_16x16x32_bf16 v[50:53], v[178:181], v[186:189], v[50:53]
	v_mfma_f32_16x16x32_bf16 v[54:57], v[170:173], v[186:189], v[54:57]
	v_mfma_f32_16x16x32_bf16 v[54:57], v[166:169], v[182:185], v[54:57]
	s_setprio 0
	s_barrier
	s_add_i32 s69, s69, 2
	s_addk_i32 s67, 0x100
	s_addk_i32 s68, 0x100
	v_add_u32_e32 v135, 0x100, v135
	s_cmp_gt_u32 s69, 29
	v_add_u32_e32 v136, 0x100, v136
.LBB0_283:
	v_add_u32_e32 v137, s42, v148
	ds_read_b128 v[138:141], v137
	ds_read_b128 v[154:157], v137 offset:1024
	ds_read_b128 v[158:161], v137 offset:2048
	ds_read_b128 v[162:165], v137 offset:3072
	v_add_u32_e32 v137, s45, v148
	ds_read_b128 v[166:169], v137
	ds_read_b128 v[170:173], v137 offset:1024
	ds_read_b128 v[174:177], v137 offset:2048
	ds_read_b128 v[178:181], v137 offset:3072
	s_cmp_eq_u32 s69, 28
	s_cselect_b32 s72, s36, s68
	s_cselect_b32 s71, s37, s67
	s_or_b32 s70, s72, 0x80
	s_add_i32 m0, s48, 0xc000
	ds_read_b128 v[182:185], v152
	ds_read_b128 v[186:189], v152 offset:1024
	ds_read_b128 v[190:193], v152 offset:2048
	ds_read_b128 v[194:197], v152 offset:3072
	ds_read_b128 v[198:201], v152 offset:4096
	ds_read_b128 v[212:215], v152 offset:5120
	ds_read_b128 v[218:221], v152 offset:6144
	ds_read_b128 v[222:225], v152 offset:7168
	global_load_lds_dwordx4 v136, s[8:9]
	s_add_i32 m0, s48, 0xe000
	s_nop 0
	global_load_lds_dwordx4 v135, s[8:9]
	s_waitcnt vmcnt(8)
	s_waitcnt lgkmcnt(0)
	s_setprio 1
	s_barrier
	v_mfma_f32_16x16x32_bf16 v[126:129], v[138:141], v[182:185], v[126:129]
	v_mfma_f32_16x16x32_bf16 v[126:129], v[154:157], v[186:189], v[126:129]
	v_mfma_f32_16x16x32_bf16 v[122:125], v[162:165], v[186:189], v[122:125]
	v_mfma_f32_16x16x32_bf16 v[122:125], v[158:161], v[182:185], v[122:125]
	v_mfma_f32_16x16x32_bf16 v[106:109], v[158:161], v[190:193], v[106:109]
	v_mfma_f32_16x16x32_bf16 v[106:109], v[162:165], v[194:197], v[106:109]
	v_mfma_f32_16x16x32_bf16 v[110:113], v[154:157], v[194:197], v[110:113]
	v_mfma_f32_16x16x32_bf16 v[110:113], v[138:141], v[190:193], v[110:113]
	v_mfma_f32_16x16x32_bf16 v[94:97], v[138:141], v[198:201], v[94:97]
	v_mfma_f32_16x16x32_bf16 v[94:97], v[154:157], v[212:215], v[94:97]
	v_mfma_f32_16x16x32_bf16 v[90:93], v[162:165], v[212:215], v[90:93]
	v_mfma_f32_16x16x32_bf16 v[90:93], v[158:161], v[198:201], v[90:93]
	v_mfma_f32_16x16x32_bf16 v[74:77], v[158:161], v[218:221], v[74:77]
	v_mfma_f32_16x16x32_bf16 v[74:77], v[162:165], v[222:225], v[74:77]
	v_mfma_f32_16x16x32_bf16 v[78:81], v[154:157], v[222:225], v[78:81]
	v_mfma_f32_16x16x32_bf16 v[78:81], v[138:141], v[218:221], v[78:81]
	s_setprio 0
	s_setprio 1
	v_mfma_f32_16x16x32_bf16 v[70:73], v[166:169], v[218:221], v[70:73]
	v_mfma_f32_16x16x32_bf16 v[70:73], v[170:173], v[222:225], v[70:73]
	v_mfma_f32_16x16x32_bf16 v[66:69], v[178:181], v[222:225], v[66:69]
	v_mfma_f32_16x16x32_bf16 v[66:69], v[174:177], v[218:221], v[66:69]
	v_mfma_f32_16x16x32_bf16 v[82:85], v[174:177], v[198:201], v[82:85]
	v_mfma_f32_16x16x32_bf16 v[82:85], v[178:181], v[212:215], v[82:85]
	v_mfma_f32_16x16x32_bf16 v[86:89], v[170:173], v[212:215], v[86:89]
	v_mfma_f32_16x16x32_bf16 v[86:89], v[166:169], v[198:201], v[86:89]
	v_mfma_f32_16x16x32_bf16 v[102:105], v[166:169], v[190:193], v[102:105]
	v_mfma_f32_16x16x32_bf16 v[102:105], v[170:173], v[194:197], v[102:105]
	v_mfma_f32_16x16x32_bf16 v[98:101], v[178:181], v[194:197], v[98:101]
	v_mfma_f32_16x16x32_bf16 v[98:101], v[174:177], v[190:193], v[98:101]
	v_mfma_f32_16x16x32_bf16 v[114:117], v[174:177], v[182:185], v[114:117]
	v_mfma_f32_16x16x32_bf16 v[114:117], v[178:181], v[186:189], v[114:117]
	v_mfma_f32_16x16x32_bf16 v[118:121], v[170:173], v[186:189], v[118:121]
	v_mfma_f32_16x16x32_bf16 v[118:121], v[166:169], v[182:185], v[118:121]
	s_setprio 0
	s_barrier
	s_mov_b32 m0, s43
	v_add_u32_e32 v137, s71, v143
	ds_read_b128 v[182:185], v152 offset:16384
	ds_read_b128 v[186:189], v152 offset:17408
	ds_read_b128 v[190:193], v152 offset:18432
	ds_read_b128 v[194:197], v152 offset:19456
	ds_read_b128 v[198:201], v152 offset:20480
	ds_read_b128 v[212:215], v152 offset:21504
	ds_read_b128 v[218:221], v152 offset:22528
	ds_read_b128 v[222:225], v152 offset:23552
	global_load_lds_dwordx4 v137, s[10:11]
	v_add_u32_e32 v137, s71, v145
	s_mov_b32 m0, s44
	s_add_i32 s73, s71, 0x80000
	global_load_lds_dwordx4 v137, s[10:11]
	v_add_u32_e32 v137, s73, v143
	s_mov_b32 m0, s46
	s_nop 0
	global_load_lds_dwordx4 v137, s[10:11]
	v_add_u32_e32 v137, s73, v145
	s_mov_b32 m0, s47
	s_nop 0
	global_load_lds_dwordx4 v137, s[10:11]
	v_add_u32_e32 v137, s72, v142
	s_mov_b32 m0, s48
	s_nop 0
	global_load_lds_dwordx4 v137, s[8:9]
	v_add_u32_e32 v137, s72, v144
	s_mov_b32 m0, s49
	s_nop 0
	global_load_lds_dwordx4 v137, s[8:9]
	s_waitcnt vmcnt(8)
	s_waitcnt lgkmcnt(0)
	s_setprio 1
	s_barrier
	v_mfma_f32_16x16x32_bf16 v[62:65], v[138:141], v[182:185], v[62:65]
	v_mfma_f32_16x16x32_bf16 v[62:65], v[154:157], v[186:189], v[62:65]
	v_mfma_f32_16x16x32_bf16 v[58:61], v[162:165], v[186:189], v[58:61]
	v_mfma_f32_16x16x32_bf16 v[58:61], v[158:161], v[182:185], v[58:61]
	v_mfma_f32_16x16x32_bf16 v[42:45], v[158:161], v[190:193], v[42:45]
	v_mfma_f32_16x16x32_bf16 v[42:45], v[162:165], v[194:197], v[42:45]
	v_mfma_f32_16x16x32_bf16 v[46:49], v[154:157], v[194:197], v[46:49]
	v_mfma_f32_16x16x32_bf16 v[46:49], v[138:141], v[190:193], v[46:49]
	v_mfma_f32_16x16x32_bf16 v[30:33], v[138:141], v[198:201], v[30:33]
	v_mfma_f32_16x16x32_bf16 v[30:33], v[154:157], v[212:215], v[30:33]
	v_mfma_f32_16x16x32_bf16 v[26:29], v[162:165], v[212:215], v[26:29]
	v_mfma_f32_16x16x32_bf16 v[26:29], v[158:161], v[198:201], v[26:29]
	v_mfma_f32_16x16x32_bf16 v[10:13], v[158:161], v[218:221], v[10:13]
	v_mfma_f32_16x16x32_bf16 v[10:13], v[162:165], v[222:225], v[10:13]
	v_mfma_f32_16x16x32_bf16 v[14:17], v[154:157], v[222:225], v[14:17]
	v_mfma_f32_16x16x32_bf16 v[14:17], v[138:141], v[218:221], v[14:17]
	s_setprio 0
	s_setprio 1
	v_mfma_f32_16x16x32_bf16 v[6:9], v[166:169], v[218:221], v[6:9]
	v_mfma_f32_16x16x32_bf16 v[6:9], v[170:173], v[222:225], v[6:9]
	v_mfma_f32_16x16x32_bf16 v[2:5], v[178:181], v[222:225], v[2:5]
	v_mfma_f32_16x16x32_bf16 v[2:5], v[174:177], v[218:221], v[2:5]
	v_mfma_f32_16x16x32_bf16 v[18:21], v[174:177], v[198:201], v[18:21]
	v_mfma_f32_16x16x32_bf16 v[18:21], v[178:181], v[212:215], v[18:21]
	v_mfma_f32_16x16x32_bf16 v[22:25], v[170:173], v[212:215], v[22:25]
	v_mfma_f32_16x16x32_bf16 v[22:25], v[166:169], v[198:201], v[22:25]
	v_mfma_f32_16x16x32_bf16 v[38:41], v[166:169], v[190:193], v[38:41]
	v_mfma_f32_16x16x32_bf16 v[38:41], v[170:173], v[194:197], v[38:41]
	v_mfma_f32_16x16x32_bf16 v[34:37], v[178:181], v[194:197], v[34:37]
	v_mfma_f32_16x16x32_bf16 v[34:37], v[174:177], v[190:193], v[34:37]
	v_mfma_f32_16x16x32_bf16 v[50:53], v[174:177], v[182:185], v[50:53]
	v_mfma_f32_16x16x32_bf16 v[50:53], v[178:181], v[186:189], v[50:53]
	v_mfma_f32_16x16x32_bf16 v[54:57], v[170:173], v[186:189], v[54:57]
	v_mfma_f32_16x16x32_bf16 v[54:57], v[166:169], v[182:185], v[54:57]
	s_setprio 0
	s_barrier
	v_add_u32_e32 v137, s52, v148
	ds_read_b128 v[138:141], v137
	ds_read_b128 v[154:157], v137 offset:1024
	ds_read_b128 v[158:161], v137 offset:2048
	ds_read_b128 v[162:165], v137 offset:3072
	v_add_u32_e32 v137, s57, v148
	ds_read_b128 v[166:169], v137
	ds_read_b128 v[170:173], v137 offset:1024
	ds_read_b128 v[174:177], v137 offset:2048
	ds_read_b128 v[178:181], v137 offset:3072
	s_add_i32 s72, s72, 0x80000
	s_mov_b32 m0, s50
	v_add_u32_e32 v137, s72, v142
	ds_read_b128 v[182:185], v152 offset:32768
	ds_read_b128 v[186:189], v152 offset:33792
	ds_read_b128 v[190:193], v152 offset:34816
	ds_read_b128 v[194:197], v152 offset:35840
	ds_read_b128 v[198:201], v152 offset:36864
	ds_read_b128 v[212:215], v152 offset:37888
	ds_read_b128 v[218:221], v152 offset:38912
	ds_read_b128 v[222:225], v152 offset:39936
	global_load_lds_dwordx4 v137, s[8:9]
	v_add_u32_e32 v137, s72, v144
	s_mov_b32 m0, s51
	s_nop 0
	global_load_lds_dwordx4 v137, s[8:9]
	s_waitcnt vmcnt(8)
	s_waitcnt lgkmcnt(0)
	s_setprio 1
	s_barrier
	v_mfma_f32_16x16x32_bf16 v[126:129], v[138:141], v[182:185], v[126:129]
	v_mfma_f32_16x16x32_bf16 v[126:129], v[154:157], v[186:189], v[126:129]
	v_mfma_f32_16x16x32_bf16 v[122:125], v[162:165], v[186:189], v[122:125]
	v_mfma_f32_16x16x32_bf16 v[122:125], v[158:161], v[182:185], v[122:125]
	v_mfma_f32_16x16x32_bf16 v[106:109], v[158:161], v[190:193], v[106:109]
	v_mfma_f32_16x16x32_bf16 v[106:109], v[162:165], v[194:197], v[106:109]
	v_mfma_f32_16x16x32_bf16 v[110:113], v[154:157], v[194:197], v[110:113]
	v_mfma_f32_16x16x32_bf16 v[110:113], v[138:141], v[190:193], v[110:113]
	v_mfma_f32_16x16x32_bf16 v[94:97], v[138:141], v[198:201], v[94:97]
	v_mfma_f32_16x16x32_bf16 v[94:97], v[154:157], v[212:215], v[94:97]
	v_mfma_f32_16x16x32_bf16 v[90:93], v[162:165], v[212:215], v[90:93]
	v_mfma_f32_16x16x32_bf16 v[90:93], v[158:161], v[198:201], v[90:93]
	v_mfma_f32_16x16x32_bf16 v[74:77], v[158:161], v[218:221], v[74:77]
	v_mfma_f32_16x16x32_bf16 v[74:77], v[162:165], v[222:225], v[74:77]
	v_mfma_f32_16x16x32_bf16 v[78:81], v[154:157], v[222:225], v[78:81]
	v_mfma_f32_16x16x32_bf16 v[78:81], v[138:141], v[218:221], v[78:81]
	s_setprio 0
	s_setprio 1
	v_mfma_f32_16x16x32_bf16 v[70:73], v[166:169], v[218:221], v[70:73]
	v_mfma_f32_16x16x32_bf16 v[70:73], v[170:173], v[222:225], v[70:73]
	v_mfma_f32_16x16x32_bf16 v[66:69], v[178:181], v[222:225], v[66:69]
	v_mfma_f32_16x16x32_bf16 v[66:69], v[174:177], v[218:221], v[66:69]
	v_mfma_f32_16x16x32_bf16 v[82:85], v[174:177], v[198:201], v[82:85]
	v_mfma_f32_16x16x32_bf16 v[82:85], v[178:181], v[212:215], v[82:85]
	v_mfma_f32_16x16x32_bf16 v[86:89], v[170:173], v[212:215], v[86:89]
	v_mfma_f32_16x16x32_bf16 v[86:89], v[166:169], v[198:201], v[86:89]
	v_mfma_f32_16x16x32_bf16 v[102:105], v[166:169], v[190:193], v[102:105]
	v_mfma_f32_16x16x32_bf16 v[102:105], v[170:173], v[194:197], v[102:105]
	v_mfma_f32_16x16x32_bf16 v[98:101], v[178:181], v[194:197], v[98:101]
	v_mfma_f32_16x16x32_bf16 v[98:101], v[174:177], v[190:193], v[98:101]
	v_mfma_f32_16x16x32_bf16 v[114:117], v[174:177], v[182:185], v[114:117]
	v_mfma_f32_16x16x32_bf16 v[114:117], v[178:181], v[186:189], v[114:117]
	v_mfma_f32_16x16x32_bf16 v[118:121], v[170:173], v[186:189], v[118:121]
	v_mfma_f32_16x16x32_bf16 v[118:121], v[166:169], v[182:185], v[118:121]
	s_setprio 0
	s_barrier
	s_or_b32 s72, s71, 0x80
	s_mov_b32 m0, s53
	v_add_u32_e32 v137, s72, v143
	ds_read_b128 v[182:185], v152 offset:49152
	ds_read_b128 v[186:189], v152 offset:50176
	ds_read_b128 v[190:193], v152 offset:51200
	ds_read_b128 v[194:197], v152 offset:52224
	ds_read_b128 v[198:201], v152 offset:53248
	ds_read_b128 v[212:215], v152 offset:54272
	ds_read_b128 v[218:221], v152 offset:55296
	ds_read_b128 v[222:225], v152 offset:56320
	global_load_lds_dwordx4 v137, s[10:11]
	v_add_u32_e32 v137, s72, v145
	s_mov_b32 m0, s54
	s_add_i32 s71, s71, 0x80080
	global_load_lds_dwordx4 v137, s[10:11]
	v_add_u32_e32 v137, s71, v143
	s_mov_b32 m0, s58
	s_nop 0
	global_load_lds_dwordx4 v137, s[10:11]
	v_add_u32_e32 v137, s71, v145
	s_mov_b32 m0, s59
	s_nop 0
	global_load_lds_dwordx4 v137, s[10:11]
	v_add_u32_e32 v137, s70, v142
	s_mov_b32 m0, s55
	s_nop 0
	global_load_lds_dwordx4 v137, s[8:9]
	v_add_u32_e32 v137, s70, v144
	s_mov_b32 m0, s56
	s_nop 0
	global_load_lds_dwordx4 v137, s[8:9]
	s_add_i32 s69, s69, 2
	s_addk_i32 s67, 0x100
	s_addk_i32 s68, 0x100
	v_add_u32_e32 v135, 0x100, v135
	s_cmp_gt_u32 s69, 29
	v_add_u32_e32 v136, 0x100, v136
	s_waitcnt vmcnt(8)
	s_waitcnt lgkmcnt(0)
	s_setprio 1
	s_barrier
	v_mfma_f32_16x16x32_bf16 v[62:65], v[138:141], v[182:185], v[62:65]
	v_mfma_f32_16x16x32_bf16 v[62:65], v[154:157], v[186:189], v[62:65]
	v_mfma_f32_16x16x32_bf16 v[58:61], v[162:165], v[186:189], v[58:61]
	v_mfma_f32_16x16x32_bf16 v[58:61], v[158:161], v[182:185], v[58:61]
	v_mfma_f32_16x16x32_bf16 v[42:45], v[158:161], v[190:193], v[42:45]
	v_mfma_f32_16x16x32_bf16 v[42:45], v[162:165], v[194:197], v[42:45]
	v_mfma_f32_16x16x32_bf16 v[46:49], v[154:157], v[194:197], v[46:49]
	v_mfma_f32_16x16x32_bf16 v[46:49], v[138:141], v[190:193], v[46:49]
	v_mfma_f32_16x16x32_bf16 v[30:33], v[138:141], v[198:201], v[30:33]
	v_mfma_f32_16x16x32_bf16 v[30:33], v[154:157], v[212:215], v[30:33]
	v_mfma_f32_16x16x32_bf16 v[26:29], v[162:165], v[212:215], v[26:29]
	v_mfma_f32_16x16x32_bf16 v[26:29], v[158:161], v[198:201], v[26:29]
	v_mfma_f32_16x16x32_bf16 v[10:13], v[158:161], v[218:221], v[10:13]
	v_mfma_f32_16x16x32_bf16 v[10:13], v[162:165], v[222:225], v[10:13]
	v_mfma_f32_16x16x32_bf16 v[14:17], v[154:157], v[222:225], v[14:17]
	v_mfma_f32_16x16x32_bf16 v[14:17], v[138:141], v[218:221], v[14:17]
	s_setprio 0
	s_setprio 1
	v_mfma_f32_16x16x32_bf16 v[6:9], v[166:169], v[218:221], v[6:9]
	v_mfma_f32_16x16x32_bf16 v[6:9], v[170:173], v[222:225], v[6:9]
	v_mfma_f32_16x16x32_bf16 v[2:5], v[178:181], v[222:225], v[2:5]
	v_mfma_f32_16x16x32_bf16 v[2:5], v[174:177], v[218:221], v[2:5]
	v_mfma_f32_16x16x32_bf16 v[18:21], v[174:177], v[198:201], v[18:21]
	v_mfma_f32_16x16x32_bf16 v[18:21], v[178:181], v[212:215], v[18:21]
	v_mfma_f32_16x16x32_bf16 v[22:25], v[170:173], v[212:215], v[22:25]
	v_mfma_f32_16x16x32_bf16 v[22:25], v[166:169], v[198:201], v[22:25]
	v_mfma_f32_16x16x32_bf16 v[38:41], v[166:169], v[190:193], v[38:41]
	v_mfma_f32_16x16x32_bf16 v[38:41], v[170:173], v[194:197], v[38:41]
	v_mfma_f32_16x16x32_bf16 v[34:37], v[178:181], v[194:197], v[34:37]
	v_mfma_f32_16x16x32_bf16 v[34:37], v[174:177], v[190:193], v[34:37]
	v_mfma_f32_16x16x32_bf16 v[50:53], v[174:177], v[182:185], v[50:53]
	v_mfma_f32_16x16x32_bf16 v[50:53], v[178:181], v[186:189], v[50:53]
	v_mfma_f32_16x16x32_bf16 v[54:57], v[170:173], v[186:189], v[54:57]
	v_mfma_f32_16x16x32_bf16 v[54:57], v[166:169], v[182:185], v[54:57]
	s_setprio 0
	s_barrier
	s_cbranch_scc0 .LBB0_283
	s_and_b64 vcc, exec, s[20:21]
	s_cbranch_vccz .LBB0_286
	s_barrier

.LBB0_313:
	v_and_b32_e32 v134, 15, v130
	v_and_b32_e32 v8, 48, v130
	v_lshlrev_b32_e32 v9, 2, v130
	s_and_b32 s14, s12, 3
	s_lshl_b32 s26, s13, 13
	v_lshl_or_b32 v8, v134, 6, v8
	v_and_b32_e32 v9, 32, v9
	v_bitop3_b32 v10, v8, s26, v9 bitop3:0xde
	s_lshl_b32 s26, s14, 12
	v_bitop3_b32 v138, v8, s26, v9 bitop3:0xde
	s_add_i32 s26, s40, 0x18000
	s_or_b32 s28, s2, 0x80
	s_add_i32 s27, s26, s34
	v_add_u32_e32 v8, s28, v133
	s_mov_b32 m0, s27
	s_waitcnt vmcnt(2)
	s_barrier
	global_load_lds_dwordx4 v8, s[10:11]
	v_add_u32_e32 v8, s28, v136
	s_add_i32 s28, s27, 0x2000
	s_mov_b32 m0, s28
	s_or_b32 s30, s21, 0x80
	s_add_i32 s29, s22, 0x8000
	global_load_lds_dwordx4 v8, s[10:11]
	v_add_u32_e32 v8, s30, v131
	s_mov_b32 m0, s29
	s_add_i32 s31, s40, 0x1c000
	global_load_lds_dwordx4 v8, s[8:9]
	v_add_u32_e32 v8, s30, v135
	s_add_i32 s30, s22, 0xa000
	s_mov_b32 m0, s30
	s_or_b32 s35, s2, 0x80080
	s_add_i32 s34, s31, s34
	global_load_lds_dwordx4 v8, s[8:9]
	v_add_u32_e32 v8, s35, v133
	s_mov_b32 m0, s34
	s_add_i32 s36, s21, 0x80080
	global_load_lds_dwordx4 v8, s[10:11]
	v_add_u32_e32 v8, s35, v136
	s_add_i32 s35, s34, 0x2000
	s_mov_b32 m0, s35
	v_lshlrev_b32_e32 v6, 12, v6
	global_load_lds_dwordx4 v8, s[10:11]
	v_lshlrev_b32_e32 v8, 15, v5
	v_and_b32_e32 v8, 0xffff0000, v8
	v_and_b32_e32 v5, 1, v5
	v_add3_u32 v6, s36, v8, v6
	v_lshlrev_b32_e32 v5, 6, v5
	v_lshlrev_b32_e32 v7, 1, v7
	v_add3_u32 v139, v6, v5, v7
	v_lshlrev_b32_e32 v5, 15, v2
	v_and_b32_e32 v5, 0xffff0000, v5
	v_lshlrev_b32_e32 v3, 12, v3
	v_and_b32_e32 v2, 1, v2
	s_waitcnt vmcnt(6)
	v_add3_u32 v3, s36, v5, v3
	v_lshlrev_b32_e32 v2, 6, v2
	v_lshlrev_b32_e32 v4, 1, v4
	s_lshl_b32 s12, s13, 6
	v_add3_u32 v140, v3, v2, v4
	v_or_b32_e32 v137, s12, v134
	s_mov_b32 s36, -2
	s_mov_b32 s37, 0
	v_add_u32_e32 v141, s40, v10
	s_barrier
	v_add_u32_e32 v154, s3, v138
	v_add_u32_e32 v170, s18, v138
	ds_read_b128 v[142:145], v154
	ds_read_b128 v[146:149], v154 offset:1024
	ds_read_b128 v[150:153], v154 offset:2048
	ds_read_b128 v[154:157], v154 offset:3072
	ds_read_b128 v[158:161], v170
	ds_read_b128 v[162:165], v170 offset:1024
	ds_read_b128 v[166:169], v170 offset:2048
	ds_read_b128 v[170:173], v170 offset:3072
	s_add_i32 s41, s37, 0x100
	s_cmp_lg_u32 s36, 28
	s_cselect_b32 s43, s41, 0
	s_add_i32 s44, s43, s21
	s_or_b32 s42, s44, 0x80
	s_add_i32 s43, s43, s2
	v_add_u32_e32 v202, s37, v140
	s_add_i32 m0, s22, 0xc000
	ds_read_b128 v[174:177], v141
	ds_read_b128 v[178:181], v141 offset:1024
	ds_read_b128 v[182:185], v141 offset:2048
	ds_read_b128 v[186:189], v141 offset:3072
	ds_read_b128 v[190:193], v141 offset:4096
	ds_read_b128 v[194:197], v141 offset:5120
	ds_read_b128 v[198:201], v141 offset:6144
	ds_read_b128 v[212:215], v141 offset:7168
	global_load_lds_dwordx4 v202, s[8:9]
	v_add_u32_e32 v202, s37, v139
	s_add_i32 m0, s22, 0xe000
	s_nop 0
	global_load_lds_dwordx4 v202, s[8:9]
	s_waitcnt vmcnt(8)
	s_waitcnt lgkmcnt(0)
	s_setprio 1
	s_barrier
	v_mfma_f32_16x16x32_bf16 v[126:129], v[142:145], v[174:177], 0
	v_mfma_f32_16x16x32_bf16 v[126:129], v[146:149], v[178:181], v[126:129]
	v_mfma_f32_16x16x32_bf16 v[122:125], v[154:157], v[178:181], 0
	v_mfma_f32_16x16x32_bf16 v[122:125], v[150:153], v[174:177], v[122:125]
	v_mfma_f32_16x16x32_bf16 v[106:109], v[150:153], v[182:185], 0
	v_mfma_f32_16x16x32_bf16 v[106:109], v[154:157], v[186:189], v[106:109]
	v_mfma_f32_16x16x32_bf16 v[110:113], v[146:149], v[186:189], 0
	v_mfma_f32_16x16x32_bf16 v[110:113], v[142:145], v[182:185], v[110:113]
	v_mfma_f32_16x16x32_bf16 v[94:97], v[142:145], v[190:193], 0
	v_mfma_f32_16x16x32_bf16 v[94:97], v[146:149], v[194:197], v[94:97]
	v_mfma_f32_16x16x32_bf16 v[90:93], v[154:157], v[194:197], 0
	v_mfma_f32_16x16x32_bf16 v[90:93], v[150:153], v[190:193], v[90:93]
	v_mfma_f32_16x16x32_bf16 v[74:77], v[150:153], v[198:201], 0
	v_mfma_f32_16x16x32_bf16 v[74:77], v[154:157], v[212:215], v[74:77]
	v_mfma_f32_16x16x32_bf16 v[78:81], v[146:149], v[212:215], 0
	v_mfma_f32_16x16x32_bf16 v[78:81], v[142:145], v[198:201], v[78:81]
	s_setprio 0
	s_setprio 1
	v_mfma_f32_16x16x32_bf16 v[70:73], v[158:161], v[198:201], 0
	v_mfma_f32_16x16x32_bf16 v[70:73], v[162:165], v[212:215], v[70:73]
	v_mfma_f32_16x16x32_bf16 v[66:69], v[170:173], v[212:215], 0
	v_mfma_f32_16x16x32_bf16 v[66:69], v[166:169], v[198:201], v[66:69]
	v_mfma_f32_16x16x32_bf16 v[82:85], v[166:169], v[190:193], 0
	v_mfma_f32_16x16x32_bf16 v[82:85], v[170:173], v[194:197], v[82:85]
	v_mfma_f32_16x16x32_bf16 v[86:89], v[162:165], v[194:197], 0
	v_mfma_f32_16x16x32_bf16 v[86:89], v[158:161], v[190:193], v[86:89]
	v_mfma_f32_16x16x32_bf16 v[102:105], v[158:161], v[182:185], 0
	v_mfma_f32_16x16x32_bf16 v[102:105], v[162:165], v[186:189], v[102:105]
	v_mfma_f32_16x16x32_bf16 v[98:101], v[170:173], v[186:189], 0
	v_mfma_f32_16x16x32_bf16 v[98:101], v[166:169], v[182:185], v[98:101]
	v_mfma_f32_16x16x32_bf16 v[114:117], v[166:169], v[174:177], 0
	v_mfma_f32_16x16x32_bf16 v[114:117], v[170:173], v[178:181], v[114:117]
	v_mfma_f32_16x16x32_bf16 v[118:121], v[162:165], v[178:181], 0
	v_mfma_f32_16x16x32_bf16 v[118:121], v[158:161], v[174:177], v[118:121]
	s_setprio 0
	s_barrier
	s_mov_b32 m0, s16
	v_add_u32_e32 v202, s43, v133
	ds_read_b128 v[174:177], v141 offset:16384
	ds_read_b128 v[178:181], v141 offset:17408
	ds_read_b128 v[182:185], v141 offset:18432
	ds_read_b128 v[186:189], v141 offset:19456
	ds_read_b128 v[190:193], v141 offset:20480
	ds_read_b128 v[194:197], v141 offset:21504
	ds_read_b128 v[198:201], v141 offset:22528
	ds_read_b128 v[212:215], v141 offset:23552
	global_load_lds_dwordx4 v202, s[10:11]
	v_add_u32_e32 v202, s43, v136
	s_mov_b32 m0, s17
	s_add_i32 s37, s43, 0x80000
	global_load_lds_dwordx4 v202, s[10:11]
	v_add_u32_e32 v202, s37, v133
	s_mov_b32 m0, s19
	s_nop 0
	global_load_lds_dwordx4 v202, s[10:11]
	v_add_u32_e32 v202, s37, v136
	s_mov_b32 m0, s20
	s_nop 0
	global_load_lds_dwordx4 v202, s[10:11]
	v_add_u32_e32 v202, s44, v131
	s_mov_b32 m0, s22
	s_nop 0
	global_load_lds_dwordx4 v202, s[8:9]
	v_add_u32_e32 v202, s44, v135
	s_mov_b32 m0, s23
	s_nop 0
	global_load_lds_dwordx4 v202, s[8:9]
	s_waitcnt vmcnt(8)
	s_waitcnt lgkmcnt(0)
	s_setprio 1
	s_barrier
	v_mfma_f32_16x16x32_bf16 v[62:65], v[142:145], v[174:177], 0
	v_mfma_f32_16x16x32_bf16 v[62:65], v[146:149], v[178:181], v[62:65]
	v_mfma_f32_16x16x32_bf16 v[58:61], v[154:157], v[178:181], 0
	v_mfma_f32_16x16x32_bf16 v[58:61], v[150:153], v[174:177], v[58:61]
	v_mfma_f32_16x16x32_bf16 v[42:45], v[150:153], v[182:185], 0
	v_mfma_f32_16x16x32_bf16 v[42:45], v[154:157], v[186:189], v[42:45]
	v_mfma_f32_16x16x32_bf16 v[46:49], v[146:149], v[186:189], 0
	v_mfma_f32_16x16x32_bf16 v[46:49], v[142:145], v[182:185], v[46:49]
	v_mfma_f32_16x16x32_bf16 v[30:33], v[142:145], v[190:193], 0
	v_mfma_f32_16x16x32_bf16 v[30:33], v[146:149], v[194:197], v[30:33]
	v_mfma_f32_16x16x32_bf16 v[26:29], v[154:157], v[194:197], 0
	v_mfma_f32_16x16x32_bf16 v[26:29], v[150:153], v[190:193], v[26:29]
	v_mfma_f32_16x16x32_bf16 v[10:13], v[150:153], v[198:201], 0
	v_mfma_f32_16x16x32_bf16 v[10:13], v[154:157], v[212:215], v[10:13]
	v_mfma_f32_16x16x32_bf16 v[14:17], v[146:149], v[212:215], 0
	v_mfma_f32_16x16x32_bf16 v[14:17], v[142:145], v[198:201], v[14:17]
	s_setprio 0
	s_setprio 1
	v_mfma_f32_16x16x32_bf16 v[6:9], v[158:161], v[198:201], 0
	v_mfma_f32_16x16x32_bf16 v[6:9], v[162:165], v[212:215], v[6:9]
	v_mfma_f32_16x16x32_bf16 v[2:5], v[170:173], v[212:215], 0
	v_mfma_f32_16x16x32_bf16 v[2:5], v[166:169], v[198:201], v[2:5]
	v_mfma_f32_16x16x32_bf16 v[18:21], v[166:169], v[190:193], 0
	v_mfma_f32_16x16x32_bf16 v[18:21], v[170:173], v[194:197], v[18:21]
	v_mfma_f32_16x16x32_bf16 v[22:25], v[162:165], v[194:197], 0
	v_mfma_f32_16x16x32_bf16 v[22:25], v[158:161], v[190:193], v[22:25]
	v_mfma_f32_16x16x32_bf16 v[38:41], v[158:161], v[182:185], 0
	v_mfma_f32_16x16x32_bf16 v[38:41], v[162:165], v[186:189], v[38:41]
	v_mfma_f32_16x16x32_bf16 v[34:37], v[170:173], v[186:189], 0
	v_mfma_f32_16x16x32_bf16 v[34:37], v[166:169], v[182:185], v[34:37]
	v_mfma_f32_16x16x32_bf16 v[50:53], v[166:169], v[174:177], 0
	v_mfma_f32_16x16x32_bf16 v[50:53], v[170:173], v[178:181], v[50:53]
	v_mfma_f32_16x16x32_bf16 v[54:57], v[162:165], v[178:181], 0
	v_mfma_f32_16x16x32_bf16 v[54:57], v[158:161], v[174:177], v[54:57]
	s_setprio 0
	s_barrier
	v_add_u32_e32 v154, s26, v138
	v_add_u32_e32 v170, s31, v138
	ds_read_b128 v[142:145], v154
	ds_read_b128 v[146:149], v154 offset:1024
	ds_read_b128 v[150:153], v154 offset:2048
	ds_read_b128 v[154:157], v154 offset:3072
	ds_read_b128 v[158:161], v170
	ds_read_b128 v[162:165], v170 offset:1024
	ds_read_b128 v[166:169], v170 offset:2048
	ds_read_b128 v[170:173], v170 offset:3072
	s_add_i32 s44, s44, 0x80000
	s_mov_b32 m0, s24
	v_add_u32_e32 v202, s44, v131
	ds_read_b128 v[174:177], v141 offset:32768
	ds_read_b128 v[178:181], v141 offset:33792
	ds_read_b128 v[182:185], v141 offset:34816
	ds_read_b128 v[186:189], v141 offset:35840
	ds_read_b128 v[190:193], v141 offset:36864
	ds_read_b128 v[194:197], v141 offset:37888
	ds_read_b128 v[198:201], v141 offset:38912
	ds_read_b128 v[212:215], v141 offset:39936
	global_load_lds_dwordx4 v202, s[8:9]
	v_add_u32_e32 v202, s44, v135
	s_mov_b32 m0, s25
	s_nop 0
	global_load_lds_dwordx4 v202, s[8:9]
	s_waitcnt vmcnt(8)
	s_waitcnt lgkmcnt(0)
	s_setprio 1
	s_barrier
	v_mfma_f32_16x16x32_bf16 v[126:129], v[142:145], v[174:177], v[126:129]
	v_mfma_f32_16x16x32_bf16 v[126:129], v[146:149], v[178:181], v[126:129]
	v_mfma_f32_16x16x32_bf16 v[122:125], v[154:157], v[178:181], v[122:125]
	v_mfma_f32_16x16x32_bf16 v[122:125], v[150:153], v[174:177], v[122:125]
	v_mfma_f32_16x16x32_bf16 v[106:109], v[150:153], v[182:185], v[106:109]
	v_mfma_f32_16x16x32_bf16 v[106:109], v[154:157], v[186:189], v[106:109]
	v_mfma_f32_16x16x32_bf16 v[110:113], v[146:149], v[186:189], v[110:113]
	v_mfma_f32_16x16x32_bf16 v[110:113], v[142:145], v[182:185], v[110:113]
	v_mfma_f32_16x16x32_bf16 v[94:97], v[142:145], v[190:193], v[94:97]
	v_mfma_f32_16x16x32_bf16 v[94:97], v[146:149], v[194:197], v[94:97]
	v_mfma_f32_16x16x32_bf16 v[90:93], v[154:157], v[194:197], v[90:93]
	v_mfma_f32_16x16x32_bf16 v[90:93], v[150:153], v[190:193], v[90:93]
	v_mfma_f32_16x16x32_bf16 v[74:77], v[150:153], v[198:201], v[74:77]
	v_mfma_f32_16x16x32_bf16 v[74:77], v[154:157], v[212:215], v[74:77]
	v_mfma_f32_16x16x32_bf16 v[78:81], v[146:149], v[212:215], v[78:81]
	v_mfma_f32_16x16x32_bf16 v[78:81], v[142:145], v[198:201], v[78:81]
	s_setprio 0
	s_setprio 1
	v_mfma_f32_16x16x32_bf16 v[70:73], v[158:161], v[198:201], v[70:73]
	v_mfma_f32_16x16x32_bf16 v[70:73], v[162:165], v[212:215], v[70:73]
	v_mfma_f32_16x16x32_bf16 v[66:69], v[170:173], v[212:215], v[66:69]
	v_mfma_f32_16x16x32_bf16 v[66:69], v[166:169], v[198:201], v[66:69]
	v_mfma_f32_16x16x32_bf16 v[82:85], v[166:169], v[190:193], v[82:85]
	v_mfma_f32_16x16x32_bf16 v[82:85], v[170:173], v[194:197], v[82:85]
	v_mfma_f32_16x16x32_bf16 v[86:89], v[162:165], v[194:197], v[86:89]
	v_mfma_f32_16x16x32_bf16 v[86:89], v[158:161], v[190:193], v[86:89]
	v_mfma_f32_16x16x32_bf16 v[102:105], v[158:161], v[182:185], v[102:105]
	v_mfma_f32_16x16x32_bf16 v[102:105], v[162:165], v[186:189], v[102:105]
	v_mfma_f32_16x16x32_bf16 v[98:101], v[170:173], v[186:189], v[98:101]
	v_mfma_f32_16x16x32_bf16 v[98:101], v[166:169], v[182:185], v[98:101]
	v_mfma_f32_16x16x32_bf16 v[114:117], v[166:169], v[174:177], v[114:117]
	v_mfma_f32_16x16x32_bf16 v[114:117], v[170:173], v[178:181], v[114:117]
	v_mfma_f32_16x16x32_bf16 v[118:121], v[162:165], v[178:181], v[118:121]
	v_mfma_f32_16x16x32_bf16 v[118:121], v[158:161], v[174:177], v[118:121]
	s_setprio 0
	s_barrier
	s_or_b32 s37, s43, 0x80
	s_mov_b32 m0, s27
	v_add_u32_e32 v202, s37, v133
	ds_read_b128 v[174:177], v141 offset:49152
	ds_read_b128 v[178:181], v141 offset:50176
	ds_read_b128 v[182:185], v141 offset:51200
	ds_read_b128 v[186:189], v141 offset:52224
	ds_read_b128 v[190:193], v141 offset:53248
	ds_read_b128 v[194:197], v141 offset:54272
	ds_read_b128 v[198:201], v141 offset:55296
	ds_read_b128 v[212:215], v141 offset:56320
	global_load_lds_dwordx4 v202, s[10:11]
	v_add_u32_e32 v202, s37, v136
	s_mov_b32 m0, s28
	s_add_i32 s43, s43, 0x80080
	global_load_lds_dwordx4 v202, s[10:11]
	v_add_u32_e32 v202, s43, v133
	s_mov_b32 m0, s34
	s_nop 0
	global_load_lds_dwordx4 v202, s[10:11]
	v_add_u32_e32 v202, s43, v136
	s_mov_b32 m0, s35
	s_nop 0
	global_load_lds_dwordx4 v202, s[10:11]
	v_add_u32_e32 v202, s42, v131
	s_mov_b32 m0, s29
	s_nop 0
	global_load_lds_dwordx4 v202, s[8:9]
	v_add_u32_e32 v202, s42, v135
	s_mov_b32 m0, s30
	s_nop 0
	global_load_lds_dwordx4 v202, s[8:9]
	s_waitcnt vmcnt(8)
	s_waitcnt lgkmcnt(0)
	s_setprio 1
	s_barrier
	v_mfma_f32_16x16x32_bf16 v[62:65], v[142:145], v[174:177], v[62:65]
	v_mfma_f32_16x16x32_bf16 v[62:65], v[146:149], v[178:181], v[62:65]
	v_mfma_f32_16x16x32_bf16 v[58:61], v[154:157], v[178:181], v[58:61]
	v_mfma_f32_16x16x32_bf16 v[58:61], v[150:153], v[174:177], v[58:61]
	v_mfma_f32_16x16x32_bf16 v[42:45], v[150:153], v[182:185], v[42:45]
	v_mfma_f32_16x16x32_bf16 v[42:45], v[154:157], v[186:189], v[42:45]
	v_mfma_f32_16x16x32_bf16 v[46:49], v[146:149], v[186:189], v[46:49]
	v_mfma_f32_16x16x32_bf16 v[46:49], v[142:145], v[182:185], v[46:49]
	v_mfma_f32_16x16x32_bf16 v[30:33], v[142:145], v[190:193], v[30:33]
	v_mfma_f32_16x16x32_bf16 v[30:33], v[146:149], v[194:197], v[30:33]
	v_mfma_f32_16x16x32_bf16 v[26:29], v[154:157], v[194:197], v[26:29]
	v_mfma_f32_16x16x32_bf16 v[26:29], v[150:153], v[190:193], v[26:29]
	v_mfma_f32_16x16x32_bf16 v[10:13], v[150:153], v[198:201], v[10:13]
	v_mfma_f32_16x16x32_bf16 v[10:13], v[154:157], v[212:215], v[10:13]
	v_mfma_f32_16x16x32_bf16 v[14:17], v[146:149], v[212:215], v[14:17]
	v_mfma_f32_16x16x32_bf16 v[14:17], v[142:145], v[198:201], v[14:17]
	s_setprio 0
	s_setprio 1
	v_mfma_f32_16x16x32_bf16 v[6:9], v[158:161], v[198:201], v[6:9]
	v_mfma_f32_16x16x32_bf16 v[6:9], v[162:165], v[212:215], v[6:9]
	v_mfma_f32_16x16x32_bf16 v[2:5], v[170:173], v[212:215], v[2:5]
	v_mfma_f32_16x16x32_bf16 v[2:5], v[166:169], v[198:201], v[2:5]
	v_mfma_f32_16x16x32_bf16 v[18:21], v[166:169], v[190:193], v[18:21]
	v_mfma_f32_16x16x32_bf16 v[18:21], v[170:173], v[194:197], v[18:21]
	v_mfma_f32_16x16x32_bf16 v[22:25], v[162:165], v[194:197], v[22:25]
	v_mfma_f32_16x16x32_bf16 v[22:25], v[158:161], v[190:193], v[22:25]
	v_mfma_f32_16x16x32_bf16 v[38:41], v[158:161], v[182:185], v[38:41]
	v_mfma_f32_16x16x32_bf16 v[38:41], v[162:165], v[186:189], v[38:41]
	v_mfma_f32_16x16x32_bf16 v[34:37], v[170:173], v[186:189], v[34:37]
	v_mfma_f32_16x16x32_bf16 v[34:37], v[166:169], v[182:185], v[34:37]
	v_mfma_f32_16x16x32_bf16 v[50:53], v[166:169], v[174:177], v[50:53]
	v_mfma_f32_16x16x32_bf16 v[50:53], v[170:173], v[178:181], v[50:53]
	v_mfma_f32_16x16x32_bf16 v[54:57], v[162:165], v[178:181], v[54:57]
	v_mfma_f32_16x16x32_bf16 v[54:57], v[158:161], v[174:177], v[54:57]
	s_setprio 0
	s_barrier
	s_add_i32 s36, s36, 2
	s_cmp_gt_u32 s36, 29
	s_mov_b32 s37, s41
.LBB0_314:
	v_add_u32_e32 v154, s3, v138
	v_add_u32_e32 v170, s18, v138
	ds_read_b128 v[142:145], v154
	ds_read_b128 v[146:149], v154 offset:1024
	ds_read_b128 v[150:153], v154 offset:2048
	ds_read_b128 v[154:157], v154 offset:3072
	ds_read_b128 v[158:161], v170
	ds_read_b128 v[162:165], v170 offset:1024
	ds_read_b128 v[166:169], v170 offset:2048
	ds_read_b128 v[170:173], v170 offset:3072
	s_add_i32 s41, s37, 0x100
	s_cmp_lg_u32 s36, 28
	s_cselect_b32 s43, s41, 0
	s_add_i32 s44, s43, s21
	s_or_b32 s42, s44, 0x80
	s_add_i32 s43, s43, s2
	v_add_u32_e32 v202, s37, v140
	s_add_i32 m0, s22, 0xc000
	ds_read_b128 v[174:177], v141
	ds_read_b128 v[178:181], v141 offset:1024
	ds_read_b128 v[182:185], v141 offset:2048
	ds_read_b128 v[186:189], v141 offset:3072
	ds_read_b128 v[190:193], v141 offset:4096
	ds_read_b128 v[194:197], v141 offset:5120
	ds_read_b128 v[198:201], v141 offset:6144
	ds_read_b128 v[212:215], v141 offset:7168
	global_load_lds_dwordx4 v202, s[8:9]
	v_add_u32_e32 v202, s37, v139
	s_add_i32 m0, s22, 0xe000
	s_nop 0
	global_load_lds_dwordx4 v202, s[8:9]
	s_waitcnt vmcnt(8)
	s_waitcnt lgkmcnt(0)
	s_setprio 1
	s_barrier
	v_mfma_f32_16x16x32_bf16 v[126:129], v[142:145], v[174:177], v[126:129]
	v_mfma_f32_16x16x32_bf16 v[126:129], v[146:149], v[178:181], v[126:129]
	v_mfma_f32_16x16x32_bf16 v[122:125], v[154:157], v[178:181], v[122:125]
	v_mfma_f32_16x16x32_bf16 v[122:125], v[150:153], v[174:177], v[122:125]
	v_mfma_f32_16x16x32_bf16 v[106:109], v[150:153], v[182:185], v[106:109]
	v_mfma_f32_16x16x32_bf16 v[106:109], v[154:157], v[186:189], v[106:109]
	v_mfma_f32_16x16x32_bf16 v[110:113], v[146:149], v[186:189], v[110:113]
	v_mfma_f32_16x16x32_bf16 v[110:113], v[142:145], v[182:185], v[110:113]
	v_mfma_f32_16x16x32_bf16 v[94:97], v[142:145], v[190:193], v[94:97]
	v_mfma_f32_16x16x32_bf16 v[94:97], v[146:149], v[194:197], v[94:97]
	v_mfma_f32_16x16x32_bf16 v[90:93], v[154:157], v[194:197], v[90:93]
	v_mfma_f32_16x16x32_bf16 v[90:93], v[150:153], v[190:193], v[90:93]
	v_mfma_f32_16x16x32_bf16 v[74:77], v[150:153], v[198:201], v[74:77]
	v_mfma_f32_16x16x32_bf16 v[74:77], v[154:157], v[212:215], v[74:77]
	v_mfma_f32_16x16x32_bf16 v[78:81], v[146:149], v[212:215], v[78:81]
	v_mfma_f32_16x16x32_bf16 v[78:81], v[142:145], v[198:201], v[78:81]
	s_setprio 0
	s_setprio 1
	v_mfma_f32_16x16x32_bf16 v[70:73], v[158:161], v[198:201], v[70:73]
	v_mfma_f32_16x16x32_bf16 v[70:73], v[162:165], v[212:215], v[70:73]
	v_mfma_f32_16x16x32_bf16 v[66:69], v[170:173], v[212:215], v[66:69]
	v_mfma_f32_16x16x32_bf16 v[66:69], v[166:169], v[198:201], v[66:69]
	v_mfma_f32_16x16x32_bf16 v[82:85], v[166:169], v[190:193], v[82:85]
	v_mfma_f32_16x16x32_bf16 v[82:85], v[170:173], v[194:197], v[82:85]
	v_mfma_f32_16x16x32_bf16 v[86:89], v[162:165], v[194:197], v[86:89]
	v_mfma_f32_16x16x32_bf16 v[86:89], v[158:161], v[190:193], v[86:89]
	v_mfma_f32_16x16x32_bf16 v[102:105], v[158:161], v[182:185], v[102:105]
	v_mfma_f32_16x16x32_bf16 v[102:105], v[162:165], v[186:189], v[102:105]
	v_mfma_f32_16x16x32_bf16 v[98:101], v[170:173], v[186:189], v[98:101]
	v_mfma_f32_16x16x32_bf16 v[98:101], v[166:169], v[182:185], v[98:101]
	v_mfma_f32_16x16x32_bf16 v[114:117], v[166:169], v[174:177], v[114:117]
	v_mfma_f32_16x16x32_bf16 v[114:117], v[170:173], v[178:181], v[114:117]
	v_mfma_f32_16x16x32_bf16 v[118:121], v[162:165], v[178:181], v[118:121]
	v_mfma_f32_16x16x32_bf16 v[118:121], v[158:161], v[174:177], v[118:121]
	s_setprio 0
	s_barrier
	s_mov_b32 m0, s16
	v_add_u32_e32 v202, s43, v133
	ds_read_b128 v[174:177], v141 offset:16384
	ds_read_b128 v[178:181], v141 offset:17408
	ds_read_b128 v[182:185], v141 offset:18432
	ds_read_b128 v[186:189], v141 offset:19456
	ds_read_b128 v[190:193], v141 offset:20480
	ds_read_b128 v[194:197], v141 offset:21504
	ds_read_b128 v[198:201], v141 offset:22528
	ds_read_b128 v[212:215], v141 offset:23552
	global_load_lds_dwordx4 v202, s[10:11]
	v_add_u32_e32 v202, s43, v136
	s_mov_b32 m0, s17
	s_add_i32 s37, s43, 0x80000
	global_load_lds_dwordx4 v202, s[10:11]
	v_add_u32_e32 v202, s37, v133
	s_mov_b32 m0, s19
	s_nop 0
	global_load_lds_dwordx4 v202, s[10:11]
	v_add_u32_e32 v202, s37, v136
	s_mov_b32 m0, s20
	s_nop 0
	global_load_lds_dwordx4 v202, s[10:11]
	v_add_u32_e32 v202, s44, v131
	s_mov_b32 m0, s22
	s_nop 0
	global_load_lds_dwordx4 v202, s[8:9]
	v_add_u32_e32 v202, s44, v135
	s_mov_b32 m0, s23
	s_nop 0
	global_load_lds_dwordx4 v202, s[8:9]
	s_waitcnt vmcnt(8)
	s_waitcnt lgkmcnt(0)
	s_setprio 1
	s_barrier
	v_mfma_f32_16x16x32_bf16 v[62:65], v[142:145], v[174:177], v[62:65]
	v_mfma_f32_16x16x32_bf16 v[62:65], v[146:149], v[178:181], v[62:65]
	v_mfma_f32_16x16x32_bf16 v[58:61], v[154:157], v[178:181], v[58:61]
	v_mfma_f32_16x16x32_bf16 v[58:61], v[150:153], v[174:177], v[58:61]
	v_mfma_f32_16x16x32_bf16 v[42:45], v[150:153], v[182:185], v[42:45]
	v_mfma_f32_16x16x32_bf16 v[42:45], v[154:157], v[186:189], v[42:45]
	v_mfma_f32_16x16x32_bf16 v[46:49], v[146:149], v[186:189], v[46:49]
	v_mfma_f32_16x16x32_bf16 v[46:49], v[142:145], v[182:185], v[46:49]
	v_mfma_f32_16x16x32_bf16 v[30:33], v[142:145], v[190:193], v[30:33]
	v_mfma_f32_16x16x32_bf16 v[30:33], v[146:149], v[194:197], v[30:33]
	v_mfma_f32_16x16x32_bf16 v[26:29], v[154:157], v[194:197], v[26:29]
	v_mfma_f32_16x16x32_bf16 v[26:29], v[150:153], v[190:193], v[26:29]
	v_mfma_f32_16x16x32_bf16 v[10:13], v[150:153], v[198:201], v[10:13]
	v_mfma_f32_16x16x32_bf16 v[10:13], v[154:157], v[212:215], v[10:13]
	v_mfma_f32_16x16x32_bf16 v[14:17], v[146:149], v[212:215], v[14:17]
	v_mfma_f32_16x16x32_bf16 v[14:17], v[142:145], v[198:201], v[14:17]
	s_setprio 0
	s_setprio 1
	v_mfma_f32_16x16x32_bf16 v[6:9], v[158:161], v[198:201], v[6:9]
	v_mfma_f32_16x16x32_bf16 v[6:9], v[162:165], v[212:215], v[6:9]
	v_mfma_f32_16x16x32_bf16 v[2:5], v[170:173], v[212:215], v[2:5]
	v_mfma_f32_16x16x32_bf16 v[2:5], v[166:169], v[198:201], v[2:5]
	v_mfma_f32_16x16x32_bf16 v[18:21], v[166:169], v[190:193], v[18:21]
	v_mfma_f32_16x16x32_bf16 v[18:21], v[170:173], v[194:197], v[18:21]
	v_mfma_f32_16x16x32_bf16 v[22:25], v[162:165], v[194:197], v[22:25]
	v_mfma_f32_16x16x32_bf16 v[22:25], v[158:161], v[190:193], v[22:25]
	v_mfma_f32_16x16x32_bf16 v[38:41], v[158:161], v[182:185], v[38:41]
	v_mfma_f32_16x16x32_bf16 v[38:41], v[162:165], v[186:189], v[38:41]
	v_mfma_f32_16x16x32_bf16 v[34:37], v[170:173], v[186:189], v[34:37]
	v_mfma_f32_16x16x32_bf16 v[34:37], v[166:169], v[182:185], v[34:37]
	v_mfma_f32_16x16x32_bf16 v[50:53], v[166:169], v[174:177], v[50:53]
	v_mfma_f32_16x16x32_bf16 v[50:53], v[170:173], v[178:181], v[50:53]
	v_mfma_f32_16x16x32_bf16 v[54:57], v[162:165], v[178:181], v[54:57]
	v_mfma_f32_16x16x32_bf16 v[54:57], v[158:161], v[174:177], v[54:57]
	s_setprio 0
	s_barrier
	v_add_u32_e32 v154, s26, v138
	v_add_u32_e32 v170, s31, v138
	ds_read_b128 v[142:145], v154
	ds_read_b128 v[146:149], v154 offset:1024
	ds_read_b128 v[150:153], v154 offset:2048
	ds_read_b128 v[154:157], v154 offset:3072
	ds_read_b128 v[158:161], v170
	ds_read_b128 v[162:165], v170 offset:1024
	ds_read_b128 v[166:169], v170 offset:2048
	ds_read_b128 v[170:173], v170 offset:3072
	s_add_i32 s44, s44, 0x80000
	s_mov_b32 m0, s24
	v_add_u32_e32 v202, s44, v131
	ds_read_b128 v[174:177], v141 offset:32768
	ds_read_b128 v[178:181], v141 offset:33792
	ds_read_b128 v[182:185], v141 offset:34816
	ds_read_b128 v[186:189], v141 offset:35840
	ds_read_b128 v[190:193], v141 offset:36864
	ds_read_b128 v[194:197], v141 offset:37888
	ds_read_b128 v[198:201], v141 offset:38912
	ds_read_b128 v[212:215], v141 offset:39936
	global_load_lds_dwordx4 v202, s[8:9]
	v_add_u32_e32 v202, s44, v135
	s_mov_b32 m0, s25
	s_nop 0
	global_load_lds_dwordx4 v202, s[8:9]
	s_waitcnt vmcnt(8)
	s_waitcnt lgkmcnt(0)
	s_setprio 1
	s_barrier
	v_mfma_f32_16x16x32_bf16 v[126:129], v[142:145], v[174:177], v[126:129]
	v_mfma_f32_16x16x32_bf16 v[126:129], v[146:149], v[178:181], v[126:129]
	v_mfma_f32_16x16x32_bf16 v[122:125], v[154:157], v[178:181], v[122:125]
	v_mfma_f32_16x16x32_bf16 v[122:125], v[150:153], v[174:177], v[122:125]
	v_mfma_f32_16x16x32_bf16 v[106:109], v[150:153], v[182:185], v[106:109]
	v_mfma_f32_16x16x32_bf16 v[106:109], v[154:157], v[186:189], v[106:109]
	v_mfma_f32_16x16x32_bf16 v[110:113], v[146:149], v[186:189], v[110:113]
	v_mfma_f32_16x16x32_bf16 v[110:113], v[142:145], v[182:185], v[110:113]
	v_mfma_f32_16x16x32_bf16 v[94:97], v[142:145], v[190:193], v[94:97]
	v_mfma_f32_16x16x32_bf16 v[94:97], v[146:149], v[194:197], v[94:97]
	v_mfma_f32_16x16x32_bf16 v[90:93], v[154:157], v[194:197], v[90:93]
	v_mfma_f32_16x16x32_bf16 v[90:93], v[150:153], v[190:193], v[90:93]
	v_mfma_f32_16x16x32_bf16 v[74:77], v[150:153], v[198:201], v[74:77]
	v_mfma_f32_16x16x32_bf16 v[74:77], v[154:157], v[212:215], v[74:77]
	v_mfma_f32_16x16x32_bf16 v[78:81], v[146:149], v[212:215], v[78:81]
	v_mfma_f32_16x16x32_bf16 v[78:81], v[142:145], v[198:201], v[78:81]
	s_setprio 0
	s_setprio 1
	v_mfma_f32_16x16x32_bf16 v[70:73], v[158:161], v[198:201], v[70:73]
	v_mfma_f32_16x16x32_bf16 v[70:73], v[162:165], v[212:215], v[70:73]
	v_mfma_f32_16x16x32_bf16 v[66:69], v[170:173], v[212:215], v[66:69]
	v_mfma_f32_16x16x32_bf16 v[66:69], v[166:169], v[198:201], v[66:69]
	v_mfma_f32_16x16x32_bf16 v[82:85], v[166:169], v[190:193], v[82:85]
	v_mfma_f32_16x16x32_bf16 v[82:85], v[170:173], v[194:197], v[82:85]
	v_mfma_f32_16x16x32_bf16 v[86:89], v[162:165], v[194:197], v[86:89]
	v_mfma_f32_16x16x32_bf16 v[86:89], v[158:161], v[190:193], v[86:89]
	v_mfma_f32_16x16x32_bf16 v[102:105], v[158:161], v[182:185], v[102:105]
	v_mfma_f32_16x16x32_bf16 v[102:105], v[162:165], v[186:189], v[102:105]
	v_mfma_f32_16x16x32_bf16 v[98:101], v[170:173], v[186:189], v[98:101]
	v_mfma_f32_16x16x32_bf16 v[98:101], v[166:169], v[182:185], v[98:101]
	v_mfma_f32_16x16x32_bf16 v[114:117], v[166:169], v[174:177], v[114:117]
	v_mfma_f32_16x16x32_bf16 v[114:117], v[170:173], v[178:181], v[114:117]
	v_mfma_f32_16x16x32_bf16 v[118:121], v[162:165], v[178:181], v[118:121]
	v_mfma_f32_16x16x32_bf16 v[118:121], v[158:161], v[174:177], v[118:121]
	s_setprio 0
	s_barrier
	s_or_b32 s37, s43, 0x80
	s_mov_b32 m0, s27
	v_add_u32_e32 v202, s37, v133
	ds_read_b128 v[174:177], v141 offset:49152
	ds_read_b128 v[178:181], v141 offset:50176
	ds_read_b128 v[182:185], v141 offset:51200
	ds_read_b128 v[186:189], v141 offset:52224
	ds_read_b128 v[190:193], v141 offset:53248
	ds_read_b128 v[194:197], v141 offset:54272
	ds_read_b128 v[198:201], v141 offset:55296
	ds_read_b128 v[212:215], v141 offset:56320
	global_load_lds_dwordx4 v202, s[10:11]
	v_add_u32_e32 v202, s37, v136
	s_mov_b32 m0, s28
	s_add_i32 s43, s43, 0x80080
	global_load_lds_dwordx4 v202, s[10:11]
	v_add_u32_e32 v202, s43, v133
	s_mov_b32 m0, s34
	s_nop 0
	global_load_lds_dwordx4 v202, s[10:11]
	v_add_u32_e32 v202, s43, v136
	s_mov_b32 m0, s35
	s_nop 0
	global_load_lds_dwordx4 v202, s[10:11]
	v_add_u32_e32 v202, s42, v131
	s_mov_b32 m0, s29
	s_nop 0
	global_load_lds_dwordx4 v202, s[8:9]
	v_add_u32_e32 v202, s42, v135
	s_mov_b32 m0, s30
	s_nop 0
	global_load_lds_dwordx4 v202, s[8:9]
	s_waitcnt vmcnt(8)
	s_waitcnt lgkmcnt(0)
	s_setprio 1
	s_barrier
	v_mfma_f32_16x16x32_bf16 v[62:65], v[142:145], v[174:177], v[62:65]
	v_mfma_f32_16x16x32_bf16 v[62:65], v[146:149], v[178:181], v[62:65]
	v_mfma_f32_16x16x32_bf16 v[58:61], v[154:157], v[178:181], v[58:61]
	v_mfma_f32_16x16x32_bf16 v[58:61], v[150:153], v[174:177], v[58:61]
	v_mfma_f32_16x16x32_bf16 v[42:45], v[150:153], v[182:185], v[42:45]
	v_mfma_f32_16x16x32_bf16 v[42:45], v[154:157], v[186:189], v[42:45]
	v_mfma_f32_16x16x32_bf16 v[46:49], v[146:149], v[186:189], v[46:49]
	v_mfma_f32_16x16x32_bf16 v[46:49], v[142:145], v[182:185], v[46:49]
	v_mfma_f32_16x16x32_bf16 v[30:33], v[142:145], v[190:193], v[30:33]
	v_mfma_f32_16x16x32_bf16 v[30:33], v[146:149], v[194:197], v[30:33]
	v_mfma_f32_16x16x32_bf16 v[26:29], v[154:157], v[194:197], v[26:29]
	v_mfma_f32_16x16x32_bf16 v[26:29], v[150:153], v[190:193], v[26:29]
	v_mfma_f32_16x16x32_bf16 v[10:13], v[150:153], v[198:201], v[10:13]
	v_mfma_f32_16x16x32_bf16 v[10:13], v[154:157], v[212:215], v[10:13]
	v_mfma_f32_16x16x32_bf16 v[14:17], v[146:149], v[212:215], v[14:17]
	v_mfma_f32_16x16x32_bf16 v[14:17], v[142:145], v[198:201], v[14:17]
	s_setprio 0
	s_setprio 1
	v_mfma_f32_16x16x32_bf16 v[6:9], v[158:161], v[198:201], v[6:9]
	v_mfma_f32_16x16x32_bf16 v[6:9], v[162:165], v[212:215], v[6:9]
	v_mfma_f32_16x16x32_bf16 v[2:5], v[170:173], v[212:215], v[2:5]
	v_mfma_f32_16x16x32_bf16 v[2:5], v[166:169], v[198:201], v[2:5]
	v_mfma_f32_16x16x32_bf16 v[18:21], v[166:169], v[190:193], v[18:21]
	v_mfma_f32_16x16x32_bf16 v[18:21], v[170:173], v[194:197], v[18:21]
	v_mfma_f32_16x16x32_bf16 v[22:25], v[162:165], v[194:197], v[22:25]
	v_mfma_f32_16x16x32_bf16 v[22:25], v[158:161], v[190:193], v[22:25]
	v_mfma_f32_16x16x32_bf16 v[38:41], v[158:161], v[182:185], v[38:41]
	v_mfma_f32_16x16x32_bf16 v[38:41], v[162:165], v[186:189], v[38:41]
	v_mfma_f32_16x16x32_bf16 v[34:37], v[170:173], v[186:189], v[34:37]
	v_mfma_f32_16x16x32_bf16 v[34:37], v[166:169], v[182:185], v[34:37]
	v_mfma_f32_16x16x32_bf16 v[50:53], v[166:169], v[174:177], v[50:53]
	v_mfma_f32_16x16x32_bf16 v[50:53], v[170:173], v[178:181], v[50:53]
	v_mfma_f32_16x16x32_bf16 v[54:57], v[162:165], v[178:181], v[54:57]
	v_mfma_f32_16x16x32_bf16 v[54:57], v[158:161], v[174:177], v[54:57]
	s_setprio 0
	s_barrier
	s_add_i32 s36, s36, 2
	s_cmp_gt_u32 s36, 29
	s_mov_b32 s37, s41
	s_cbranch_scc0 .LBB0_314
	s_cmpk_lt_u32 s15, 0x100
	s_cbranch_scc0 .LBB0_317
	s_barrier

.LBB0_568:
	v_add_u32_e32 v142, s29, v201
	v_add_u32_e32 v158, s34, v201
	ds_read_b128 v[130:133], v142
	ds_read_b128 v[134:137], v142 offset:1024
	ds_read_b128 v[138:141], v142 offset:2048
	ds_read_b128 v[142:145], v142 offset:3072
	ds_read_b128 v[146:149], v158
	ds_read_b128 v[150:153], v158 offset:1024
	ds_read_b128 v[154:157], v158 offset:2048
	ds_read_b128 v[158:161], v158 offset:3072
	s_add_i32 s22, s62, 0x100
	s_add_i32 s23, s22, s59
	s_add_i32 s24, s15, s62
	s_cmpk_eq_i32 s62, 0xf00
	s_cselect_b32 s25, s60, s23
	s_cselect_b32 s24, s61, s24
	s_or_b32 s23, s25, 0x80
	v_add_u32_e32 v204, s62, v218
	s_add_i32 m0, s37, 0xc000
	ds_read_b128 v[162:165], v215
	ds_read_b128 v[166:169], v215 offset:1024
	ds_read_b128 v[170:173], v215 offset:2048
	ds_read_b128 v[174:177], v215 offset:3072
	ds_read_b128 v[178:181], v215 offset:4096
	ds_read_b128 v[182:185], v215 offset:5120
	ds_read_b128 v[186:189], v215 offset:6144
	ds_read_b128 v[190:193], v215 offset:7168
	global_load_lds_dwordx4 v204, s[0:1]
	v_add_u32_e32 v204, s62, v216
	s_add_i32 m0, s37, 0xe000
	s_nop 0
	global_load_lds_dwordx4 v204, s[0:1]
	s_waitcnt vmcnt(8)
	s_waitcnt lgkmcnt(0)
	s_setprio 1
	s_barrier
	v_mfma_f32_16x16x32_bf16 v[126:129], v[130:133], v[162:165], v[126:129]
	v_mfma_f32_16x16x32_bf16 v[126:129], v[134:137], v[166:169], v[126:129]
	v_mfma_f32_16x16x32_bf16 v[122:125], v[142:145], v[166:169], v[122:125]
	v_mfma_f32_16x16x32_bf16 v[122:125], v[138:141], v[162:165], v[122:125]
	v_mfma_f32_16x16x32_bf16 v[106:109], v[138:141], v[170:173], v[106:109]
	v_mfma_f32_16x16x32_bf16 v[106:109], v[142:145], v[174:177], v[106:109]
	v_mfma_f32_16x16x32_bf16 v[110:113], v[134:137], v[174:177], v[110:113]
	v_mfma_f32_16x16x32_bf16 v[110:113], v[130:133], v[170:173], v[110:113]
	v_mfma_f32_16x16x32_bf16 v[94:97], v[130:133], v[178:181], v[94:97]
	v_mfma_f32_16x16x32_bf16 v[94:97], v[134:137], v[182:185], v[94:97]
	v_mfma_f32_16x16x32_bf16 v[90:93], v[142:145], v[182:185], v[90:93]
	v_mfma_f32_16x16x32_bf16 v[90:93], v[138:141], v[178:181], v[90:93]
	v_mfma_f32_16x16x32_bf16 v[74:77], v[138:141], v[186:189], v[74:77]
	v_mfma_f32_16x16x32_bf16 v[74:77], v[142:145], v[190:193], v[74:77]
	v_mfma_f32_16x16x32_bf16 v[78:81], v[134:137], v[190:193], v[78:81]
	v_mfma_f32_16x16x32_bf16 v[78:81], v[130:133], v[186:189], v[78:81]
	s_setprio 0
	s_setprio 1
	v_mfma_f32_16x16x32_bf16 v[70:73], v[146:149], v[186:189], v[70:73]
	v_mfma_f32_16x16x32_bf16 v[70:73], v[150:153], v[190:193], v[70:73]
	v_mfma_f32_16x16x32_bf16 v[66:69], v[158:161], v[190:193], v[66:69]
	v_mfma_f32_16x16x32_bf16 v[66:69], v[154:157], v[186:189], v[66:69]
	v_mfma_f32_16x16x32_bf16 v[82:85], v[154:157], v[178:181], v[82:85]
	v_mfma_f32_16x16x32_bf16 v[82:85], v[158:161], v[182:185], v[82:85]
	v_mfma_f32_16x16x32_bf16 v[86:89], v[150:153], v[182:185], v[86:89]
	v_mfma_f32_16x16x32_bf16 v[86:89], v[146:149], v[178:181], v[86:89]
	v_mfma_f32_16x16x32_bf16 v[102:105], v[146:149], v[170:173], v[102:105]
	v_mfma_f32_16x16x32_bf16 v[102:105], v[150:153], v[174:177], v[102:105]
	v_mfma_f32_16x16x32_bf16 v[98:101], v[158:161], v[174:177], v[98:101]
	v_mfma_f32_16x16x32_bf16 v[98:101], v[154:157], v[170:173], v[98:101]
	v_mfma_f32_16x16x32_bf16 v[114:117], v[154:157], v[162:165], v[114:117]
	v_mfma_f32_16x16x32_bf16 v[114:117], v[158:161], v[166:169], v[114:117]
	v_mfma_f32_16x16x32_bf16 v[118:121], v[150:153], v[166:169], v[118:121]
	v_mfma_f32_16x16x32_bf16 v[118:121], v[146:149], v[162:165], v[118:121]
	s_setprio 0
	s_barrier
	s_mov_b32 m0, s30
	v_add_u32_e32 v204, s24, v197
	ds_read_b128 v[162:165], v215 offset:16384
	ds_read_b128 v[166:169], v215 offset:17408
	ds_read_b128 v[170:173], v215 offset:18432
	ds_read_b128 v[174:177], v215 offset:19456
	ds_read_b128 v[178:181], v215 offset:20480
	ds_read_b128 v[182:185], v215 offset:21504
	ds_read_b128 v[186:189], v215 offset:22528
	ds_read_b128 v[190:193], v215 offset:23552
	global_load_lds_dwordx4 v204, s[2:3]
	v_add_u32_e32 v204, s24, v199
	s_mov_b32 m0, s31
	s_add_i32 s62, s24, 0x80000
	global_load_lds_dwordx4 v204, s[2:3]
	v_add_u32_e32 v204, s62, v197
	s_mov_b32 m0, s35
	s_nop 0
	global_load_lds_dwordx4 v204, s[2:3]
	v_add_u32_e32 v204, s62, v199
	s_mov_b32 m0, s36
	s_nop 0
	global_load_lds_dwordx4 v204, s[2:3]
	v_add_u32_e32 v204, s25, v196
	s_mov_b32 m0, s37
	s_nop 0
	global_load_lds_dwordx4 v204, s[0:1]
	v_add_u32_e32 v204, s25, v198
	s_mov_b32 m0, s38
	s_nop 0
	global_load_lds_dwordx4 v204, s[0:1]
	s_waitcnt vmcnt(8)
	s_waitcnt lgkmcnt(0)
	s_setprio 1
	s_barrier
	v_mfma_f32_16x16x32_bf16 v[62:65], v[130:133], v[162:165], v[62:65]
	v_mfma_f32_16x16x32_bf16 v[62:65], v[134:137], v[166:169], v[62:65]
	v_mfma_f32_16x16x32_bf16 v[58:61], v[142:145], v[166:169], v[58:61]
	v_mfma_f32_16x16x32_bf16 v[58:61], v[138:141], v[162:165], v[58:61]
	v_mfma_f32_16x16x32_bf16 v[42:45], v[138:141], v[170:173], v[42:45]
	v_mfma_f32_16x16x32_bf16 v[42:45], v[142:145], v[174:177], v[42:45]
	v_mfma_f32_16x16x32_bf16 v[46:49], v[134:137], v[174:177], v[46:49]
	v_mfma_f32_16x16x32_bf16 v[46:49], v[130:133], v[170:173], v[46:49]
	v_mfma_f32_16x16x32_bf16 v[30:33], v[130:133], v[178:181], v[30:33]
	v_mfma_f32_16x16x32_bf16 v[30:33], v[134:137], v[182:185], v[30:33]
	v_mfma_f32_16x16x32_bf16 v[26:29], v[142:145], v[182:185], v[26:29]
	v_mfma_f32_16x16x32_bf16 v[26:29], v[138:141], v[178:181], v[26:29]
	v_mfma_f32_16x16x32_bf16 v[10:13], v[138:141], v[186:189], v[10:13]
	v_mfma_f32_16x16x32_bf16 v[10:13], v[142:145], v[190:193], v[10:13]
	v_mfma_f32_16x16x32_bf16 v[14:17], v[134:137], v[190:193], v[14:17]
	v_mfma_f32_16x16x32_bf16 v[14:17], v[130:133], v[186:189], v[14:17]
	s_setprio 0
	s_setprio 1
	v_mfma_f32_16x16x32_bf16 v[6:9], v[146:149], v[186:189], v[6:9]
	v_mfma_f32_16x16x32_bf16 v[6:9], v[150:153], v[190:193], v[6:9]
	v_mfma_f32_16x16x32_bf16 v[2:5], v[158:161], v[190:193], v[2:5]
	v_mfma_f32_16x16x32_bf16 v[2:5], v[154:157], v[186:189], v[2:5]
	v_mfma_f32_16x16x32_bf16 v[18:21], v[154:157], v[178:181], v[18:21]
	v_mfma_f32_16x16x32_bf16 v[18:21], v[158:161], v[182:185], v[18:21]
	v_mfma_f32_16x16x32_bf16 v[22:25], v[150:153], v[182:185], v[22:25]
	v_mfma_f32_16x16x32_bf16 v[22:25], v[146:149], v[178:181], v[22:25]
	v_mfma_f32_16x16x32_bf16 v[38:41], v[146:149], v[170:173], v[38:41]
	v_mfma_f32_16x16x32_bf16 v[38:41], v[150:153], v[174:177], v[38:41]
	v_mfma_f32_16x16x32_bf16 v[34:37], v[158:161], v[174:177], v[34:37]
	v_mfma_f32_16x16x32_bf16 v[34:37], v[154:157], v[170:173], v[34:37]
	v_mfma_f32_16x16x32_bf16 v[50:53], v[154:157], v[162:165], v[50:53]
	v_mfma_f32_16x16x32_bf16 v[50:53], v[158:161], v[166:169], v[50:53]
	v_mfma_f32_16x16x32_bf16 v[54:57], v[150:153], v[166:169], v[54:57]
	v_mfma_f32_16x16x32_bf16 v[54:57], v[146:149], v[162:165], v[54:57]
	s_setprio 0
	s_barrier
	v_add_u32_e32 v142, s43, v201
	v_add_u32_e32 v158, s48, v201
	ds_read_b128 v[130:133], v142
	ds_read_b128 v[134:137], v142 offset:1024
	ds_read_b128 v[138:141], v142 offset:2048
	ds_read_b128 v[142:145], v142 offset:3072
	ds_read_b128 v[146:149], v158
	ds_read_b128 v[150:153], v158 offset:1024
	ds_read_b128 v[154:157], v158 offset:2048
	ds_read_b128 v[158:161], v158 offset:3072
	s_add_i32 s25, s25, 0x80000
	s_mov_b32 m0, s39
	v_add_u32_e32 v204, s25, v196
	ds_read_b128 v[162:165], v215 offset:32768
	ds_read_b128 v[166:169], v215 offset:33792
	ds_read_b128 v[170:173], v215 offset:34816
	ds_read_b128 v[174:177], v215 offset:35840
	ds_read_b128 v[178:181], v215 offset:36864
	ds_read_b128 v[182:185], v215 offset:37888
	ds_read_b128 v[186:189], v215 offset:38912
	ds_read_b128 v[190:193], v215 offset:39936
	global_load_lds_dwordx4 v204, s[0:1]
	v_add_u32_e32 v204, s25, v198
	s_mov_b32 m0, s40
	s_nop 0
	global_load_lds_dwordx4 v204, s[0:1]
	s_waitcnt vmcnt(8)
	s_waitcnt lgkmcnt(0)
	s_setprio 1
	s_barrier
	v_mfma_f32_16x16x32_bf16 v[126:129], v[130:133], v[162:165], v[126:129]
	v_mfma_f32_16x16x32_bf16 v[126:129], v[134:137], v[166:169], v[126:129]
	v_mfma_f32_16x16x32_bf16 v[122:125], v[142:145], v[166:169], v[122:125]
	v_mfma_f32_16x16x32_bf16 v[122:125], v[138:141], v[162:165], v[122:125]
	v_mfma_f32_16x16x32_bf16 v[106:109], v[138:141], v[170:173], v[106:109]
	v_mfma_f32_16x16x32_bf16 v[106:109], v[142:145], v[174:177], v[106:109]
	v_mfma_f32_16x16x32_bf16 v[110:113], v[134:137], v[174:177], v[110:113]
	v_mfma_f32_16x16x32_bf16 v[110:113], v[130:133], v[170:173], v[110:113]
	v_mfma_f32_16x16x32_bf16 v[94:97], v[130:133], v[178:181], v[94:97]
	v_mfma_f32_16x16x32_bf16 v[94:97], v[134:137], v[182:185], v[94:97]
	v_mfma_f32_16x16x32_bf16 v[90:93], v[142:145], v[182:185], v[90:93]
	v_mfma_f32_16x16x32_bf16 v[90:93], v[138:141], v[178:181], v[90:93]
	v_mfma_f32_16x16x32_bf16 v[74:77], v[138:141], v[186:189], v[74:77]
	v_mfma_f32_16x16x32_bf16 v[74:77], v[142:145], v[190:193], v[74:77]
	v_mfma_f32_16x16x32_bf16 v[78:81], v[134:137], v[190:193], v[78:81]
	v_mfma_f32_16x16x32_bf16 v[78:81], v[130:133], v[186:189], v[78:81]
	s_setprio 0
	s_setprio 1
	v_mfma_f32_16x16x32_bf16 v[70:73], v[146:149], v[186:189], v[70:73]
	v_mfma_f32_16x16x32_bf16 v[70:73], v[150:153], v[190:193], v[70:73]
	v_mfma_f32_16x16x32_bf16 v[66:69], v[158:161], v[190:193], v[66:69]
	v_mfma_f32_16x16x32_bf16 v[66:69], v[154:157], v[186:189], v[66:69]
	v_mfma_f32_16x16x32_bf16 v[82:85], v[154:157], v[178:181], v[82:85]
	v_mfma_f32_16x16x32_bf16 v[82:85], v[158:161], v[182:185], v[82:85]
	v_mfma_f32_16x16x32_bf16 v[86:89], v[150:153], v[182:185], v[86:89]
	v_mfma_f32_16x16x32_bf16 v[86:89], v[146:149], v[178:181], v[86:89]
	v_mfma_f32_16x16x32_bf16 v[102:105], v[146:149], v[170:173], v[102:105]
	v_mfma_f32_16x16x32_bf16 v[102:105], v[150:153], v[174:177], v[102:105]
	v_mfma_f32_16x16x32_bf16 v[98:101], v[158:161], v[174:177], v[98:101]
	v_mfma_f32_16x16x32_bf16 v[98:101], v[154:157], v[170:173], v[98:101]
	v_mfma_f32_16x16x32_bf16 v[114:117], v[154:157], v[162:165], v[114:117]
	v_mfma_f32_16x16x32_bf16 v[114:117], v[158:161], v[166:169], v[114:117]
	v_mfma_f32_16x16x32_bf16 v[118:121], v[150:153], v[166:169], v[118:121]
	v_mfma_f32_16x16x32_bf16 v[118:121], v[146:149], v[162:165], v[118:121]
	s_setprio 0
	s_barrier
	s_or_b32 s25, s24, 0x80
	s_mov_b32 m0, s44
	v_add_u32_e32 v204, s25, v197
	ds_read_b128 v[162:165], v215 offset:49152
	ds_read_b128 v[166:169], v215 offset:50176
	ds_read_b128 v[170:173], v215 offset:51200
	ds_read_b128 v[174:177], v215 offset:52224
	ds_read_b128 v[178:181], v215 offset:53248
	ds_read_b128 v[182:185], v215 offset:54272
	ds_read_b128 v[186:189], v215 offset:55296
	ds_read_b128 v[190:193], v215 offset:56320
	global_load_lds_dwordx4 v204, s[2:3]
	v_add_u32_e32 v204, s25, v199
	s_mov_b32 m0, s45
	s_add_i32 s24, s24, 0x80080
	global_load_lds_dwordx4 v204, s[2:3]
	v_add_u32_e32 v204, s24, v197
	s_mov_b32 m0, s49
	s_nop 0
	global_load_lds_dwordx4 v204, s[2:3]
	v_add_u32_e32 v204, s24, v199
	s_mov_b32 m0, s50
	s_nop 0
	global_load_lds_dwordx4 v204, s[2:3]
	v_add_u32_e32 v204, s23, v196
	s_mov_b32 m0, s46
	s_nop 0
	global_load_lds_dwordx4 v204, s[0:1]
	v_add_u32_e32 v204, s23, v198
	s_mov_b32 m0, s47
	s_nop 0
	global_load_lds_dwordx4 v204, s[0:1]
	s_waitcnt vmcnt(8)
	s_waitcnt lgkmcnt(0)
	s_setprio 1
	s_barrier
	v_mfma_f32_16x16x32_bf16 v[62:65], v[130:133], v[162:165], v[62:65]
	v_mfma_f32_16x16x32_bf16 v[62:65], v[134:137], v[166:169], v[62:65]
	v_mfma_f32_16x16x32_bf16 v[58:61], v[142:145], v[166:169], v[58:61]
	v_mfma_f32_16x16x32_bf16 v[58:61], v[138:141], v[162:165], v[58:61]
	v_mfma_f32_16x16x32_bf16 v[42:45], v[138:141], v[170:173], v[42:45]
	v_mfma_f32_16x16x32_bf16 v[42:45], v[142:145], v[174:177], v[42:45]
	v_mfma_f32_16x16x32_bf16 v[46:49], v[134:137], v[174:177], v[46:49]
	v_mfma_f32_16x16x32_bf16 v[46:49], v[130:133], v[170:173], v[46:49]
	v_mfma_f32_16x16x32_bf16 v[30:33], v[130:133], v[178:181], v[30:33]
	v_mfma_f32_16x16x32_bf16 v[30:33], v[134:137], v[182:185], v[30:33]
	v_mfma_f32_16x16x32_bf16 v[26:29], v[142:145], v[182:185], v[26:29]
	v_mfma_f32_16x16x32_bf16 v[26:29], v[138:141], v[178:181], v[26:29]
	v_mfma_f32_16x16x32_bf16 v[10:13], v[138:141], v[186:189], v[10:13]
	v_mfma_f32_16x16x32_bf16 v[10:13], v[142:145], v[190:193], v[10:13]
	v_mfma_f32_16x16x32_bf16 v[14:17], v[134:137], v[190:193], v[14:17]
	v_mfma_f32_16x16x32_bf16 v[14:17], v[130:133], v[186:189], v[14:17]
	s_setprio 0
	s_setprio 1
	v_mfma_f32_16x16x32_bf16 v[6:9], v[146:149], v[186:189], v[6:9]
	v_mfma_f32_16x16x32_bf16 v[6:9], v[150:153], v[190:193], v[6:9]
	v_mfma_f32_16x16x32_bf16 v[2:5], v[158:161], v[190:193], v[2:5]
	v_mfma_f32_16x16x32_bf16 v[2:5], v[154:157], v[186:189], v[2:5]
	v_mfma_f32_16x16x32_bf16 v[18:21], v[154:157], v[178:181], v[18:21]
	v_mfma_f32_16x16x32_bf16 v[18:21], v[158:161], v[182:185], v[18:21]
	v_mfma_f32_16x16x32_bf16 v[22:25], v[150:153], v[182:185], v[22:25]
	v_mfma_f32_16x16x32_bf16 v[22:25], v[146:149], v[178:181], v[22:25]
	v_mfma_f32_16x16x32_bf16 v[38:41], v[146:149], v[170:173], v[38:41]
	v_mfma_f32_16x16x32_bf16 v[38:41], v[150:153], v[174:177], v[38:41]
	v_mfma_f32_16x16x32_bf16 v[34:37], v[158:161], v[174:177], v[34:37]
	v_mfma_f32_16x16x32_bf16 v[34:37], v[154:157], v[170:173], v[34:37]
	v_mfma_f32_16x16x32_bf16 v[50:53], v[154:157], v[162:165], v[50:53]
	v_mfma_f32_16x16x32_bf16 v[50:53], v[158:161], v[166:169], v[50:53]
	v_mfma_f32_16x16x32_bf16 v[54:57], v[150:153], v[166:169], v[54:57]
	v_mfma_f32_16x16x32_bf16 v[54:57], v[146:149], v[162:165], v[54:57]
	s_setprio 0
	s_barrier
	s_add_i32 s23, s17, 2
	s_cmp_gt_u32 s17, 29
	s_cbranch_scc1 .LBB0_571
	s_mov_b32 s62, s22
	s_mov_b32 s17, s23
	s_cmp_lt_i32 s17, 24
	s_cbranch_scc1 .LBB0_564

.LBB0_615:
	s_lshl_b32 s12, s40, 20
	s_and_b64 s[48:49], s[4:5], exec
	s_cselect_b32 s43, s12, s46
	s_lshl_b32 s13, s39, 20
	s_and_b64 s[48:49], s[4:5], exec
	s_cselect_b32 s44, s13, s45
	v_add_u32_e32 v130, s46, v139
	v_add_u32_e32 v131, s46, v140
	s_addk_i32 s45, 0x100
	s_addk_i32 s46, 0x100
	s_mov_b32 s47, -2
	v_add_u32_e32 v154, s17, v137
	v_add_u32_e32 v170, s20, v137
	ds_read_b128 v[142:145], v154
	ds_read_b128 v[146:149], v154 offset:1024
	ds_read_b128 v[150:153], v154 offset:2048
	ds_read_b128 v[154:157], v154 offset:3072
	ds_read_b128 v[158:161], v170
	ds_read_b128 v[162:165], v170 offset:1024
	ds_read_b128 v[166:169], v170 offset:2048
	ds_read_b128 v[170:173], v170 offset:3072
	s_cmp_eq_u32 s47, 28
	s_cselect_b32 s50, s43, s46
	s_cselect_b32 s49, s44, s45
	s_or_b32 s48, s50, 0x80
	s_add_i32 m0, s23, 0xc000
	ds_read_b128 v[174:177], v141
	ds_read_b128 v[178:181], v141 offset:1024
	ds_read_b128 v[182:185], v141 offset:2048
	ds_read_b128 v[186:189], v141 offset:3072
	ds_read_b128 v[190:193], v141 offset:4096
	ds_read_b128 v[194:197], v141 offset:5120
	ds_read_b128 v[198:201], v141 offset:6144
	ds_read_b128 v[204:207], v141 offset:7168
	global_load_lds_dwordx4 v131, s[0:1]
	s_add_i32 m0, s23, 0xe000
	s_nop 0
	global_load_lds_dwordx4 v130, s[0:1]
	s_waitcnt vmcnt(8)
	s_waitcnt lgkmcnt(0)
	s_setprio 1
	s_barrier
	v_mfma_f32_16x16x32_bf16 v[126:129], v[142:145], v[174:177], 0
	v_mfma_f32_16x16x32_bf16 v[126:129], v[146:149], v[178:181], v[126:129]
	v_mfma_f32_16x16x32_bf16 v[122:125], v[154:157], v[178:181], 0
	v_mfma_f32_16x16x32_bf16 v[122:125], v[150:153], v[174:177], v[122:125]
	v_mfma_f32_16x16x32_bf16 v[110:113], v[150:153], v[182:185], 0
	v_mfma_f32_16x16x32_bf16 v[110:113], v[154:157], v[186:189], v[110:113]
	v_mfma_f32_16x16x32_bf16 v[118:121], v[146:149], v[186:189], 0
	v_mfma_f32_16x16x32_bf16 v[118:121], v[142:145], v[182:185], v[118:121]
	v_mfma_f32_16x16x32_bf16 v[102:105], v[142:145], v[190:193], 0
	v_mfma_f32_16x16x32_bf16 v[102:105], v[146:149], v[194:197], v[102:105]
	v_mfma_f32_16x16x32_bf16 v[94:97], v[154:157], v[194:197], 0
	v_mfma_f32_16x16x32_bf16 v[94:97], v[150:153], v[190:193], v[94:97]
	v_mfma_f32_16x16x32_bf16 v[78:81], v[150:153], v[198:201], 0
	v_mfma_f32_16x16x32_bf16 v[78:81], v[154:157], v[204:207], v[78:81]
	v_mfma_f32_16x16x32_bf16 v[86:89], v[146:149], v[204:207], 0
	v_mfma_f32_16x16x32_bf16 v[86:89], v[142:145], v[198:201], v[86:89]
	s_setprio 0
	s_setprio 1
	v_mfma_f32_16x16x32_bf16 v[70:73], v[158:161], v[198:201], 0
	v_mfma_f32_16x16x32_bf16 v[70:73], v[162:165], v[204:207], v[70:73]
	v_mfma_f32_16x16x32_bf16 v[66:69], v[170:173], v[204:207], 0
	v_mfma_f32_16x16x32_bf16 v[66:69], v[166:169], v[198:201], v[66:69]
	v_mfma_f32_16x16x32_bf16 v[74:77], v[166:169], v[190:193], 0
	v_mfma_f32_16x16x32_bf16 v[74:77], v[170:173], v[194:197], v[74:77]
	v_mfma_f32_16x16x32_bf16 v[82:85], v[162:165], v[194:197], 0
	v_mfma_f32_16x16x32_bf16 v[82:85], v[158:161], v[190:193], v[82:85]
	v_mfma_f32_16x16x32_bf16 v[98:101], v[158:161], v[182:185], 0
	v_mfma_f32_16x16x32_bf16 v[98:101], v[162:165], v[186:189], v[98:101]
	v_mfma_f32_16x16x32_bf16 v[90:93], v[170:173], v[186:189], 0
	v_mfma_f32_16x16x32_bf16 v[90:93], v[166:169], v[182:185], v[90:93]
	v_mfma_f32_16x16x32_bf16 v[106:109], v[166:169], v[174:177], 0
	v_mfma_f32_16x16x32_bf16 v[106:109], v[170:173], v[178:181], v[106:109]
	v_mfma_f32_16x16x32_bf16 v[114:117], v[162:165], v[178:181], 0
	v_mfma_f32_16x16x32_bf16 v[114:117], v[158:161], v[174:177], v[114:117]
	s_setprio 0
	s_barrier
	s_mov_b32 m0, s18
	v_add_u32_e32 v202, s49, v133
	ds_read_b128 v[174:177], v141 offset:16384
	ds_read_b128 v[178:181], v141 offset:17408
	ds_read_b128 v[182:185], v141 offset:18432
	ds_read_b128 v[186:189], v141 offset:19456
	ds_read_b128 v[190:193], v141 offset:20480
	ds_read_b128 v[194:197], v141 offset:21504
	ds_read_b128 v[198:201], v141 offset:22528
	ds_read_b128 v[204:207], v141 offset:23552
	global_load_lds_dwordx4 v202, s[2:3]
	v_add_u32_e32 v202, s49, v135
	s_mov_b32 m0, s19
	s_add_i32 s51, s49, 0x80000
	global_load_lds_dwordx4 v202, s[2:3]
	v_add_u32_e32 v202, s51, v133
	s_mov_b32 m0, s21
	s_nop 0
	global_load_lds_dwordx4 v202, s[2:3]
	v_add_u32_e32 v202, s51, v135
	s_mov_b32 m0, s22
	s_nop 0
	global_load_lds_dwordx4 v202, s[2:3]
	v_add_u32_e32 v202, s50, v132
	s_mov_b32 m0, s23
	s_nop 0
	global_load_lds_dwordx4 v202, s[0:1]
	v_add_u32_e32 v202, s50, v134
	s_mov_b32 m0, s24
	s_nop 0
	global_load_lds_dwordx4 v202, s[0:1]
	s_waitcnt vmcnt(8)
	s_waitcnt lgkmcnt(0)
	s_setprio 1
	s_barrier
	v_mfma_f32_16x16x32_bf16 v[62:65], v[142:145], v[174:177], 0
	v_mfma_f32_16x16x32_bf16 v[62:65], v[146:149], v[178:181], v[62:65]
	v_mfma_f32_16x16x32_bf16 v[58:61], v[154:157], v[178:181], 0
	v_mfma_f32_16x16x32_bf16 v[58:61], v[150:153], v[174:177], v[58:61]
	v_mfma_f32_16x16x32_bf16 v[46:49], v[150:153], v[182:185], 0
	v_mfma_f32_16x16x32_bf16 v[46:49], v[154:157], v[186:189], v[46:49]
	v_mfma_f32_16x16x32_bf16 v[54:57], v[146:149], v[186:189], 0
	v_mfma_f32_16x16x32_bf16 v[54:57], v[142:145], v[182:185], v[54:57]
	v_mfma_f32_16x16x32_bf16 v[38:41], v[142:145], v[190:193], 0
	v_mfma_f32_16x16x32_bf16 v[38:41], v[146:149], v[194:197], v[38:41]
	v_mfma_f32_16x16x32_bf16 v[30:33], v[154:157], v[194:197], 0
	v_mfma_f32_16x16x32_bf16 v[30:33], v[150:153], v[190:193], v[30:33]
	v_mfma_f32_16x16x32_bf16 v[14:17], v[150:153], v[198:201], 0
	v_mfma_f32_16x16x32_bf16 v[14:17], v[154:157], v[204:207], v[14:17]
	v_mfma_f32_16x16x32_bf16 v[22:25], v[146:149], v[204:207], 0
	v_mfma_f32_16x16x32_bf16 v[22:25], v[142:145], v[198:201], v[22:25]
	s_setprio 0
	s_setprio 1
	v_mfma_f32_16x16x32_bf16 v[6:9], v[158:161], v[198:201], 0
	v_mfma_f32_16x16x32_bf16 v[6:9], v[162:165], v[204:207], v[6:9]
	v_mfma_f32_16x16x32_bf16 v[2:5], v[170:173], v[204:207], 0
	v_mfma_f32_16x16x32_bf16 v[2:5], v[166:169], v[198:201], v[2:5]
	v_mfma_f32_16x16x32_bf16 v[10:13], v[166:169], v[190:193], 0
	v_mfma_f32_16x16x32_bf16 v[10:13], v[170:173], v[194:197], v[10:13]
	v_mfma_f32_16x16x32_bf16 v[18:21], v[162:165], v[194:197], 0
	v_mfma_f32_16x16x32_bf16 v[18:21], v[158:161], v[190:193], v[18:21]
	v_mfma_f32_16x16x32_bf16 v[34:37], v[158:161], v[182:185], 0
	v_mfma_f32_16x16x32_bf16 v[34:37], v[162:165], v[186:189], v[34:37]
	v_mfma_f32_16x16x32_bf16 v[26:29], v[170:173], v[186:189], 0
	v_mfma_f32_16x16x32_bf16 v[26:29], v[166:169], v[182:185], v[26:29]
	v_mfma_f32_16x16x32_bf16 v[42:45], v[166:169], v[174:177], 0
	v_mfma_f32_16x16x32_bf16 v[42:45], v[170:173], v[178:181], v[42:45]
	v_mfma_f32_16x16x32_bf16 v[50:53], v[162:165], v[178:181], 0
	v_mfma_f32_16x16x32_bf16 v[50:53], v[158:161], v[174:177], v[50:53]
	s_setprio 0
	s_barrier
	v_add_u32_e32 v154, s27, v137
	v_add_u32_e32 v170, s34, v137
	ds_read_b128 v[142:145], v154
	ds_read_b128 v[146:149], v154 offset:1024
	ds_read_b128 v[150:153], v154 offset:2048
	ds_read_b128 v[154:157], v154 offset:3072
	ds_read_b128 v[158:161], v170
	ds_read_b128 v[162:165], v170 offset:1024
	ds_read_b128 v[166:169], v170 offset:2048
	ds_read_b128 v[170:173], v170 offset:3072
	s_add_i32 s50, s50, 0x80000
	s_mov_b32 m0, s25
	v_add_u32_e32 v202, s50, v132
	ds_read_b128 v[174:177], v141 offset:32768
	ds_read_b128 v[178:181], v141 offset:33792
	ds_read_b128 v[182:185], v141 offset:34816
	ds_read_b128 v[186:189], v141 offset:35840
	ds_read_b128 v[190:193], v141 offset:36864
	ds_read_b128 v[194:197], v141 offset:37888
	ds_read_b128 v[198:201], v141 offset:38912
	ds_read_b128 v[204:207], v141 offset:39936
	global_load_lds_dwordx4 v202, s[0:1]
	v_add_u32_e32 v202, s50, v134
	s_mov_b32 m0, s26
	s_nop 0
	global_load_lds_dwordx4 v202, s[0:1]
	s_waitcnt vmcnt(8)
	s_waitcnt lgkmcnt(0)
	s_setprio 1
	s_barrier
	v_mfma_f32_16x16x32_bf16 v[126:129], v[142:145], v[174:177], v[126:129]
	v_mfma_f32_16x16x32_bf16 v[126:129], v[146:149], v[178:181], v[126:129]
	v_mfma_f32_16x16x32_bf16 v[122:125], v[154:157], v[178:181], v[122:125]
	v_mfma_f32_16x16x32_bf16 v[122:125], v[150:153], v[174:177], v[122:125]
	v_mfma_f32_16x16x32_bf16 v[110:113], v[150:153], v[182:185], v[110:113]
	v_mfma_f32_16x16x32_bf16 v[110:113], v[154:157], v[186:189], v[110:113]
	v_mfma_f32_16x16x32_bf16 v[118:121], v[146:149], v[186:189], v[118:121]
	v_mfma_f32_16x16x32_bf16 v[118:121], v[142:145], v[182:185], v[118:121]
	v_mfma_f32_16x16x32_bf16 v[102:105], v[142:145], v[190:193], v[102:105]
	v_mfma_f32_16x16x32_bf16 v[102:105], v[146:149], v[194:197], v[102:105]
	v_mfma_f32_16x16x32_bf16 v[94:97], v[154:157], v[194:197], v[94:97]
	v_mfma_f32_16x16x32_bf16 v[94:97], v[150:153], v[190:193], v[94:97]
	v_mfma_f32_16x16x32_bf16 v[78:81], v[150:153], v[198:201], v[78:81]
	v_mfma_f32_16x16x32_bf16 v[78:81], v[154:157], v[204:207], v[78:81]
	v_mfma_f32_16x16x32_bf16 v[86:89], v[146:149], v[204:207], v[86:89]
	v_mfma_f32_16x16x32_bf16 v[86:89], v[142:145], v[198:201], v[86:89]
	s_setprio 0
	s_setprio 1
	v_mfma_f32_16x16x32_bf16 v[70:73], v[158:161], v[198:201], v[70:73]
	v_mfma_f32_16x16x32_bf16 v[70:73], v[162:165], v[204:207], v[70:73]
	v_mfma_f32_16x16x32_bf16 v[66:69], v[170:173], v[204:207], v[66:69]
	v_mfma_f32_16x16x32_bf16 v[66:69], v[166:169], v[198:201], v[66:69]
	v_mfma_f32_16x16x32_bf16 v[74:77], v[166:169], v[190:193], v[74:77]
	v_mfma_f32_16x16x32_bf16 v[74:77], v[170:173], v[194:197], v[74:77]
	v_mfma_f32_16x16x32_bf16 v[82:85], v[162:165], v[194:197], v[82:85]
	v_mfma_f32_16x16x32_bf16 v[82:85], v[158:161], v[190:193], v[82:85]
	v_mfma_f32_16x16x32_bf16 v[98:101], v[158:161], v[182:185], v[98:101]
	v_mfma_f32_16x16x32_bf16 v[98:101], v[162:165], v[186:189], v[98:101]
	v_mfma_f32_16x16x32_bf16 v[90:93], v[170:173], v[186:189], v[90:93]
	v_mfma_f32_16x16x32_bf16 v[90:93], v[166:169], v[182:185], v[90:93]
	v_mfma_f32_16x16x32_bf16 v[106:109], v[166:169], v[174:177], v[106:109]
	v_mfma_f32_16x16x32_bf16 v[106:109], v[170:173], v[178:181], v[106:109]
	v_mfma_f32_16x16x32_bf16 v[114:117], v[162:165], v[178:181], v[114:117]
	v_mfma_f32_16x16x32_bf16 v[114:117], v[158:161], v[174:177], v[114:117]
	s_setprio 0
	s_barrier
	s_or_b32 s50, s49, 0x80
	s_mov_b32 m0, s28
	v_add_u32_e32 v202, s50, v133
	ds_read_b128 v[174:177], v141 offset:49152
	ds_read_b128 v[178:181], v141 offset:50176
	ds_read_b128 v[182:185], v141 offset:51200
	ds_read_b128 v[186:189], v141 offset:52224
	ds_read_b128 v[190:193], v141 offset:53248
	ds_read_b128 v[194:197], v141 offset:54272
	ds_read_b128 v[198:201], v141 offset:55296
	ds_read_b128 v[204:207], v141 offset:56320
	global_load_lds_dwordx4 v202, s[2:3]
	v_add_u32_e32 v202, s50, v135
	s_mov_b32 m0, s29
	s_add_i32 s49, s49, 0x80080
	global_load_lds_dwordx4 v202, s[2:3]
	v_add_u32_e32 v202, s49, v133
	s_mov_b32 m0, s35
	s_nop 0
	global_load_lds_dwordx4 v202, s[2:3]
	v_add_u32_e32 v202, s49, v135
	s_mov_b32 m0, s36
	s_nop 0
	global_load_lds_dwordx4 v202, s[2:3]
	v_add_u32_e32 v202, s48, v132
	s_mov_b32 m0, s30
	s_nop 0
	global_load_lds_dwordx4 v202, s[0:1]
	v_add_u32_e32 v202, s48, v134
	s_mov_b32 m0, s31
	s_nop 0
	global_load_lds_dwordx4 v202, s[0:1]
	s_waitcnt vmcnt(8)
	s_waitcnt lgkmcnt(0)
	s_setprio 1
	s_barrier
	v_mfma_f32_16x16x32_bf16 v[62:65], v[142:145], v[174:177], v[62:65]
	v_mfma_f32_16x16x32_bf16 v[62:65], v[146:149], v[178:181], v[62:65]
	v_mfma_f32_16x16x32_bf16 v[58:61], v[154:157], v[178:181], v[58:61]
	v_mfma_f32_16x16x32_bf16 v[58:61], v[150:153], v[174:177], v[58:61]
	v_mfma_f32_16x16x32_bf16 v[46:49], v[150:153], v[182:185], v[46:49]
	v_mfma_f32_16x16x32_bf16 v[46:49], v[154:157], v[186:189], v[46:49]
	v_mfma_f32_16x16x32_bf16 v[54:57], v[146:149], v[186:189], v[54:57]
	v_mfma_f32_16x16x32_bf16 v[54:57], v[142:145], v[182:185], v[54:57]
	v_mfma_f32_16x16x32_bf16 v[38:41], v[142:145], v[190:193], v[38:41]
	v_mfma_f32_16x16x32_bf16 v[38:41], v[146:149], v[194:197], v[38:41]
	v_mfma_f32_16x16x32_bf16 v[30:33], v[154:157], v[194:197], v[30:33]
	v_mfma_f32_16x16x32_bf16 v[30:33], v[150:153], v[190:193], v[30:33]
	v_mfma_f32_16x16x32_bf16 v[14:17], v[150:153], v[198:201], v[14:17]
	v_mfma_f32_16x16x32_bf16 v[14:17], v[154:157], v[204:207], v[14:17]
	v_mfma_f32_16x16x32_bf16 v[22:25], v[146:149], v[204:207], v[22:25]
	v_mfma_f32_16x16x32_bf16 v[22:25], v[142:145], v[198:201], v[22:25]
	s_setprio 0
	s_setprio 1
	v_mfma_f32_16x16x32_bf16 v[6:9], v[158:161], v[198:201], v[6:9]
	v_mfma_f32_16x16x32_bf16 v[6:9], v[162:165], v[204:207], v[6:9]
	v_mfma_f32_16x16x32_bf16 v[2:5], v[170:173], v[204:207], v[2:5]
	v_mfma_f32_16x16x32_bf16 v[2:5], v[166:169], v[198:201], v[2:5]
	v_mfma_f32_16x16x32_bf16 v[10:13], v[166:169], v[190:193], v[10:13]
	v_mfma_f32_16x16x32_bf16 v[10:13], v[170:173], v[194:197], v[10:13]
	v_mfma_f32_16x16x32_bf16 v[18:21], v[162:165], v[194:197], v[18:21]
	v_mfma_f32_16x16x32_bf16 v[18:21], v[158:161], v[190:193], v[18:21]
	v_mfma_f32_16x16x32_bf16 v[34:37], v[158:161], v[182:185], v[34:37]
	v_mfma_f32_16x16x32_bf16 v[34:37], v[162:165], v[186:189], v[34:37]
	v_mfma_f32_16x16x32_bf16 v[26:29], v[170:173], v[186:189], v[26:29]
	v_mfma_f32_16x16x32_bf16 v[26:29], v[166:169], v[182:185], v[26:29]
	v_mfma_f32_16x16x32_bf16 v[42:45], v[166:169], v[174:177], v[42:45]
	v_mfma_f32_16x16x32_bf16 v[42:45], v[170:173], v[178:181], v[42:45]
	v_mfma_f32_16x16x32_bf16 v[50:53], v[162:165], v[178:181], v[50:53]
	v_mfma_f32_16x16x32_bf16 v[50:53], v[158:161], v[174:177], v[50:53]
	s_setprio 0
	s_barrier
	s_add_i32 s47, s47, 2
	s_addk_i32 s45, 0x100
	s_addk_i32 s46, 0x100
	v_add_u32_e32 v130, 0x100, v130
	s_cmp_gt_u32 s47, 29
	v_add_u32_e32 v131, 0x100, v131
.LBB0_616:
	v_add_u32_e32 v154, s17, v137
	v_add_u32_e32 v170, s20, v137
	ds_read_b128 v[142:145], v154
	ds_read_b128 v[146:149], v154 offset:1024
	ds_read_b128 v[150:153], v154 offset:2048
	ds_read_b128 v[154:157], v154 offset:3072
	ds_read_b128 v[158:161], v170
	ds_read_b128 v[162:165], v170 offset:1024
	ds_read_b128 v[166:169], v170 offset:2048
	ds_read_b128 v[170:173], v170 offset:3072
	s_cmp_eq_u32 s47, 28
	s_cselect_b32 s50, s43, s46
	s_cselect_b32 s49, s44, s45
	s_or_b32 s48, s50, 0x80
	s_add_i32 m0, s23, 0xc000
	ds_read_b128 v[174:177], v141
	ds_read_b128 v[178:181], v141 offset:1024
	ds_read_b128 v[182:185], v141 offset:2048
	ds_read_b128 v[186:189], v141 offset:3072
	ds_read_b128 v[190:193], v141 offset:4096
	ds_read_b128 v[194:197], v141 offset:5120
	ds_read_b128 v[198:201], v141 offset:6144
	ds_read_b128 v[204:207], v141 offset:7168
	global_load_lds_dwordx4 v131, s[0:1]
	s_add_i32 m0, s23, 0xe000
	s_nop 0
	global_load_lds_dwordx4 v130, s[0:1]
	s_waitcnt vmcnt(8)
	s_waitcnt lgkmcnt(0)
	s_setprio 1
	s_barrier
	v_mfma_f32_16x16x32_bf16 v[126:129], v[142:145], v[174:177], v[126:129]
	v_mfma_f32_16x16x32_bf16 v[126:129], v[146:149], v[178:181], v[126:129]
	v_mfma_f32_16x16x32_bf16 v[122:125], v[154:157], v[178:181], v[122:125]
	v_mfma_f32_16x16x32_bf16 v[122:125], v[150:153], v[174:177], v[122:125]
	v_mfma_f32_16x16x32_bf16 v[110:113], v[150:153], v[182:185], v[110:113]
	v_mfma_f32_16x16x32_bf16 v[110:113], v[154:157], v[186:189], v[110:113]
	v_mfma_f32_16x16x32_bf16 v[118:121], v[146:149], v[186:189], v[118:121]
	v_mfma_f32_16x16x32_bf16 v[118:121], v[142:145], v[182:185], v[118:121]
	v_mfma_f32_16x16x32_bf16 v[102:105], v[142:145], v[190:193], v[102:105]
	v_mfma_f32_16x16x32_bf16 v[102:105], v[146:149], v[194:197], v[102:105]
	v_mfma_f32_16x16x32_bf16 v[94:97], v[154:157], v[194:197], v[94:97]
	v_mfma_f32_16x16x32_bf16 v[94:97], v[150:153], v[190:193], v[94:97]
	v_mfma_f32_16x16x32_bf16 v[78:81], v[150:153], v[198:201], v[78:81]
	v_mfma_f32_16x16x32_bf16 v[78:81], v[154:157], v[204:207], v[78:81]
	v_mfma_f32_16x16x32_bf16 v[86:89], v[146:149], v[204:207], v[86:89]
	v_mfma_f32_16x16x32_bf16 v[86:89], v[142:145], v[198:201], v[86:89]
	s_setprio 0
	s_setprio 1
	v_mfma_f32_16x16x32_bf16 v[70:73], v[158:161], v[198:201], v[70:73]
	v_mfma_f32_16x16x32_bf16 v[70:73], v[162:165], v[204:207], v[70:73]
	v_mfma_f32_16x16x32_bf16 v[66:69], v[170:173], v[204:207], v[66:69]
	v_mfma_f32_16x16x32_bf16 v[66:69], v[166:169], v[198:201], v[66:69]
	v_mfma_f32_16x16x32_bf16 v[74:77], v[166:169], v[190:193], v[74:77]
	v_mfma_f32_16x16x32_bf16 v[74:77], v[170:173], v[194:197], v[74:77]
	v_mfma_f32_16x16x32_bf16 v[82:85], v[162:165], v[194:197], v[82:85]
	v_mfma_f32_16x16x32_bf16 v[82:85], v[158:161], v[190:193], v[82:85]
	v_mfma_f32_16x16x32_bf16 v[98:101], v[158:161], v[182:185], v[98:101]
	v_mfma_f32_16x16x32_bf16 v[98:101], v[162:165], v[186:189], v[98:101]
	v_mfma_f32_16x16x32_bf16 v[90:93], v[170:173], v[186:189], v[90:93]
	v_mfma_f32_16x16x32_bf16 v[90:93], v[166:169], v[182:185], v[90:93]
	v_mfma_f32_16x16x32_bf16 v[106:109], v[166:169], v[174:177], v[106:109]
	v_mfma_f32_16x16x32_bf16 v[106:109], v[170:173], v[178:181], v[106:109]
	v_mfma_f32_16x16x32_bf16 v[114:117], v[162:165], v[178:181], v[114:117]
	v_mfma_f32_16x16x32_bf16 v[114:117], v[158:161], v[174:177], v[114:117]
	s_setprio 0
	s_barrier
	s_mov_b32 m0, s18
	v_add_u32_e32 v202, s49, v133
	ds_read_b128 v[174:177], v141 offset:16384
	ds_read_b128 v[178:181], v141 offset:17408
	ds_read_b128 v[182:185], v141 offset:18432
	ds_read_b128 v[186:189], v141 offset:19456
	ds_read_b128 v[190:193], v141 offset:20480
	ds_read_b128 v[194:197], v141 offset:21504
	ds_read_b128 v[198:201], v141 offset:22528
	ds_read_b128 v[204:207], v141 offset:23552
	global_load_lds_dwordx4 v202, s[2:3]
	v_add_u32_e32 v202, s49, v135
	s_mov_b32 m0, s19
	s_add_i32 s51, s49, 0x80000
	global_load_lds_dwordx4 v202, s[2:3]
	v_add_u32_e32 v202, s51, v133
	s_mov_b32 m0, s21
	s_nop 0
	global_load_lds_dwordx4 v202, s[2:3]
	v_add_u32_e32 v202, s51, v135
	s_mov_b32 m0, s22
	s_nop 0
	global_load_lds_dwordx4 v202, s[2:3]
	v_add_u32_e32 v202, s50, v132
	s_mov_b32 m0, s23
	s_nop 0
	global_load_lds_dwordx4 v202, s[0:1]
	v_add_u32_e32 v202, s50, v134
	s_mov_b32 m0, s24
	s_nop 0
	global_load_lds_dwordx4 v202, s[0:1]
	s_waitcnt vmcnt(8)
	s_waitcnt lgkmcnt(0)
	s_setprio 1
	s_barrier
	v_mfma_f32_16x16x32_bf16 v[62:65], v[142:145], v[174:177], v[62:65]
	v_mfma_f32_16x16x32_bf16 v[62:65], v[146:149], v[178:181], v[62:65]
	v_mfma_f32_16x16x32_bf16 v[58:61], v[154:157], v[178:181], v[58:61]
	v_mfma_f32_16x16x32_bf16 v[58:61], v[150:153], v[174:177], v[58:61]
	v_mfma_f32_16x16x32_bf16 v[46:49], v[150:153], v[182:185], v[46:49]
	v_mfma_f32_16x16x32_bf16 v[46:49], v[154:157], v[186:189], v[46:49]
	v_mfma_f32_16x16x32_bf16 v[54:57], v[146:149], v[186:189], v[54:57]
	v_mfma_f32_16x16x32_bf16 v[54:57], v[142:145], v[182:185], v[54:57]
	v_mfma_f32_16x16x32_bf16 v[38:41], v[142:145], v[190:193], v[38:41]
	v_mfma_f32_16x16x32_bf16 v[38:41], v[146:149], v[194:197], v[38:41]
	v_mfma_f32_16x16x32_bf16 v[30:33], v[154:157], v[194:197], v[30:33]
	v_mfma_f32_16x16x32_bf16 v[30:33], v[150:153], v[190:193], v[30:33]
	v_mfma_f32_16x16x32_bf16 v[14:17], v[150:153], v[198:201], v[14:17]
	v_mfma_f32_16x16x32_bf16 v[14:17], v[154:157], v[204:207], v[14:17]
	v_mfma_f32_16x16x32_bf16 v[22:25], v[146:149], v[204:207], v[22:25]
	v_mfma_f32_16x16x32_bf16 v[22:25], v[142:145], v[198:201], v[22:25]
	s_setprio 0
	s_setprio 1
	v_mfma_f32_16x16x32_bf16 v[6:9], v[158:161], v[198:201], v[6:9]
	v_mfma_f32_16x16x32_bf16 v[6:9], v[162:165], v[204:207], v[6:9]
	v_mfma_f32_16x16x32_bf16 v[2:5], v[170:173], v[204:207], v[2:5]
	v_mfma_f32_16x16x32_bf16 v[2:5], v[166:169], v[198:201], v[2:5]
	v_mfma_f32_16x16x32_bf16 v[10:13], v[166:169], v[190:193], v[10:13]
	v_mfma_f32_16x16x32_bf16 v[10:13], v[170:173], v[194:197], v[10:13]
	v_mfma_f32_16x16x32_bf16 v[18:21], v[162:165], v[194:197], v[18:21]
	v_mfma_f32_16x16x32_bf16 v[18:21], v[158:161], v[190:193], v[18:21]
	v_mfma_f32_16x16x32_bf16 v[34:37], v[158:161], v[182:185], v[34:37]
	v_mfma_f32_16x16x32_bf16 v[34:37], v[162:165], v[186:189], v[34:37]
	v_mfma_f32_16x16x32_bf16 v[26:29], v[170:173], v[186:189], v[26:29]
	v_mfma_f32_16x16x32_bf16 v[26:29], v[166:169], v[182:185], v[26:29]
	v_mfma_f32_16x16x32_bf16 v[42:45], v[166:169], v[174:177], v[42:45]
	v_mfma_f32_16x16x32_bf16 v[42:45], v[170:173], v[178:181], v[42:45]
	v_mfma_f32_16x16x32_bf16 v[50:53], v[162:165], v[178:181], v[50:53]
	v_mfma_f32_16x16x32_bf16 v[50:53], v[158:161], v[174:177], v[50:53]
	s_setprio 0
	s_barrier
	v_add_u32_e32 v154, s27, v137
	v_add_u32_e32 v170, s34, v137
	ds_read_b128 v[142:145], v154
	ds_read_b128 v[146:149], v154 offset:1024
	ds_read_b128 v[150:153], v154 offset:2048
	ds_read_b128 v[154:157], v154 offset:3072
	ds_read_b128 v[158:161], v170
	ds_read_b128 v[162:165], v170 offset:1024
	ds_read_b128 v[166:169], v170 offset:2048
	ds_read_b128 v[170:173], v170 offset:3072
	s_add_i32 s50, s50, 0x80000
	s_mov_b32 m0, s25
	v_add_u32_e32 v202, s50, v132
	ds_read_b128 v[174:177], v141 offset:32768
	ds_read_b128 v[178:181], v141 offset:33792
	ds_read_b128 v[182:185], v141 offset:34816
	ds_read_b128 v[186:189], v141 offset:35840
	ds_read_b128 v[190:193], v141 offset:36864
	ds_read_b128 v[194:197], v141 offset:37888
	ds_read_b128 v[198:201], v141 offset:38912
	ds_read_b128 v[204:207], v141 offset:39936
	global_load_lds_dwordx4 v202, s[0:1]
	v_add_u32_e32 v202, s50, v134
	s_mov_b32 m0, s26
	s_nop 0
	global_load_lds_dwordx4 v202, s[0:1]
	s_waitcnt vmcnt(8)
	s_waitcnt lgkmcnt(0)
	s_setprio 1
	s_barrier
	v_mfma_f32_16x16x32_bf16 v[126:129], v[142:145], v[174:177], v[126:129]
	v_mfma_f32_16x16x32_bf16 v[126:129], v[146:149], v[178:181], v[126:129]
	v_mfma_f32_16x16x32_bf16 v[122:125], v[154:157], v[178:181], v[122:125]
	v_mfma_f32_16x16x32_bf16 v[122:125], v[150:153], v[174:177], v[122:125]
	v_mfma_f32_16x16x32_bf16 v[110:113], v[150:153], v[182:185], v[110:113]
	v_mfma_f32_16x16x32_bf16 v[110:113], v[154:157], v[186:189], v[110:113]
	v_mfma_f32_16x16x32_bf16 v[118:121], v[146:149], v[186:189], v[118:121]
	v_mfma_f32_16x16x32_bf16 v[118:121], v[142:145], v[182:185], v[118:121]
	v_mfma_f32_16x16x32_bf16 v[102:105], v[142:145], v[190:193], v[102:105]
	v_mfma_f32_16x16x32_bf16 v[102:105], v[146:149], v[194:197], v[102:105]
	v_mfma_f32_16x16x32_bf16 v[94:97], v[154:157], v[194:197], v[94:97]
	v_mfma_f32_16x16x32_bf16 v[94:97], v[150:153], v[190:193], v[94:97]
	v_mfma_f32_16x16x32_bf16 v[78:81], v[150:153], v[198:201], v[78:81]
	v_mfma_f32_16x16x32_bf16 v[78:81], v[154:157], v[204:207], v[78:81]
	v_mfma_f32_16x16x32_bf16 v[86:89], v[146:149], v[204:207], v[86:89]
	v_mfma_f32_16x16x32_bf16 v[86:89], v[142:145], v[198:201], v[86:89]
	s_setprio 0
	s_setprio 1
	v_mfma_f32_16x16x32_bf16 v[70:73], v[158:161], v[198:201], v[70:73]
	v_mfma_f32_16x16x32_bf16 v[70:73], v[162:165], v[204:207], v[70:73]
	v_mfma_f32_16x16x32_bf16 v[66:69], v[170:173], v[204:207], v[66:69]
	v_mfma_f32_16x16x32_bf16 v[66:69], v[166:169], v[198:201], v[66:69]
	v_mfma_f32_16x16x32_bf16 v[74:77], v[166:169], v[190:193], v[74:77]
	v_mfma_f32_16x16x32_bf16 v[74:77], v[170:173], v[194:197], v[74:77]
	v_mfma_f32_16x16x32_bf16 v[82:85], v[162:165], v[194:197], v[82:85]
	v_mfma_f32_16x16x32_bf16 v[82:85], v[158:161], v[190:193], v[82:85]
	v_mfma_f32_16x16x32_bf16 v[98:101], v[158:161], v[182:185], v[98:101]
	v_mfma_f32_16x16x32_bf16 v[98:101], v[162:165], v[186:189], v[98:101]
	v_mfma_f32_16x16x32_bf16 v[90:93], v[170:173], v[186:189], v[90:93]
	v_mfma_f32_16x16x32_bf16 v[90:93], v[166:169], v[182:185], v[90:93]
	v_mfma_f32_16x16x32_bf16 v[106:109], v[166:169], v[174:177], v[106:109]
	v_mfma_f32_16x16x32_bf16 v[106:109], v[170:173], v[178:181], v[106:109]
	v_mfma_f32_16x16x32_bf16 v[114:117], v[162:165], v[178:181], v[114:117]
	v_mfma_f32_16x16x32_bf16 v[114:117], v[158:161], v[174:177], v[114:117]
	s_setprio 0
	s_barrier
	s_or_b32 s50, s49, 0x80
	s_mov_b32 m0, s28
	v_add_u32_e32 v202, s50, v133
	ds_read_b128 v[174:177], v141 offset:49152
	ds_read_b128 v[178:181], v141 offset:50176
	ds_read_b128 v[182:185], v141 offset:51200
	ds_read_b128 v[186:189], v141 offset:52224
	ds_read_b128 v[190:193], v141 offset:53248
	ds_read_b128 v[194:197], v141 offset:54272
	ds_read_b128 v[198:201], v141 offset:55296
	ds_read_b128 v[204:207], v141 offset:56320
	global_load_lds_dwordx4 v202, s[2:3]
	v_add_u32_e32 v202, s50, v135
	s_mov_b32 m0, s29
	s_add_i32 s49, s49, 0x80080
	global_load_lds_dwordx4 v202, s[2:3]
	v_add_u32_e32 v202, s49, v133
	s_mov_b32 m0, s35
	s_nop 0
	global_load_lds_dwordx4 v202, s[2:3]
	v_add_u32_e32 v202, s49, v135
	s_mov_b32 m0, s36
	s_nop 0
	global_load_lds_dwordx4 v202, s[2:3]
	v_add_u32_e32 v202, s48, v132
	s_mov_b32 m0, s30
	s_nop 0
	global_load_lds_dwordx4 v202, s[0:1]
	v_add_u32_e32 v202, s48, v134
	s_mov_b32 m0, s31
	s_nop 0
	global_load_lds_dwordx4 v202, s[0:1]
	s_add_i32 s47, s47, 2
	s_addk_i32 s45, 0x100
	s_addk_i32 s46, 0x100
	v_add_u32_e32 v130, 0x100, v130
	s_cmp_gt_u32 s47, 29
	v_add_u32_e32 v131, 0x100, v131
	s_waitcnt vmcnt(8)
	s_waitcnt lgkmcnt(0)
	s_setprio 1
	s_barrier
	v_mfma_f32_16x16x32_bf16 v[62:65], v[142:145], v[174:177], v[62:65]
	v_mfma_f32_16x16x32_bf16 v[62:65], v[146:149], v[178:181], v[62:65]
	v_mfma_f32_16x16x32_bf16 v[58:61], v[154:157], v[178:181], v[58:61]
	v_mfma_f32_16x16x32_bf16 v[58:61], v[150:153], v[174:177], v[58:61]
	v_mfma_f32_16x16x32_bf16 v[46:49], v[150:153], v[182:185], v[46:49]
	v_mfma_f32_16x16x32_bf16 v[46:49], v[154:157], v[186:189], v[46:49]
	v_mfma_f32_16x16x32_bf16 v[54:57], v[146:149], v[186:189], v[54:57]
	v_mfma_f32_16x16x32_bf16 v[54:57], v[142:145], v[182:185], v[54:57]
	v_mfma_f32_16x16x32_bf16 v[38:41], v[142:145], v[190:193], v[38:41]
	v_mfma_f32_16x16x32_bf16 v[38:41], v[146:149], v[194:197], v[38:41]
	v_mfma_f32_16x16x32_bf16 v[30:33], v[154:157], v[194:197], v[30:33]
	v_mfma_f32_16x16x32_bf16 v[30:33], v[150:153], v[190:193], v[30:33]
	v_mfma_f32_16x16x32_bf16 v[14:17], v[150:153], v[198:201], v[14:17]
	v_mfma_f32_16x16x32_bf16 v[14:17], v[154:157], v[204:207], v[14:17]
	v_mfma_f32_16x16x32_bf16 v[22:25], v[146:149], v[204:207], v[22:25]
	v_mfma_f32_16x16x32_bf16 v[22:25], v[142:145], v[198:201], v[22:25]
	s_setprio 0
	s_setprio 1
	v_mfma_f32_16x16x32_bf16 v[6:9], v[158:161], v[198:201], v[6:9]
	v_mfma_f32_16x16x32_bf16 v[6:9], v[162:165], v[204:207], v[6:9]
	v_mfma_f32_16x16x32_bf16 v[2:5], v[170:173], v[204:207], v[2:5]
	v_mfma_f32_16x16x32_bf16 v[2:5], v[166:169], v[198:201], v[2:5]
	v_mfma_f32_16x16x32_bf16 v[10:13], v[166:169], v[190:193], v[10:13]
	v_mfma_f32_16x16x32_bf16 v[10:13], v[170:173], v[194:197], v[10:13]
	v_mfma_f32_16x16x32_bf16 v[18:21], v[162:165], v[194:197], v[18:21]
	v_mfma_f32_16x16x32_bf16 v[18:21], v[158:161], v[190:193], v[18:21]
	v_mfma_f32_16x16x32_bf16 v[34:37], v[158:161], v[182:185], v[34:37]
	v_mfma_f32_16x16x32_bf16 v[34:37], v[162:165], v[186:189], v[34:37]
	v_mfma_f32_16x16x32_bf16 v[26:29], v[170:173], v[186:189], v[26:29]
	v_mfma_f32_16x16x32_bf16 v[26:29], v[166:169], v[182:185], v[26:29]
	v_mfma_f32_16x16x32_bf16 v[42:45], v[166:169], v[174:177], v[42:45]
	v_mfma_f32_16x16x32_bf16 v[42:45], v[170:173], v[178:181], v[42:45]
	v_mfma_f32_16x16x32_bf16 v[50:53], v[162:165], v[178:181], v[50:53]
	v_mfma_f32_16x16x32_bf16 v[50:53], v[158:161], v[174:177], v[50:53]
	s_setprio 0
	s_barrier
	s_cbranch_scc0 .LBB0_616
	s_and_b64 vcc, exec, s[10:11]
	s_cbranch_vccz .LBB0_619
	s_barrier

.LBB0_703:
	s_lshl_b32 s26, s20, 20
	s_and_b64 s[54:55], s[22:23], exec
	s_cselect_b32 s54, s26, s57
	s_lshl_b32 s27, s52, 20
	s_and_b64 s[58:59], s[22:23], exec
	s_cselect_b32 s55, s27, s56
	v_add_u32_e32 v132, s57, v144
	v_add_u32_e32 v133, s57, v145
	s_addk_i32 s56, 0x100
	s_addk_i32 s57, 0x100
	s_mov_b32 s58, -2
	v_add_u32_e32 v134, s25, v141
	ds_read_b128 v[148:151], v134
	ds_read_b128 v[152:155], v134 offset:1024
	ds_read_b128 v[156:159], v134 offset:2048
	ds_read_b128 v[160:163], v134 offset:3072
	v_add_u32_e32 v134, s34, v141
	ds_read_b128 v[164:167], v134
	ds_read_b128 v[168:171], v134 offset:1024
	ds_read_b128 v[172:175], v134 offset:2048
	ds_read_b128 v[176:179], v134 offset:3072
	s_cmp_eq_u32 s58, 28
	s_cselect_b32 s61, s54, s57
	s_cselect_b32 s60, s55, s56
	s_or_b32 s59, s61, 0x80
	s_add_i32 m0, s37, 0xc000
	ds_read_b128 v[180:183], v146
	ds_read_b128 v[184:187], v146 offset:1024
	ds_read_b128 v[188:191], v146 offset:2048
	ds_read_b128 v[192:195], v146 offset:3072
	ds_read_b128 v[196:199], v146 offset:4096
	ds_read_b128 v[204:207], v146 offset:5120
	ds_read_b128 v[212:215], v146 offset:6144
	ds_read_b128 v[218:221], v146 offset:7168
	global_load_lds_dwordx4 v133, s[4:5]
	s_add_i32 m0, s37, 0xe000
	s_nop 0
	global_load_lds_dwordx4 v132, s[4:5]
	s_waitcnt vmcnt(8)
	s_waitcnt lgkmcnt(0)
	s_setprio 1
	s_barrier
	v_mfma_f32_16x16x32_bf16 v[126:129], v[148:151], v[180:183], 0
	v_mfma_f32_16x16x32_bf16 v[126:129], v[152:155], v[184:187], v[126:129]
	v_mfma_f32_16x16x32_bf16 v[122:125], v[160:163], v[184:187], 0
	v_mfma_f32_16x16x32_bf16 v[122:125], v[156:159], v[180:183], v[122:125]
	v_mfma_f32_16x16x32_bf16 v[106:109], v[156:159], v[188:191], 0
	v_mfma_f32_16x16x32_bf16 v[106:109], v[160:163], v[192:195], v[106:109]
	v_mfma_f32_16x16x32_bf16 v[110:113], v[152:155], v[192:195], 0
	v_mfma_f32_16x16x32_bf16 v[110:113], v[148:151], v[188:191], v[110:113]
	v_mfma_f32_16x16x32_bf16 v[94:97], v[148:151], v[196:199], 0
	v_mfma_f32_16x16x32_bf16 v[94:97], v[152:155], v[204:207], v[94:97]
	v_mfma_f32_16x16x32_bf16 v[90:93], v[160:163], v[204:207], 0
	v_mfma_f32_16x16x32_bf16 v[90:93], v[156:159], v[196:199], v[90:93]
	v_mfma_f32_16x16x32_bf16 v[74:77], v[156:159], v[212:215], 0
	v_mfma_f32_16x16x32_bf16 v[74:77], v[160:163], v[218:221], v[74:77]
	v_mfma_f32_16x16x32_bf16 v[78:81], v[152:155], v[218:221], 0
	v_mfma_f32_16x16x32_bf16 v[78:81], v[148:151], v[212:215], v[78:81]
	s_setprio 0
	s_setprio 1
	v_mfma_f32_16x16x32_bf16 v[70:73], v[164:167], v[212:215], 0
	v_mfma_f32_16x16x32_bf16 v[70:73], v[168:171], v[218:221], v[70:73]
	v_mfma_f32_16x16x32_bf16 v[66:69], v[176:179], v[218:221], 0
	v_mfma_f32_16x16x32_bf16 v[66:69], v[172:175], v[212:215], v[66:69]
	v_mfma_f32_16x16x32_bf16 v[82:85], v[172:175], v[196:199], 0
	v_mfma_f32_16x16x32_bf16 v[82:85], v[176:179], v[204:207], v[82:85]
	v_mfma_f32_16x16x32_bf16 v[86:89], v[168:171], v[204:207], 0
	v_mfma_f32_16x16x32_bf16 v[86:89], v[164:167], v[196:199], v[86:89]
	v_mfma_f32_16x16x32_bf16 v[102:105], v[164:167], v[188:191], 0
	v_mfma_f32_16x16x32_bf16 v[102:105], v[168:171], v[192:195], v[102:105]
	v_mfma_f32_16x16x32_bf16 v[98:101], v[176:179], v[192:195], 0
	v_mfma_f32_16x16x32_bf16 v[98:101], v[172:175], v[188:191], v[98:101]
	v_mfma_f32_16x16x32_bf16 v[114:117], v[172:175], v[180:183], 0
	v_mfma_f32_16x16x32_bf16 v[114:117], v[176:179], v[184:187], v[114:117]
	v_mfma_f32_16x16x32_bf16 v[118:121], v[168:171], v[184:187], 0
	v_mfma_f32_16x16x32_bf16 v[118:121], v[164:167], v[180:183], v[118:121]
	s_setprio 0
	s_barrier
	s_mov_b32 m0, s30
	v_add_u32_e32 v134, s60, v137
	ds_read_b128 v[180:183], v146 offset:16384
	ds_read_b128 v[184:187], v146 offset:17408
	ds_read_b128 v[188:191], v146 offset:18432
	ds_read_b128 v[192:195], v146 offset:19456
	ds_read_b128 v[196:199], v146 offset:20480
	ds_read_b128 v[204:207], v146 offset:21504
	ds_read_b128 v[212:215], v146 offset:22528
	ds_read_b128 v[218:221], v146 offset:23552
	global_load_lds_dwordx4 v134, s[6:7]
	v_add_u32_e32 v134, s60, v139
	s_mov_b32 m0, s31
	s_add_i32 s62, s60, 0x80000
	global_load_lds_dwordx4 v134, s[6:7]
	v_add_u32_e32 v134, s62, v137
	s_mov_b32 m0, s35
	s_nop 0
	global_load_lds_dwordx4 v134, s[6:7]
	v_add_u32_e32 v134, s62, v139
	s_mov_b32 m0, s36
	s_nop 0
	global_load_lds_dwordx4 v134, s[6:7]
	v_add_u32_e32 v134, s61, v136
	s_mov_b32 m0, s37
	s_nop 0
	global_load_lds_dwordx4 v134, s[4:5]
	v_add_u32_e32 v134, s61, v138
	s_mov_b32 m0, s38
	s_nop 0
	global_load_lds_dwordx4 v134, s[4:5]
	s_waitcnt vmcnt(8)
	s_waitcnt lgkmcnt(0)
	s_setprio 1
	s_barrier
	v_mfma_f32_16x16x32_bf16 v[62:65], v[148:151], v[180:183], 0
	v_mfma_f32_16x16x32_bf16 v[62:65], v[152:155], v[184:187], v[62:65]
	v_mfma_f32_16x16x32_bf16 v[58:61], v[160:163], v[184:187], 0
	v_mfma_f32_16x16x32_bf16 v[58:61], v[156:159], v[180:183], v[58:61]
	v_mfma_f32_16x16x32_bf16 v[42:45], v[156:159], v[188:191], 0
	v_mfma_f32_16x16x32_bf16 v[42:45], v[160:163], v[192:195], v[42:45]
	v_mfma_f32_16x16x32_bf16 v[46:49], v[152:155], v[192:195], 0
	v_mfma_f32_16x16x32_bf16 v[46:49], v[148:151], v[188:191], v[46:49]
	v_mfma_f32_16x16x32_bf16 v[30:33], v[148:151], v[196:199], 0
	v_mfma_f32_16x16x32_bf16 v[30:33], v[152:155], v[204:207], v[30:33]
	v_mfma_f32_16x16x32_bf16 v[26:29], v[160:163], v[204:207], 0
	v_mfma_f32_16x16x32_bf16 v[26:29], v[156:159], v[196:199], v[26:29]
	v_mfma_f32_16x16x32_bf16 v[10:13], v[156:159], v[212:215], 0
	v_mfma_f32_16x16x32_bf16 v[10:13], v[160:163], v[218:221], v[10:13]
	v_mfma_f32_16x16x32_bf16 v[14:17], v[152:155], v[218:221], 0
	v_mfma_f32_16x16x32_bf16 v[14:17], v[148:151], v[212:215], v[14:17]
	s_setprio 0
	s_setprio 1
	v_mfma_f32_16x16x32_bf16 v[6:9], v[164:167], v[212:215], 0
	v_mfma_f32_16x16x32_bf16 v[6:9], v[168:171], v[218:221], v[6:9]
	v_mfma_f32_16x16x32_bf16 v[2:5], v[176:179], v[218:221], 0
	v_mfma_f32_16x16x32_bf16 v[2:5], v[172:175], v[212:215], v[2:5]
	v_mfma_f32_16x16x32_bf16 v[18:21], v[172:175], v[196:199], 0
	v_mfma_f32_16x16x32_bf16 v[18:21], v[176:179], v[204:207], v[18:21]
	v_mfma_f32_16x16x32_bf16 v[22:25], v[168:171], v[204:207], 0
	v_mfma_f32_16x16x32_bf16 v[22:25], v[164:167], v[196:199], v[22:25]
	v_mfma_f32_16x16x32_bf16 v[38:41], v[164:167], v[188:191], 0
	v_mfma_f32_16x16x32_bf16 v[38:41], v[168:171], v[192:195], v[38:41]
	v_mfma_f32_16x16x32_bf16 v[34:37], v[176:179], v[192:195], 0
	v_mfma_f32_16x16x32_bf16 v[34:37], v[172:175], v[188:191], v[34:37]
	v_mfma_f32_16x16x32_bf16 v[50:53], v[172:175], v[180:183], 0
	v_mfma_f32_16x16x32_bf16 v[50:53], v[176:179], v[184:187], v[50:53]
	v_mfma_f32_16x16x32_bf16 v[54:57], v[168:171], v[184:187], 0
	v_mfma_f32_16x16x32_bf16 v[54:57], v[164:167], v[180:183], v[54:57]
	s_setprio 0
	s_barrier
	v_add_u32_e32 v134, s41, v141
	ds_read_b128 v[148:151], v134
	ds_read_b128 v[152:155], v134 offset:1024
	ds_read_b128 v[156:159], v134 offset:2048
	ds_read_b128 v[160:163], v134 offset:3072
	v_add_u32_e32 v134, s46, v141
	ds_read_b128 v[164:167], v134
	ds_read_b128 v[168:171], v134 offset:1024
	ds_read_b128 v[172:175], v134 offset:2048
	ds_read_b128 v[176:179], v134 offset:3072
	s_add_i32 s61, s61, 0x80000
	s_mov_b32 m0, s39
	v_add_u32_e32 v134, s61, v136
	ds_read_b128 v[180:183], v146 offset:32768
	ds_read_b128 v[184:187], v146 offset:33792
	ds_read_b128 v[188:191], v146 offset:34816
	ds_read_b128 v[192:195], v146 offset:35840
	ds_read_b128 v[196:199], v146 offset:36864
	ds_read_b128 v[204:207], v146 offset:37888
	ds_read_b128 v[212:215], v146 offset:38912
	ds_read_b128 v[218:221], v146 offset:39936
	global_load_lds_dwordx4 v134, s[4:5]
	v_add_u32_e32 v134, s61, v138
	s_mov_b32 m0, s40
	s_nop 0
	global_load_lds_dwordx4 v134, s[4:5]
	s_waitcnt vmcnt(8)
	s_waitcnt lgkmcnt(0)
	s_setprio 1
	s_barrier
	v_mfma_f32_16x16x32_bf16 v[126:129], v[148:151], v[180:183], v[126:129]
	v_mfma_f32_16x16x32_bf16 v[126:129], v[152:155], v[184:187], v[126:129]
	v_mfma_f32_16x16x32_bf16 v[122:125], v[160:163], v[184:187], v[122:125]
	v_mfma_f32_16x16x32_bf16 v[122:125], v[156:159], v[180:183], v[122:125]
	v_mfma_f32_16x16x32_bf16 v[106:109], v[156:159], v[188:191], v[106:109]
	v_mfma_f32_16x16x32_bf16 v[106:109], v[160:163], v[192:195], v[106:109]
	v_mfma_f32_16x16x32_bf16 v[110:113], v[152:155], v[192:195], v[110:113]
	v_mfma_f32_16x16x32_bf16 v[110:113], v[148:151], v[188:191], v[110:113]
	v_mfma_f32_16x16x32_bf16 v[94:97], v[148:151], v[196:199], v[94:97]
	v_mfma_f32_16x16x32_bf16 v[94:97], v[152:155], v[204:207], v[94:97]
	v_mfma_f32_16x16x32_bf16 v[90:93], v[160:163], v[204:207], v[90:93]
	v_mfma_f32_16x16x32_bf16 v[90:93], v[156:159], v[196:199], v[90:93]
	v_mfma_f32_16x16x32_bf16 v[74:77], v[156:159], v[212:215], v[74:77]
	v_mfma_f32_16x16x32_bf16 v[74:77], v[160:163], v[218:221], v[74:77]
	v_mfma_f32_16x16x32_bf16 v[78:81], v[152:155], v[218:221], v[78:81]
	v_mfma_f32_16x16x32_bf16 v[78:81], v[148:151], v[212:215], v[78:81]
	s_setprio 0
	s_setprio 1
	v_mfma_f32_16x16x32_bf16 v[70:73], v[164:167], v[212:215], v[70:73]
	v_mfma_f32_16x16x32_bf16 v[70:73], v[168:171], v[218:221], v[70:73]
	v_mfma_f32_16x16x32_bf16 v[66:69], v[176:179], v[218:221], v[66:69]
	v_mfma_f32_16x16x32_bf16 v[66:69], v[172:175], v[212:215], v[66:69]
	v_mfma_f32_16x16x32_bf16 v[82:85], v[172:175], v[196:199], v[82:85]
	v_mfma_f32_16x16x32_bf16 v[82:85], v[176:179], v[204:207], v[82:85]
	v_mfma_f32_16x16x32_bf16 v[86:89], v[168:171], v[204:207], v[86:89]
	v_mfma_f32_16x16x32_bf16 v[86:89], v[164:167], v[196:199], v[86:89]
	v_mfma_f32_16x16x32_bf16 v[102:105], v[164:167], v[188:191], v[102:105]
	v_mfma_f32_16x16x32_bf16 v[102:105], v[168:171], v[192:195], v[102:105]
	v_mfma_f32_16x16x32_bf16 v[98:101], v[176:179], v[192:195], v[98:101]
	v_mfma_f32_16x16x32_bf16 v[98:101], v[172:175], v[188:191], v[98:101]
	v_mfma_f32_16x16x32_bf16 v[114:117], v[172:175], v[180:183], v[114:117]
	v_mfma_f32_16x16x32_bf16 v[114:117], v[176:179], v[184:187], v[114:117]
	v_mfma_f32_16x16x32_bf16 v[118:121], v[168:171], v[184:187], v[118:121]
	v_mfma_f32_16x16x32_bf16 v[118:121], v[164:167], v[180:183], v[118:121]
	s_setprio 0
	s_barrier
	s_or_b32 s61, s60, 0x80
	s_mov_b32 m0, s42
	v_add_u32_e32 v134, s61, v137
	ds_read_b128 v[180:183], v146 offset:49152
	ds_read_b128 v[184:187], v146 offset:50176
	ds_read_b128 v[188:191], v146 offset:51200
	ds_read_b128 v[192:195], v146 offset:52224
	ds_read_b128 v[196:199], v146 offset:53248
	ds_read_b128 v[204:207], v146 offset:54272
	ds_read_b128 v[212:215], v146 offset:55296
	ds_read_b128 v[218:221], v146 offset:56320
	global_load_lds_dwordx4 v134, s[6:7]
	v_add_u32_e32 v134, s61, v139
	s_mov_b32 m0, s43
	s_add_i32 s60, s60, 0x80080
	global_load_lds_dwordx4 v134, s[6:7]
	v_add_u32_e32 v134, s60, v137
	s_mov_b32 m0, s47
	s_nop 0
	global_load_lds_dwordx4 v134, s[6:7]
	v_add_u32_e32 v134, s60, v139
	s_mov_b32 m0, s48
	s_nop 0
	global_load_lds_dwordx4 v134, s[6:7]
	v_add_u32_e32 v134, s59, v136
	s_mov_b32 m0, s44
	s_nop 0
	global_load_lds_dwordx4 v134, s[4:5]
	v_add_u32_e32 v134, s59, v138
	s_mov_b32 m0, s45
	s_nop 0
	global_load_lds_dwordx4 v134, s[4:5]
	s_waitcnt vmcnt(8)
	s_waitcnt lgkmcnt(0)
	s_setprio 1
	s_barrier
	v_mfma_f32_16x16x32_bf16 v[62:65], v[148:151], v[180:183], v[62:65]
	v_mfma_f32_16x16x32_bf16 v[62:65], v[152:155], v[184:187], v[62:65]
	v_mfma_f32_16x16x32_bf16 v[58:61], v[160:163], v[184:187], v[58:61]
	v_mfma_f32_16x16x32_bf16 v[58:61], v[156:159], v[180:183], v[58:61]
	v_mfma_f32_16x16x32_bf16 v[42:45], v[156:159], v[188:191], v[42:45]
	v_mfma_f32_16x16x32_bf16 v[42:45], v[160:163], v[192:195], v[42:45]
	v_mfma_f32_16x16x32_bf16 v[46:49], v[152:155], v[192:195], v[46:49]
	v_mfma_f32_16x16x32_bf16 v[46:49], v[148:151], v[188:191], v[46:49]
	v_mfma_f32_16x16x32_bf16 v[30:33], v[148:151], v[196:199], v[30:33]
	v_mfma_f32_16x16x32_bf16 v[30:33], v[152:155], v[204:207], v[30:33]
	v_mfma_f32_16x16x32_bf16 v[26:29], v[160:163], v[204:207], v[26:29]
	v_mfma_f32_16x16x32_bf16 v[26:29], v[156:159], v[196:199], v[26:29]
	v_mfma_f32_16x16x32_bf16 v[10:13], v[156:159], v[212:215], v[10:13]
	v_mfma_f32_16x16x32_bf16 v[10:13], v[160:163], v[218:221], v[10:13]
	v_mfma_f32_16x16x32_bf16 v[14:17], v[152:155], v[218:221], v[14:17]
	v_mfma_f32_16x16x32_bf16 v[14:17], v[148:151], v[212:215], v[14:17]
	s_setprio 0
	s_setprio 1
	v_mfma_f32_16x16x32_bf16 v[6:9], v[164:167], v[212:215], v[6:9]
	v_mfma_f32_16x16x32_bf16 v[6:9], v[168:171], v[218:221], v[6:9]
	v_mfma_f32_16x16x32_bf16 v[2:5], v[176:179], v[218:221], v[2:5]
	v_mfma_f32_16x16x32_bf16 v[2:5], v[172:175], v[212:215], v[2:5]
	v_mfma_f32_16x16x32_bf16 v[18:21], v[172:175], v[196:199], v[18:21]
	v_mfma_f32_16x16x32_bf16 v[18:21], v[176:179], v[204:207], v[18:21]
	v_mfma_f32_16x16x32_bf16 v[22:25], v[168:171], v[204:207], v[22:25]
	v_mfma_f32_16x16x32_bf16 v[22:25], v[164:167], v[196:199], v[22:25]
	v_mfma_f32_16x16x32_bf16 v[38:41], v[164:167], v[188:191], v[38:41]
	v_mfma_f32_16x16x32_bf16 v[38:41], v[168:171], v[192:195], v[38:41]
	v_mfma_f32_16x16x32_bf16 v[34:37], v[176:179], v[192:195], v[34:37]
	v_mfma_f32_16x16x32_bf16 v[34:37], v[172:175], v[188:191], v[34:37]
	v_mfma_f32_16x16x32_bf16 v[50:53], v[172:175], v[180:183], v[50:53]
	v_mfma_f32_16x16x32_bf16 v[50:53], v[176:179], v[184:187], v[50:53]
	v_mfma_f32_16x16x32_bf16 v[54:57], v[168:171], v[184:187], v[54:57]
	v_mfma_f32_16x16x32_bf16 v[54:57], v[164:167], v[180:183], v[54:57]
	s_setprio 0
	s_barrier
	s_add_i32 s58, s58, 2
	s_addk_i32 s56, 0x100
	s_addk_i32 s57, 0x100
	v_add_u32_e32 v132, 0x100, v132
	s_cmp_gt_u32 s58, 29
	v_add_u32_e32 v133, 0x100, v133
.LBB0_704:
	v_add_u32_e32 v134, s25, v141
	ds_read_b128 v[148:151], v134
	ds_read_b128 v[152:155], v134 offset:1024
	ds_read_b128 v[156:159], v134 offset:2048
	ds_read_b128 v[160:163], v134 offset:3072
	v_add_u32_e32 v134, s34, v141
	ds_read_b128 v[164:167], v134
	ds_read_b128 v[168:171], v134 offset:1024
	ds_read_b128 v[172:175], v134 offset:2048
	ds_read_b128 v[176:179], v134 offset:3072
	s_cmp_eq_u32 s58, 28
	s_cselect_b32 s61, s54, s57
	s_cselect_b32 s60, s55, s56
	s_or_b32 s59, s61, 0x80
	s_add_i32 m0, s37, 0xc000
	ds_read_b128 v[180:183], v146
	ds_read_b128 v[184:187], v146 offset:1024
	ds_read_b128 v[188:191], v146 offset:2048
	ds_read_b128 v[192:195], v146 offset:3072
	ds_read_b128 v[196:199], v146 offset:4096
	ds_read_b128 v[204:207], v146 offset:5120
	ds_read_b128 v[212:215], v146 offset:6144
	ds_read_b128 v[218:221], v146 offset:7168
	global_load_lds_dwordx4 v133, s[4:5]
	s_add_i32 m0, s37, 0xe000
	s_nop 0
	global_load_lds_dwordx4 v132, s[4:5]
	s_waitcnt vmcnt(8)
	s_waitcnt lgkmcnt(0)
	s_setprio 1
	s_barrier
	v_mfma_f32_16x16x32_bf16 v[126:129], v[148:151], v[180:183], v[126:129]
	v_mfma_f32_16x16x32_bf16 v[126:129], v[152:155], v[184:187], v[126:129]
	v_mfma_f32_16x16x32_bf16 v[122:125], v[160:163], v[184:187], v[122:125]
	v_mfma_f32_16x16x32_bf16 v[122:125], v[156:159], v[180:183], v[122:125]
	v_mfma_f32_16x16x32_bf16 v[106:109], v[156:159], v[188:191], v[106:109]
	v_mfma_f32_16x16x32_bf16 v[106:109], v[160:163], v[192:195], v[106:109]
	v_mfma_f32_16x16x32_bf16 v[110:113], v[152:155], v[192:195], v[110:113]
	v_mfma_f32_16x16x32_bf16 v[110:113], v[148:151], v[188:191], v[110:113]
	v_mfma_f32_16x16x32_bf16 v[94:97], v[148:151], v[196:199], v[94:97]
	v_mfma_f32_16x16x32_bf16 v[94:97], v[152:155], v[204:207], v[94:97]
	v_mfma_f32_16x16x32_bf16 v[90:93], v[160:163], v[204:207], v[90:93]
	v_mfma_f32_16x16x32_bf16 v[90:93], v[156:159], v[196:199], v[90:93]
	v_mfma_f32_16x16x32_bf16 v[74:77], v[156:159], v[212:215], v[74:77]
	v_mfma_f32_16x16x32_bf16 v[74:77], v[160:163], v[218:221], v[74:77]
	v_mfma_f32_16x16x32_bf16 v[78:81], v[152:155], v[218:221], v[78:81]
	v_mfma_f32_16x16x32_bf16 v[78:81], v[148:151], v[212:215], v[78:81]
	s_setprio 0
	s_setprio 1
	v_mfma_f32_16x16x32_bf16 v[70:73], v[164:167], v[212:215], v[70:73]
	v_mfma_f32_16x16x32_bf16 v[70:73], v[168:171], v[218:221], v[70:73]
	v_mfma_f32_16x16x32_bf16 v[66:69], v[176:179], v[218:221], v[66:69]
	v_mfma_f32_16x16x32_bf16 v[66:69], v[172:175], v[212:215], v[66:69]
	v_mfma_f32_16x16x32_bf16 v[82:85], v[172:175], v[196:199], v[82:85]
	v_mfma_f32_16x16x32_bf16 v[82:85], v[176:179], v[204:207], v[82:85]
	v_mfma_f32_16x16x32_bf16 v[86:89], v[168:171], v[204:207], v[86:89]
	v_mfma_f32_16x16x32_bf16 v[86:89], v[164:167], v[196:199], v[86:89]
	v_mfma_f32_16x16x32_bf16 v[102:105], v[164:167], v[188:191], v[102:105]
	v_mfma_f32_16x16x32_bf16 v[102:105], v[168:171], v[192:195], v[102:105]
	v_mfma_f32_16x16x32_bf16 v[98:101], v[176:179], v[192:195], v[98:101]
	v_mfma_f32_16x16x32_bf16 v[98:101], v[172:175], v[188:191], v[98:101]
	v_mfma_f32_16x16x32_bf16 v[114:117], v[172:175], v[180:183], v[114:117]
	v_mfma_f32_16x16x32_bf16 v[114:117], v[176:179], v[184:187], v[114:117]
	v_mfma_f32_16x16x32_bf16 v[118:121], v[168:171], v[184:187], v[118:121]
	v_mfma_f32_16x16x32_bf16 v[118:121], v[164:167], v[180:183], v[118:121]
	s_setprio 0
	s_barrier
	s_mov_b32 m0, s30
	v_add_u32_e32 v134, s60, v137
	ds_read_b128 v[180:183], v146 offset:16384
	ds_read_b128 v[184:187], v146 offset:17408
	ds_read_b128 v[188:191], v146 offset:18432
	ds_read_b128 v[192:195], v146 offset:19456
	ds_read_b128 v[196:199], v146 offset:20480
	ds_read_b128 v[204:207], v146 offset:21504
	ds_read_b128 v[212:215], v146 offset:22528
	ds_read_b128 v[218:221], v146 offset:23552
	global_load_lds_dwordx4 v134, s[6:7]
	v_add_u32_e32 v134, s60, v139
	s_mov_b32 m0, s31
	s_add_i32 s62, s60, 0x80000
	global_load_lds_dwordx4 v134, s[6:7]
	v_add_u32_e32 v134, s62, v137
	s_mov_b32 m0, s35
	s_nop 0
	global_load_lds_dwordx4 v134, s[6:7]
	v_add_u32_e32 v134, s62, v139
	s_mov_b32 m0, s36
	s_nop 0
	global_load_lds_dwordx4 v134, s[6:7]
	v_add_u32_e32 v134, s61, v136
	s_mov_b32 m0, s37
	s_nop 0
	global_load_lds_dwordx4 v134, s[4:5]
	v_add_u32_e32 v134, s61, v138
	s_mov_b32 m0, s38
	s_nop 0
	global_load_lds_dwordx4 v134, s[4:5]
	s_waitcnt vmcnt(8)
	s_waitcnt lgkmcnt(0)
	s_setprio 1
	s_barrier
	v_mfma_f32_16x16x32_bf16 v[62:65], v[148:151], v[180:183], v[62:65]
	v_mfma_f32_16x16x32_bf16 v[62:65], v[152:155], v[184:187], v[62:65]
	v_mfma_f32_16x16x32_bf16 v[58:61], v[160:163], v[184:187], v[58:61]
	v_mfma_f32_16x16x32_bf16 v[58:61], v[156:159], v[180:183], v[58:61]
	v_mfma_f32_16x16x32_bf16 v[42:45], v[156:159], v[188:191], v[42:45]
	v_mfma_f32_16x16x32_bf16 v[42:45], v[160:163], v[192:195], v[42:45]
	v_mfma_f32_16x16x32_bf16 v[46:49], v[152:155], v[192:195], v[46:49]
	v_mfma_f32_16x16x32_bf16 v[46:49], v[148:151], v[188:191], v[46:49]
	v_mfma_f32_16x16x32_bf16 v[30:33], v[148:151], v[196:199], v[30:33]
	v_mfma_f32_16x16x32_bf16 v[30:33], v[152:155], v[204:207], v[30:33]
	v_mfma_f32_16x16x32_bf16 v[26:29], v[160:163], v[204:207], v[26:29]
	v_mfma_f32_16x16x32_bf16 v[26:29], v[156:159], v[196:199], v[26:29]
	v_mfma_f32_16x16x32_bf16 v[10:13], v[156:159], v[212:215], v[10:13]
	v_mfma_f32_16x16x32_bf16 v[10:13], v[160:163], v[218:221], v[10:13]
	v_mfma_f32_16x16x32_bf16 v[14:17], v[152:155], v[218:221], v[14:17]
	v_mfma_f32_16x16x32_bf16 v[14:17], v[148:151], v[212:215], v[14:17]
	s_setprio 0
	s_setprio 1
	v_mfma_f32_16x16x32_bf16 v[6:9], v[164:167], v[212:215], v[6:9]
	v_mfma_f32_16x16x32_bf16 v[6:9], v[168:171], v[218:221], v[6:9]
	v_mfma_f32_16x16x32_bf16 v[2:5], v[176:179], v[218:221], v[2:5]
	v_mfma_f32_16x16x32_bf16 v[2:5], v[172:175], v[212:215], v[2:5]
	v_mfma_f32_16x16x32_bf16 v[18:21], v[172:175], v[196:199], v[18:21]
	v_mfma_f32_16x16x32_bf16 v[18:21], v[176:179], v[204:207], v[18:21]
	v_mfma_f32_16x16x32_bf16 v[22:25], v[168:171], v[204:207], v[22:25]
	v_mfma_f32_16x16x32_bf16 v[22:25], v[164:167], v[196:199], v[22:25]
	v_mfma_f32_16x16x32_bf16 v[38:41], v[164:167], v[188:191], v[38:41]
	v_mfma_f32_16x16x32_bf16 v[38:41], v[168:171], v[192:195], v[38:41]
	v_mfma_f32_16x16x32_bf16 v[34:37], v[176:179], v[192:195], v[34:37]
	v_mfma_f32_16x16x32_bf16 v[34:37], v[172:175], v[188:191], v[34:37]
	v_mfma_f32_16x16x32_bf16 v[50:53], v[172:175], v[180:183], v[50:53]
	v_mfma_f32_16x16x32_bf16 v[50:53], v[176:179], v[184:187], v[50:53]
	v_mfma_f32_16x16x32_bf16 v[54:57], v[168:171], v[184:187], v[54:57]
	v_mfma_f32_16x16x32_bf16 v[54:57], v[164:167], v[180:183], v[54:57]
	s_setprio 0
	s_barrier
	v_add_u32_e32 v134, s41, v141
	ds_read_b128 v[148:151], v134
	ds_read_b128 v[152:155], v134 offset:1024
	ds_read_b128 v[156:159], v134 offset:2048
	ds_read_b128 v[160:163], v134 offset:3072
	v_add_u32_e32 v134, s46, v141
	ds_read_b128 v[164:167], v134
	ds_read_b128 v[168:171], v134 offset:1024
	ds_read_b128 v[172:175], v134 offset:2048
	ds_read_b128 v[176:179], v134 offset:3072
	s_add_i32 s61, s61, 0x80000
	s_mov_b32 m0, s39
	v_add_u32_e32 v134, s61, v136
	ds_read_b128 v[180:183], v146 offset:32768
	ds_read_b128 v[184:187], v146 offset:33792
	ds_read_b128 v[188:191], v146 offset:34816
	ds_read_b128 v[192:195], v146 offset:35840
	ds_read_b128 v[196:199], v146 offset:36864
	ds_read_b128 v[204:207], v146 offset:37888
	ds_read_b128 v[212:215], v146 offset:38912
	ds_read_b128 v[218:221], v146 offset:39936
	global_load_lds_dwordx4 v134, s[4:5]
	v_add_u32_e32 v134, s61, v138
	s_mov_b32 m0, s40
	s_nop 0
	global_load_lds_dwordx4 v134, s[4:5]
	s_waitcnt vmcnt(8)
	s_waitcnt lgkmcnt(0)
	s_setprio 1
	s_barrier
	v_mfma_f32_16x16x32_bf16 v[126:129], v[148:151], v[180:183], v[126:129]
	v_mfma_f32_16x16x32_bf16 v[126:129], v[152:155], v[184:187], v[126:129]
	v_mfma_f32_16x16x32_bf16 v[122:125], v[160:163], v[184:187], v[122:125]
	v_mfma_f32_16x16x32_bf16 v[122:125], v[156:159], v[180:183], v[122:125]
	v_mfma_f32_16x16x32_bf16 v[106:109], v[156:159], v[188:191], v[106:109]
	v_mfma_f32_16x16x32_bf16 v[106:109], v[160:163], v[192:195], v[106:109]
	v_mfma_f32_16x16x32_bf16 v[110:113], v[152:155], v[192:195], v[110:113]
	v_mfma_f32_16x16x32_bf16 v[110:113], v[148:151], v[188:191], v[110:113]
	v_mfma_f32_16x16x32_bf16 v[94:97], v[148:151], v[196:199], v[94:97]
	v_mfma_f32_16x16x32_bf16 v[94:97], v[152:155], v[204:207], v[94:97]
	v_mfma_f32_16x16x32_bf16 v[90:93], v[160:163], v[204:207], v[90:93]
	v_mfma_f32_16x16x32_bf16 v[90:93], v[156:159], v[196:199], v[90:93]
	v_mfma_f32_16x16x32_bf16 v[74:77], v[156:159], v[212:215], v[74:77]
	v_mfma_f32_16x16x32_bf16 v[74:77], v[160:163], v[218:221], v[74:77]
	v_mfma_f32_16x16x32_bf16 v[78:81], v[152:155], v[218:221], v[78:81]
	v_mfma_f32_16x16x32_bf16 v[78:81], v[148:151], v[212:215], v[78:81]
	s_setprio 0
	s_setprio 1
	v_mfma_f32_16x16x32_bf16 v[70:73], v[164:167], v[212:215], v[70:73]
	v_mfma_f32_16x16x32_bf16 v[70:73], v[168:171], v[218:221], v[70:73]
	v_mfma_f32_16x16x32_bf16 v[66:69], v[176:179], v[218:221], v[66:69]
	v_mfma_f32_16x16x32_bf16 v[66:69], v[172:175], v[212:215], v[66:69]
	v_mfma_f32_16x16x32_bf16 v[82:85], v[172:175], v[196:199], v[82:85]
	v_mfma_f32_16x16x32_bf16 v[82:85], v[176:179], v[204:207], v[82:85]
	v_mfma_f32_16x16x32_bf16 v[86:89], v[168:171], v[204:207], v[86:89]
	v_mfma_f32_16x16x32_bf16 v[86:89], v[164:167], v[196:199], v[86:89]
	v_mfma_f32_16x16x32_bf16 v[102:105], v[164:167], v[188:191], v[102:105]
	v_mfma_f32_16x16x32_bf16 v[102:105], v[168:171], v[192:195], v[102:105]
	v_mfma_f32_16x16x32_bf16 v[98:101], v[176:179], v[192:195], v[98:101]
	v_mfma_f32_16x16x32_bf16 v[98:101], v[172:175], v[188:191], v[98:101]
	v_mfma_f32_16x16x32_bf16 v[114:117], v[172:175], v[180:183], v[114:117]
	v_mfma_f32_16x16x32_bf16 v[114:117], v[176:179], v[184:187], v[114:117]
	v_mfma_f32_16x16x32_bf16 v[118:121], v[168:171], v[184:187], v[118:121]
	v_mfma_f32_16x16x32_bf16 v[118:121], v[164:167], v[180:183], v[118:121]
	s_setprio 0
	s_barrier
	s_or_b32 s61, s60, 0x80
	s_mov_b32 m0, s42
	v_add_u32_e32 v134, s61, v137
	ds_read_b128 v[180:183], v146 offset:49152
	ds_read_b128 v[184:187], v146 offset:50176
	ds_read_b128 v[188:191], v146 offset:51200
	ds_read_b128 v[192:195], v146 offset:52224
	ds_read_b128 v[196:199], v146 offset:53248
	ds_read_b128 v[204:207], v146 offset:54272
	ds_read_b128 v[212:215], v146 offset:55296
	ds_read_b128 v[218:221], v146 offset:56320
	global_load_lds_dwordx4 v134, s[6:7]
	v_add_u32_e32 v134, s61, v139
	s_mov_b32 m0, s43
	s_add_i32 s60, s60, 0x80080
	global_load_lds_dwordx4 v134, s[6:7]
	v_add_u32_e32 v134, s60, v137
	s_mov_b32 m0, s47
	s_nop 0
	global_load_lds_dwordx4 v134, s[6:7]
	v_add_u32_e32 v134, s60, v139
	s_mov_b32 m0, s48
	s_nop 0
	global_load_lds_dwordx4 v134, s[6:7]
	v_add_u32_e32 v134, s59, v136
	s_mov_b32 m0, s44
	s_nop 0
	global_load_lds_dwordx4 v134, s[4:5]
	v_add_u32_e32 v134, s59, v138
	s_mov_b32 m0, s45
	s_nop 0
	global_load_lds_dwordx4 v134, s[4:5]
	s_add_i32 s58, s58, 2
	s_addk_i32 s56, 0x100
	s_addk_i32 s57, 0x100
	v_add_u32_e32 v132, 0x100, v132
	s_cmp_gt_u32 s58, 29
	v_add_u32_e32 v133, 0x100, v133
	s_waitcnt vmcnt(8)
	s_waitcnt lgkmcnt(0)
	s_setprio 1
	s_barrier
	v_mfma_f32_16x16x32_bf16 v[62:65], v[148:151], v[180:183], v[62:65]
	v_mfma_f32_16x16x32_bf16 v[62:65], v[152:155], v[184:187], v[62:65]
	v_mfma_f32_16x16x32_bf16 v[58:61], v[160:163], v[184:187], v[58:61]
	v_mfma_f32_16x16x32_bf16 v[58:61], v[156:159], v[180:183], v[58:61]
	v_mfma_f32_16x16x32_bf16 v[42:45], v[156:159], v[188:191], v[42:45]
	v_mfma_f32_16x16x32_bf16 v[42:45], v[160:163], v[192:195], v[42:45]
	v_mfma_f32_16x16x32_bf16 v[46:49], v[152:155], v[192:195], v[46:49]
	v_mfma_f32_16x16x32_bf16 v[46:49], v[148:151], v[188:191], v[46:49]
	v_mfma_f32_16x16x32_bf16 v[30:33], v[148:151], v[196:199], v[30:33]
	v_mfma_f32_16x16x32_bf16 v[30:33], v[152:155], v[204:207], v[30:33]
	v_mfma_f32_16x16x32_bf16 v[26:29], v[160:163], v[204:207], v[26:29]
	v_mfma_f32_16x16x32_bf16 v[26:29], v[156:159], v[196:199], v[26:29]
	v_mfma_f32_16x16x32_bf16 v[10:13], v[156:159], v[212:215], v[10:13]
	v_mfma_f32_16x16x32_bf16 v[10:13], v[160:163], v[218:221], v[10:13]
	v_mfma_f32_16x16x32_bf16 v[14:17], v[152:155], v[218:221], v[14:17]
	v_mfma_f32_16x16x32_bf16 v[14:17], v[148:151], v[212:215], v[14:17]
	s_setprio 0
	s_setprio 1
	v_mfma_f32_16x16x32_bf16 v[6:9], v[164:167], v[212:215], v[6:9]
	v_mfma_f32_16x16x32_bf16 v[6:9], v[168:171], v[218:221], v[6:9]
	v_mfma_f32_16x16x32_bf16 v[2:5], v[176:179], v[218:221], v[2:5]
	v_mfma_f32_16x16x32_bf16 v[2:5], v[172:175], v[212:215], v[2:5]
	v_mfma_f32_16x16x32_bf16 v[18:21], v[172:175], v[196:199], v[18:21]
	v_mfma_f32_16x16x32_bf16 v[18:21], v[176:179], v[204:207], v[18:21]
	v_mfma_f32_16x16x32_bf16 v[22:25], v[168:171], v[204:207], v[22:25]
	v_mfma_f32_16x16x32_bf16 v[22:25], v[164:167], v[196:199], v[22:25]
	v_mfma_f32_16x16x32_bf16 v[38:41], v[164:167], v[188:191], v[38:41]
	v_mfma_f32_16x16x32_bf16 v[38:41], v[168:171], v[192:195], v[38:41]
	v_mfma_f32_16x16x32_bf16 v[34:37], v[176:179], v[192:195], v[34:37]
	v_mfma_f32_16x16x32_bf16 v[34:37], v[172:175], v[188:191], v[34:37]
	v_mfma_f32_16x16x32_bf16 v[50:53], v[172:175], v[180:183], v[50:53]
	v_mfma_f32_16x16x32_bf16 v[50:53], v[176:179], v[184:187], v[50:53]
	v_mfma_f32_16x16x32_bf16 v[54:57], v[168:171], v[184:187], v[54:57]
	v_mfma_f32_16x16x32_bf16 v[54:57], v[164:167], v[180:183], v[54:57]
	s_setprio 0
	s_barrier
	s_cbranch_scc0 .LBB0_704
	s_and_b64 vcc, exec, s[16:17]
	s_cbranch_vccz .LBB0_707
	s_barrier

.LBB0_724:
	v_lshrrev_b32_e32 v9, 1, v5
	v_and_b32_e32 v135, 24, v9
	v_and_b32_e32 v136, 15, v5
	v_lshlrev_b32_e32 v9, 1, v135
	v_lshlrev_b32_e32 v5, 2, v5
	s_lshl_b32 s27, s27, 5
	s_lshl_b32 s26, s29, 6
	v_lshl_or_b32 v9, v136, 6, v9
	s_lshl_b32 s29, s29, 13
	v_and_b32_e32 v5, 32, v5
	s_and_b32 s27, s27, 0x60
	v_bitop3_b32 v10, v9, s29, v5 bitop3:0xde
	s_lshl_b32 s29, s27, 7
	v_bitop3_b32 v137, v9, s29, v5 bitop3:0xde
	s_add_i32 s29, s28, 0x18000
	s_or_b32 s31, s12, 0x80
	s_add_i32 s30, s29, s37
	v_add_u32_e32 v5, s31, v131
	s_mov_b32 m0, s30
	s_waitcnt vmcnt(2)
	s_barrier
	global_load_lds_dwordx4 v5, s[6:7]
	v_add_u32_e32 v5, s31, v133
	s_add_i32 s31, s30, 0x2000
	s_mov_b32 m0, s31
	s_or_b32 s35, s21, 0x80
	s_add_i32 s34, s22, 0x8000
	global_load_lds_dwordx4 v5, s[6:7]
	v_add_u32_e32 v5, s35, v130
	s_mov_b32 m0, s34
	s_add_i32 s36, s28, 0x1c000
	global_load_lds_dwordx4 v5, s[4:5]
	v_add_u32_e32 v5, s35, v132
	s_add_i32 s35, s22, 0xa000
	s_mov_b32 m0, s35
	s_or_b32 s38, s12, 0x80080
	s_add_i32 s37, s36, s37
	global_load_lds_dwordx4 v5, s[4:5]
	v_add_u32_e32 v5, s38, v131
	s_mov_b32 m0, s37
	s_add_i32 s39, s21, 0x80080
	global_load_lds_dwordx4 v5, s[6:7]
	v_add_u32_e32 v5, s38, v133
	s_add_i32 s38, s37, 0x2000
	s_mov_b32 m0, s38
	v_lshlrev_b32_e32 v7, 12, v7
	global_load_lds_dwordx4 v5, s[6:7]
	v_lshlrev_b32_e32 v5, 15, v6
	v_and_b32_e32 v5, 0xffff0000, v5
	v_and_b32_e32 v6, 1, v6
	v_add3_u32 v5, s39, v5, v7
	v_lshlrev_b32_e32 v6, 6, v6
	v_lshlrev_b32_e32 v7, 1, v8
	v_add3_u32 v138, v5, v6, v7
	v_lshlrev_b32_e32 v5, 15, v2
	v_and_b32_e32 v5, 0xffff0000, v5
	v_lshlrev_b32_e32 v3, 12, v3
	v_and_b32_e32 v2, 1, v2
	s_waitcnt vmcnt(6)
	v_add3_u32 v3, s39, v5, v3
	v_lshlrev_b32_e32 v2, 6, v2
	v_lshlrev_b32_e32 v4, 1, v4
	v_add3_u32 v139, v3, v2, v4
	v_or_b32_e32 v134, s26, v136
	s_mov_b32 s39, -2
	s_mov_b32 s40, 0
	v_add_u32_e32 v140, s28, v10
	s_barrier
	v_add_u32_e32 v141, s13, v137
	ds_read_b128 v[142:145], v141
	ds_read_b128 v[146:149], v141 offset:1024
	ds_read_b128 v[150:153], v141 offset:2048
	ds_read_b128 v[154:157], v141 offset:3072
	v_add_u32_e32 v141, s16, v137
	ds_read_b128 v[158:161], v141
	ds_read_b128 v[162:165], v141 offset:1024
	ds_read_b128 v[166:169], v141 offset:2048
	ds_read_b128 v[170:173], v141 offset:3072
	s_add_i32 s41, s40, 0x100
	s_cmp_lg_u32 s39, 28
	s_cselect_b32 s43, s41, 0
	s_add_i32 s44, s43, s21
	s_or_b32 s42, s44, 0x80
	s_add_i32 s43, s43, s12
	v_add_u32_e32 v141, s40, v139
	s_add_i32 m0, s22, 0xc000
	ds_read_b128 v[174:177], v140
	ds_read_b128 v[178:181], v140 offset:1024
	ds_read_b128 v[182:185], v140 offset:2048
	ds_read_b128 v[186:189], v140 offset:3072
	ds_read_b128 v[190:193], v140 offset:4096
	ds_read_b128 v[194:197], v140 offset:5120
	ds_read_b128 v[198:201], v140 offset:6144
	ds_read_b128 v[204:207], v140 offset:7168
	global_load_lds_dwordx4 v141, s[4:5]
	v_add_u32_e32 v141, s40, v138
	s_add_i32 m0, s22, 0xe000
	s_nop 0
	global_load_lds_dwordx4 v141, s[4:5]
	s_waitcnt vmcnt(8)
	s_waitcnt lgkmcnt(0)
	s_setprio 1
	s_barrier
	v_mfma_f32_16x16x32_bf16 v[126:129], v[142:145], v[174:177], 0
	v_mfma_f32_16x16x32_bf16 v[126:129], v[146:149], v[178:181], v[126:129]
	v_mfma_f32_16x16x32_bf16 v[122:125], v[154:157], v[178:181], 0
	v_mfma_f32_16x16x32_bf16 v[122:125], v[150:153], v[174:177], v[122:125]
	v_mfma_f32_16x16x32_bf16 v[106:109], v[150:153], v[182:185], 0
	v_mfma_f32_16x16x32_bf16 v[106:109], v[154:157], v[186:189], v[106:109]
	v_mfma_f32_16x16x32_bf16 v[110:113], v[146:149], v[186:189], 0
	v_mfma_f32_16x16x32_bf16 v[110:113], v[142:145], v[182:185], v[110:113]
	v_mfma_f32_16x16x32_bf16 v[94:97], v[142:145], v[190:193], 0
	v_mfma_f32_16x16x32_bf16 v[94:97], v[146:149], v[194:197], v[94:97]
	v_mfma_f32_16x16x32_bf16 v[90:93], v[154:157], v[194:197], 0
	v_mfma_f32_16x16x32_bf16 v[90:93], v[150:153], v[190:193], v[90:93]
	v_mfma_f32_16x16x32_bf16 v[74:77], v[150:153], v[198:201], 0
	v_mfma_f32_16x16x32_bf16 v[74:77], v[154:157], v[204:207], v[74:77]
	v_mfma_f32_16x16x32_bf16 v[78:81], v[146:149], v[204:207], 0
	v_mfma_f32_16x16x32_bf16 v[78:81], v[142:145], v[198:201], v[78:81]
	s_setprio 0
	s_setprio 1
	v_mfma_f32_16x16x32_bf16 v[70:73], v[158:161], v[198:201], 0
	v_mfma_f32_16x16x32_bf16 v[70:73], v[162:165], v[204:207], v[70:73]
	v_mfma_f32_16x16x32_bf16 v[66:69], v[170:173], v[204:207], 0
	v_mfma_f32_16x16x32_bf16 v[66:69], v[166:169], v[198:201], v[66:69]
	v_mfma_f32_16x16x32_bf16 v[82:85], v[166:169], v[190:193], 0
	v_mfma_f32_16x16x32_bf16 v[82:85], v[170:173], v[194:197], v[82:85]
	v_mfma_f32_16x16x32_bf16 v[86:89], v[162:165], v[194:197], 0
	v_mfma_f32_16x16x32_bf16 v[86:89], v[158:161], v[190:193], v[86:89]
	v_mfma_f32_16x16x32_bf16 v[102:105], v[158:161], v[182:185], 0
	v_mfma_f32_16x16x32_bf16 v[102:105], v[162:165], v[186:189], v[102:105]
	v_mfma_f32_16x16x32_bf16 v[98:101], v[170:173], v[186:189], 0
	v_mfma_f32_16x16x32_bf16 v[98:101], v[166:169], v[182:185], v[98:101]
	v_mfma_f32_16x16x32_bf16 v[114:117], v[166:169], v[174:177], 0
	v_mfma_f32_16x16x32_bf16 v[114:117], v[170:173], v[178:181], v[114:117]
	v_mfma_f32_16x16x32_bf16 v[118:121], v[162:165], v[178:181], 0
	v_mfma_f32_16x16x32_bf16 v[118:121], v[158:161], v[174:177], v[118:121]
	s_setprio 0
	s_barrier
	s_mov_b32 m0, s14
	v_add_u32_e32 v141, s43, v131
	ds_read_b128 v[174:177], v140 offset:16384
	ds_read_b128 v[178:181], v140 offset:17408
	ds_read_b128 v[182:185], v140 offset:18432
	ds_read_b128 v[186:189], v140 offset:19456
	ds_read_b128 v[190:193], v140 offset:20480
	ds_read_b128 v[194:197], v140 offset:21504
	ds_read_b128 v[198:201], v140 offset:22528
	ds_read_b128 v[204:207], v140 offset:23552
	global_load_lds_dwordx4 v141, s[6:7]
	v_add_u32_e32 v141, s43, v133
	s_mov_b32 m0, s15
	s_add_i32 s40, s43, 0x80000
	global_load_lds_dwordx4 v141, s[6:7]
	v_add_u32_e32 v141, s40, v131
	s_mov_b32 m0, s17
	s_nop 0
	global_load_lds_dwordx4 v141, s[6:7]
	v_add_u32_e32 v141, s40, v133
	s_mov_b32 m0, s20
	s_nop 0
	global_load_lds_dwordx4 v141, s[6:7]
	v_add_u32_e32 v141, s44, v130
	s_mov_b32 m0, s22
	s_nop 0
	global_load_lds_dwordx4 v141, s[4:5]
	v_add_u32_e32 v141, s44, v132
	s_mov_b32 m0, s23
	s_nop 0
	global_load_lds_dwordx4 v141, s[4:5]
	s_waitcnt vmcnt(8)
	s_waitcnt lgkmcnt(0)
	s_setprio 1
	s_barrier
	v_mfma_f32_16x16x32_bf16 v[62:65], v[142:145], v[174:177], 0
	v_mfma_f32_16x16x32_bf16 v[62:65], v[146:149], v[178:181], v[62:65]
	v_mfma_f32_16x16x32_bf16 v[58:61], v[154:157], v[178:181], 0
	v_mfma_f32_16x16x32_bf16 v[58:61], v[150:153], v[174:177], v[58:61]
	v_mfma_f32_16x16x32_bf16 v[42:45], v[150:153], v[182:185], 0
	v_mfma_f32_16x16x32_bf16 v[42:45], v[154:157], v[186:189], v[42:45]
	v_mfma_f32_16x16x32_bf16 v[46:49], v[146:149], v[186:189], 0
	v_mfma_f32_16x16x32_bf16 v[46:49], v[142:145], v[182:185], v[46:49]
	v_mfma_f32_16x16x32_bf16 v[30:33], v[142:145], v[190:193], 0
	v_mfma_f32_16x16x32_bf16 v[30:33], v[146:149], v[194:197], v[30:33]
	v_mfma_f32_16x16x32_bf16 v[26:29], v[154:157], v[194:197], 0
	v_mfma_f32_16x16x32_bf16 v[26:29], v[150:153], v[190:193], v[26:29]
	v_mfma_f32_16x16x32_bf16 v[10:13], v[150:153], v[198:201], 0
	v_mfma_f32_16x16x32_bf16 v[10:13], v[154:157], v[204:207], v[10:13]
	v_mfma_f32_16x16x32_bf16 v[14:17], v[146:149], v[204:207], 0
	v_mfma_f32_16x16x32_bf16 v[14:17], v[142:145], v[198:201], v[14:17]
	s_setprio 0
	s_setprio 1
	v_mfma_f32_16x16x32_bf16 v[6:9], v[158:161], v[198:201], 0
	v_mfma_f32_16x16x32_bf16 v[6:9], v[162:165], v[204:207], v[6:9]
	v_mfma_f32_16x16x32_bf16 v[2:5], v[170:173], v[204:207], 0
	v_mfma_f32_16x16x32_bf16 v[2:5], v[166:169], v[198:201], v[2:5]
	v_mfma_f32_16x16x32_bf16 v[18:21], v[166:169], v[190:193], 0
	v_mfma_f32_16x16x32_bf16 v[18:21], v[170:173], v[194:197], v[18:21]
	v_mfma_f32_16x16x32_bf16 v[22:25], v[162:165], v[194:197], 0
	v_mfma_f32_16x16x32_bf16 v[22:25], v[158:161], v[190:193], v[22:25]
	v_mfma_f32_16x16x32_bf16 v[38:41], v[158:161], v[182:185], 0
	v_mfma_f32_16x16x32_bf16 v[38:41], v[162:165], v[186:189], v[38:41]
	v_mfma_f32_16x16x32_bf16 v[34:37], v[170:173], v[186:189], 0
	v_mfma_f32_16x16x32_bf16 v[34:37], v[166:169], v[182:185], v[34:37]
	v_mfma_f32_16x16x32_bf16 v[50:53], v[166:169], v[174:177], 0
	v_mfma_f32_16x16x32_bf16 v[50:53], v[170:173], v[178:181], v[50:53]
	v_mfma_f32_16x16x32_bf16 v[54:57], v[162:165], v[178:181], 0
	v_mfma_f32_16x16x32_bf16 v[54:57], v[158:161], v[174:177], v[54:57]
	s_setprio 0
	s_barrier
	v_add_u32_e32 v141, s29, v137
	ds_read_b128 v[142:145], v141
	ds_read_b128 v[146:149], v141 offset:1024
	ds_read_b128 v[150:153], v141 offset:2048
	ds_read_b128 v[154:157], v141 offset:3072
	v_add_u32_e32 v141, s36, v137
	ds_read_b128 v[158:161], v141
	ds_read_b128 v[162:165], v141 offset:1024
	ds_read_b128 v[166:169], v141 offset:2048
	ds_read_b128 v[170:173], v141 offset:3072
	s_add_i32 s44, s44, 0x80000
	s_mov_b32 m0, s24
	v_add_u32_e32 v141, s44, v130
	ds_read_b128 v[174:177], v140 offset:32768
	ds_read_b128 v[178:181], v140 offset:33792
	ds_read_b128 v[182:185], v140 offset:34816
	ds_read_b128 v[186:189], v140 offset:35840
	ds_read_b128 v[190:193], v140 offset:36864
	ds_read_b128 v[194:197], v140 offset:37888
	ds_read_b128 v[198:201], v140 offset:38912
	ds_read_b128 v[204:207], v140 offset:39936
	global_load_lds_dwordx4 v141, s[4:5]
	v_add_u32_e32 v141, s44, v132
	s_mov_b32 m0, s25
	s_nop 0
	global_load_lds_dwordx4 v141, s[4:5]
	s_waitcnt vmcnt(8)
	s_waitcnt lgkmcnt(0)
	s_setprio 1
	s_barrier
	v_mfma_f32_16x16x32_bf16 v[126:129], v[142:145], v[174:177], v[126:129]
	v_mfma_f32_16x16x32_bf16 v[126:129], v[146:149], v[178:181], v[126:129]
	v_mfma_f32_16x16x32_bf16 v[122:125], v[154:157], v[178:181], v[122:125]
	v_mfma_f32_16x16x32_bf16 v[122:125], v[150:153], v[174:177], v[122:125]
	v_mfma_f32_16x16x32_bf16 v[106:109], v[150:153], v[182:185], v[106:109]
	v_mfma_f32_16x16x32_bf16 v[106:109], v[154:157], v[186:189], v[106:109]
	v_mfma_f32_16x16x32_bf16 v[110:113], v[146:149], v[186:189], v[110:113]
	v_mfma_f32_16x16x32_bf16 v[110:113], v[142:145], v[182:185], v[110:113]
	v_mfma_f32_16x16x32_bf16 v[94:97], v[142:145], v[190:193], v[94:97]
	v_mfma_f32_16x16x32_bf16 v[94:97], v[146:149], v[194:197], v[94:97]
	v_mfma_f32_16x16x32_bf16 v[90:93], v[154:157], v[194:197], v[90:93]
	v_mfma_f32_16x16x32_bf16 v[90:93], v[150:153], v[190:193], v[90:93]
	v_mfma_f32_16x16x32_bf16 v[74:77], v[150:153], v[198:201], v[74:77]
	v_mfma_f32_16x16x32_bf16 v[74:77], v[154:157], v[204:207], v[74:77]
	v_mfma_f32_16x16x32_bf16 v[78:81], v[146:149], v[204:207], v[78:81]
	v_mfma_f32_16x16x32_bf16 v[78:81], v[142:145], v[198:201], v[78:81]
	s_setprio 0
	s_setprio 1
	v_mfma_f32_16x16x32_bf16 v[70:73], v[158:161], v[198:201], v[70:73]
	v_mfma_f32_16x16x32_bf16 v[70:73], v[162:165], v[204:207], v[70:73]
	v_mfma_f32_16x16x32_bf16 v[66:69], v[170:173], v[204:207], v[66:69]
	v_mfma_f32_16x16x32_bf16 v[66:69], v[166:169], v[198:201], v[66:69]
	v_mfma_f32_16x16x32_bf16 v[82:85], v[166:169], v[190:193], v[82:85]
	v_mfma_f32_16x16x32_bf16 v[82:85], v[170:173], v[194:197], v[82:85]
	v_mfma_f32_16x16x32_bf16 v[86:89], v[162:165], v[194:197], v[86:89]
	v_mfma_f32_16x16x32_bf16 v[86:89], v[158:161], v[190:193], v[86:89]
	v_mfma_f32_16x16x32_bf16 v[102:105], v[158:161], v[182:185], v[102:105]
	v_mfma_f32_16x16x32_bf16 v[102:105], v[162:165], v[186:189], v[102:105]
	v_mfma_f32_16x16x32_bf16 v[98:101], v[170:173], v[186:189], v[98:101]
	v_mfma_f32_16x16x32_bf16 v[98:101], v[166:169], v[182:185], v[98:101]
	v_mfma_f32_16x16x32_bf16 v[114:117], v[166:169], v[174:177], v[114:117]
	v_mfma_f32_16x16x32_bf16 v[114:117], v[170:173], v[178:181], v[114:117]
	v_mfma_f32_16x16x32_bf16 v[118:121], v[162:165], v[178:181], v[118:121]
	v_mfma_f32_16x16x32_bf16 v[118:121], v[158:161], v[174:177], v[118:121]
	s_setprio 0
	s_barrier
	s_or_b32 s40, s43, 0x80
	s_mov_b32 m0, s30
	v_add_u32_e32 v141, s40, v131
	ds_read_b128 v[174:177], v140 offset:49152
	ds_read_b128 v[178:181], v140 offset:50176
	ds_read_b128 v[182:185], v140 offset:51200
	ds_read_b128 v[186:189], v140 offset:52224
	ds_read_b128 v[190:193], v140 offset:53248
	ds_read_b128 v[194:197], v140 offset:54272
	ds_read_b128 v[198:201], v140 offset:55296
	ds_read_b128 v[204:207], v140 offset:56320
	global_load_lds_dwordx4 v141, s[6:7]
	v_add_u32_e32 v141, s40, v133
	s_mov_b32 m0, s31
	s_add_i32 s43, s43, 0x80080
	global_load_lds_dwordx4 v141, s[6:7]
	v_add_u32_e32 v141, s43, v131
	s_mov_b32 m0, s37
	s_nop 0
	global_load_lds_dwordx4 v141, s[6:7]
	v_add_u32_e32 v141, s43, v133
	s_mov_b32 m0, s38
	s_nop 0
	global_load_lds_dwordx4 v141, s[6:7]
	v_add_u32_e32 v141, s42, v130
	s_mov_b32 m0, s34
	s_nop 0
	global_load_lds_dwordx4 v141, s[4:5]
	v_add_u32_e32 v141, s42, v132
	s_mov_b32 m0, s35
	s_nop 0
	global_load_lds_dwordx4 v141, s[4:5]
	s_waitcnt vmcnt(8)
	s_waitcnt lgkmcnt(0)
	s_setprio 1
	s_barrier
	v_mfma_f32_16x16x32_bf16 v[62:65], v[142:145], v[174:177], v[62:65]
	v_mfma_f32_16x16x32_bf16 v[62:65], v[146:149], v[178:181], v[62:65]
	v_mfma_f32_16x16x32_bf16 v[58:61], v[154:157], v[178:181], v[58:61]
	v_mfma_f32_16x16x32_bf16 v[58:61], v[150:153], v[174:177], v[58:61]
	v_mfma_f32_16x16x32_bf16 v[42:45], v[150:153], v[182:185], v[42:45]
	v_mfma_f32_16x16x32_bf16 v[42:45], v[154:157], v[186:189], v[42:45]
	v_mfma_f32_16x16x32_bf16 v[46:49], v[146:149], v[186:189], v[46:49]
	v_mfma_f32_16x16x32_bf16 v[46:49], v[142:145], v[182:185], v[46:49]
	v_mfma_f32_16x16x32_bf16 v[30:33], v[142:145], v[190:193], v[30:33]
	v_mfma_f32_16x16x32_bf16 v[30:33], v[146:149], v[194:197], v[30:33]
	v_mfma_f32_16x16x32_bf16 v[26:29], v[154:157], v[194:197], v[26:29]
	v_mfma_f32_16x16x32_bf16 v[26:29], v[150:153], v[190:193], v[26:29]
	v_mfma_f32_16x16x32_bf16 v[10:13], v[150:153], v[198:201], v[10:13]
	v_mfma_f32_16x16x32_bf16 v[10:13], v[154:157], v[204:207], v[10:13]
	v_mfma_f32_16x16x32_bf16 v[14:17], v[146:149], v[204:207], v[14:17]
	v_mfma_f32_16x16x32_bf16 v[14:17], v[142:145], v[198:201], v[14:17]
	s_setprio 0
	s_setprio 1
	v_mfma_f32_16x16x32_bf16 v[6:9], v[158:161], v[198:201], v[6:9]
	v_mfma_f32_16x16x32_bf16 v[6:9], v[162:165], v[204:207], v[6:9]
	v_mfma_f32_16x16x32_bf16 v[2:5], v[170:173], v[204:207], v[2:5]
	v_mfma_f32_16x16x32_bf16 v[2:5], v[166:169], v[198:201], v[2:5]
	v_mfma_f32_16x16x32_bf16 v[18:21], v[166:169], v[190:193], v[18:21]
	v_mfma_f32_16x16x32_bf16 v[18:21], v[170:173], v[194:197], v[18:21]
	v_mfma_f32_16x16x32_bf16 v[22:25], v[162:165], v[194:197], v[22:25]
	v_mfma_f32_16x16x32_bf16 v[22:25], v[158:161], v[190:193], v[22:25]
	v_mfma_f32_16x16x32_bf16 v[38:41], v[158:161], v[182:185], v[38:41]
	v_mfma_f32_16x16x32_bf16 v[38:41], v[162:165], v[186:189], v[38:41]
	v_mfma_f32_16x16x32_bf16 v[34:37], v[170:173], v[186:189], v[34:37]
	v_mfma_f32_16x16x32_bf16 v[34:37], v[166:169], v[182:185], v[34:37]
	v_mfma_f32_16x16x32_bf16 v[50:53], v[166:169], v[174:177], v[50:53]
	v_mfma_f32_16x16x32_bf16 v[50:53], v[170:173], v[178:181], v[50:53]
	v_mfma_f32_16x16x32_bf16 v[54:57], v[162:165], v[178:181], v[54:57]
	v_mfma_f32_16x16x32_bf16 v[54:57], v[158:161], v[174:177], v[54:57]
	s_setprio 0
	s_barrier
	s_add_i32 s39, s39, 2
	s_cmp_gt_u32 s39, 29
	s_mov_b32 s40, s41
.LBB0_725:
	v_add_u32_e32 v141, s13, v137
	ds_read_b128 v[142:145], v141
	ds_read_b128 v[146:149], v141 offset:1024
	ds_read_b128 v[150:153], v141 offset:2048
	ds_read_b128 v[154:157], v141 offset:3072
	v_add_u32_e32 v141, s16, v137
	ds_read_b128 v[158:161], v141
	ds_read_b128 v[162:165], v141 offset:1024
	ds_read_b128 v[166:169], v141 offset:2048
	ds_read_b128 v[170:173], v141 offset:3072
	s_add_i32 s41, s40, 0x100
	s_cmp_lg_u32 s39, 28
	s_cselect_b32 s43, s41, 0
	s_add_i32 s44, s43, s21
	s_or_b32 s42, s44, 0x80
	s_add_i32 s43, s43, s12
	v_add_u32_e32 v141, s40, v139
	s_add_i32 m0, s22, 0xc000
	ds_read_b128 v[174:177], v140
	ds_read_b128 v[178:181], v140 offset:1024
	ds_read_b128 v[182:185], v140 offset:2048
	ds_read_b128 v[186:189], v140 offset:3072
	ds_read_b128 v[190:193], v140 offset:4096
	ds_read_b128 v[194:197], v140 offset:5120
	ds_read_b128 v[198:201], v140 offset:6144
	ds_read_b128 v[204:207], v140 offset:7168
	global_load_lds_dwordx4 v141, s[4:5]
	v_add_u32_e32 v141, s40, v138
	s_add_i32 m0, s22, 0xe000
	s_nop 0
	global_load_lds_dwordx4 v141, s[4:5]
	s_waitcnt vmcnt(8)
	s_waitcnt lgkmcnt(0)
	s_setprio 1
	s_barrier
	v_mfma_f32_16x16x32_bf16 v[126:129], v[142:145], v[174:177], v[126:129]
	v_mfma_f32_16x16x32_bf16 v[126:129], v[146:149], v[178:181], v[126:129]
	v_mfma_f32_16x16x32_bf16 v[122:125], v[154:157], v[178:181], v[122:125]
	v_mfma_f32_16x16x32_bf16 v[122:125], v[150:153], v[174:177], v[122:125]
	v_mfma_f32_16x16x32_bf16 v[106:109], v[150:153], v[182:185], v[106:109]
	v_mfma_f32_16x16x32_bf16 v[106:109], v[154:157], v[186:189], v[106:109]
	v_mfma_f32_16x16x32_bf16 v[110:113], v[146:149], v[186:189], v[110:113]
	v_mfma_f32_16x16x32_bf16 v[110:113], v[142:145], v[182:185], v[110:113]
	v_mfma_f32_16x16x32_bf16 v[94:97], v[142:145], v[190:193], v[94:97]
	v_mfma_f32_16x16x32_bf16 v[94:97], v[146:149], v[194:197], v[94:97]
	v_mfma_f32_16x16x32_bf16 v[90:93], v[154:157], v[194:197], v[90:93]
	v_mfma_f32_16x16x32_bf16 v[90:93], v[150:153], v[190:193], v[90:93]
	v_mfma_f32_16x16x32_bf16 v[74:77], v[150:153], v[198:201], v[74:77]
	v_mfma_f32_16x16x32_bf16 v[74:77], v[154:157], v[204:207], v[74:77]
	v_mfma_f32_16x16x32_bf16 v[78:81], v[146:149], v[204:207], v[78:81]
	v_mfma_f32_16x16x32_bf16 v[78:81], v[142:145], v[198:201], v[78:81]
	s_setprio 0
	s_setprio 1
	v_mfma_f32_16x16x32_bf16 v[70:73], v[158:161], v[198:201], v[70:73]
	v_mfma_f32_16x16x32_bf16 v[70:73], v[162:165], v[204:207], v[70:73]
	v_mfma_f32_16x16x32_bf16 v[66:69], v[170:173], v[204:207], v[66:69]
	v_mfma_f32_16x16x32_bf16 v[66:69], v[166:169], v[198:201], v[66:69]
	v_mfma_f32_16x16x32_bf16 v[82:85], v[166:169], v[190:193], v[82:85]
	v_mfma_f32_16x16x32_bf16 v[82:85], v[170:173], v[194:197], v[82:85]
	v_mfma_f32_16x16x32_bf16 v[86:89], v[162:165], v[194:197], v[86:89]
	v_mfma_f32_16x16x32_bf16 v[86:89], v[158:161], v[190:193], v[86:89]
	v_mfma_f32_16x16x32_bf16 v[102:105], v[158:161], v[182:185], v[102:105]
	v_mfma_f32_16x16x32_bf16 v[102:105], v[162:165], v[186:189], v[102:105]
	v_mfma_f32_16x16x32_bf16 v[98:101], v[170:173], v[186:189], v[98:101]
	v_mfma_f32_16x16x32_bf16 v[98:101], v[166:169], v[182:185], v[98:101]
	v_mfma_f32_16x16x32_bf16 v[114:117], v[166:169], v[174:177], v[114:117]
	v_mfma_f32_16x16x32_bf16 v[114:117], v[170:173], v[178:181], v[114:117]
	v_mfma_f32_16x16x32_bf16 v[118:121], v[162:165], v[178:181], v[118:121]
	v_mfma_f32_16x16x32_bf16 v[118:121], v[158:161], v[174:177], v[118:121]
	s_setprio 0
	s_barrier
	s_mov_b32 m0, s14
	v_add_u32_e32 v141, s43, v131
	ds_read_b128 v[174:177], v140 offset:16384
	ds_read_b128 v[178:181], v140 offset:17408
	ds_read_b128 v[182:185], v140 offset:18432
	ds_read_b128 v[186:189], v140 offset:19456
	ds_read_b128 v[190:193], v140 offset:20480
	ds_read_b128 v[194:197], v140 offset:21504
	ds_read_b128 v[198:201], v140 offset:22528
	ds_read_b128 v[204:207], v140 offset:23552
	global_load_lds_dwordx4 v141, s[6:7]
	v_add_u32_e32 v141, s43, v133
	s_mov_b32 m0, s15
	s_add_i32 s40, s43, 0x80000
	global_load_lds_dwordx4 v141, s[6:7]
	v_add_u32_e32 v141, s40, v131
	s_mov_b32 m0, s17
	s_nop 0
	global_load_lds_dwordx4 v141, s[6:7]
	v_add_u32_e32 v141, s40, v133
	s_mov_b32 m0, s20
	s_nop 0
	global_load_lds_dwordx4 v141, s[6:7]
	v_add_u32_e32 v141, s44, v130
	s_mov_b32 m0, s22
	s_nop 0
	global_load_lds_dwordx4 v141, s[4:5]
	v_add_u32_e32 v141, s44, v132
	s_mov_b32 m0, s23
	s_nop 0
	global_load_lds_dwordx4 v141, s[4:5]
	s_waitcnt vmcnt(8)
	s_waitcnt lgkmcnt(0)
	s_setprio 1
	s_barrier
	v_mfma_f32_16x16x32_bf16 v[62:65], v[142:145], v[174:177], v[62:65]
	v_mfma_f32_16x16x32_bf16 v[62:65], v[146:149], v[178:181], v[62:65]
	v_mfma_f32_16x16x32_bf16 v[58:61], v[154:157], v[178:181], v[58:61]
	v_mfma_f32_16x16x32_bf16 v[58:61], v[150:153], v[174:177], v[58:61]
	v_mfma_f32_16x16x32_bf16 v[42:45], v[150:153], v[182:185], v[42:45]
	v_mfma_f32_16x16x32_bf16 v[42:45], v[154:157], v[186:189], v[42:45]
	v_mfma_f32_16x16x32_bf16 v[46:49], v[146:149], v[186:189], v[46:49]
	v_mfma_f32_16x16x32_bf16 v[46:49], v[142:145], v[182:185], v[46:49]
	v_mfma_f32_16x16x32_bf16 v[30:33], v[142:145], v[190:193], v[30:33]
	v_mfma_f32_16x16x32_bf16 v[30:33], v[146:149], v[194:197], v[30:33]
	v_mfma_f32_16x16x32_bf16 v[26:29], v[154:157], v[194:197], v[26:29]
	v_mfma_f32_16x16x32_bf16 v[26:29], v[150:153], v[190:193], v[26:29]
	v_mfma_f32_16x16x32_bf16 v[10:13], v[150:153], v[198:201], v[10:13]
	v_mfma_f32_16x16x32_bf16 v[10:13], v[154:157], v[204:207], v[10:13]
	v_mfma_f32_16x16x32_bf16 v[14:17], v[146:149], v[204:207], v[14:17]
	v_mfma_f32_16x16x32_bf16 v[14:17], v[142:145], v[198:201], v[14:17]
	s_setprio 0
	s_setprio 1
	v_mfma_f32_16x16x32_bf16 v[6:9], v[158:161], v[198:201], v[6:9]
	v_mfma_f32_16x16x32_bf16 v[6:9], v[162:165], v[204:207], v[6:9]
	v_mfma_f32_16x16x32_bf16 v[2:5], v[170:173], v[204:207], v[2:5]
	v_mfma_f32_16x16x32_bf16 v[2:5], v[166:169], v[198:201], v[2:5]
	v_mfma_f32_16x16x32_bf16 v[18:21], v[166:169], v[190:193], v[18:21]
	v_mfma_f32_16x16x32_bf16 v[18:21], v[170:173], v[194:197], v[18:21]
	v_mfma_f32_16x16x32_bf16 v[22:25], v[162:165], v[194:197], v[22:25]
	v_mfma_f32_16x16x32_bf16 v[22:25], v[158:161], v[190:193], v[22:25]
	v_mfma_f32_16x16x32_bf16 v[38:41], v[158:161], v[182:185], v[38:41]
	v_mfma_f32_16x16x32_bf16 v[38:41], v[162:165], v[186:189], v[38:41]
	v_mfma_f32_16x16x32_bf16 v[34:37], v[170:173], v[186:189], v[34:37]
	v_mfma_f32_16x16x32_bf16 v[34:37], v[166:169], v[182:185], v[34:37]
	v_mfma_f32_16x16x32_bf16 v[50:53], v[166:169], v[174:177], v[50:53]
	v_mfma_f32_16x16x32_bf16 v[50:53], v[170:173], v[178:181], v[50:53]
	v_mfma_f32_16x16x32_bf16 v[54:57], v[162:165], v[178:181], v[54:57]
	v_mfma_f32_16x16x32_bf16 v[54:57], v[158:161], v[174:177], v[54:57]
	s_setprio 0
	s_barrier
	v_add_u32_e32 v141, s29, v137
	ds_read_b128 v[142:145], v141
	ds_read_b128 v[146:149], v141 offset:1024
	ds_read_b128 v[150:153], v141 offset:2048
	ds_read_b128 v[154:157], v141 offset:3072
	v_add_u32_e32 v141, s36, v137
	ds_read_b128 v[158:161], v141
	ds_read_b128 v[162:165], v141 offset:1024
	ds_read_b128 v[166:169], v141 offset:2048
	ds_read_b128 v[170:173], v141 offset:3072
	s_add_i32 s44, s44, 0x80000
	s_mov_b32 m0, s24
	v_add_u32_e32 v141, s44, v130
	ds_read_b128 v[174:177], v140 offset:32768
	ds_read_b128 v[178:181], v140 offset:33792
	ds_read_b128 v[182:185], v140 offset:34816
	ds_read_b128 v[186:189], v140 offset:35840
	ds_read_b128 v[190:193], v140 offset:36864
	ds_read_b128 v[194:197], v140 offset:37888
	ds_read_b128 v[198:201], v140 offset:38912
	ds_read_b128 v[204:207], v140 offset:39936
	global_load_lds_dwordx4 v141, s[4:5]
	v_add_u32_e32 v141, s44, v132
	s_mov_b32 m0, s25
	s_nop 0
	global_load_lds_dwordx4 v141, s[4:5]
	s_waitcnt vmcnt(8)
	s_waitcnt lgkmcnt(0)
	s_setprio 1
	s_barrier
	v_mfma_f32_16x16x32_bf16 v[126:129], v[142:145], v[174:177], v[126:129]
	v_mfma_f32_16x16x32_bf16 v[126:129], v[146:149], v[178:181], v[126:129]
	v_mfma_f32_16x16x32_bf16 v[122:125], v[154:157], v[178:181], v[122:125]
	v_mfma_f32_16x16x32_bf16 v[122:125], v[150:153], v[174:177], v[122:125]
	v_mfma_f32_16x16x32_bf16 v[106:109], v[150:153], v[182:185], v[106:109]
	v_mfma_f32_16x16x32_bf16 v[106:109], v[154:157], v[186:189], v[106:109]
	v_mfma_f32_16x16x32_bf16 v[110:113], v[146:149], v[186:189], v[110:113]
	v_mfma_f32_16x16x32_bf16 v[110:113], v[142:145], v[182:185], v[110:113]
	v_mfma_f32_16x16x32_bf16 v[94:97], v[142:145], v[190:193], v[94:97]
	v_mfma_f32_16x16x32_bf16 v[94:97], v[146:149], v[194:197], v[94:97]
	v_mfma_f32_16x16x32_bf16 v[90:93], v[154:157], v[194:197], v[90:93]
	v_mfma_f32_16x16x32_bf16 v[90:93], v[150:153], v[190:193], v[90:93]
	v_mfma_f32_16x16x32_bf16 v[74:77], v[150:153], v[198:201], v[74:77]
	v_mfma_f32_16x16x32_bf16 v[74:77], v[154:157], v[204:207], v[74:77]
	v_mfma_f32_16x16x32_bf16 v[78:81], v[146:149], v[204:207], v[78:81]
	v_mfma_f32_16x16x32_bf16 v[78:81], v[142:145], v[198:201], v[78:81]
	s_setprio 0
	s_setprio 1
	v_mfma_f32_16x16x32_bf16 v[70:73], v[158:161], v[198:201], v[70:73]
	v_mfma_f32_16x16x32_bf16 v[70:73], v[162:165], v[204:207], v[70:73]
	v_mfma_f32_16x16x32_bf16 v[66:69], v[170:173], v[204:207], v[66:69]
	v_mfma_f32_16x16x32_bf16 v[66:69], v[166:169], v[198:201], v[66:69]
	v_mfma_f32_16x16x32_bf16 v[82:85], v[166:169], v[190:193], v[82:85]
	v_mfma_f32_16x16x32_bf16 v[82:85], v[170:173], v[194:197], v[82:85]
	v_mfma_f32_16x16x32_bf16 v[86:89], v[162:165], v[194:197], v[86:89]
	v_mfma_f32_16x16x32_bf16 v[86:89], v[158:161], v[190:193], v[86:89]
	v_mfma_f32_16x16x32_bf16 v[102:105], v[158:161], v[182:185], v[102:105]
	v_mfma_f32_16x16x32_bf16 v[102:105], v[162:165], v[186:189], v[102:105]
	v_mfma_f32_16x16x32_bf16 v[98:101], v[170:173], v[186:189], v[98:101]
	v_mfma_f32_16x16x32_bf16 v[98:101], v[166:169], v[182:185], v[98:101]
	v_mfma_f32_16x16x32_bf16 v[114:117], v[166:169], v[174:177], v[114:117]
	v_mfma_f32_16x16x32_bf16 v[114:117], v[170:173], v[178:181], v[114:117]
	v_mfma_f32_16x16x32_bf16 v[118:121], v[162:165], v[178:181], v[118:121]
	v_mfma_f32_16x16x32_bf16 v[118:121], v[158:161], v[174:177], v[118:121]
	s_setprio 0
	s_barrier
	s_or_b32 s40, s43, 0x80
	s_mov_b32 m0, s30
	v_add_u32_e32 v141, s40, v131
	ds_read_b128 v[174:177], v140 offset:49152
	ds_read_b128 v[178:181], v140 offset:50176
	ds_read_b128 v[182:185], v140 offset:51200
	ds_read_b128 v[186:189], v140 offset:52224
	ds_read_b128 v[190:193], v140 offset:53248
	ds_read_b128 v[194:197], v140 offset:54272
	ds_read_b128 v[198:201], v140 offset:55296
	ds_read_b128 v[204:207], v140 offset:56320
	global_load_lds_dwordx4 v141, s[6:7]
	v_add_u32_e32 v141, s40, v133
	s_mov_b32 m0, s31
	s_add_i32 s43, s43, 0x80080
	global_load_lds_dwordx4 v141, s[6:7]
	v_add_u32_e32 v141, s43, v131
	s_mov_b32 m0, s37
	s_nop 0
	global_load_lds_dwordx4 v141, s[6:7]
	v_add_u32_e32 v141, s43, v133
	s_mov_b32 m0, s38
	s_nop 0
	global_load_lds_dwordx4 v141, s[6:7]
	v_add_u32_e32 v141, s42, v130
	s_mov_b32 m0, s34
	s_nop 0
	global_load_lds_dwordx4 v141, s[4:5]
	v_add_u32_e32 v141, s42, v132
	s_mov_b32 m0, s35
	s_nop 0
	global_load_lds_dwordx4 v141, s[4:5]
	s_waitcnt vmcnt(8)
	s_waitcnt lgkmcnt(0)
	s_setprio 1
	s_barrier
	v_mfma_f32_16x16x32_bf16 v[62:65], v[142:145], v[174:177], v[62:65]
	v_mfma_f32_16x16x32_bf16 v[62:65], v[146:149], v[178:181], v[62:65]
	v_mfma_f32_16x16x32_bf16 v[58:61], v[154:157], v[178:181], v[58:61]
	v_mfma_f32_16x16x32_bf16 v[58:61], v[150:153], v[174:177], v[58:61]
	v_mfma_f32_16x16x32_bf16 v[42:45], v[150:153], v[182:185], v[42:45]
	v_mfma_f32_16x16x32_bf16 v[42:45], v[154:157], v[186:189], v[42:45]
	v_mfma_f32_16x16x32_bf16 v[46:49], v[146:149], v[186:189], v[46:49]
	v_mfma_f32_16x16x32_bf16 v[46:49], v[142:145], v[182:185], v[46:49]
	v_mfma_f32_16x16x32_bf16 v[30:33], v[142:145], v[190:193], v[30:33]
	v_mfma_f32_16x16x32_bf16 v[30:33], v[146:149], v[194:197], v[30:33]
	v_mfma_f32_16x16x32_bf16 v[26:29], v[154:157], v[194:197], v[26:29]
	v_mfma_f32_16x16x32_bf16 v[26:29], v[150:153], v[190:193], v[26:29]
	v_mfma_f32_16x16x32_bf16 v[10:13], v[150:153], v[198:201], v[10:13]
	v_mfma_f32_16x16x32_bf16 v[10:13], v[154:157], v[204:207], v[10:13]
	v_mfma_f32_16x16x32_bf16 v[14:17], v[146:149], v[204:207], v[14:17]
	v_mfma_f32_16x16x32_bf16 v[14:17], v[142:145], v[198:201], v[14:17]
	s_setprio 0
	s_setprio 1
	v_mfma_f32_16x16x32_bf16 v[6:9], v[158:161], v[198:201], v[6:9]
	v_mfma_f32_16x16x32_bf16 v[6:9], v[162:165], v[204:207], v[6:9]
	v_mfma_f32_16x16x32_bf16 v[2:5], v[170:173], v[204:207], v[2:5]
	v_mfma_f32_16x16x32_bf16 v[2:5], v[166:169], v[198:201], v[2:5]
	v_mfma_f32_16x16x32_bf16 v[18:21], v[166:169], v[190:193], v[18:21]
	v_mfma_f32_16x16x32_bf16 v[18:21], v[170:173], v[194:197], v[18:21]
	v_mfma_f32_16x16x32_bf16 v[22:25], v[162:165], v[194:197], v[22:25]
	v_mfma_f32_16x16x32_bf16 v[22:25], v[158:161], v[190:193], v[22:25]
	v_mfma_f32_16x16x32_bf16 v[38:41], v[158:161], v[182:185], v[38:41]
	v_mfma_f32_16x16x32_bf16 v[38:41], v[162:165], v[186:189], v[38:41]
	v_mfma_f32_16x16x32_bf16 v[34:37], v[170:173], v[186:189], v[34:37]
	v_mfma_f32_16x16x32_bf16 v[34:37], v[166:169], v[182:185], v[34:37]
	v_mfma_f32_16x16x32_bf16 v[50:53], v[166:169], v[174:177], v[50:53]
	v_mfma_f32_16x16x32_bf16 v[50:53], v[170:173], v[178:181], v[50:53]
	v_mfma_f32_16x16x32_bf16 v[54:57], v[162:165], v[178:181], v[54:57]
	v_mfma_f32_16x16x32_bf16 v[54:57], v[158:161], v[174:177], v[54:57]
	s_setprio 0
	s_barrier
	s_add_i32 s39, s39, 2
	s_cmp_gt_u32 s39, 29
	s_mov_b32 s40, s41
	s_cbranch_scc0 .LBB0_725
	s_cmpk_lt_u32 s9, 0x100
	s_cbranch_scc0 .LBB0_728
	s_barrier

.LBB0_740:
	v_lshrrev_b32_e32 v9, 1, v5
	v_and_b32_e32 v135, 24, v9
	v_and_b32_e32 v136, 15, v5
	v_lshlrev_b32_e32 v9, 1, v135
	v_lshlrev_b32_e32 v5, 2, v5
	s_lshl_b32 s20, s20, 5
	s_lshl_b32 s19, s21, 6
	v_lshl_or_b32 v9, v136, 6, v9
	s_lshl_b32 s21, s21, 13
	v_and_b32_e32 v5, 32, v5
	s_and_b32 s20, s20, 0x60
	v_bitop3_b32 v10, v9, s21, v5 bitop3:0xde
	s_lshl_b32 s21, s20, 7
	v_bitop3_b32 v137, v9, s21, v5 bitop3:0xde
	s_add_i32 s21, s28, 0x18000
	s_or_b32 s23, s2, 0x80
	s_add_i32 s22, s21, s27
	v_add_u32_e32 v5, s23, v131
	s_mov_b32 m0, s22
	s_waitcnt vmcnt(2)
	s_barrier
	global_load_lds_dwordx4 v5, s[6:7]
	v_add_u32_e32 v5, s23, v133
	s_add_i32 s23, s22, 0x2000
	s_mov_b32 m0, s23
	s_or_b32 s25, s14, 0x80
	s_add_i32 s24, s15, 0x8000
	global_load_lds_dwordx4 v5, s[6:7]
	v_add_u32_e32 v5, s25, v130
	s_mov_b32 m0, s24
	s_add_i32 s26, s28, 0x1c000
	global_load_lds_dwordx4 v5, s[4:5]
	v_add_u32_e32 v5, s25, v132
	s_add_i32 s25, s15, 0xa000
	s_mov_b32 m0, s25
	s_or_b32 s29, s2, 0x80080
	s_add_i32 s27, s26, s27
	global_load_lds_dwordx4 v5, s[4:5]
	v_add_u32_e32 v5, s29, v131
	s_mov_b32 m0, s27
	s_add_i32 s30, s14, 0x80080
	global_load_lds_dwordx4 v5, s[6:7]
	v_add_u32_e32 v5, s29, v133
	s_add_i32 s29, s27, 0x2000
	s_mov_b32 m0, s29
	v_lshlrev_b32_e32 v7, 12, v7
	global_load_lds_dwordx4 v5, s[6:7]
	v_lshlrev_b32_e32 v5, 15, v6
	v_and_b32_e32 v5, 0xffff0000, v5
	v_and_b32_e32 v6, 1, v6
	v_add3_u32 v5, s30, v5, v7
	v_lshlrev_b32_e32 v6, 6, v6
	v_lshlrev_b32_e32 v7, 1, v8
	v_add3_u32 v138, v5, v6, v7
	v_lshlrev_b32_e32 v5, 15, v2
	v_and_b32_e32 v5, 0xffff0000, v5
	v_lshlrev_b32_e32 v3, 12, v3
	v_and_b32_e32 v2, 1, v2
	s_waitcnt vmcnt(6)
	v_add3_u32 v3, s30, v5, v3
	v_lshlrev_b32_e32 v2, 6, v2
	v_lshlrev_b32_e32 v4, 1, v4
	v_add3_u32 v139, v3, v2, v4
	v_or_b32_e32 v134, s19, v136
	s_mov_b32 s30, -2
	s_mov_b32 s31, 0
	v_add_u32_e32 v140, s28, v10
	s_barrier
	v_add_u32_e32 v141, s3, v137
	ds_read_b128 v[142:145], v141
	ds_read_b128 v[146:149], v141 offset:1024
	ds_read_b128 v[150:153], v141 offset:2048
	ds_read_b128 v[154:157], v141 offset:3072
	v_add_u32_e32 v141, s11, v137
	ds_read_b128 v[158:161], v141
	ds_read_b128 v[162:165], v141 offset:1024
	ds_read_b128 v[166:169], v141 offset:2048
	ds_read_b128 v[170:173], v141 offset:3072
	s_add_i32 s34, s31, 0x100
	s_cmp_lg_u32 s30, 28
	s_cselect_b32 s36, s34, 0
	s_add_i32 s37, s36, s14
	s_or_b32 s35, s37, 0x80
	s_add_i32 s36, s36, s2
	v_add_u32_e32 v141, s31, v139
	s_add_i32 m0, s15, 0xc000
	ds_read_b128 v[174:177], v140
	ds_read_b128 v[178:181], v140 offset:1024
	ds_read_b128 v[182:185], v140 offset:2048
	ds_read_b128 v[186:189], v140 offset:3072
	ds_read_b128 v[190:193], v140 offset:4096
	ds_read_b128 v[194:197], v140 offset:5120
	ds_read_b128 v[198:201], v140 offset:6144
	ds_read_b128 v[204:207], v140 offset:7168
	global_load_lds_dwordx4 v141, s[4:5]
	v_add_u32_e32 v141, s31, v138
	s_add_i32 m0, s15, 0xe000
	s_nop 0
	global_load_lds_dwordx4 v141, s[4:5]
	s_waitcnt vmcnt(8)
	s_waitcnt lgkmcnt(0)
	s_setprio 1
	s_barrier
	v_mfma_f32_16x16x32_bf16 v[126:129], v[142:145], v[174:177], 0
	v_mfma_f32_16x16x32_bf16 v[126:129], v[146:149], v[178:181], v[126:129]
	v_mfma_f32_16x16x32_bf16 v[122:125], v[154:157], v[178:181], 0
	v_mfma_f32_16x16x32_bf16 v[122:125], v[150:153], v[174:177], v[122:125]
	v_mfma_f32_16x16x32_bf16 v[106:109], v[150:153], v[182:185], 0
	v_mfma_f32_16x16x32_bf16 v[106:109], v[154:157], v[186:189], v[106:109]
	v_mfma_f32_16x16x32_bf16 v[110:113], v[146:149], v[186:189], 0
	v_mfma_f32_16x16x32_bf16 v[110:113], v[142:145], v[182:185], v[110:113]
	v_mfma_f32_16x16x32_bf16 v[94:97], v[142:145], v[190:193], 0
	v_mfma_f32_16x16x32_bf16 v[94:97], v[146:149], v[194:197], v[94:97]
	v_mfma_f32_16x16x32_bf16 v[90:93], v[154:157], v[194:197], 0
	v_mfma_f32_16x16x32_bf16 v[90:93], v[150:153], v[190:193], v[90:93]
	v_mfma_f32_16x16x32_bf16 v[74:77], v[150:153], v[198:201], 0
	v_mfma_f32_16x16x32_bf16 v[74:77], v[154:157], v[204:207], v[74:77]
	v_mfma_f32_16x16x32_bf16 v[78:81], v[146:149], v[204:207], 0
	v_mfma_f32_16x16x32_bf16 v[78:81], v[142:145], v[198:201], v[78:81]
	s_setprio 0
	s_setprio 1
	v_mfma_f32_16x16x32_bf16 v[70:73], v[158:161], v[198:201], 0
	v_mfma_f32_16x16x32_bf16 v[70:73], v[162:165], v[204:207], v[70:73]
	v_mfma_f32_16x16x32_bf16 v[66:69], v[170:173], v[204:207], 0
	v_mfma_f32_16x16x32_bf16 v[66:69], v[166:169], v[198:201], v[66:69]
	v_mfma_f32_16x16x32_bf16 v[82:85], v[166:169], v[190:193], 0
	v_mfma_f32_16x16x32_bf16 v[82:85], v[170:173], v[194:197], v[82:85]
	v_mfma_f32_16x16x32_bf16 v[86:89], v[162:165], v[194:197], 0
	v_mfma_f32_16x16x32_bf16 v[86:89], v[158:161], v[190:193], v[86:89]
	v_mfma_f32_16x16x32_bf16 v[102:105], v[158:161], v[182:185], 0
	v_mfma_f32_16x16x32_bf16 v[102:105], v[162:165], v[186:189], v[102:105]
	v_mfma_f32_16x16x32_bf16 v[98:101], v[170:173], v[186:189], 0
	v_mfma_f32_16x16x32_bf16 v[98:101], v[166:169], v[182:185], v[98:101]
	v_mfma_f32_16x16x32_bf16 v[114:117], v[166:169], v[174:177], 0
	v_mfma_f32_16x16x32_bf16 v[114:117], v[170:173], v[178:181], v[114:117]
	v_mfma_f32_16x16x32_bf16 v[118:121], v[162:165], v[178:181], 0
	v_mfma_f32_16x16x32_bf16 v[118:121], v[158:161], v[174:177], v[118:121]
	s_setprio 0
	s_barrier
	s_mov_b32 m0, s9
	v_add_u32_e32 v141, s36, v131
	ds_read_b128 v[174:177], v140 offset:16384
	ds_read_b128 v[178:181], v140 offset:17408
	ds_read_b128 v[182:185], v140 offset:18432
	ds_read_b128 v[186:189], v140 offset:19456
	ds_read_b128 v[190:193], v140 offset:20480
	ds_read_b128 v[194:197], v140 offset:21504
	ds_read_b128 v[198:201], v140 offset:22528
	ds_read_b128 v[204:207], v140 offset:23552
	global_load_lds_dwordx4 v141, s[6:7]
	v_add_u32_e32 v141, s36, v133
	s_mov_b32 m0, s10
	s_add_i32 s31, s36, 0x80000
	global_load_lds_dwordx4 v141, s[6:7]
	v_add_u32_e32 v141, s31, v131
	s_mov_b32 m0, s12
	s_nop 0
	global_load_lds_dwordx4 v141, s[6:7]
	v_add_u32_e32 v141, s31, v133
	s_mov_b32 m0, s13
	s_nop 0
	global_load_lds_dwordx4 v141, s[6:7]
	v_add_u32_e32 v141, s37, v130
	s_mov_b32 m0, s15
	s_nop 0
	global_load_lds_dwordx4 v141, s[4:5]
	v_add_u32_e32 v141, s37, v132
	s_mov_b32 m0, s16
	s_nop 0
	global_load_lds_dwordx4 v141, s[4:5]
	s_waitcnt vmcnt(8)
	s_waitcnt lgkmcnt(0)
	s_setprio 1
	s_barrier
	v_mfma_f32_16x16x32_bf16 v[62:65], v[142:145], v[174:177], 0
	v_mfma_f32_16x16x32_bf16 v[62:65], v[146:149], v[178:181], v[62:65]
	v_mfma_f32_16x16x32_bf16 v[58:61], v[154:157], v[178:181], 0
	v_mfma_f32_16x16x32_bf16 v[58:61], v[150:153], v[174:177], v[58:61]
	v_mfma_f32_16x16x32_bf16 v[42:45], v[150:153], v[182:185], 0
	v_mfma_f32_16x16x32_bf16 v[42:45], v[154:157], v[186:189], v[42:45]
	v_mfma_f32_16x16x32_bf16 v[46:49], v[146:149], v[186:189], 0
	v_mfma_f32_16x16x32_bf16 v[46:49], v[142:145], v[182:185], v[46:49]
	v_mfma_f32_16x16x32_bf16 v[30:33], v[142:145], v[190:193], 0
	v_mfma_f32_16x16x32_bf16 v[30:33], v[146:149], v[194:197], v[30:33]
	v_mfma_f32_16x16x32_bf16 v[26:29], v[154:157], v[194:197], 0
	v_mfma_f32_16x16x32_bf16 v[26:29], v[150:153], v[190:193], v[26:29]
	v_mfma_f32_16x16x32_bf16 v[10:13], v[150:153], v[198:201], 0
	v_mfma_f32_16x16x32_bf16 v[10:13], v[154:157], v[204:207], v[10:13]
	v_mfma_f32_16x16x32_bf16 v[14:17], v[146:149], v[204:207], 0
	v_mfma_f32_16x16x32_bf16 v[14:17], v[142:145], v[198:201], v[14:17]
	s_setprio 0
	s_setprio 1
	v_mfma_f32_16x16x32_bf16 v[6:9], v[158:161], v[198:201], 0
	v_mfma_f32_16x16x32_bf16 v[6:9], v[162:165], v[204:207], v[6:9]
	v_mfma_f32_16x16x32_bf16 v[2:5], v[170:173], v[204:207], 0
	v_mfma_f32_16x16x32_bf16 v[2:5], v[166:169], v[198:201], v[2:5]
	v_mfma_f32_16x16x32_bf16 v[18:21], v[166:169], v[190:193], 0
	v_mfma_f32_16x16x32_bf16 v[18:21], v[170:173], v[194:197], v[18:21]
	v_mfma_f32_16x16x32_bf16 v[22:25], v[162:165], v[194:197], 0
	v_mfma_f32_16x16x32_bf16 v[22:25], v[158:161], v[190:193], v[22:25]
	v_mfma_f32_16x16x32_bf16 v[38:41], v[158:161], v[182:185], 0
	v_mfma_f32_16x16x32_bf16 v[38:41], v[162:165], v[186:189], v[38:41]
	v_mfma_f32_16x16x32_bf16 v[34:37], v[170:173], v[186:189], 0
	v_mfma_f32_16x16x32_bf16 v[34:37], v[166:169], v[182:185], v[34:37]
	v_mfma_f32_16x16x32_bf16 v[50:53], v[166:169], v[174:177], 0
	v_mfma_f32_16x16x32_bf16 v[50:53], v[170:173], v[178:181], v[50:53]
	v_mfma_f32_16x16x32_bf16 v[54:57], v[162:165], v[178:181], 0
	v_mfma_f32_16x16x32_bf16 v[54:57], v[158:161], v[174:177], v[54:57]
	s_setprio 0
	s_barrier
	v_add_u32_e32 v141, s21, v137
	ds_read_b128 v[142:145], v141
	ds_read_b128 v[146:149], v141 offset:1024
	ds_read_b128 v[150:153], v141 offset:2048
	ds_read_b128 v[154:157], v141 offset:3072
	v_add_u32_e32 v141, s26, v137
	ds_read_b128 v[158:161], v141
	ds_read_b128 v[162:165], v141 offset:1024
	ds_read_b128 v[166:169], v141 offset:2048
	ds_read_b128 v[170:173], v141 offset:3072
	s_add_i32 s37, s37, 0x80000
	s_mov_b32 m0, s17
	v_add_u32_e32 v141, s37, v130
	ds_read_b128 v[174:177], v140 offset:32768
	ds_read_b128 v[178:181], v140 offset:33792
	ds_read_b128 v[182:185], v140 offset:34816
	ds_read_b128 v[186:189], v140 offset:35840
	ds_read_b128 v[190:193], v140 offset:36864
	ds_read_b128 v[194:197], v140 offset:37888
	ds_read_b128 v[198:201], v140 offset:38912
	ds_read_b128 v[204:207], v140 offset:39936
	global_load_lds_dwordx4 v141, s[4:5]
	v_add_u32_e32 v141, s37, v132
	s_mov_b32 m0, s18
	s_nop 0
	global_load_lds_dwordx4 v141, s[4:5]
	s_waitcnt vmcnt(8)
	s_waitcnt lgkmcnt(0)
	s_setprio 1
	s_barrier
	v_mfma_f32_16x16x32_bf16 v[126:129], v[142:145], v[174:177], v[126:129]
	v_mfma_f32_16x16x32_bf16 v[126:129], v[146:149], v[178:181], v[126:129]
	v_mfma_f32_16x16x32_bf16 v[122:125], v[154:157], v[178:181], v[122:125]
	v_mfma_f32_16x16x32_bf16 v[122:125], v[150:153], v[174:177], v[122:125]
	v_mfma_f32_16x16x32_bf16 v[106:109], v[150:153], v[182:185], v[106:109]
	v_mfma_f32_16x16x32_bf16 v[106:109], v[154:157], v[186:189], v[106:109]
	v_mfma_f32_16x16x32_bf16 v[110:113], v[146:149], v[186:189], v[110:113]
	v_mfma_f32_16x16x32_bf16 v[110:113], v[142:145], v[182:185], v[110:113]
	v_mfma_f32_16x16x32_bf16 v[94:97], v[142:145], v[190:193], v[94:97]
	v_mfma_f32_16x16x32_bf16 v[94:97], v[146:149], v[194:197], v[94:97]
	v_mfma_f32_16x16x32_bf16 v[90:93], v[154:157], v[194:197], v[90:93]
	v_mfma_f32_16x16x32_bf16 v[90:93], v[150:153], v[190:193], v[90:93]
	v_mfma_f32_16x16x32_bf16 v[74:77], v[150:153], v[198:201], v[74:77]
	v_mfma_f32_16x16x32_bf16 v[74:77], v[154:157], v[204:207], v[74:77]
	v_mfma_f32_16x16x32_bf16 v[78:81], v[146:149], v[204:207], v[78:81]
	v_mfma_f32_16x16x32_bf16 v[78:81], v[142:145], v[198:201], v[78:81]
	s_setprio 0
	s_setprio 1
	v_mfma_f32_16x16x32_bf16 v[70:73], v[158:161], v[198:201], v[70:73]
	v_mfma_f32_16x16x32_bf16 v[70:73], v[162:165], v[204:207], v[70:73]
	v_mfma_f32_16x16x32_bf16 v[66:69], v[170:173], v[204:207], v[66:69]
	v_mfma_f32_16x16x32_bf16 v[66:69], v[166:169], v[198:201], v[66:69]
	v_mfma_f32_16x16x32_bf16 v[82:85], v[166:169], v[190:193], v[82:85]
	v_mfma_f32_16x16x32_bf16 v[82:85], v[170:173], v[194:197], v[82:85]
	v_mfma_f32_16x16x32_bf16 v[86:89], v[162:165], v[194:197], v[86:89]
	v_mfma_f32_16x16x32_bf16 v[86:89], v[158:161], v[190:193], v[86:89]
	v_mfma_f32_16x16x32_bf16 v[102:105], v[158:161], v[182:185], v[102:105]
	v_mfma_f32_16x16x32_bf16 v[102:105], v[162:165], v[186:189], v[102:105]
	v_mfma_f32_16x16x32_bf16 v[98:101], v[170:173], v[186:189], v[98:101]
	v_mfma_f32_16x16x32_bf16 v[98:101], v[166:169], v[182:185], v[98:101]
	v_mfma_f32_16x16x32_bf16 v[114:117], v[166:169], v[174:177], v[114:117]
	v_mfma_f32_16x16x32_bf16 v[114:117], v[170:173], v[178:181], v[114:117]
	v_mfma_f32_16x16x32_bf16 v[118:121], v[162:165], v[178:181], v[118:121]
	v_mfma_f32_16x16x32_bf16 v[118:121], v[158:161], v[174:177], v[118:121]
	s_setprio 0
	s_barrier
	s_or_b32 s31, s36, 0x80
	s_mov_b32 m0, s22
	v_add_u32_e32 v141, s31, v131
	ds_read_b128 v[174:177], v140 offset:49152
	ds_read_b128 v[178:181], v140 offset:50176
	ds_read_b128 v[182:185], v140 offset:51200
	ds_read_b128 v[186:189], v140 offset:52224
	ds_read_b128 v[190:193], v140 offset:53248
	ds_read_b128 v[194:197], v140 offset:54272
	ds_read_b128 v[198:201], v140 offset:55296
	ds_read_b128 v[204:207], v140 offset:56320
	global_load_lds_dwordx4 v141, s[6:7]
	v_add_u32_e32 v141, s31, v133
	s_mov_b32 m0, s23
	s_add_i32 s36, s36, 0x80080
	global_load_lds_dwordx4 v141, s[6:7]
	v_add_u32_e32 v141, s36, v131
	s_mov_b32 m0, s27
	s_nop 0
	global_load_lds_dwordx4 v141, s[6:7]
	v_add_u32_e32 v141, s36, v133
	s_mov_b32 m0, s29
	s_nop 0
	global_load_lds_dwordx4 v141, s[6:7]
	v_add_u32_e32 v141, s35, v130
	s_mov_b32 m0, s24
	s_nop 0
	global_load_lds_dwordx4 v141, s[4:5]
	v_add_u32_e32 v141, s35, v132
	s_mov_b32 m0, s25
	s_nop 0
	global_load_lds_dwordx4 v141, s[4:5]
	s_waitcnt vmcnt(8)
	s_waitcnt lgkmcnt(0)
	s_setprio 1
	s_barrier
	v_mfma_f32_16x16x32_bf16 v[62:65], v[142:145], v[174:177], v[62:65]
	v_mfma_f32_16x16x32_bf16 v[62:65], v[146:149], v[178:181], v[62:65]
	v_mfma_f32_16x16x32_bf16 v[58:61], v[154:157], v[178:181], v[58:61]
	v_mfma_f32_16x16x32_bf16 v[58:61], v[150:153], v[174:177], v[58:61]
	v_mfma_f32_16x16x32_bf16 v[42:45], v[150:153], v[182:185], v[42:45]
	v_mfma_f32_16x16x32_bf16 v[42:45], v[154:157], v[186:189], v[42:45]
	v_mfma_f32_16x16x32_bf16 v[46:49], v[146:149], v[186:189], v[46:49]
	v_mfma_f32_16x16x32_bf16 v[46:49], v[142:145], v[182:185], v[46:49]
	v_mfma_f32_16x16x32_bf16 v[30:33], v[142:145], v[190:193], v[30:33]
	v_mfma_f32_16x16x32_bf16 v[30:33], v[146:149], v[194:197], v[30:33]
	v_mfma_f32_16x16x32_bf16 v[26:29], v[154:157], v[194:197], v[26:29]
	v_mfma_f32_16x16x32_bf16 v[26:29], v[150:153], v[190:193], v[26:29]
	v_mfma_f32_16x16x32_bf16 v[10:13], v[150:153], v[198:201], v[10:13]
	v_mfma_f32_16x16x32_bf16 v[10:13], v[154:157], v[204:207], v[10:13]
	v_mfma_f32_16x16x32_bf16 v[14:17], v[146:149], v[204:207], v[14:17]
	v_mfma_f32_16x16x32_bf16 v[14:17], v[142:145], v[198:201], v[14:17]
	s_setprio 0
	s_setprio 1
	v_mfma_f32_16x16x32_bf16 v[6:9], v[158:161], v[198:201], v[6:9]
	v_mfma_f32_16x16x32_bf16 v[6:9], v[162:165], v[204:207], v[6:9]
	v_mfma_f32_16x16x32_bf16 v[2:5], v[170:173], v[204:207], v[2:5]
	v_mfma_f32_16x16x32_bf16 v[2:5], v[166:169], v[198:201], v[2:5]
	v_mfma_f32_16x16x32_bf16 v[18:21], v[166:169], v[190:193], v[18:21]
	v_mfma_f32_16x16x32_bf16 v[18:21], v[170:173], v[194:197], v[18:21]
	v_mfma_f32_16x16x32_bf16 v[22:25], v[162:165], v[194:197], v[22:25]
	v_mfma_f32_16x16x32_bf16 v[22:25], v[158:161], v[190:193], v[22:25]
	v_mfma_f32_16x16x32_bf16 v[38:41], v[158:161], v[182:185], v[38:41]
	v_mfma_f32_16x16x32_bf16 v[38:41], v[162:165], v[186:189], v[38:41]
	v_mfma_f32_16x16x32_bf16 v[34:37], v[170:173], v[186:189], v[34:37]
	v_mfma_f32_16x16x32_bf16 v[34:37], v[166:169], v[182:185], v[34:37]
	v_mfma_f32_16x16x32_bf16 v[50:53], v[166:169], v[174:177], v[50:53]
	v_mfma_f32_16x16x32_bf16 v[50:53], v[170:173], v[178:181], v[50:53]
	v_mfma_f32_16x16x32_bf16 v[54:57], v[162:165], v[178:181], v[54:57]
	v_mfma_f32_16x16x32_bf16 v[54:57], v[158:161], v[174:177], v[54:57]
	s_setprio 0
	s_barrier
	s_add_i32 s30, s30, 2
	s_cmp_gt_u32 s30, 29
	s_mov_b32 s31, s34
.LBB0_741:
	v_add_u32_e32 v141, s3, v137
	ds_read_b128 v[142:145], v141
	ds_read_b128 v[146:149], v141 offset:1024
	ds_read_b128 v[150:153], v141 offset:2048
	ds_read_b128 v[154:157], v141 offset:3072
	v_add_u32_e32 v141, s11, v137
	ds_read_b128 v[158:161], v141
	ds_read_b128 v[162:165], v141 offset:1024
	ds_read_b128 v[166:169], v141 offset:2048
	ds_read_b128 v[170:173], v141 offset:3072
	s_add_i32 s34, s31, 0x100
	s_cmp_lg_u32 s30, 28
	s_cselect_b32 s36, s34, 0
	s_add_i32 s37, s36, s14
	s_or_b32 s35, s37, 0x80
	s_add_i32 s36, s36, s2
	v_add_u32_e32 v141, s31, v139
	s_add_i32 m0, s15, 0xc000
	ds_read_b128 v[174:177], v140
	ds_read_b128 v[178:181], v140 offset:1024
	ds_read_b128 v[182:185], v140 offset:2048
	ds_read_b128 v[186:189], v140 offset:3072
	ds_read_b128 v[190:193], v140 offset:4096
	ds_read_b128 v[194:197], v140 offset:5120
	ds_read_b128 v[198:201], v140 offset:6144
	ds_read_b128 v[204:207], v140 offset:7168
	global_load_lds_dwordx4 v141, s[4:5]
	v_add_u32_e32 v141, s31, v138
	s_add_i32 m0, s15, 0xe000
	s_nop 0
	global_load_lds_dwordx4 v141, s[4:5]
	s_waitcnt vmcnt(8)
	s_waitcnt lgkmcnt(0)
	s_setprio 1
	s_barrier
	v_mfma_f32_16x16x32_bf16 v[126:129], v[142:145], v[174:177], v[126:129]
	v_mfma_f32_16x16x32_bf16 v[126:129], v[146:149], v[178:181], v[126:129]
	v_mfma_f32_16x16x32_bf16 v[122:125], v[154:157], v[178:181], v[122:125]
	v_mfma_f32_16x16x32_bf16 v[122:125], v[150:153], v[174:177], v[122:125]
	v_mfma_f32_16x16x32_bf16 v[106:109], v[150:153], v[182:185], v[106:109]
	v_mfma_f32_16x16x32_bf16 v[106:109], v[154:157], v[186:189], v[106:109]
	v_mfma_f32_16x16x32_bf16 v[110:113], v[146:149], v[186:189], v[110:113]
	v_mfma_f32_16x16x32_bf16 v[110:113], v[142:145], v[182:185], v[110:113]
	v_mfma_f32_16x16x32_bf16 v[94:97], v[142:145], v[190:193], v[94:97]
	v_mfma_f32_16x16x32_bf16 v[94:97], v[146:149], v[194:197], v[94:97]
	v_mfma_f32_16x16x32_bf16 v[90:93], v[154:157], v[194:197], v[90:93]
	v_mfma_f32_16x16x32_bf16 v[90:93], v[150:153], v[190:193], v[90:93]
	v_mfma_f32_16x16x32_bf16 v[74:77], v[150:153], v[198:201], v[74:77]
	v_mfma_f32_16x16x32_bf16 v[74:77], v[154:157], v[204:207], v[74:77]
	v_mfma_f32_16x16x32_bf16 v[78:81], v[146:149], v[204:207], v[78:81]
	v_mfma_f32_16x16x32_bf16 v[78:81], v[142:145], v[198:201], v[78:81]
	s_setprio 0
	s_setprio 1
	v_mfma_f32_16x16x32_bf16 v[70:73], v[158:161], v[198:201], v[70:73]
	v_mfma_f32_16x16x32_bf16 v[70:73], v[162:165], v[204:207], v[70:73]
	v_mfma_f32_16x16x32_bf16 v[66:69], v[170:173], v[204:207], v[66:69]
	v_mfma_f32_16x16x32_bf16 v[66:69], v[166:169], v[198:201], v[66:69]
	v_mfma_f32_16x16x32_bf16 v[82:85], v[166:169], v[190:193], v[82:85]
	v_mfma_f32_16x16x32_bf16 v[82:85], v[170:173], v[194:197], v[82:85]
	v_mfma_f32_16x16x32_bf16 v[86:89], v[162:165], v[194:197], v[86:89]
	v_mfma_f32_16x16x32_bf16 v[86:89], v[158:161], v[190:193], v[86:89]
	v_mfma_f32_16x16x32_bf16 v[102:105], v[158:161], v[182:185], v[102:105]
	v_mfma_f32_16x16x32_bf16 v[102:105], v[162:165], v[186:189], v[102:105]
	v_mfma_f32_16x16x32_bf16 v[98:101], v[170:173], v[186:189], v[98:101]
	v_mfma_f32_16x16x32_bf16 v[98:101], v[166:169], v[182:185], v[98:101]
	v_mfma_f32_16x16x32_bf16 v[114:117], v[166:169], v[174:177], v[114:117]
	v_mfma_f32_16x16x32_bf16 v[114:117], v[170:173], v[178:181], v[114:117]
	v_mfma_f32_16x16x32_bf16 v[118:121], v[162:165], v[178:181], v[118:121]
	v_mfma_f32_16x16x32_bf16 v[118:121], v[158:161], v[174:177], v[118:121]
	s_setprio 0
	s_barrier
	s_mov_b32 m0, s9
	v_add_u32_e32 v141, s36, v131
	ds_read_b128 v[174:177], v140 offset:16384
	ds_read_b128 v[178:181], v140 offset:17408
	ds_read_b128 v[182:185], v140 offset:18432
	ds_read_b128 v[186:189], v140 offset:19456
	ds_read_b128 v[190:193], v140 offset:20480
	ds_read_b128 v[194:197], v140 offset:21504
	ds_read_b128 v[198:201], v140 offset:22528
	ds_read_b128 v[204:207], v140 offset:23552
	global_load_lds_dwordx4 v141, s[6:7]
	v_add_u32_e32 v141, s36, v133
	s_mov_b32 m0, s10
	s_add_i32 s31, s36, 0x80000
	global_load_lds_dwordx4 v141, s[6:7]
	v_add_u32_e32 v141, s31, v131
	s_mov_b32 m0, s12
	s_nop 0
	global_load_lds_dwordx4 v141, s[6:7]
	v_add_u32_e32 v141, s31, v133
	s_mov_b32 m0, s13
	s_nop 0
	global_load_lds_dwordx4 v141, s[6:7]
	v_add_u32_e32 v141, s37, v130
	s_mov_b32 m0, s15
	s_nop 0
	global_load_lds_dwordx4 v141, s[4:5]
	v_add_u32_e32 v141, s37, v132
	s_mov_b32 m0, s16
	s_nop 0
	global_load_lds_dwordx4 v141, s[4:5]
	s_waitcnt vmcnt(8)
	s_waitcnt lgkmcnt(0)
	s_setprio 1
	s_barrier
	v_mfma_f32_16x16x32_bf16 v[62:65], v[142:145], v[174:177], v[62:65]
	v_mfma_f32_16x16x32_bf16 v[62:65], v[146:149], v[178:181], v[62:65]
	v_mfma_f32_16x16x32_bf16 v[58:61], v[154:157], v[178:181], v[58:61]
	v_mfma_f32_16x16x32_bf16 v[58:61], v[150:153], v[174:177], v[58:61]
	v_mfma_f32_16x16x32_bf16 v[42:45], v[150:153], v[182:185], v[42:45]
	v_mfma_f32_16x16x32_bf16 v[42:45], v[154:157], v[186:189], v[42:45]
	v_mfma_f32_16x16x32_bf16 v[46:49], v[146:149], v[186:189], v[46:49]
	v_mfma_f32_16x16x32_bf16 v[46:49], v[142:145], v[182:185], v[46:49]
	v_mfma_f32_16x16x32_bf16 v[30:33], v[142:145], v[190:193], v[30:33]
	v_mfma_f32_16x16x32_bf16 v[30:33], v[146:149], v[194:197], v[30:33]
	v_mfma_f32_16x16x32_bf16 v[26:29], v[154:157], v[194:197], v[26:29]
	v_mfma_f32_16x16x32_bf16 v[26:29], v[150:153], v[190:193], v[26:29]
	v_mfma_f32_16x16x32_bf16 v[10:13], v[150:153], v[198:201], v[10:13]
	v_mfma_f32_16x16x32_bf16 v[10:13], v[154:157], v[204:207], v[10:13]
	v_mfma_f32_16x16x32_bf16 v[14:17], v[146:149], v[204:207], v[14:17]
	v_mfma_f32_16x16x32_bf16 v[14:17], v[142:145], v[198:201], v[14:17]
	s_setprio 0
	s_setprio 1
	v_mfma_f32_16x16x32_bf16 v[6:9], v[158:161], v[198:201], v[6:9]
	v_mfma_f32_16x16x32_bf16 v[6:9], v[162:165], v[204:207], v[6:9]
	v_mfma_f32_16x16x32_bf16 v[2:5], v[170:173], v[204:207], v[2:5]
	v_mfma_f32_16x16x32_bf16 v[2:5], v[166:169], v[198:201], v[2:5]
	v_mfma_f32_16x16x32_bf16 v[18:21], v[166:169], v[190:193], v[18:21]
	v_mfma_f32_16x16x32_bf16 v[18:21], v[170:173], v[194:197], v[18:21]
	v_mfma_f32_16x16x32_bf16 v[22:25], v[162:165], v[194:197], v[22:25]
	v_mfma_f32_16x16x32_bf16 v[22:25], v[158:161], v[190:193], v[22:25]
	v_mfma_f32_16x16x32_bf16 v[38:41], v[158:161], v[182:185], v[38:41]
	v_mfma_f32_16x16x32_bf16 v[38:41], v[162:165], v[186:189], v[38:41]
	v_mfma_f32_16x16x32_bf16 v[34:37], v[170:173], v[186:189], v[34:37]
	v_mfma_f32_16x16x32_bf16 v[34:37], v[166:169], v[182:185], v[34:37]
	v_mfma_f32_16x16x32_bf16 v[50:53], v[166:169], v[174:177], v[50:53]
	v_mfma_f32_16x16x32_bf16 v[50:53], v[170:173], v[178:181], v[50:53]
	v_mfma_f32_16x16x32_bf16 v[54:57], v[162:165], v[178:181], v[54:57]
	v_mfma_f32_16x16x32_bf16 v[54:57], v[158:161], v[174:177], v[54:57]
	s_setprio 0
	s_barrier
	v_add_u32_e32 v141, s21, v137
	ds_read_b128 v[142:145], v141
	ds_read_b128 v[146:149], v141 offset:1024
	ds_read_b128 v[150:153], v141 offset:2048
	ds_read_b128 v[154:157], v141 offset:3072
	v_add_u32_e32 v141, s26, v137
	ds_read_b128 v[158:161], v141
	ds_read_b128 v[162:165], v141 offset:1024
	ds_read_b128 v[166:169], v141 offset:2048
	ds_read_b128 v[170:173], v141 offset:3072
	s_add_i32 s37, s37, 0x80000
	s_mov_b32 m0, s17
	v_add_u32_e32 v141, s37, v130
	ds_read_b128 v[174:177], v140 offset:32768
	ds_read_b128 v[178:181], v140 offset:33792
	ds_read_b128 v[182:185], v140 offset:34816
	ds_read_b128 v[186:189], v140 offset:35840
	ds_read_b128 v[190:193], v140 offset:36864
	ds_read_b128 v[194:197], v140 offset:37888
	ds_read_b128 v[198:201], v140 offset:38912
	ds_read_b128 v[204:207], v140 offset:39936
	global_load_lds_dwordx4 v141, s[4:5]
	v_add_u32_e32 v141, s37, v132
	s_mov_b32 m0, s18
	s_nop 0
	global_load_lds_dwordx4 v141, s[4:5]
	s_waitcnt vmcnt(8)
	s_waitcnt lgkmcnt(0)
	s_setprio 1
	s_barrier
	v_mfma_f32_16x16x32_bf16 v[126:129], v[142:145], v[174:177], v[126:129]
	v_mfma_f32_16x16x32_bf16 v[126:129], v[146:149], v[178:181], v[126:129]
	v_mfma_f32_16x16x32_bf16 v[122:125], v[154:157], v[178:181], v[122:125]
	v_mfma_f32_16x16x32_bf16 v[122:125], v[150:153], v[174:177], v[122:125]
	v_mfma_f32_16x16x32_bf16 v[106:109], v[150:153], v[182:185], v[106:109]
	v_mfma_f32_16x16x32_bf16 v[106:109], v[154:157], v[186:189], v[106:109]
	v_mfma_f32_16x16x32_bf16 v[110:113], v[146:149], v[186:189], v[110:113]
	v_mfma_f32_16x16x32_bf16 v[110:113], v[142:145], v[182:185], v[110:113]
	v_mfma_f32_16x16x32_bf16 v[94:97], v[142:145], v[190:193], v[94:97]
	v_mfma_f32_16x16x32_bf16 v[94:97], v[146:149], v[194:197], v[94:97]
	v_mfma_f32_16x16x32_bf16 v[90:93], v[154:157], v[194:197], v[90:93]
	v_mfma_f32_16x16x32_bf16 v[90:93], v[150:153], v[190:193], v[90:93]
	v_mfma_f32_16x16x32_bf16 v[74:77], v[150:153], v[198:201], v[74:77]
	v_mfma_f32_16x16x32_bf16 v[74:77], v[154:157], v[204:207], v[74:77]
	v_mfma_f32_16x16x32_bf16 v[78:81], v[146:149], v[204:207], v[78:81]
	v_mfma_f32_16x16x32_bf16 v[78:81], v[142:145], v[198:201], v[78:81]
	s_setprio 0
	s_setprio 1
	v_mfma_f32_16x16x32_bf16 v[70:73], v[158:161], v[198:201], v[70:73]
	v_mfma_f32_16x16x32_bf16 v[70:73], v[162:165], v[204:207], v[70:73]
	v_mfma_f32_16x16x32_bf16 v[66:69], v[170:173], v[204:207], v[66:69]
	v_mfma_f32_16x16x32_bf16 v[66:69], v[166:169], v[198:201], v[66:69]
	v_mfma_f32_16x16x32_bf16 v[82:85], v[166:169], v[190:193], v[82:85]
	v_mfma_f32_16x16x32_bf16 v[82:85], v[170:173], v[194:197], v[82:85]
	v_mfma_f32_16x16x32_bf16 v[86:89], v[162:165], v[194:197], v[86:89]
	v_mfma_f32_16x16x32_bf16 v[86:89], v[158:161], v[190:193], v[86:89]
	v_mfma_f32_16x16x32_bf16 v[102:105], v[158:161], v[182:185], v[102:105]
	v_mfma_f32_16x16x32_bf16 v[102:105], v[162:165], v[186:189], v[102:105]
	v_mfma_f32_16x16x32_bf16 v[98:101], v[170:173], v[186:189], v[98:101]
	v_mfma_f32_16x16x32_bf16 v[98:101], v[166:169], v[182:185], v[98:101]
	v_mfma_f32_16x16x32_bf16 v[114:117], v[166:169], v[174:177], v[114:117]
	v_mfma_f32_16x16x32_bf16 v[114:117], v[170:173], v[178:181], v[114:117]
	v_mfma_f32_16x16x32_bf16 v[118:121], v[162:165], v[178:181], v[118:121]
	v_mfma_f32_16x16x32_bf16 v[118:121], v[158:161], v[174:177], v[118:121]
	s_setprio 0
	s_barrier
	s_or_b32 s31, s36, 0x80
	s_mov_b32 m0, s22
	v_add_u32_e32 v141, s31, v131
	ds_read_b128 v[174:177], v140 offset:49152
	ds_read_b128 v[178:181], v140 offset:50176
	ds_read_b128 v[182:185], v140 offset:51200
	ds_read_b128 v[186:189], v140 offset:52224
	ds_read_b128 v[190:193], v140 offset:53248
	ds_read_b128 v[194:197], v140 offset:54272
	ds_read_b128 v[198:201], v140 offset:55296
	ds_read_b128 v[204:207], v140 offset:56320
	global_load_lds_dwordx4 v141, s[6:7]
	v_add_u32_e32 v141, s31, v133
	s_mov_b32 m0, s23
	s_add_i32 s36, s36, 0x80080
	global_load_lds_dwordx4 v141, s[6:7]
	v_add_u32_e32 v141, s36, v131
	s_mov_b32 m0, s27
	s_nop 0
	global_load_lds_dwordx4 v141, s[6:7]
	v_add_u32_e32 v141, s36, v133
	s_mov_b32 m0, s29
	s_nop 0
	global_load_lds_dwordx4 v141, s[6:7]
	v_add_u32_e32 v141, s35, v130
	s_mov_b32 m0, s24
	s_nop 0
	global_load_lds_dwordx4 v141, s[4:5]
	v_add_u32_e32 v141, s35, v132
	s_mov_b32 m0, s25
	s_nop 0
	global_load_lds_dwordx4 v141, s[4:5]
	s_waitcnt vmcnt(8)
	s_waitcnt lgkmcnt(0)
	s_setprio 1
	s_barrier
	v_mfma_f32_16x16x32_bf16 v[62:65], v[142:145], v[174:177], v[62:65]
	v_mfma_f32_16x16x32_bf16 v[62:65], v[146:149], v[178:181], v[62:65]
	v_mfma_f32_16x16x32_bf16 v[58:61], v[154:157], v[178:181], v[58:61]
	v_mfma_f32_16x16x32_bf16 v[58:61], v[150:153], v[174:177], v[58:61]
	v_mfma_f32_16x16x32_bf16 v[42:45], v[150:153], v[182:185], v[42:45]
	v_mfma_f32_16x16x32_bf16 v[42:45], v[154:157], v[186:189], v[42:45]
	v_mfma_f32_16x16x32_bf16 v[46:49], v[146:149], v[186:189], v[46:49]
	v_mfma_f32_16x16x32_bf16 v[46:49], v[142:145], v[182:185], v[46:49]
	v_mfma_f32_16x16x32_bf16 v[30:33], v[142:145], v[190:193], v[30:33]
	v_mfma_f32_16x16x32_bf16 v[30:33], v[146:149], v[194:197], v[30:33]
	v_mfma_f32_16x16x32_bf16 v[26:29], v[154:157], v[194:197], v[26:29]
	v_mfma_f32_16x16x32_bf16 v[26:29], v[150:153], v[190:193], v[26:29]
	v_mfma_f32_16x16x32_bf16 v[10:13], v[150:153], v[198:201], v[10:13]
	v_mfma_f32_16x16x32_bf16 v[10:13], v[154:157], v[204:207], v[10:13]
	v_mfma_f32_16x16x32_bf16 v[14:17], v[146:149], v[204:207], v[14:17]
	v_mfma_f32_16x16x32_bf16 v[14:17], v[142:145], v[198:201], v[14:17]
	s_setprio 0
	s_setprio 1
	v_mfma_f32_16x16x32_bf16 v[6:9], v[158:161], v[198:201], v[6:9]
	v_mfma_f32_16x16x32_bf16 v[6:9], v[162:165], v[204:207], v[6:9]
	v_mfma_f32_16x16x32_bf16 v[2:5], v[170:173], v[204:207], v[2:5]
	v_mfma_f32_16x16x32_bf16 v[2:5], v[166:169], v[198:201], v[2:5]
	v_mfma_f32_16x16x32_bf16 v[18:21], v[166:169], v[190:193], v[18:21]
	v_mfma_f32_16x16x32_bf16 v[18:21], v[170:173], v[194:197], v[18:21]
	v_mfma_f32_16x16x32_bf16 v[22:25], v[162:165], v[194:197], v[22:25]
	v_mfma_f32_16x16x32_bf16 v[22:25], v[158:161], v[190:193], v[22:25]
	v_mfma_f32_16x16x32_bf16 v[38:41], v[158:161], v[182:185], v[38:41]
	v_mfma_f32_16x16x32_bf16 v[38:41], v[162:165], v[186:189], v[38:41]
	v_mfma_f32_16x16x32_bf16 v[34:37], v[170:173], v[186:189], v[34:37]
	v_mfma_f32_16x16x32_bf16 v[34:37], v[166:169], v[182:185], v[34:37]
	v_mfma_f32_16x16x32_bf16 v[50:53], v[166:169], v[174:177], v[50:53]
	v_mfma_f32_16x16x32_bf16 v[50:53], v[170:173], v[178:181], v[50:53]
	v_mfma_f32_16x16x32_bf16 v[54:57], v[162:165], v[178:181], v[54:57]
	v_mfma_f32_16x16x32_bf16 v[54:57], v[158:161], v[174:177], v[54:57]
	s_setprio 0
	s_barrier
	s_add_i32 s30, s30, 2
	s_cmp_gt_u32 s30, 29
	s_mov_b32 s31, s34
	s_cbranch_scc0 .LBB0_741
	s_cmpk_lt_u32 s8, 0x100
	s_cbranch_scc0 .LBB0_744
	s_barrier

.LBB0_783:
	s_mul_i32 s12, s40, 0x2c0000
	s_and_b64 s[48:49], s[4:5], exec
	s_mul_i32 s13, s39, 0x2c0000
	s_cselect_b32 s43, s12, s45
	s_cselect_b32 s44, s13, s46
	s_add_i32 s45, s45, 0x160080
	s_addk_i32 s46, 0x100
	s_mov_b32 s47, -2
	v_add_u32_e32 v130, s17, v137
	ds_read_b128 v[142:145], v130
	ds_read_b128 v[146:149], v130 offset:1024
	ds_read_b128 v[150:153], v130 offset:2048
	ds_read_b128 v[154:157], v130 offset:3072
	v_add_u32_e32 v130, s20, v137
	ds_read_b128 v[158:161], v130
	ds_read_b128 v[162:165], v130 offset:1024
	ds_read_b128 v[166:169], v130 offset:2048
	ds_read_b128 v[170:173], v130 offset:3072
	s_add_i32 s48, s45, 0xffea0080
	s_cmpk_eq_i32 s47, 0x54
	s_cselect_b32 s50, s43, s48
	s_cselect_b32 s49, s44, s46
	s_or_b32 s48, s50, 0x80
	v_add_u32_e32 v130, s45, v140
	s_add_i32 m0, s23, 0xc000
	ds_read_b128 v[174:177], v141
	ds_read_b128 v[178:181], v141 offset:1024
	ds_read_b128 v[182:185], v141 offset:2048
	ds_read_b128 v[186:189], v141 offset:3072
	ds_read_b128 v[190:193], v141 offset:4096
	ds_read_b128 v[194:197], v141 offset:5120
	ds_read_b128 v[198:201], v141 offset:6144
	ds_read_b128 v[204:207], v141 offset:7168
	global_load_lds_dwordx4 v130, s[0:1]
	v_add_u32_e32 v130, s45, v139
	s_add_i32 m0, s23, 0xe000
	s_nop 0
	global_load_lds_dwordx4 v130, s[0:1]
	s_waitcnt vmcnt(8)
	s_waitcnt lgkmcnt(0)
	s_setprio 1
	s_barrier
	v_mfma_f32_16x16x32_bf16 v[126:129], v[142:145], v[174:177], 0
	v_mfma_f32_16x16x32_bf16 v[126:129], v[146:149], v[178:181], v[126:129]
	v_mfma_f32_16x16x32_bf16 v[122:125], v[154:157], v[178:181], 0
	v_mfma_f32_16x16x32_bf16 v[122:125], v[150:153], v[174:177], v[122:125]
	v_mfma_f32_16x16x32_bf16 v[110:113], v[150:153], v[182:185], 0
	v_mfma_f32_16x16x32_bf16 v[110:113], v[154:157], v[186:189], v[110:113]
	v_mfma_f32_16x16x32_bf16 v[118:121], v[146:149], v[186:189], 0
	v_mfma_f32_16x16x32_bf16 v[118:121], v[142:145], v[182:185], v[118:121]
	v_mfma_f32_16x16x32_bf16 v[102:105], v[142:145], v[190:193], 0
	v_mfma_f32_16x16x32_bf16 v[102:105], v[146:149], v[194:197], v[102:105]
	v_mfma_f32_16x16x32_bf16 v[94:97], v[154:157], v[194:197], 0
	v_mfma_f32_16x16x32_bf16 v[94:97], v[150:153], v[190:193], v[94:97]
	v_mfma_f32_16x16x32_bf16 v[78:81], v[150:153], v[198:201], 0
	v_mfma_f32_16x16x32_bf16 v[78:81], v[154:157], v[204:207], v[78:81]
	v_mfma_f32_16x16x32_bf16 v[86:89], v[146:149], v[204:207], 0
	v_mfma_f32_16x16x32_bf16 v[86:89], v[142:145], v[198:201], v[86:89]
	s_setprio 0
	s_setprio 1
	v_mfma_f32_16x16x32_bf16 v[70:73], v[158:161], v[198:201], 0
	v_mfma_f32_16x16x32_bf16 v[70:73], v[162:165], v[204:207], v[70:73]
	v_mfma_f32_16x16x32_bf16 v[66:69], v[170:173], v[204:207], 0
	v_mfma_f32_16x16x32_bf16 v[66:69], v[166:169], v[198:201], v[66:69]
	v_mfma_f32_16x16x32_bf16 v[74:77], v[166:169], v[190:193], 0
	v_mfma_f32_16x16x32_bf16 v[74:77], v[170:173], v[194:197], v[74:77]
	v_mfma_f32_16x16x32_bf16 v[82:85], v[162:165], v[194:197], 0
	v_mfma_f32_16x16x32_bf16 v[82:85], v[158:161], v[190:193], v[82:85]
	v_mfma_f32_16x16x32_bf16 v[98:101], v[158:161], v[182:185], 0
	v_mfma_f32_16x16x32_bf16 v[98:101], v[162:165], v[186:189], v[98:101]
	v_mfma_f32_16x16x32_bf16 v[90:93], v[170:173], v[186:189], 0
	v_mfma_f32_16x16x32_bf16 v[90:93], v[166:169], v[182:185], v[90:93]
	v_mfma_f32_16x16x32_bf16 v[106:109], v[166:169], v[174:177], 0
	v_mfma_f32_16x16x32_bf16 v[106:109], v[170:173], v[178:181], v[106:109]
	v_mfma_f32_16x16x32_bf16 v[114:117], v[162:165], v[178:181], 0
	v_mfma_f32_16x16x32_bf16 v[114:117], v[158:161], v[174:177], v[114:117]
	s_setprio 0
	s_barrier
	s_mov_b32 m0, s18
	v_add_u32_e32 v130, s49, v133
	ds_read_b128 v[174:177], v141 offset:16384
	ds_read_b128 v[178:181], v141 offset:17408
	ds_read_b128 v[182:185], v141 offset:18432
	ds_read_b128 v[186:189], v141 offset:19456
	ds_read_b128 v[190:193], v141 offset:20480
	ds_read_b128 v[194:197], v141 offset:21504
	ds_read_b128 v[198:201], v141 offset:22528
	ds_read_b128 v[204:207], v141 offset:23552
	global_load_lds_dwordx4 v130, s[2:3]
	v_add_u32_e32 v130, s49, v135
	s_mov_b32 m0, s19
	s_add_i32 s51, s49, 0x160000
	global_load_lds_dwordx4 v130, s[2:3]
	v_add_u32_e32 v130, s51, v133
	s_mov_b32 m0, s21
	s_nop 0
	global_load_lds_dwordx4 v130, s[2:3]
	v_add_u32_e32 v130, s51, v135
	s_mov_b32 m0, s22
	s_nop 0
	global_load_lds_dwordx4 v130, s[2:3]
	v_add_u32_e32 v130, s50, v132
	s_mov_b32 m0, s23
	s_nop 0
	global_load_lds_dwordx4 v130, s[0:1]
	v_add_u32_e32 v130, s50, v134
	s_mov_b32 m0, s24
	s_nop 0
	global_load_lds_dwordx4 v130, s[0:1]
	s_waitcnt vmcnt(8)
	s_waitcnt lgkmcnt(0)
	s_setprio 1
	s_barrier
	v_mfma_f32_16x16x32_bf16 v[62:65], v[142:145], v[174:177], 0
	v_mfma_f32_16x16x32_bf16 v[62:65], v[146:149], v[178:181], v[62:65]
	v_mfma_f32_16x16x32_bf16 v[58:61], v[154:157], v[178:181], 0
	v_mfma_f32_16x16x32_bf16 v[58:61], v[150:153], v[174:177], v[58:61]
	v_mfma_f32_16x16x32_bf16 v[46:49], v[150:153], v[182:185], 0
	v_mfma_f32_16x16x32_bf16 v[46:49], v[154:157], v[186:189], v[46:49]
	v_mfma_f32_16x16x32_bf16 v[54:57], v[146:149], v[186:189], 0
	v_mfma_f32_16x16x32_bf16 v[54:57], v[142:145], v[182:185], v[54:57]
	v_mfma_f32_16x16x32_bf16 v[38:41], v[142:145], v[190:193], 0
	v_mfma_f32_16x16x32_bf16 v[38:41], v[146:149], v[194:197], v[38:41]
	v_mfma_f32_16x16x32_bf16 v[30:33], v[154:157], v[194:197], 0
	v_mfma_f32_16x16x32_bf16 v[30:33], v[150:153], v[190:193], v[30:33]
	v_mfma_f32_16x16x32_bf16 v[14:17], v[150:153], v[198:201], 0
	v_mfma_f32_16x16x32_bf16 v[14:17], v[154:157], v[204:207], v[14:17]
	v_mfma_f32_16x16x32_bf16 v[22:25], v[146:149], v[204:207], 0
	v_mfma_f32_16x16x32_bf16 v[22:25], v[142:145], v[198:201], v[22:25]
	s_setprio 0
	s_setprio 1
	v_mfma_f32_16x16x32_bf16 v[6:9], v[158:161], v[198:201], 0
	v_mfma_f32_16x16x32_bf16 v[6:9], v[162:165], v[204:207], v[6:9]
	v_mfma_f32_16x16x32_bf16 v[2:5], v[170:173], v[204:207], 0
	v_mfma_f32_16x16x32_bf16 v[2:5], v[166:169], v[198:201], v[2:5]
	v_mfma_f32_16x16x32_bf16 v[10:13], v[166:169], v[190:193], 0
	v_mfma_f32_16x16x32_bf16 v[10:13], v[170:173], v[194:197], v[10:13]
	v_mfma_f32_16x16x32_bf16 v[18:21], v[162:165], v[194:197], 0
	v_mfma_f32_16x16x32_bf16 v[18:21], v[158:161], v[190:193], v[18:21]
	v_mfma_f32_16x16x32_bf16 v[34:37], v[158:161], v[182:185], 0
	v_mfma_f32_16x16x32_bf16 v[34:37], v[162:165], v[186:189], v[34:37]
	v_mfma_f32_16x16x32_bf16 v[26:29], v[170:173], v[186:189], 0
	v_mfma_f32_16x16x32_bf16 v[26:29], v[166:169], v[182:185], v[26:29]
	v_mfma_f32_16x16x32_bf16 v[42:45], v[166:169], v[174:177], 0
	v_mfma_f32_16x16x32_bf16 v[42:45], v[170:173], v[178:181], v[42:45]
	v_mfma_f32_16x16x32_bf16 v[50:53], v[162:165], v[178:181], 0
	v_mfma_f32_16x16x32_bf16 v[50:53], v[158:161], v[174:177], v[50:53]
	s_setprio 0
	s_barrier
	v_add_u32_e32 v130, s27, v137
	ds_read_b128 v[142:145], v130
	ds_read_b128 v[146:149], v130 offset:1024
	ds_read_b128 v[150:153], v130 offset:2048
	ds_read_b128 v[154:157], v130 offset:3072
	v_add_u32_e32 v130, s34, v137
	ds_read_b128 v[158:161], v130
	ds_read_b128 v[162:165], v130 offset:1024
	ds_read_b128 v[166:169], v130 offset:2048
	ds_read_b128 v[170:173], v130 offset:3072
	s_add_i32 s50, s50, 0x160000
	s_mov_b32 m0, s25
	v_add_u32_e32 v130, s50, v132
	ds_read_b128 v[174:177], v141 offset:32768
	ds_read_b128 v[178:181], v141 offset:33792
	ds_read_b128 v[182:185], v141 offset:34816
	ds_read_b128 v[186:189], v141 offset:35840
	ds_read_b128 v[190:193], v141 offset:36864
	ds_read_b128 v[194:197], v141 offset:37888
	ds_read_b128 v[198:201], v141 offset:38912
	ds_read_b128 v[204:207], v141 offset:39936
	global_load_lds_dwordx4 v130, s[0:1]
	v_add_u32_e32 v130, s50, v134
	s_mov_b32 m0, s26
	s_nop 0
	global_load_lds_dwordx4 v130, s[0:1]
	s_waitcnt vmcnt(8)
	s_waitcnt lgkmcnt(0)
	s_setprio 1
	s_barrier
	v_mfma_f32_16x16x32_bf16 v[126:129], v[142:145], v[174:177], v[126:129]
	v_mfma_f32_16x16x32_bf16 v[126:129], v[146:149], v[178:181], v[126:129]
	v_mfma_f32_16x16x32_bf16 v[122:125], v[154:157], v[178:181], v[122:125]
	v_mfma_f32_16x16x32_bf16 v[122:125], v[150:153], v[174:177], v[122:125]
	v_mfma_f32_16x16x32_bf16 v[110:113], v[150:153], v[182:185], v[110:113]
	v_mfma_f32_16x16x32_bf16 v[110:113], v[154:157], v[186:189], v[110:113]
	v_mfma_f32_16x16x32_bf16 v[118:121], v[146:149], v[186:189], v[118:121]
	v_mfma_f32_16x16x32_bf16 v[118:121], v[142:145], v[182:185], v[118:121]
	v_mfma_f32_16x16x32_bf16 v[102:105], v[142:145], v[190:193], v[102:105]
	v_mfma_f32_16x16x32_bf16 v[102:105], v[146:149], v[194:197], v[102:105]
	v_mfma_f32_16x16x32_bf16 v[94:97], v[154:157], v[194:197], v[94:97]
	v_mfma_f32_16x16x32_bf16 v[94:97], v[150:153], v[190:193], v[94:97]
	v_mfma_f32_16x16x32_bf16 v[78:81], v[150:153], v[198:201], v[78:81]
	v_mfma_f32_16x16x32_bf16 v[78:81], v[154:157], v[204:207], v[78:81]
	v_mfma_f32_16x16x32_bf16 v[86:89], v[146:149], v[204:207], v[86:89]
	v_mfma_f32_16x16x32_bf16 v[86:89], v[142:145], v[198:201], v[86:89]
	s_setprio 0
	s_setprio 1
	v_mfma_f32_16x16x32_bf16 v[70:73], v[158:161], v[198:201], v[70:73]
	v_mfma_f32_16x16x32_bf16 v[70:73], v[162:165], v[204:207], v[70:73]
	v_mfma_f32_16x16x32_bf16 v[66:69], v[170:173], v[204:207], v[66:69]
	v_mfma_f32_16x16x32_bf16 v[66:69], v[166:169], v[198:201], v[66:69]
	v_mfma_f32_16x16x32_bf16 v[74:77], v[166:169], v[190:193], v[74:77]
	v_mfma_f32_16x16x32_bf16 v[74:77], v[170:173], v[194:197], v[74:77]
	v_mfma_f32_16x16x32_bf16 v[82:85], v[162:165], v[194:197], v[82:85]
	v_mfma_f32_16x16x32_bf16 v[82:85], v[158:161], v[190:193], v[82:85]
	v_mfma_f32_16x16x32_bf16 v[98:101], v[158:161], v[182:185], v[98:101]
	v_mfma_f32_16x16x32_bf16 v[98:101], v[162:165], v[186:189], v[98:101]
	v_mfma_f32_16x16x32_bf16 v[90:93], v[170:173], v[186:189], v[90:93]
	v_mfma_f32_16x16x32_bf16 v[90:93], v[166:169], v[182:185], v[90:93]
	v_mfma_f32_16x16x32_bf16 v[106:109], v[166:169], v[174:177], v[106:109]
	v_mfma_f32_16x16x32_bf16 v[106:109], v[170:173], v[178:181], v[106:109]
	v_mfma_f32_16x16x32_bf16 v[114:117], v[162:165], v[178:181], v[114:117]
	v_mfma_f32_16x16x32_bf16 v[114:117], v[158:161], v[174:177], v[114:117]
	s_setprio 0
	s_barrier
	s_or_b32 s50, s49, 0x80
	s_mov_b32 m0, s28
	v_add_u32_e32 v130, s50, v133
	ds_read_b128 v[174:177], v141 offset:49152
	ds_read_b128 v[178:181], v141 offset:50176
	ds_read_b128 v[182:185], v141 offset:51200
	ds_read_b128 v[186:189], v141 offset:52224
	ds_read_b128 v[190:193], v141 offset:53248
	ds_read_b128 v[194:197], v141 offset:54272
	ds_read_b128 v[198:201], v141 offset:55296
	ds_read_b128 v[204:207], v141 offset:56320
	global_load_lds_dwordx4 v130, s[2:3]
	v_add_u32_e32 v130, s50, v135
	s_mov_b32 m0, s29
	s_add_i32 s49, s49, 0x160080
	global_load_lds_dwordx4 v130, s[2:3]
	v_add_u32_e32 v130, s49, v133
	s_mov_b32 m0, s35
	s_nop 0
	global_load_lds_dwordx4 v130, s[2:3]
	v_add_u32_e32 v130, s49, v135
	s_mov_b32 m0, s36
	s_nop 0
	global_load_lds_dwordx4 v130, s[2:3]
	v_add_u32_e32 v130, s48, v132
	s_mov_b32 m0, s30
	s_nop 0
	global_load_lds_dwordx4 v130, s[0:1]
	v_add_u32_e32 v130, s48, v134
	s_mov_b32 m0, s31
	s_nop 0
	global_load_lds_dwordx4 v130, s[0:1]
	s_waitcnt vmcnt(8)
	s_waitcnt lgkmcnt(0)
	s_setprio 1
	s_barrier
	v_mfma_f32_16x16x32_bf16 v[62:65], v[142:145], v[174:177], v[62:65]
	v_mfma_f32_16x16x32_bf16 v[62:65], v[146:149], v[178:181], v[62:65]
	v_mfma_f32_16x16x32_bf16 v[58:61], v[154:157], v[178:181], v[58:61]
	v_mfma_f32_16x16x32_bf16 v[58:61], v[150:153], v[174:177], v[58:61]
	v_mfma_f32_16x16x32_bf16 v[46:49], v[150:153], v[182:185], v[46:49]
	v_mfma_f32_16x16x32_bf16 v[46:49], v[154:157], v[186:189], v[46:49]
	v_mfma_f32_16x16x32_bf16 v[54:57], v[146:149], v[186:189], v[54:57]
	v_mfma_f32_16x16x32_bf16 v[54:57], v[142:145], v[182:185], v[54:57]
	v_mfma_f32_16x16x32_bf16 v[38:41], v[142:145], v[190:193], v[38:41]
	v_mfma_f32_16x16x32_bf16 v[38:41], v[146:149], v[194:197], v[38:41]
	v_mfma_f32_16x16x32_bf16 v[30:33], v[154:157], v[194:197], v[30:33]
	v_mfma_f32_16x16x32_bf16 v[30:33], v[150:153], v[190:193], v[30:33]
	v_mfma_f32_16x16x32_bf16 v[14:17], v[150:153], v[198:201], v[14:17]
	v_mfma_f32_16x16x32_bf16 v[14:17], v[154:157], v[204:207], v[14:17]
	v_mfma_f32_16x16x32_bf16 v[22:25], v[146:149], v[204:207], v[22:25]
	v_mfma_f32_16x16x32_bf16 v[22:25], v[142:145], v[198:201], v[22:25]
	s_setprio 0
	s_setprio 1
	v_mfma_f32_16x16x32_bf16 v[6:9], v[158:161], v[198:201], v[6:9]
	v_mfma_f32_16x16x32_bf16 v[6:9], v[162:165], v[204:207], v[6:9]
	v_mfma_f32_16x16x32_bf16 v[2:5], v[170:173], v[204:207], v[2:5]
	v_mfma_f32_16x16x32_bf16 v[2:5], v[166:169], v[198:201], v[2:5]
	v_mfma_f32_16x16x32_bf16 v[10:13], v[166:169], v[190:193], v[10:13]
	v_mfma_f32_16x16x32_bf16 v[10:13], v[170:173], v[194:197], v[10:13]
	v_mfma_f32_16x16x32_bf16 v[18:21], v[162:165], v[194:197], v[18:21]
	v_mfma_f32_16x16x32_bf16 v[18:21], v[158:161], v[190:193], v[18:21]
	v_mfma_f32_16x16x32_bf16 v[34:37], v[158:161], v[182:185], v[34:37]
	v_mfma_f32_16x16x32_bf16 v[34:37], v[162:165], v[186:189], v[34:37]
	v_mfma_f32_16x16x32_bf16 v[26:29], v[170:173], v[186:189], v[26:29]
	v_mfma_f32_16x16x32_bf16 v[26:29], v[166:169], v[182:185], v[26:29]
	v_mfma_f32_16x16x32_bf16 v[42:45], v[166:169], v[174:177], v[42:45]
	v_mfma_f32_16x16x32_bf16 v[42:45], v[170:173], v[178:181], v[42:45]
	v_mfma_f32_16x16x32_bf16 v[50:53], v[162:165], v[178:181], v[50:53]
	v_mfma_f32_16x16x32_bf16 v[50:53], v[158:161], v[174:177], v[50:53]
	s_setprio 0
	s_barrier
	s_add_i32 s47, s47, 2
	s_addk_i32 s45, 0x100
	s_addk_i32 s46, 0x100
	s_cmpk_gt_u32 s47, 0x55
.LBB0_784:
	v_add_u32_e32 v130, s17, v137
	ds_read_b128 v[142:145], v130
	ds_read_b128 v[146:149], v130 offset:1024
	ds_read_b128 v[150:153], v130 offset:2048
	ds_read_b128 v[154:157], v130 offset:3072
	v_add_u32_e32 v130, s20, v137
	ds_read_b128 v[158:161], v130
	ds_read_b128 v[162:165], v130 offset:1024
	ds_read_b128 v[166:169], v130 offset:2048
	ds_read_b128 v[170:173], v130 offset:3072
	s_add_i32 s48, s45, 0xffea0080
	s_cmpk_eq_i32 s47, 0x54
	s_cselect_b32 s50, s43, s48
	s_cselect_b32 s49, s44, s46
	s_or_b32 s48, s50, 0x80
	v_add_u32_e32 v130, s45, v140
	s_add_i32 m0, s23, 0xc000
	ds_read_b128 v[174:177], v141
	ds_read_b128 v[178:181], v141 offset:1024
	ds_read_b128 v[182:185], v141 offset:2048
	ds_read_b128 v[186:189], v141 offset:3072
	ds_read_b128 v[190:193], v141 offset:4096
	ds_read_b128 v[194:197], v141 offset:5120
	ds_read_b128 v[198:201], v141 offset:6144
	ds_read_b128 v[204:207], v141 offset:7168
	global_load_lds_dwordx4 v130, s[0:1]
	v_add_u32_e32 v130, s45, v139
	s_add_i32 m0, s23, 0xe000
	s_nop 0
	global_load_lds_dwordx4 v130, s[0:1]
	s_waitcnt vmcnt(8)
	s_waitcnt lgkmcnt(0)
	s_setprio 1
	s_barrier
	v_mfma_f32_16x16x32_bf16 v[126:129], v[142:145], v[174:177], v[126:129]
	v_mfma_f32_16x16x32_bf16 v[126:129], v[146:149], v[178:181], v[126:129]
	v_mfma_f32_16x16x32_bf16 v[122:125], v[154:157], v[178:181], v[122:125]
	v_mfma_f32_16x16x32_bf16 v[122:125], v[150:153], v[174:177], v[122:125]
	v_mfma_f32_16x16x32_bf16 v[110:113], v[150:153], v[182:185], v[110:113]
	v_mfma_f32_16x16x32_bf16 v[110:113], v[154:157], v[186:189], v[110:113]
	v_mfma_f32_16x16x32_bf16 v[118:121], v[146:149], v[186:189], v[118:121]
	v_mfma_f32_16x16x32_bf16 v[118:121], v[142:145], v[182:185], v[118:121]
	v_mfma_f32_16x16x32_bf16 v[102:105], v[142:145], v[190:193], v[102:105]
	v_mfma_f32_16x16x32_bf16 v[102:105], v[146:149], v[194:197], v[102:105]
	v_mfma_f32_16x16x32_bf16 v[94:97], v[154:157], v[194:197], v[94:97]
	v_mfma_f32_16x16x32_bf16 v[94:97], v[150:153], v[190:193], v[94:97]
	v_mfma_f32_16x16x32_bf16 v[78:81], v[150:153], v[198:201], v[78:81]
	v_mfma_f32_16x16x32_bf16 v[78:81], v[154:157], v[204:207], v[78:81]
	v_mfma_f32_16x16x32_bf16 v[86:89], v[146:149], v[204:207], v[86:89]
	v_mfma_f32_16x16x32_bf16 v[86:89], v[142:145], v[198:201], v[86:89]
	s_setprio 0
	s_setprio 1
	v_mfma_f32_16x16x32_bf16 v[70:73], v[158:161], v[198:201], v[70:73]
	v_mfma_f32_16x16x32_bf16 v[70:73], v[162:165], v[204:207], v[70:73]
	v_mfma_f32_16x16x32_bf16 v[66:69], v[170:173], v[204:207], v[66:69]
	v_mfma_f32_16x16x32_bf16 v[66:69], v[166:169], v[198:201], v[66:69]
	v_mfma_f32_16x16x32_bf16 v[74:77], v[166:169], v[190:193], v[74:77]
	v_mfma_f32_16x16x32_bf16 v[74:77], v[170:173], v[194:197], v[74:77]
	v_mfma_f32_16x16x32_bf16 v[82:85], v[162:165], v[194:197], v[82:85]
	v_mfma_f32_16x16x32_bf16 v[82:85], v[158:161], v[190:193], v[82:85]
	v_mfma_f32_16x16x32_bf16 v[98:101], v[158:161], v[182:185], v[98:101]
	v_mfma_f32_16x16x32_bf16 v[98:101], v[162:165], v[186:189], v[98:101]
	v_mfma_f32_16x16x32_bf16 v[90:93], v[170:173], v[186:189], v[90:93]
	v_mfma_f32_16x16x32_bf16 v[90:93], v[166:169], v[182:185], v[90:93]
	v_mfma_f32_16x16x32_bf16 v[106:109], v[166:169], v[174:177], v[106:109]
	v_mfma_f32_16x16x32_bf16 v[106:109], v[170:173], v[178:181], v[106:109]
	v_mfma_f32_16x16x32_bf16 v[114:117], v[162:165], v[178:181], v[114:117]
	v_mfma_f32_16x16x32_bf16 v[114:117], v[158:161], v[174:177], v[114:117]
	s_setprio 0
	s_barrier
	s_mov_b32 m0, s18
	v_add_u32_e32 v130, s49, v133
	ds_read_b128 v[174:177], v141 offset:16384
	ds_read_b128 v[178:181], v141 offset:17408
	ds_read_b128 v[182:185], v141 offset:18432
	ds_read_b128 v[186:189], v141 offset:19456
	ds_read_b128 v[190:193], v141 offset:20480
	ds_read_b128 v[194:197], v141 offset:21504
	ds_read_b128 v[198:201], v141 offset:22528
	ds_read_b128 v[204:207], v141 offset:23552
	global_load_lds_dwordx4 v130, s[2:3]
	v_add_u32_e32 v130, s49, v135
	s_mov_b32 m0, s19
	s_add_i32 s51, s49, 0x160000
	global_load_lds_dwordx4 v130, s[2:3]
	v_add_u32_e32 v130, s51, v133
	s_mov_b32 m0, s21
	s_nop 0
	global_load_lds_dwordx4 v130, s[2:3]
	v_add_u32_e32 v130, s51, v135
	s_mov_b32 m0, s22
	s_nop 0
	global_load_lds_dwordx4 v130, s[2:3]
	v_add_u32_e32 v130, s50, v132
	s_mov_b32 m0, s23
	s_nop 0
	global_load_lds_dwordx4 v130, s[0:1]
	v_add_u32_e32 v130, s50, v134
	s_mov_b32 m0, s24
	s_nop 0
	global_load_lds_dwordx4 v130, s[0:1]
	s_waitcnt vmcnt(8)
	s_waitcnt lgkmcnt(0)
	s_setprio 1
	s_barrier
	v_mfma_f32_16x16x32_bf16 v[62:65], v[142:145], v[174:177], v[62:65]
	v_mfma_f32_16x16x32_bf16 v[62:65], v[146:149], v[178:181], v[62:65]
	v_mfma_f32_16x16x32_bf16 v[58:61], v[154:157], v[178:181], v[58:61]
	v_mfma_f32_16x16x32_bf16 v[58:61], v[150:153], v[174:177], v[58:61]
	v_mfma_f32_16x16x32_bf16 v[46:49], v[150:153], v[182:185], v[46:49]
	v_mfma_f32_16x16x32_bf16 v[46:49], v[154:157], v[186:189], v[46:49]
	v_mfma_f32_16x16x32_bf16 v[54:57], v[146:149], v[186:189], v[54:57]
	v_mfma_f32_16x16x32_bf16 v[54:57], v[142:145], v[182:185], v[54:57]
	v_mfma_f32_16x16x32_bf16 v[38:41], v[142:145], v[190:193], v[38:41]
	v_mfma_f32_16x16x32_bf16 v[38:41], v[146:149], v[194:197], v[38:41]
	v_mfma_f32_16x16x32_bf16 v[30:33], v[154:157], v[194:197], v[30:33]
	v_mfma_f32_16x16x32_bf16 v[30:33], v[150:153], v[190:193], v[30:33]
	v_mfma_f32_16x16x32_bf16 v[14:17], v[150:153], v[198:201], v[14:17]
	v_mfma_f32_16x16x32_bf16 v[14:17], v[154:157], v[204:207], v[14:17]
	v_mfma_f32_16x16x32_bf16 v[22:25], v[146:149], v[204:207], v[22:25]
	v_mfma_f32_16x16x32_bf16 v[22:25], v[142:145], v[198:201], v[22:25]
	s_setprio 0
	s_setprio 1
	v_mfma_f32_16x16x32_bf16 v[6:9], v[158:161], v[198:201], v[6:9]
	v_mfma_f32_16x16x32_bf16 v[6:9], v[162:165], v[204:207], v[6:9]
	v_mfma_f32_16x16x32_bf16 v[2:5], v[170:173], v[204:207], v[2:5]
	v_mfma_f32_16x16x32_bf16 v[2:5], v[166:169], v[198:201], v[2:5]
	v_mfma_f32_16x16x32_bf16 v[10:13], v[166:169], v[190:193], v[10:13]
	v_mfma_f32_16x16x32_bf16 v[10:13], v[170:173], v[194:197], v[10:13]
	v_mfma_f32_16x16x32_bf16 v[18:21], v[162:165], v[194:197], v[18:21]
	v_mfma_f32_16x16x32_bf16 v[18:21], v[158:161], v[190:193], v[18:21]
	v_mfma_f32_16x16x32_bf16 v[34:37], v[158:161], v[182:185], v[34:37]
	v_mfma_f32_16x16x32_bf16 v[34:37], v[162:165], v[186:189], v[34:37]
	v_mfma_f32_16x16x32_bf16 v[26:29], v[170:173], v[186:189], v[26:29]
	v_mfma_f32_16x16x32_bf16 v[26:29], v[166:169], v[182:185], v[26:29]
	v_mfma_f32_16x16x32_bf16 v[42:45], v[166:169], v[174:177], v[42:45]
	v_mfma_f32_16x16x32_bf16 v[42:45], v[170:173], v[178:181], v[42:45]
	v_mfma_f32_16x16x32_bf16 v[50:53], v[162:165], v[178:181], v[50:53]
	v_mfma_f32_16x16x32_bf16 v[50:53], v[158:161], v[174:177], v[50:53]
	s_setprio 0
	s_barrier
	v_add_u32_e32 v130, s27, v137
	ds_read_b128 v[142:145], v130
	ds_read_b128 v[146:149], v130 offset:1024
	ds_read_b128 v[150:153], v130 offset:2048
	ds_read_b128 v[154:157], v130 offset:3072
	v_add_u32_e32 v130, s34, v137
	ds_read_b128 v[158:161], v130
	ds_read_b128 v[162:165], v130 offset:1024
	ds_read_b128 v[166:169], v130 offset:2048
	ds_read_b128 v[170:173], v130 offset:3072
	s_add_i32 s50, s50, 0x160000
	s_mov_b32 m0, s25
	v_add_u32_e32 v130, s50, v132
	ds_read_b128 v[174:177], v141 offset:32768
	ds_read_b128 v[178:181], v141 offset:33792
	ds_read_b128 v[182:185], v141 offset:34816
	ds_read_b128 v[186:189], v141 offset:35840
	ds_read_b128 v[190:193], v141 offset:36864
	ds_read_b128 v[194:197], v141 offset:37888
	ds_read_b128 v[198:201], v141 offset:38912
	ds_read_b128 v[204:207], v141 offset:39936
	global_load_lds_dwordx4 v130, s[0:1]
	v_add_u32_e32 v130, s50, v134
	s_mov_b32 m0, s26
	s_nop 0
	global_load_lds_dwordx4 v130, s[0:1]
	s_waitcnt vmcnt(8)
	s_waitcnt lgkmcnt(0)
	s_setprio 1
	s_barrier
	v_mfma_f32_16x16x32_bf16 v[126:129], v[142:145], v[174:177], v[126:129]
	v_mfma_f32_16x16x32_bf16 v[126:129], v[146:149], v[178:181], v[126:129]
	v_mfma_f32_16x16x32_bf16 v[122:125], v[154:157], v[178:181], v[122:125]
	v_mfma_f32_16x16x32_bf16 v[122:125], v[150:153], v[174:177], v[122:125]
	v_mfma_f32_16x16x32_bf16 v[110:113], v[150:153], v[182:185], v[110:113]
	v_mfma_f32_16x16x32_bf16 v[110:113], v[154:157], v[186:189], v[110:113]
	v_mfma_f32_16x16x32_bf16 v[118:121], v[146:149], v[186:189], v[118:121]
	v_mfma_f32_16x16x32_bf16 v[118:121], v[142:145], v[182:185], v[118:121]
	v_mfma_f32_16x16x32_bf16 v[102:105], v[142:145], v[190:193], v[102:105]
	v_mfma_f32_16x16x32_bf16 v[102:105], v[146:149], v[194:197], v[102:105]
	v_mfma_f32_16x16x32_bf16 v[94:97], v[154:157], v[194:197], v[94:97]
	v_mfma_f32_16x16x32_bf16 v[94:97], v[150:153], v[190:193], v[94:97]
	v_mfma_f32_16x16x32_bf16 v[78:81], v[150:153], v[198:201], v[78:81]
	v_mfma_f32_16x16x32_bf16 v[78:81], v[154:157], v[204:207], v[78:81]
	v_mfma_f32_16x16x32_bf16 v[86:89], v[146:149], v[204:207], v[86:89]
	v_mfma_f32_16x16x32_bf16 v[86:89], v[142:145], v[198:201], v[86:89]
	s_setprio 0
	s_setprio 1
	v_mfma_f32_16x16x32_bf16 v[70:73], v[158:161], v[198:201], v[70:73]
	v_mfma_f32_16x16x32_bf16 v[70:73], v[162:165], v[204:207], v[70:73]
	v_mfma_f32_16x16x32_bf16 v[66:69], v[170:173], v[204:207], v[66:69]
	v_mfma_f32_16x16x32_bf16 v[66:69], v[166:169], v[198:201], v[66:69]
	v_mfma_f32_16x16x32_bf16 v[74:77], v[166:169], v[190:193], v[74:77]
	v_mfma_f32_16x16x32_bf16 v[74:77], v[170:173], v[194:197], v[74:77]
	v_mfma_f32_16x16x32_bf16 v[82:85], v[162:165], v[194:197], v[82:85]
	v_mfma_f32_16x16x32_bf16 v[82:85], v[158:161], v[190:193], v[82:85]
	v_mfma_f32_16x16x32_bf16 v[98:101], v[158:161], v[182:185], v[98:101]
	v_mfma_f32_16x16x32_bf16 v[98:101], v[162:165], v[186:189], v[98:101]
	v_mfma_f32_16x16x32_bf16 v[90:93], v[170:173], v[186:189], v[90:93]
	v_mfma_f32_16x16x32_bf16 v[90:93], v[166:169], v[182:185], v[90:93]
	v_mfma_f32_16x16x32_bf16 v[106:109], v[166:169], v[174:177], v[106:109]
	v_mfma_f32_16x16x32_bf16 v[106:109], v[170:173], v[178:181], v[106:109]
	v_mfma_f32_16x16x32_bf16 v[114:117], v[162:165], v[178:181], v[114:117]
	v_mfma_f32_16x16x32_bf16 v[114:117], v[158:161], v[174:177], v[114:117]
	s_setprio 0
	s_barrier
	s_or_b32 s50, s49, 0x80
	s_mov_b32 m0, s28
	v_add_u32_e32 v130, s50, v133
	ds_read_b128 v[174:177], v141 offset:49152
	ds_read_b128 v[178:181], v141 offset:50176
	ds_read_b128 v[182:185], v141 offset:51200
	ds_read_b128 v[186:189], v141 offset:52224
	ds_read_b128 v[190:193], v141 offset:53248
	ds_read_b128 v[194:197], v141 offset:54272
	ds_read_b128 v[198:201], v141 offset:55296
	ds_read_b128 v[204:207], v141 offset:56320
	global_load_lds_dwordx4 v130, s[2:3]
	v_add_u32_e32 v130, s50, v135
	s_mov_b32 m0, s29
	s_add_i32 s49, s49, 0x160080
	global_load_lds_dwordx4 v130, s[2:3]
	v_add_u32_e32 v130, s49, v133
	s_mov_b32 m0, s35
	s_nop 0
	global_load_lds_dwordx4 v130, s[2:3]
	v_add_u32_e32 v130, s49, v135
	s_mov_b32 m0, s36
	s_nop 0
	global_load_lds_dwordx4 v130, s[2:3]
	v_add_u32_e32 v130, s48, v132
	s_mov_b32 m0, s30
	s_nop 0
	global_load_lds_dwordx4 v130, s[0:1]
	v_add_u32_e32 v130, s48, v134
	s_mov_b32 m0, s31
	s_nop 0
	global_load_lds_dwordx4 v130, s[0:1]
	s_add_i32 s47, s47, 2
	s_addk_i32 s45, 0x100
	s_addk_i32 s46, 0x100
	s_cmpk_gt_u32 s47, 0x55
	s_waitcnt vmcnt(8)
	s_waitcnt lgkmcnt(0)
	s_setprio 1
	s_barrier
	v_mfma_f32_16x16x32_bf16 v[62:65], v[142:145], v[174:177], v[62:65]
	v_mfma_f32_16x16x32_bf16 v[62:65], v[146:149], v[178:181], v[62:65]
	v_mfma_f32_16x16x32_bf16 v[58:61], v[154:157], v[178:181], v[58:61]
	v_mfma_f32_16x16x32_bf16 v[58:61], v[150:153], v[174:177], v[58:61]
	v_mfma_f32_16x16x32_bf16 v[46:49], v[150:153], v[182:185], v[46:49]
	v_mfma_f32_16x16x32_bf16 v[46:49], v[154:157], v[186:189], v[46:49]
	v_mfma_f32_16x16x32_bf16 v[54:57], v[146:149], v[186:189], v[54:57]
	v_mfma_f32_16x16x32_bf16 v[54:57], v[142:145], v[182:185], v[54:57]
	v_mfma_f32_16x16x32_bf16 v[38:41], v[142:145], v[190:193], v[38:41]
	v_mfma_f32_16x16x32_bf16 v[38:41], v[146:149], v[194:197], v[38:41]
	v_mfma_f32_16x16x32_bf16 v[30:33], v[154:157], v[194:197], v[30:33]
	v_mfma_f32_16x16x32_bf16 v[30:33], v[150:153], v[190:193], v[30:33]
	v_mfma_f32_16x16x32_bf16 v[14:17], v[150:153], v[198:201], v[14:17]
	v_mfma_f32_16x16x32_bf16 v[14:17], v[154:157], v[204:207], v[14:17]
	v_mfma_f32_16x16x32_bf16 v[22:25], v[146:149], v[204:207], v[22:25]
	v_mfma_f32_16x16x32_bf16 v[22:25], v[142:145], v[198:201], v[22:25]
	s_setprio 0
	s_setprio 1
	v_mfma_f32_16x16x32_bf16 v[6:9], v[158:161], v[198:201], v[6:9]
	v_mfma_f32_16x16x32_bf16 v[6:9], v[162:165], v[204:207], v[6:9]
	v_mfma_f32_16x16x32_bf16 v[2:5], v[170:173], v[204:207], v[2:5]
	v_mfma_f32_16x16x32_bf16 v[2:5], v[166:169], v[198:201], v[2:5]
	v_mfma_f32_16x16x32_bf16 v[10:13], v[166:169], v[190:193], v[10:13]
	v_mfma_f32_16x16x32_bf16 v[10:13], v[170:173], v[194:197], v[10:13]
	v_mfma_f32_16x16x32_bf16 v[18:21], v[162:165], v[194:197], v[18:21]
	v_mfma_f32_16x16x32_bf16 v[18:21], v[158:161], v[190:193], v[18:21]
	v_mfma_f32_16x16x32_bf16 v[34:37], v[158:161], v[182:185], v[34:37]
	v_mfma_f32_16x16x32_bf16 v[34:37], v[162:165], v[186:189], v[34:37]
	v_mfma_f32_16x16x32_bf16 v[26:29], v[170:173], v[186:189], v[26:29]
	v_mfma_f32_16x16x32_bf16 v[26:29], v[166:169], v[182:185], v[26:29]
	v_mfma_f32_16x16x32_bf16 v[42:45], v[166:169], v[174:177], v[42:45]
	v_mfma_f32_16x16x32_bf16 v[42:45], v[170:173], v[178:181], v[42:45]
	v_mfma_f32_16x16x32_bf16 v[50:53], v[162:165], v[178:181], v[50:53]
	v_mfma_f32_16x16x32_bf16 v[50:53], v[158:161], v[174:177], v[50:53]
	s_setprio 0
	s_barrier
	s_cbranch_scc0 .LBB0_784
	s_and_b64 vcc, exec, s[10:11]
	s_cbranch_vccz .LBB0_787
	s_barrier
